# GEMM K-loops: loop-edge rotation (next segment scalar setup moved into the previous load segment's wait shadow) + LDS fragment base addresses precomputed per unit, on top of the peeled first iteration
# baseline (speedup 1.0000x reference)
; #define PG8_STAGE(bufoff, gbase, voff) do { _Pragma("unroll") for (int _i = 0; _i < 2; ++_i) \
;         __builtin_amdgcn_global_load_lds((const unsigned*)((const char*)(gbase) + (voff)[_i]), (PG8_LAS unsigned*)(lds + (bufoff) + ldsw + _i * 8192), 16, 0, 0); } while (0)
; #define PG8_LDA(dst, b, h) do { _Pragma("unroll") for (int m = 0; m < 4; ++m) _Pragma("unroll") for (int k = 0; k < 2; ++k) dst[m][k] = *(const PG8_LAS bf16x8*)(lds + PG8_SA(b, h) + aoff + m * 2048 + k * 1024); } while (0)
; #define PG8_LDB(dst, b, h) do { _Pragma("unroll") for (int n = 0; n < 2; ++n) _Pragma("unroll") for (int k = 0; k < 2; ++k) dst[n][k] = *(const PG8_LAS bf16x8*)(lds + PG8_SB(b, h) + boff + n * 2048 + k * 1024); } while (0)
; #define PG8_MMA(ai, bj, At, Bt) do { __builtin_amdgcn_s_setprio(1); _Pragma("unroll") for (int m = 0; m < 4; ++m) _Pragma("unroll") for (int n = 0; n < 2; ++n) _Pragma("unroll") for (int k = 0; k < 2; ++k) \
;         acc[ai][bj][m][n] = __builtin_amdgcn_mfma_f32_16x16x32_bf16(Bt[n][k], At[m][k], acc[ai][bj][m][n], 0, 0, 0); __builtin_amdgcn_s_setprio(0); } while (0)
; template <class Epi, class Sched, bool ALIGN_EPI = false, bool SP2 = false>
; __device__ __forceinline__ void gemm_phase(PG8_LAS unsigned char* lds, const Gemm g, const Sched& S, const Epi& E, const int tid_in) {
;     ...
;     const unsigned ldsw = (unsigned)wid * 1024u;
;     const int aoff = lds_byte(wr * 64 + fr, fq * 8), boff = lds_byte(wc * 32 + fr, fq * 8);
;     ...
;             const bool last = (t == nt - 2);
;             const char* a1 = cA + (size_t)(t + 1) * kstep;
;             const char* a2 = last ? nA : cA + (size_t)(t + 2) * kstep; const char* b2 = last ? nB : cB + (size_t)(t + 2) * kstep;
;             const char* a3 = a2 + kstep; const char* b3 = b2 + kstep;
;             if (last && has_next) S.a_ready(nxt);
;             if constexpr (SP2) {
;             PG8_LDB(B0, 0, 0); PG8_LDB(B1, 0, 1); PG8_SCHED; PG8_LDA(At, 0, 0); PG8_STAGE(PG8_SA(1, 1), a1 + hstep, voffA);
;             PG8_WAIT_V(8); PG8_WAIT_L(0); PG8_BAR; PG8_MMA(0, 0, At, B0); PG8_MMA(0, 1, At, B1); PG8_BAR; PG8_SCHED;
;             PG8_LDA(At, 0, 1); PG8_STAGE(PG8_SB(0, 0), b2, voffB); PG8_STAGE(PG8_SB(0, 1), b2 + hstep, voffB); PG8_STAGE(PG8_SA(0, 0), a2, voffA);
;             PG8_WAIT_V(8); PG8_WAIT_L(0); PG8_BAR; PG8_MMA(1, 0, At, B0); PG8_MMA(1, 1, At, B1); PG8_BAR; PG8_SCHED;
.LBB0_351:
	s_ashr_i32 s27, s26, 31
	s_lshl_b64 s[28:29], s[26:27], 20
	s_add_u32 s28, s1, s28
	s_addc_u32 s29, s5, s29
	s_and_b64 s[30:31], s[36:37], exec
	s_cselect_b32 s27, s29, s35
	s_cselect_b32 s53, s28, s34
	s_ashr_i32 s25, s24, 31
	s_lshl_b64 s[30:31], s[24:25], 20
	s_add_u32 s30, s8, s30
	s_addc_u32 s31, s10, s31
	s_and_b64 s[42:43], s[36:37], exec
	s_cselect_b32 s25, s31, s39
	s_cselect_b32 s54, s30, s38
	s_add_u32 s34, s34, 0x80080
	s_addc_u32 s35, s35, 0
	s_add_u32 s55, s38, 0x100
	v_mov_b32_e32 v0, 0
	s_addc_u32 s56, s39, 0
	s_mov_b32 s57, -2
	v_add_u32_e32 v212, 0x10000, v142
	v_add_u32_e32 v213, 0x14000, v142
	v_add_u32_e32 v214, 0x18000, v142
	v_add_u32_e32 v215, 0x1c000, v142
	s_add_u32 s38, s34, 0xfff80080
	s_addc_u32 s39, s35, -1
	s_add_i32 s58, 0, 0x10000
	s_cmp_eq_u32 s57, 28
	s_cselect_b32 s43, s27, s39
	s_cselect_b32 s42, s53, s38
	s_cselect_b32 s39, s25, s56
	s_cselect_b32 s38, s54, s55
	s_add_i32 s60, 0, 0x14000
	s_mov_b32 m0, s49
	s_nop 0
	global_load_lds_dwordx4 v132, s[100:101]
	ds_read_b128 v[146:149], v212
	ds_read_b128 v[150:153], v212 offset:1024
	ds_read_b128 v[154:157], v212 offset:2048
	ds_read_b128 v[158:161], v212 offset:3072
	ds_read_b128 v[162:165], v213
	ds_read_b128 v[166:169], v213 offset:1024
	ds_read_b128 v[170:173], v213 offset:2048
	ds_read_b128 v[174:177], v213 offset:3072
	s_add_i32 m0, s44, 0xc000
	ds_read_b128 v[178:181], v144
	ds_read_b128 v[182:185], v144 offset:1024
	ds_read_b128 v[186:189], v144 offset:2048
	ds_read_b128 v[190:193], v144 offset:3072
	ds_read_b128 v[194:197], v144 offset:4096
	ds_read_b128 v[198:201], v144 offset:5120
	ds_read_b128 v[202:205], v144 offset:6144
	ds_read_b128 v[208:211], v144 offset:7168
	global_load_lds_dwordx4 v138, s[34:35]
	s_add_i32 m0, s44, 0xe000
	s_nop 0
	global_load_lds_dwordx4 v140, s[34:35]
	s_add_i32 s58, s58, s19
	s_add_u32 s98, s38, 0x80
	s_addc_u32 s99, s39, 0
	s_mov_b32 m0, s58
	s_waitcnt vmcnt(8)
	s_waitcnt lgkmcnt(0)
	s_barrier
	s_setprio 1
	v_mfma_f32_16x16x32_bf16 v[126:129], v[146:149], v[178:181], 0
	v_mfma_f32_16x16x32_bf16 v[122:125], v[154:157], v[178:181], 0
	v_mfma_f32_16x16x32_bf16 v[114:117], v[146:149], v[186:189], 0
	v_mfma_f32_16x16x32_bf16 v[106:109], v[154:157], v[186:189], 0
	v_mfma_f32_16x16x32_bf16 v[98:101], v[146:149], v[194:197], 0
	v_mfma_f32_16x16x32_bf16 v[90:93], v[154:157], v[194:197], 0
	v_mfma_f32_16x16x32_bf16 v[82:85], v[146:149], v[202:205], 0
	v_mfma_f32_16x16x32_bf16 v[74:77], v[154:157], v[202:205], 0
	v_mfma_f32_16x16x32_bf16 v[126:129], v[150:153], v[182:185], v[126:129]
	v_mfma_f32_16x16x32_bf16 v[122:125], v[158:161], v[182:185], v[122:125]
	v_mfma_f32_16x16x32_bf16 v[114:117], v[150:153], v[190:193], v[114:117]
	v_mfma_f32_16x16x32_bf16 v[106:109], v[158:161], v[190:193], v[106:109]
	v_mfma_f32_16x16x32_bf16 v[98:101], v[150:153], v[198:201], v[98:101]
	v_mfma_f32_16x16x32_bf16 v[90:93], v[158:161], v[198:201], v[90:93]
	v_mfma_f32_16x16x32_bf16 v[82:85], v[150:153], v[208:211], v[82:85]
	v_mfma_f32_16x16x32_bf16 v[74:77], v[158:161], v[208:211], v[74:77]
	s_setprio 0
	s_setprio 1
	v_mfma_f32_16x16x32_bf16 v[118:121], v[162:165], v[178:181], 0
	v_mfma_f32_16x16x32_bf16 v[110:113], v[170:173], v[178:181], 0
	v_mfma_f32_16x16x32_bf16 v[102:105], v[162:165], v[186:189], 0
	v_mfma_f32_16x16x32_bf16 v[94:97], v[170:173], v[186:189], 0
	v_mfma_f32_16x16x32_bf16 v[86:89], v[162:165], v[194:197], 0
	v_mfma_f32_16x16x32_bf16 v[78:81], v[170:173], v[194:197], 0
	v_mfma_f32_16x16x32_bf16 v[70:73], v[162:165], v[202:205], 0
	v_mfma_f32_16x16x32_bf16 v[66:69], v[170:173], v[202:205], 0
	v_mfma_f32_16x16x32_bf16 v[118:121], v[166:169], v[182:185], v[118:121]
	v_mfma_f32_16x16x32_bf16 v[110:113], v[174:177], v[182:185], v[110:113]
	v_mfma_f32_16x16x32_bf16 v[102:105], v[166:169], v[190:193], v[102:105]
	v_mfma_f32_16x16x32_bf16 v[94:97], v[174:177], v[190:193], v[94:97]
	v_mfma_f32_16x16x32_bf16 v[86:89], v[166:169], v[198:201], v[86:89]
	v_mfma_f32_16x16x32_bf16 v[78:81], v[174:177], v[198:201], v[78:81]
	v_mfma_f32_16x16x32_bf16 v[70:73], v[166:169], v[208:211], v[70:73]
	v_mfma_f32_16x16x32_bf16 v[66:69], v[174:177], v[208:211], v[66:69]
	s_setprio 0
	s_barrier
	ds_read_b128 v[178:181], v144 offset:16384
	ds_read_b128 v[182:185], v144 offset:17408
	ds_read_b128 v[186:189], v144 offset:18432
	ds_read_b128 v[190:193], v144 offset:19456
	ds_read_b128 v[194:197], v144 offset:20480
	ds_read_b128 v[198:201], v144 offset:21504
	ds_read_b128 v[202:205], v144 offset:22528
	ds_read_b128 v[208:211], v144 offset:23552
	global_load_lds_dwordx4 v134, s[38:39]
	s_add_i32 m0, s58, 0x2000
	s_add_u32 s58, s38, 0x80000
	s_addc_u32 s59, s39, 0
	s_add_i32 s60, s60, s19
	global_load_lds_dwordx4 v130, s[38:39]
	s_mov_b32 m0, s60
	s_add_u32 s100, s42, 0x80
	s_addc_u32 s101, s43, 0
	global_load_lds_dwordx4 v134, s[58:59]
	s_add_i32 m0, s60, 0x2000
	s_nop 0
	global_load_lds_dwordx4 v130, s[58:59]
	s_mov_b32 m0, s44
	s_nop 0
	global_load_lds_dwordx4 v136, s[42:43]
	s_add_i32 s58, 0, 0x18000
	s_add_i32 s59, 0, 0x1c000
	s_waitcnt vmcnt(7)
	s_waitcnt lgkmcnt(0)
	s_barrier
; #define PG8_STAGE(bufoff, gbase, voff) do { _Pragma("unroll") for (int _i = 0; _i < 2; ++_i) \
;         __builtin_amdgcn_global_load_lds((const unsigned*)((const char*)(gbase) + (voff)[_i]), (PG8_LAS unsigned*)(lds + (bufoff) + ldsw + _i * 8192), 16, 0, 0); } while (0)
; #define PG8_LDA(dst, b, h) do { _Pragma("unroll") for (int m = 0; m < 4; ++m) _Pragma("unroll") for (int k = 0; k < 2; ++k) dst[m][k] = *(const PG8_LAS bf16x8*)(lds + PG8_SA(b, h) + aoff + m * 2048 + k * 1024); } while (0)
; #define PG8_LDB(dst, b, h) do { _Pragma("unroll") for (int n = 0; n < 2; ++n) _Pragma("unroll") for (int k = 0; k < 2; ++k) dst[n][k] = *(const PG8_LAS bf16x8*)(lds + PG8_SB(b, h) + boff + n * 2048 + k * 1024); } while (0)
; #define PG8_MMA(ai, bj, At, Bt) do { __builtin_amdgcn_s_setprio(1); _Pragma("unroll") for (int m = 0; m < 4; ++m) _Pragma("unroll") for (int n = 0; n < 2; ++n) _Pragma("unroll") for (int k = 0; k < 2; ++k) \
;         acc[ai][bj][m][n] = __builtin_amdgcn_mfma_f32_16x16x32_bf16(Bt[n][k], At[m][k], acc[ai][bj][m][n], 0, 0, 0); __builtin_amdgcn_s_setprio(0); } while (0)
; #define PG8_WAIT_V(n) asm volatile("s_waitcnt vmcnt(" #n ")" ::: "memory")
; #define PG8_WAIT_L(n) asm volatile("s_waitcnt lgkmcnt(" #n ")" ::: "memory")
; #define PG8_BAR __builtin_amdgcn_s_barrier()
; #define PG8_SCHED __builtin_amdgcn_sched_barrier(0)
; template <class Epi, class Sched, bool ALIGN_EPI = false, bool SP2 = false>
; __device__ __forceinline__ void gemm_phase(PG8_LAS unsigned char* lds, const Gemm g, const Sched& S, const Epi& E, const int tid_in) {
;     ...
;             PG8_WAIT_V(8); PG8_WAIT_L(0); PG8_BAR; PG8_MMA(1, 0, At, B0); PG8_MMA(1, 1, At, B1); PG8_BAR; PG8_SCHED;
;             PG8_LDB(B0, 1, 0); PG8_LDB(B1, 1, 1); PG8_SCHED; PG8_LDA(At, 1, 0); PG8_STAGE(PG8_SA(0, 1), a2 + hstep, voffA);
;             PG8_WAIT_V(8); PG8_WAIT_L(0); PG8_BAR; PG8_MMA(0, 0, At, B0); PG8_MMA(0, 1, At, B1); PG8_BAR; PG8_SCHED;
	s_setprio 1
	v_mfma_f32_16x16x32_bf16 v[62:65], v[146:149], v[178:181], 0
	v_mfma_f32_16x16x32_bf16 v[58:61], v[154:157], v[178:181], 0
	v_mfma_f32_16x16x32_bf16 v[50:53], v[146:149], v[186:189], 0
	v_mfma_f32_16x16x32_bf16 v[42:45], v[154:157], v[186:189], 0
	v_mfma_f32_16x16x32_bf16 v[34:37], v[146:149], v[194:197], 0
	v_mfma_f32_16x16x32_bf16 v[26:29], v[154:157], v[194:197], 0
	v_mfma_f32_16x16x32_bf16 v[16:19], v[146:149], v[202:205], 0
	v_mfma_f32_16x16x32_bf16 v[8:11], v[154:157], v[202:205], 0
	v_mfma_f32_16x16x32_bf16 v[62:65], v[150:153], v[182:185], v[62:65]
	v_mfma_f32_16x16x32_bf16 v[58:61], v[158:161], v[182:185], v[58:61]
	v_mfma_f32_16x16x32_bf16 v[50:53], v[150:153], v[190:193], v[50:53]
	v_mfma_f32_16x16x32_bf16 v[42:45], v[158:161], v[190:193], v[42:45]
	v_mfma_f32_16x16x32_bf16 v[34:37], v[150:153], v[198:201], v[34:37]
	v_mfma_f32_16x16x32_bf16 v[26:29], v[158:161], v[198:201], v[26:29]
	v_mfma_f32_16x16x32_bf16 v[16:19], v[150:153], v[208:211], v[16:19]
	v_mfma_f32_16x16x32_bf16 v[8:11], v[158:161], v[208:211], v[8:11]
	s_setprio 0
	s_setprio 1
	v_mfma_f32_16x16x32_bf16 v[54:57], v[162:165], v[178:181], 0
	v_mfma_f32_16x16x32_bf16 v[46:49], v[170:173], v[178:181], 0
	v_mfma_f32_16x16x32_bf16 v[38:41], v[162:165], v[186:189], 0
	v_mfma_f32_16x16x32_bf16 v[30:33], v[170:173], v[186:189], 0
	v_mfma_f32_16x16x32_bf16 v[22:25], v[162:165], v[194:197], 0
	v_mfma_f32_16x16x32_bf16 v[12:15], v[170:173], v[194:197], 0
	v_mfma_f32_16x16x32_bf16 v[4:7], v[162:165], v[202:205], 0
	v_mfma_f32_16x16x32_bf16 v[0:3], v[170:173], v[202:205], 0
	v_mfma_f32_16x16x32_bf16 v[54:57], v[166:169], v[182:185], v[54:57]
	v_mfma_f32_16x16x32_bf16 v[46:49], v[174:177], v[182:185], v[46:49]
	v_mfma_f32_16x16x32_bf16 v[38:41], v[166:169], v[190:193], v[38:41]
	v_mfma_f32_16x16x32_bf16 v[30:33], v[174:177], v[190:193], v[30:33]
	v_mfma_f32_16x16x32_bf16 v[22:25], v[166:169], v[198:201], v[22:25]
	v_mfma_f32_16x16x32_bf16 v[12:15], v[174:177], v[198:201], v[12:15]
	v_mfma_f32_16x16x32_bf16 v[4:7], v[166:169], v[208:211], v[4:7]
	v_mfma_f32_16x16x32_bf16 v[0:3], v[174:177], v[208:211], v[0:3]
	s_setprio 0
	s_barrier
	ds_read_b128 v[146:149], v214
	ds_read_b128 v[150:153], v214 offset:1024
	ds_read_b128 v[154:157], v214 offset:2048
	ds_read_b128 v[158:161], v214 offset:3072
	ds_read_b128 v[162:165], v215
	ds_read_b128 v[166:169], v215 offset:1024
	ds_read_b128 v[170:173], v215 offset:2048
	ds_read_b128 v[174:177], v215 offset:3072
	s_mov_b32 m0, s45
	s_nop 0
	global_load_lds_dwordx4 v132, s[42:43]
	s_add_u32 s42, s42, 0x80000
	s_addc_u32 s43, s43, 0
	s_mov_b32 m0, s46
	ds_read_b128 v[178:181], v144 offset:32768
	ds_read_b128 v[182:185], v144 offset:33792
	ds_read_b128 v[186:189], v144 offset:34816
	ds_read_b128 v[190:193], v144 offset:35840
	ds_read_b128 v[194:197], v144 offset:36864
	ds_read_b128 v[198:201], v144 offset:37888
	ds_read_b128 v[202:205], v144 offset:38912
	ds_read_b128 v[208:211], v144 offset:39936
	global_load_lds_dwordx4 v136, s[42:43]
	s_mov_b32 m0, s47
	s_nop 0
	global_load_lds_dwordx4 v132, s[42:43]
	s_add_i32 s42, s58, s19
	s_mov_b32 m0, s42
	s_waitcnt vmcnt(8)
	s_waitcnt lgkmcnt(0)
	s_barrier
	s_setprio 1
	v_mfma_f32_16x16x32_bf16 v[126:129], v[146:149], v[178:181], v[126:129]
	v_mfma_f32_16x16x32_bf16 v[122:125], v[154:157], v[178:181], v[122:125]
	v_mfma_f32_16x16x32_bf16 v[114:117], v[146:149], v[186:189], v[114:117]
	v_mfma_f32_16x16x32_bf16 v[106:109], v[154:157], v[186:189], v[106:109]
	v_mfma_f32_16x16x32_bf16 v[98:101], v[146:149], v[194:197], v[98:101]
	v_mfma_f32_16x16x32_bf16 v[90:93], v[154:157], v[194:197], v[90:93]
	v_mfma_f32_16x16x32_bf16 v[82:85], v[146:149], v[202:205], v[82:85]
	v_mfma_f32_16x16x32_bf16 v[74:77], v[154:157], v[202:205], v[74:77]
	v_mfma_f32_16x16x32_bf16 v[126:129], v[150:153], v[182:185], v[126:129]
	v_mfma_f32_16x16x32_bf16 v[122:125], v[158:161], v[182:185], v[122:125]
	v_mfma_f32_16x16x32_bf16 v[114:117], v[150:153], v[190:193], v[114:117]
	v_mfma_f32_16x16x32_bf16 v[106:109], v[158:161], v[190:193], v[106:109]
	v_mfma_f32_16x16x32_bf16 v[98:101], v[150:153], v[198:201], v[98:101]
	v_mfma_f32_16x16x32_bf16 v[90:93], v[158:161], v[198:201], v[90:93]
	v_mfma_f32_16x16x32_bf16 v[82:85], v[150:153], v[208:211], v[82:85]
	v_mfma_f32_16x16x32_bf16 v[74:77], v[158:161], v[208:211], v[74:77]
	s_setprio 0
	s_setprio 1
	v_mfma_f32_16x16x32_bf16 v[118:121], v[162:165], v[178:181], v[118:121]
	v_mfma_f32_16x16x32_bf16 v[110:113], v[170:173], v[178:181], v[110:113]
	v_mfma_f32_16x16x32_bf16 v[102:105], v[162:165], v[186:189], v[102:105]
	v_mfma_f32_16x16x32_bf16 v[94:97], v[170:173], v[186:189], v[94:97]
	v_mfma_f32_16x16x32_bf16 v[86:89], v[162:165], v[194:197], v[86:89]
	v_mfma_f32_16x16x32_bf16 v[78:81], v[170:173], v[194:197], v[78:81]
	v_mfma_f32_16x16x32_bf16 v[70:73], v[162:165], v[202:205], v[70:73]
	v_mfma_f32_16x16x32_bf16 v[66:69], v[170:173], v[202:205], v[66:69]
	v_mfma_f32_16x16x32_bf16 v[118:121], v[166:169], v[182:185], v[118:121]
	v_mfma_f32_16x16x32_bf16 v[110:113], v[174:177], v[182:185], v[110:113]
	v_mfma_f32_16x16x32_bf16 v[102:105], v[166:169], v[190:193], v[102:105]
	v_mfma_f32_16x16x32_bf16 v[94:97], v[174:177], v[190:193], v[94:97]
	v_mfma_f32_16x16x32_bf16 v[86:89], v[166:169], v[198:201], v[86:89]
	v_mfma_f32_16x16x32_bf16 v[78:81], v[174:177], v[198:201], v[78:81]
	v_mfma_f32_16x16x32_bf16 v[70:73], v[166:169], v[208:211], v[70:73]
	v_mfma_f32_16x16x32_bf16 v[66:69], v[174:177], v[208:211], v[66:69]
	s_setprio 0
	s_barrier
; #define PG8_STAGE(bufoff, gbase, voff) do { _Pragma("unroll") for (int _i = 0; _i < 2; ++_i) \
;         __builtin_amdgcn_global_load_lds((const unsigned*)((const char*)(gbase) + (voff)[_i]), (PG8_LAS unsigned*)(lds + (bufoff) + ldsw + _i * 8192), 16, 0, 0); } while (0)
; #define PG8_LDA(dst, b, h) do { _Pragma("unroll") for (int m = 0; m < 4; ++m) _Pragma("unroll") for (int k = 0; k < 2; ++k) dst[m][k] = *(const PG8_LAS bf16x8*)(lds + PG8_SA(b, h) + aoff + m * 2048 + k * 1024); } while (0)
; #define PG8_LDB(dst, b, h) do { _Pragma("unroll") for (int n = 0; n < 2; ++n) _Pragma("unroll") for (int k = 0; k < 2; ++k) dst[n][k] = *(const PG8_LAS bf16x8*)(lds + PG8_SB(b, h) + boff + n * 2048 + k * 1024); } while (0)
; #define PG8_MMA(ai, bj, At, Bt) do { __builtin_amdgcn_s_setprio(1); _Pragma("unroll") for (int m = 0; m < 4; ++m) _Pragma("unroll") for (int n = 0; n < 2; ++n) _Pragma("unroll") for (int k = 0; k < 2; ++k) \
;         acc[ai][bj][m][n] = __builtin_amdgcn_mfma_f32_16x16x32_bf16(Bt[n][k], At[m][k], acc[ai][bj][m][n], 0, 0, 0); __builtin_amdgcn_s_setprio(0); } while (0)
; #define PG8_WAIT_V(n) asm volatile("s_waitcnt vmcnt(" #n ")" ::: "memory")
; #define PG8_BAR __builtin_amdgcn_s_barrier()
; template <class Epi, class Sched, bool ALIGN_EPI = false, bool SP2 = false>
; __device__ __forceinline__ void gemm_phase(PG8_LAS unsigned char* lds, const Gemm g, const Sched& S, const Epi& E, const int tid_in) {
;     ...
;         for (int t = 0; t < nt; t += 2) {
;             if constexpr (Epi::KSPLIT > 0) { if (t == Epi::KSPLIT / BK) E.midk(acc, cur, wr, wc, fr, fq); }
;             const bool last = (t == nt - 2);
;             const char* a1 = cA + (size_t)(t + 1) * kstep;
;             const char* a2 = last ? nA : cA + (size_t)(t + 2) * kstep; const char* b2 = last ? nB : cB + (size_t)(t + 2) * kstep;
;             const char* a3 = a2 + kstep; const char* b3 = b2 + kstep;
;             if (last && has_next) S.a_ready(nxt);
;             if constexpr (SP2) {
;             PG8_LDB(B0, 0, 0); PG8_LDB(B1, 0, 1); PG8_SCHED; PG8_LDA(At, 0, 0); PG8_STAGE(PG8_SA(1, 1), a1 + hstep, voffA);
;     ...
;             PG8_LDA(At, 1, 1); PG8_STAGE(PG8_SB(1, 0), b3, voffB); PG8_STAGE(PG8_SB(1, 1), b3 + hstep, voffB); PG8_STAGE(PG8_SA(1, 0), a3, voffA);
;             PG8_WAIT_V(8); PG8_WAIT_L(0); PG8_BAR; PG8_MMA(1, 0, At, B0); PG8_MMA(1, 1, At, B1); PG8_BAR; PG8_SCHED;
	ds_read_b128 v[178:181], v144 offset:49152
	ds_read_b128 v[182:185], v144 offset:50176
	ds_read_b128 v[186:189], v144 offset:51200
	ds_read_b128 v[190:193], v144 offset:52224
	ds_read_b128 v[194:197], v144 offset:53248
	ds_read_b128 v[198:201], v144 offset:54272
	ds_read_b128 v[202:205], v144 offset:55296
	ds_read_b128 v[208:211], v144 offset:56320
	global_load_lds_dwordx4 v134, s[98:99]
	s_add_i32 m0, s42, 0x2000
	s_add_u32 s38, s38, 0x80080
	s_addc_u32 s39, s39, 0
	s_add_i32 s42, s59, s19
	global_load_lds_dwordx4 v130, s[98:99]
	s_mov_b32 m0, s42
	s_nop 0
	global_load_lds_dwordx4 v134, s[38:39]
	s_add_i32 m0, s42, 0x2000
	s_nop 0
	global_load_lds_dwordx4 v130, s[38:39]
	s_mov_b32 m0, s48
	s_nop 0
	global_load_lds_dwordx4 v136, s[100:101]
	s_add_i32 s57, s57, 2
	s_add_u32 s34, s34, 0x100
	s_addc_u32 s35, s35, 0
	s_add_u32 s55, s55, 0x100
	s_addc_u32 s56, s56, 0
	s_add_u32 s38, s34, 0xfff80080
	s_addc_u32 s39, s35, -1
	s_add_i32 s58, 0, 0x10000
	s_cmp_eq_u32 s57, 28
	s_cselect_b32 s43, s27, s39
	s_cselect_b32 s42, s53, s38
	s_cselect_b32 s39, s25, s56
	s_cselect_b32 s38, s54, s55
	s_add_i32 s60, 0, 0x14000
	s_cmp_gt_u32 s57, 29
	s_waitcnt vmcnt(7)
	s_waitcnt lgkmcnt(0)
	s_barrier
	s_setprio 1
	v_mfma_f32_16x16x32_bf16 v[62:65], v[146:149], v[178:181], v[62:65]
	v_mfma_f32_16x16x32_bf16 v[58:61], v[154:157], v[178:181], v[58:61]
	v_mfma_f32_16x16x32_bf16 v[50:53], v[146:149], v[186:189], v[50:53]
	v_mfma_f32_16x16x32_bf16 v[42:45], v[154:157], v[186:189], v[42:45]
	v_mfma_f32_16x16x32_bf16 v[34:37], v[146:149], v[194:197], v[34:37]
	v_mfma_f32_16x16x32_bf16 v[26:29], v[154:157], v[194:197], v[26:29]
	v_mfma_f32_16x16x32_bf16 v[16:19], v[146:149], v[202:205], v[16:19]
	v_mfma_f32_16x16x32_bf16 v[8:11], v[154:157], v[202:205], v[8:11]
	v_mfma_f32_16x16x32_bf16 v[62:65], v[150:153], v[182:185], v[62:65]
	v_mfma_f32_16x16x32_bf16 v[58:61], v[158:161], v[182:185], v[58:61]
	v_mfma_f32_16x16x32_bf16 v[50:53], v[150:153], v[190:193], v[50:53]
	v_mfma_f32_16x16x32_bf16 v[42:45], v[158:161], v[190:193], v[42:45]
	v_mfma_f32_16x16x32_bf16 v[34:37], v[150:153], v[198:201], v[34:37]
	v_mfma_f32_16x16x32_bf16 v[26:29], v[158:161], v[198:201], v[26:29]
	v_mfma_f32_16x16x32_bf16 v[16:19], v[150:153], v[208:211], v[16:19]
	v_mfma_f32_16x16x32_bf16 v[8:11], v[158:161], v[208:211], v[8:11]
	s_setprio 0
	s_setprio 1
	v_mfma_f32_16x16x32_bf16 v[54:57], v[162:165], v[178:181], v[54:57]
	v_mfma_f32_16x16x32_bf16 v[46:49], v[170:173], v[178:181], v[46:49]
	v_mfma_f32_16x16x32_bf16 v[38:41], v[162:165], v[186:189], v[38:41]
	v_mfma_f32_16x16x32_bf16 v[30:33], v[170:173], v[186:189], v[30:33]
	v_mfma_f32_16x16x32_bf16 v[22:25], v[162:165], v[194:197], v[22:25]
	v_mfma_f32_16x16x32_bf16 v[12:15], v[170:173], v[194:197], v[12:15]
	v_mfma_f32_16x16x32_bf16 v[4:7], v[162:165], v[202:205], v[4:7]
	v_mfma_f32_16x16x32_bf16 v[0:3], v[170:173], v[202:205], v[0:3]
	v_mfma_f32_16x16x32_bf16 v[54:57], v[166:169], v[182:185], v[54:57]
	v_mfma_f32_16x16x32_bf16 v[46:49], v[174:177], v[182:185], v[46:49]
	v_mfma_f32_16x16x32_bf16 v[38:41], v[166:169], v[190:193], v[38:41]
	v_mfma_f32_16x16x32_bf16 v[30:33], v[174:177], v[190:193], v[30:33]
	v_mfma_f32_16x16x32_bf16 v[22:25], v[166:169], v[198:201], v[22:25]
	v_mfma_f32_16x16x32_bf16 v[12:15], v[174:177], v[198:201], v[12:15]
	v_mfma_f32_16x16x32_bf16 v[4:7], v[166:169], v[208:211], v[4:7]
	v_mfma_f32_16x16x32_bf16 v[0:3], v[174:177], v[208:211], v[0:3]
	s_setprio 0
	s_barrier
.LBB0_352:
	s_mov_b32 m0, s49
	s_nop 0
	global_load_lds_dwordx4 v132, s[100:101]
	ds_read_b128 v[146:149], v212
	ds_read_b128 v[150:153], v212 offset:1024
	ds_read_b128 v[154:157], v212 offset:2048
	ds_read_b128 v[158:161], v212 offset:3072
	ds_read_b128 v[162:165], v213
	ds_read_b128 v[166:169], v213 offset:1024
	ds_read_b128 v[170:173], v213 offset:2048
	ds_read_b128 v[174:177], v213 offset:3072
	s_add_i32 m0, s44, 0xc000
	ds_read_b128 v[178:181], v144
	ds_read_b128 v[182:185], v144 offset:1024
	ds_read_b128 v[186:189], v144 offset:2048
	ds_read_b128 v[190:193], v144 offset:3072
	ds_read_b128 v[194:197], v144 offset:4096
	ds_read_b128 v[198:201], v144 offset:5120
	ds_read_b128 v[202:205], v144 offset:6144
	ds_read_b128 v[208:211], v144 offset:7168
	global_load_lds_dwordx4 v138, s[34:35]
	s_add_i32 m0, s44, 0xe000
	s_nop 0
	global_load_lds_dwordx4 v140, s[34:35]
	s_add_i32 s58, s58, s19
	s_add_u32 s98, s38, 0x80
	s_addc_u32 s99, s39, 0
	s_mov_b32 m0, s58
	s_waitcnt vmcnt(8)
	s_waitcnt lgkmcnt(0)
	s_barrier
	s_setprio 1
	v_mfma_f32_16x16x32_bf16 v[126:129], v[146:149], v[178:181], v[126:129]
	v_mfma_f32_16x16x32_bf16 v[122:125], v[154:157], v[178:181], v[122:125]
	v_mfma_f32_16x16x32_bf16 v[114:117], v[146:149], v[186:189], v[114:117]
	v_mfma_f32_16x16x32_bf16 v[106:109], v[154:157], v[186:189], v[106:109]
	v_mfma_f32_16x16x32_bf16 v[98:101], v[146:149], v[194:197], v[98:101]
	v_mfma_f32_16x16x32_bf16 v[90:93], v[154:157], v[194:197], v[90:93]
	v_mfma_f32_16x16x32_bf16 v[82:85], v[146:149], v[202:205], v[82:85]
	v_mfma_f32_16x16x32_bf16 v[74:77], v[154:157], v[202:205], v[74:77]
	v_mfma_f32_16x16x32_bf16 v[126:129], v[150:153], v[182:185], v[126:129]
	v_mfma_f32_16x16x32_bf16 v[122:125], v[158:161], v[182:185], v[122:125]
	v_mfma_f32_16x16x32_bf16 v[114:117], v[150:153], v[190:193], v[114:117]
	v_mfma_f32_16x16x32_bf16 v[106:109], v[158:161], v[190:193], v[106:109]
	v_mfma_f32_16x16x32_bf16 v[98:101], v[150:153], v[198:201], v[98:101]
	v_mfma_f32_16x16x32_bf16 v[90:93], v[158:161], v[198:201], v[90:93]
	v_mfma_f32_16x16x32_bf16 v[82:85], v[150:153], v[208:211], v[82:85]
	v_mfma_f32_16x16x32_bf16 v[74:77], v[158:161], v[208:211], v[74:77]
	s_setprio 0
	s_setprio 1
	v_mfma_f32_16x16x32_bf16 v[118:121], v[162:165], v[178:181], v[118:121]
	v_mfma_f32_16x16x32_bf16 v[110:113], v[170:173], v[178:181], v[110:113]
	v_mfma_f32_16x16x32_bf16 v[102:105], v[162:165], v[186:189], v[102:105]
	v_mfma_f32_16x16x32_bf16 v[94:97], v[170:173], v[186:189], v[94:97]
	v_mfma_f32_16x16x32_bf16 v[86:89], v[162:165], v[194:197], v[86:89]
	v_mfma_f32_16x16x32_bf16 v[78:81], v[170:173], v[194:197], v[78:81]
	v_mfma_f32_16x16x32_bf16 v[70:73], v[162:165], v[202:205], v[70:73]
	v_mfma_f32_16x16x32_bf16 v[66:69], v[170:173], v[202:205], v[66:69]
	v_mfma_f32_16x16x32_bf16 v[118:121], v[166:169], v[182:185], v[118:121]
	v_mfma_f32_16x16x32_bf16 v[110:113], v[174:177], v[182:185], v[110:113]
	v_mfma_f32_16x16x32_bf16 v[102:105], v[166:169], v[190:193], v[102:105]
	v_mfma_f32_16x16x32_bf16 v[94:97], v[174:177], v[190:193], v[94:97]
	v_mfma_f32_16x16x32_bf16 v[86:89], v[166:169], v[198:201], v[86:89]
	v_mfma_f32_16x16x32_bf16 v[78:81], v[174:177], v[198:201], v[78:81]
	v_mfma_f32_16x16x32_bf16 v[70:73], v[166:169], v[208:211], v[70:73]
	v_mfma_f32_16x16x32_bf16 v[66:69], v[174:177], v[208:211], v[66:69]
	s_setprio 0
	s_barrier
; #define PG8_STAGE(bufoff, gbase, voff) do { _Pragma("unroll") for (int _i = 0; _i < 2; ++_i) \
;         __builtin_amdgcn_global_load_lds((const unsigned*)((const char*)(gbase) + (voff)[_i]), (PG8_LAS unsigned*)(lds + (bufoff) + ldsw + _i * 8192), 16, 0, 0); } while (0)
; #define PG8_LDA(dst, b, h) do { _Pragma("unroll") for (int m = 0; m < 4; ++m) _Pragma("unroll") for (int k = 0; k < 2; ++k) dst[m][k] = *(const PG8_LAS bf16x8*)(lds + PG8_SA(b, h) + aoff + m * 2048 + k * 1024); } while (0)
; #define PG8_LDB(dst, b, h) do { _Pragma("unroll") for (int n = 0; n < 2; ++n) _Pragma("unroll") for (int k = 0; k < 2; ++k) dst[n][k] = *(const PG8_LAS bf16x8*)(lds + PG8_SB(b, h) + boff + n * 2048 + k * 1024); } while (0)
; #define PG8_MMA(ai, bj, At, Bt) do { __builtin_amdgcn_s_setprio(1); _Pragma("unroll") for (int m = 0; m < 4; ++m) _Pragma("unroll") for (int n = 0; n < 2; ++n) _Pragma("unroll") for (int k = 0; k < 2; ++k) \
;         acc[ai][bj][m][n] = __builtin_amdgcn_mfma_f32_16x16x32_bf16(Bt[n][k], At[m][k], acc[ai][bj][m][n], 0, 0, 0); __builtin_amdgcn_s_setprio(0); } while (0)
; #define PG8_WAIT_V(n) asm volatile("s_waitcnt vmcnt(" #n ")" ::: "memory")
; #define PG8_WAIT_L(n) asm volatile("s_waitcnt lgkmcnt(" #n ")" ::: "memory")
; #define PG8_BAR __builtin_amdgcn_s_barrier()
; #define PG8_SCHED __builtin_amdgcn_sched_barrier(0)
; template <class Epi, class Sched, bool ALIGN_EPI = false, bool SP2 = false>
; __device__ __forceinline__ void gemm_phase(PG8_LAS unsigned char* lds, const Gemm g, const Sched& S, const Epi& E, const int tid_in) {
;     ...
;             PG8_WAIT_V(8); PG8_WAIT_L(0); PG8_BAR; PG8_MMA(1, 0, At, B0); PG8_MMA(1, 1, At, B1); PG8_BAR; PG8_SCHED;
;             PG8_LDB(B0, 1, 0); PG8_LDB(B1, 1, 1); PG8_SCHED; PG8_LDA(At, 1, 0); PG8_STAGE(PG8_SA(0, 1), a2 + hstep, voffA);
;             PG8_WAIT_V(8); PG8_WAIT_L(0); PG8_BAR; PG8_MMA(0, 0, At, B0); PG8_MMA(0, 1, At, B1); PG8_BAR; PG8_SCHED;
	ds_read_b128 v[178:181], v144 offset:16384
	ds_read_b128 v[182:185], v144 offset:17408
	ds_read_b128 v[186:189], v144 offset:18432
	ds_read_b128 v[190:193], v144 offset:19456
	ds_read_b128 v[194:197], v144 offset:20480
	ds_read_b128 v[198:201], v144 offset:21504
	ds_read_b128 v[202:205], v144 offset:22528
	ds_read_b128 v[208:211], v144 offset:23552
	global_load_lds_dwordx4 v134, s[38:39]
	s_add_i32 m0, s58, 0x2000
	s_add_u32 s58, s38, 0x80000
	s_addc_u32 s59, s39, 0
	s_add_i32 s60, s60, s19
	global_load_lds_dwordx4 v130, s[38:39]
	s_mov_b32 m0, s60
	s_add_u32 s100, s42, 0x80
	s_addc_u32 s101, s43, 0
	global_load_lds_dwordx4 v134, s[58:59]
	s_add_i32 m0, s60, 0x2000
	s_nop 0
	global_load_lds_dwordx4 v130, s[58:59]
	s_mov_b32 m0, s44
	s_nop 0
	global_load_lds_dwordx4 v136, s[42:43]
	s_add_i32 s58, 0, 0x18000
	s_add_i32 s59, 0, 0x1c000
	s_waitcnt vmcnt(7)
	s_waitcnt lgkmcnt(0)
	s_barrier
	s_setprio 1
	v_mfma_f32_16x16x32_bf16 v[62:65], v[146:149], v[178:181], v[62:65]
	v_mfma_f32_16x16x32_bf16 v[58:61], v[154:157], v[178:181], v[58:61]
	v_mfma_f32_16x16x32_bf16 v[50:53], v[146:149], v[186:189], v[50:53]
	v_mfma_f32_16x16x32_bf16 v[42:45], v[154:157], v[186:189], v[42:45]
	v_mfma_f32_16x16x32_bf16 v[34:37], v[146:149], v[194:197], v[34:37]
	v_mfma_f32_16x16x32_bf16 v[26:29], v[154:157], v[194:197], v[26:29]
	v_mfma_f32_16x16x32_bf16 v[16:19], v[146:149], v[202:205], v[16:19]
	v_mfma_f32_16x16x32_bf16 v[8:11], v[154:157], v[202:205], v[8:11]
	v_mfma_f32_16x16x32_bf16 v[62:65], v[150:153], v[182:185], v[62:65]
	v_mfma_f32_16x16x32_bf16 v[58:61], v[158:161], v[182:185], v[58:61]
	v_mfma_f32_16x16x32_bf16 v[50:53], v[150:153], v[190:193], v[50:53]
	v_mfma_f32_16x16x32_bf16 v[42:45], v[158:161], v[190:193], v[42:45]
	v_mfma_f32_16x16x32_bf16 v[34:37], v[150:153], v[198:201], v[34:37]
	v_mfma_f32_16x16x32_bf16 v[26:29], v[158:161], v[198:201], v[26:29]
	v_mfma_f32_16x16x32_bf16 v[16:19], v[150:153], v[208:211], v[16:19]
	v_mfma_f32_16x16x32_bf16 v[8:11], v[158:161], v[208:211], v[8:11]
	s_setprio 0
	s_setprio 1
	v_mfma_f32_16x16x32_bf16 v[54:57], v[162:165], v[178:181], v[54:57]
	v_mfma_f32_16x16x32_bf16 v[46:49], v[170:173], v[178:181], v[46:49]
	v_mfma_f32_16x16x32_bf16 v[38:41], v[162:165], v[186:189], v[38:41]
	v_mfma_f32_16x16x32_bf16 v[30:33], v[170:173], v[186:189], v[30:33]
	v_mfma_f32_16x16x32_bf16 v[22:25], v[162:165], v[194:197], v[22:25]
	v_mfma_f32_16x16x32_bf16 v[12:15], v[170:173], v[194:197], v[12:15]
	v_mfma_f32_16x16x32_bf16 v[4:7], v[162:165], v[202:205], v[4:7]
	v_mfma_f32_16x16x32_bf16 v[0:3], v[170:173], v[202:205], v[0:3]
	v_mfma_f32_16x16x32_bf16 v[54:57], v[166:169], v[182:185], v[54:57]
	v_mfma_f32_16x16x32_bf16 v[46:49], v[174:177], v[182:185], v[46:49]
	v_mfma_f32_16x16x32_bf16 v[38:41], v[166:169], v[190:193], v[38:41]
	v_mfma_f32_16x16x32_bf16 v[30:33], v[174:177], v[190:193], v[30:33]
	v_mfma_f32_16x16x32_bf16 v[22:25], v[166:169], v[198:201], v[22:25]
	v_mfma_f32_16x16x32_bf16 v[12:15], v[174:177], v[198:201], v[12:15]
	v_mfma_f32_16x16x32_bf16 v[4:7], v[166:169], v[208:211], v[4:7]
	v_mfma_f32_16x16x32_bf16 v[0:3], v[174:177], v[208:211], v[0:3]
	s_setprio 0
	s_barrier
	ds_read_b128 v[146:149], v214
	ds_read_b128 v[150:153], v214 offset:1024
	ds_read_b128 v[154:157], v214 offset:2048
	ds_read_b128 v[158:161], v214 offset:3072
	ds_read_b128 v[162:165], v215
	ds_read_b128 v[166:169], v215 offset:1024
	ds_read_b128 v[170:173], v215 offset:2048
	ds_read_b128 v[174:177], v215 offset:3072
	s_mov_b32 m0, s45
	s_nop 0
	global_load_lds_dwordx4 v132, s[42:43]
	s_add_u32 s42, s42, 0x80000
	s_addc_u32 s43, s43, 0
	s_mov_b32 m0, s46
	ds_read_b128 v[178:181], v144 offset:32768
	ds_read_b128 v[182:185], v144 offset:33792
	ds_read_b128 v[186:189], v144 offset:34816
	ds_read_b128 v[190:193], v144 offset:35840
	ds_read_b128 v[194:197], v144 offset:36864
	ds_read_b128 v[198:201], v144 offset:37888
	ds_read_b128 v[202:205], v144 offset:38912
	ds_read_b128 v[208:211], v144 offset:39936
	global_load_lds_dwordx4 v136, s[42:43]
	s_mov_b32 m0, s47
	s_nop 0
	global_load_lds_dwordx4 v132, s[42:43]
	s_add_i32 s42, s58, s19
	s_mov_b32 m0, s42
	s_waitcnt vmcnt(8)
	s_waitcnt lgkmcnt(0)
	s_barrier
; #define PG8_STAGE(bufoff, gbase, voff) do { _Pragma("unroll") for (int _i = 0; _i < 2; ++_i) \
;         __builtin_amdgcn_global_load_lds((const unsigned*)((const char*)(gbase) + (voff)[_i]), (PG8_LAS unsigned*)(lds + (bufoff) + ldsw + _i * 8192), 16, 0, 0); } while (0)
; #define PG8_LDA(dst, b, h) do { _Pragma("unroll") for (int m = 0; m < 4; ++m) _Pragma("unroll") for (int k = 0; k < 2; ++k) dst[m][k] = *(const PG8_LAS bf16x8*)(lds + PG8_SA(b, h) + aoff + m * 2048 + k * 1024); } while (0)
; #define PG8_MMA(ai, bj, At, Bt) do { __builtin_amdgcn_s_setprio(1); _Pragma("unroll") for (int m = 0; m < 4; ++m) _Pragma("unroll") for (int n = 0; n < 2; ++n) _Pragma("unroll") for (int k = 0; k < 2; ++k) \
;         acc[ai][bj][m][n] = __builtin_amdgcn_mfma_f32_16x16x32_bf16(Bt[n][k], At[m][k], acc[ai][bj][m][n], 0, 0, 0); __builtin_amdgcn_s_setprio(0); } while (0)
; #define PG8_WAIT_V(n) asm volatile("s_waitcnt vmcnt(" #n ")" ::: "memory")
; #define PG8_WAIT_L(n) asm volatile("s_waitcnt lgkmcnt(" #n ")" ::: "memory")
; #define PG8_BAR __builtin_amdgcn_s_barrier()
; #define PG8_SCHED __builtin_amdgcn_sched_barrier(0)
; template <class Epi, class Sched, bool ALIGN_EPI = false, bool SP2 = false>
; __device__ __forceinline__ void gemm_phase(PG8_LAS unsigned char* lds, const Gemm g, const Sched& S, const Epi& E, const int tid_in) {
;     ...
;         for (int t = 0; t < nt; t += 2) {
;     ...
;             PG8_LDA(At, 1, 1); PG8_STAGE(PG8_SB(1, 0), b3, voffB); PG8_STAGE(PG8_SB(1, 1), b3 + hstep, voffB); PG8_STAGE(PG8_SA(1, 0), a3, voffA);
;             PG8_WAIT_V(8); PG8_WAIT_L(0); PG8_BAR; PG8_MMA(1, 0, At, B0); PG8_MMA(1, 1, At, B1); PG8_BAR; PG8_SCHED;
	s_setprio 1
	v_mfma_f32_16x16x32_bf16 v[126:129], v[146:149], v[178:181], v[126:129]
	v_mfma_f32_16x16x32_bf16 v[122:125], v[154:157], v[178:181], v[122:125]
	v_mfma_f32_16x16x32_bf16 v[114:117], v[146:149], v[186:189], v[114:117]
	v_mfma_f32_16x16x32_bf16 v[106:109], v[154:157], v[186:189], v[106:109]
	v_mfma_f32_16x16x32_bf16 v[98:101], v[146:149], v[194:197], v[98:101]
	v_mfma_f32_16x16x32_bf16 v[90:93], v[154:157], v[194:197], v[90:93]
	v_mfma_f32_16x16x32_bf16 v[82:85], v[146:149], v[202:205], v[82:85]
	v_mfma_f32_16x16x32_bf16 v[74:77], v[154:157], v[202:205], v[74:77]
	v_mfma_f32_16x16x32_bf16 v[126:129], v[150:153], v[182:185], v[126:129]
	v_mfma_f32_16x16x32_bf16 v[122:125], v[158:161], v[182:185], v[122:125]
	v_mfma_f32_16x16x32_bf16 v[114:117], v[150:153], v[190:193], v[114:117]
	v_mfma_f32_16x16x32_bf16 v[106:109], v[158:161], v[190:193], v[106:109]
	v_mfma_f32_16x16x32_bf16 v[98:101], v[150:153], v[198:201], v[98:101]
	v_mfma_f32_16x16x32_bf16 v[90:93], v[158:161], v[198:201], v[90:93]
	v_mfma_f32_16x16x32_bf16 v[82:85], v[150:153], v[208:211], v[82:85]
	v_mfma_f32_16x16x32_bf16 v[74:77], v[158:161], v[208:211], v[74:77]
	s_setprio 0
	s_setprio 1
	v_mfma_f32_16x16x32_bf16 v[118:121], v[162:165], v[178:181], v[118:121]
	v_mfma_f32_16x16x32_bf16 v[110:113], v[170:173], v[178:181], v[110:113]
	v_mfma_f32_16x16x32_bf16 v[102:105], v[162:165], v[186:189], v[102:105]
	v_mfma_f32_16x16x32_bf16 v[94:97], v[170:173], v[186:189], v[94:97]
	v_mfma_f32_16x16x32_bf16 v[86:89], v[162:165], v[194:197], v[86:89]
	v_mfma_f32_16x16x32_bf16 v[78:81], v[170:173], v[194:197], v[78:81]
	v_mfma_f32_16x16x32_bf16 v[70:73], v[162:165], v[202:205], v[70:73]
	v_mfma_f32_16x16x32_bf16 v[66:69], v[170:173], v[202:205], v[66:69]
	v_mfma_f32_16x16x32_bf16 v[118:121], v[166:169], v[182:185], v[118:121]
	v_mfma_f32_16x16x32_bf16 v[110:113], v[174:177], v[182:185], v[110:113]
	v_mfma_f32_16x16x32_bf16 v[102:105], v[166:169], v[190:193], v[102:105]
	v_mfma_f32_16x16x32_bf16 v[94:97], v[174:177], v[190:193], v[94:97]
	v_mfma_f32_16x16x32_bf16 v[86:89], v[166:169], v[198:201], v[86:89]
	v_mfma_f32_16x16x32_bf16 v[78:81], v[174:177], v[198:201], v[78:81]
	v_mfma_f32_16x16x32_bf16 v[70:73], v[166:169], v[208:211], v[70:73]
	v_mfma_f32_16x16x32_bf16 v[66:69], v[174:177], v[208:211], v[66:69]
	s_setprio 0
	s_barrier
	ds_read_b128 v[178:181], v144 offset:49152
	ds_read_b128 v[182:185], v144 offset:50176
	ds_read_b128 v[186:189], v144 offset:51200
	ds_read_b128 v[190:193], v144 offset:52224
	ds_read_b128 v[194:197], v144 offset:53248
	ds_read_b128 v[198:201], v144 offset:54272
	ds_read_b128 v[202:205], v144 offset:55296
	ds_read_b128 v[208:211], v144 offset:56320
	global_load_lds_dwordx4 v134, s[98:99]
	s_add_i32 m0, s42, 0x2000
	s_add_u32 s38, s38, 0x80080
	s_addc_u32 s39, s39, 0
	s_add_i32 s42, s59, s19
	global_load_lds_dwordx4 v130, s[98:99]
	s_mov_b32 m0, s42
	s_nop 0
	global_load_lds_dwordx4 v134, s[38:39]
	s_add_i32 m0, s42, 0x2000
	s_nop 0
	global_load_lds_dwordx4 v130, s[38:39]
	s_mov_b32 m0, s48
	s_nop 0
	global_load_lds_dwordx4 v136, s[100:101]
	s_add_i32 s57, s57, 2
	s_add_u32 s34, s34, 0x100
	s_addc_u32 s35, s35, 0
	s_add_u32 s55, s55, 0x100
	s_addc_u32 s56, s56, 0
	s_add_u32 s38, s34, 0xfff80080
	s_addc_u32 s39, s35, -1
	s_add_i32 s58, 0, 0x10000
	s_cmp_eq_u32 s57, 28
	s_cselect_b32 s43, s27, s39
	s_cselect_b32 s42, s53, s38
	s_cselect_b32 s39, s25, s56
	s_cselect_b32 s38, s54, s55
	s_add_i32 s60, 0, 0x14000
	s_cmp_gt_u32 s57, 29
	s_waitcnt vmcnt(7)
	s_waitcnt lgkmcnt(0)
	s_barrier
	s_setprio 1
	v_mfma_f32_16x16x32_bf16 v[62:65], v[146:149], v[178:181], v[62:65]
	v_mfma_f32_16x16x32_bf16 v[58:61], v[154:157], v[178:181], v[58:61]
	v_mfma_f32_16x16x32_bf16 v[50:53], v[146:149], v[186:189], v[50:53]
	v_mfma_f32_16x16x32_bf16 v[42:45], v[154:157], v[186:189], v[42:45]
	v_mfma_f32_16x16x32_bf16 v[34:37], v[146:149], v[194:197], v[34:37]
	v_mfma_f32_16x16x32_bf16 v[26:29], v[154:157], v[194:197], v[26:29]
	v_mfma_f32_16x16x32_bf16 v[16:19], v[146:149], v[202:205], v[16:19]
	v_mfma_f32_16x16x32_bf16 v[8:11], v[154:157], v[202:205], v[8:11]
	v_mfma_f32_16x16x32_bf16 v[62:65], v[150:153], v[182:185], v[62:65]
	v_mfma_f32_16x16x32_bf16 v[58:61], v[158:161], v[182:185], v[58:61]
	v_mfma_f32_16x16x32_bf16 v[50:53], v[150:153], v[190:193], v[50:53]
	v_mfma_f32_16x16x32_bf16 v[42:45], v[158:161], v[190:193], v[42:45]
	v_mfma_f32_16x16x32_bf16 v[34:37], v[150:153], v[198:201], v[34:37]
	v_mfma_f32_16x16x32_bf16 v[26:29], v[158:161], v[198:201], v[26:29]
	v_mfma_f32_16x16x32_bf16 v[16:19], v[150:153], v[208:211], v[16:19]
	v_mfma_f32_16x16x32_bf16 v[8:11], v[158:161], v[208:211], v[8:11]
	s_setprio 0
	s_setprio 1
	v_mfma_f32_16x16x32_bf16 v[54:57], v[162:165], v[178:181], v[54:57]
	v_mfma_f32_16x16x32_bf16 v[46:49], v[170:173], v[178:181], v[46:49]
	v_mfma_f32_16x16x32_bf16 v[38:41], v[162:165], v[186:189], v[38:41]
	v_mfma_f32_16x16x32_bf16 v[30:33], v[170:173], v[186:189], v[30:33]
	v_mfma_f32_16x16x32_bf16 v[22:25], v[162:165], v[194:197], v[22:25]
	v_mfma_f32_16x16x32_bf16 v[12:15], v[170:173], v[194:197], v[12:15]
	v_mfma_f32_16x16x32_bf16 v[4:7], v[162:165], v[202:205], v[4:7]
	v_mfma_f32_16x16x32_bf16 v[0:3], v[170:173], v[202:205], v[0:3]
	v_mfma_f32_16x16x32_bf16 v[54:57], v[166:169], v[182:185], v[54:57]
	v_mfma_f32_16x16x32_bf16 v[46:49], v[174:177], v[182:185], v[46:49]
	v_mfma_f32_16x16x32_bf16 v[38:41], v[166:169], v[190:193], v[38:41]
	v_mfma_f32_16x16x32_bf16 v[30:33], v[174:177], v[190:193], v[30:33]
	v_mfma_f32_16x16x32_bf16 v[22:25], v[166:169], v[198:201], v[22:25]
	v_mfma_f32_16x16x32_bf16 v[12:15], v[174:177], v[198:201], v[12:15]
	v_mfma_f32_16x16x32_bf16 v[4:7], v[166:169], v[208:211], v[4:7]
	v_mfma_f32_16x16x32_bf16 v[0:3], v[174:177], v[208:211], v[0:3]
	s_setprio 0
	s_barrier
	s_cbranch_scc0 .LBB0_352
	s_and_b64 vcc, exec, s[22:23]
	s_cbranch_vccz .LBB0_355
	s_barrier

; #define PG8_STAGE(bufoff, gbase, voff) do { _Pragma("unroll") for (int _i = 0; _i < 2; ++_i) \
;         __builtin_amdgcn_global_load_lds((const unsigned*)((const char*)(gbase) + (voff)[_i]), (PG8_LAS unsigned*)(lds + (bufoff) + ldsw + _i * 8192), 16, 0, 0); } while (0)
; #define PG8_LDA(dst, b, h) do { _Pragma("unroll") for (int m = 0; m < 4; ++m) _Pragma("unroll") for (int k = 0; k < 2; ++k) dst[m][k] = *(const PG8_LAS bf16x8*)(lds + PG8_SA(b, h) + aoff + m * 2048 + k * 1024); } while (0)
; #define PG8_LDB(dst, b, h) do { _Pragma("unroll") for (int n = 0; n < 2; ++n) _Pragma("unroll") for (int k = 0; k < 2; ++k) dst[n][k] = *(const PG8_LAS bf16x8*)(lds + PG8_SB(b, h) + boff + n * 2048 + k * 1024); } while (0)
; #define PG8_MMA(ai, bj, At, Bt) do { __builtin_amdgcn_s_setprio(1); _Pragma("unroll") for (int m = 0; m < 4; ++m) _Pragma("unroll") for (int n = 0; n < 2; ++n) _Pragma("unroll") for (int k = 0; k < 2; ++k) \
;         acc[ai][bj][m][n] = __builtin_amdgcn_mfma_f32_16x16x32_bf16(Bt[n][k], At[m][k], acc[ai][bj][m][n], 0, 0, 0); __builtin_amdgcn_s_setprio(0); } while (0)
; template <class Epi, class Sched, bool ALIGN_EPI = false, bool SP2 = false>
; __device__ __forceinline__ void gemm_phase(PG8_LAS unsigned char* lds, const Gemm g, const Sched& S, const Epi& E, const int tid_in) {
;     ...
;     const unsigned ldsw = (unsigned)wid * 1024u;
;     const int aoff = lds_byte(wr * 64 + fr, fq * 8), boff = lds_byte(wc * 32 + fr, fq * 8);
;     ...
;             const bool last = (t == nt - 2);
;             const char* a1 = cA + (size_t)(t + 1) * kstep;
;             const char* a2 = last ? nA : cA + (size_t)(t + 2) * kstep; const char* b2 = last ? nB : cB + (size_t)(t + 2) * kstep;
;             const char* a3 = a2 + kstep; const char* b3 = b2 + kstep;
;             if (last && has_next) S.a_ready(nxt);
;             if constexpr (SP2) {
;             PG8_LDB(B0, 0, 0); PG8_LDB(B1, 0, 1); PG8_SCHED; PG8_LDA(At, 0, 0); PG8_STAGE(PG8_SA(1, 1), a1 + hstep, voffA);
;             PG8_WAIT_V(8); PG8_WAIT_L(0); PG8_BAR; PG8_MMA(0, 0, At, B0); PG8_MMA(0, 1, At, B1); PG8_BAR; PG8_SCHED;
;             PG8_LDA(At, 0, 1); PG8_STAGE(PG8_SB(0, 0), b2, voffB); PG8_STAGE(PG8_SB(0, 1), b2 + hstep, voffB); PG8_STAGE(PG8_SA(0, 0), a2, voffA);
;             PG8_WAIT_V(8); PG8_WAIT_L(0); PG8_BAR; PG8_MMA(1, 0, At, B0); PG8_MMA(1, 1, At, B1); PG8_BAR; PG8_SCHED;
.LBB0_373:
	s_ashr_i32 s25, s24, 31
	s_lshl_b64 s[26:27], s[24:25], 20
	s_add_u32 s26, s1, s26
	s_addc_u32 s27, s5, s27
	s_and_b64 s[28:29], s[36:37], exec
	s_cselect_b32 s21, s27, s35
	s_cselect_b32 s25, s26, s34
	s_ashr_i32 s23, s22, 31
	s_lshl_b64 s[28:29], s[22:23], 20
	s_add_u32 s28, s8, s28
	s_addc_u32 s29, s10, s29
	s_and_b64 s[42:43], s[36:37], exec
	s_cselect_b32 s23, s29, s39
	s_cselect_b32 s51, s28, s38
	s_add_u32 s34, s34, 0x80080
	s_addc_u32 s35, s35, 0
	s_add_u32 s52, s38, 0x100
	v_mov_b32_e32 v0, 0
	s_addc_u32 s53, s39, 0
	s_mov_b32 s54, -2
	v_add_u32_e32 v216, 0x10000, v21
	v_add_u32_e32 v217, 0x14000, v21
	v_add_u32_e32 v218, 0x18000, v21
	v_add_u32_e32 v219, 0x1c000, v21
	s_add_u32 s38, s34, 0xfff80080
	s_addc_u32 s39, s35, -1
	s_add_i32 s55, 0, 0x10000
	s_cmp_eq_u32 s54, 28
	s_cselect_b32 s43, s21, s39
	s_cselect_b32 s42, s25, s38
	s_cselect_b32 s39, s23, s53
	s_cselect_b32 s38, s51, s52
	s_add_i32 s58, 0, 0x14000
	s_mov_b32 m0, s49
	s_nop 0
	global_load_lds_dwordx4 v134, s[100:101]
	ds_read_b128 v[148:151], v216
	ds_read_b128 v[152:155], v216 offset:1024
	ds_read_b128 v[156:159], v216 offset:2048
	ds_read_b128 v[160:163], v216 offset:3072
	ds_read_b128 v[164:167], v217
	ds_read_b128 v[168:171], v217 offset:1024
	ds_read_b128 v[172:175], v217 offset:2048
	ds_read_b128 v[176:179], v217 offset:3072
	s_add_i32 m0, s44, 0xc000
	ds_read_b128 v[180:183], v147
	ds_read_b128 v[184:187], v147 offset:1024
	ds_read_b128 v[188:191], v147 offset:2048
	ds_read_b128 v[192:195], v147 offset:3072
	ds_read_b128 v[196:199], v147 offset:4096
	ds_read_b128 v[200:203], v147 offset:5120
	ds_read_b128 v[208:211], v147 offset:6144
	ds_read_b128 v[212:215], v147 offset:7168
	global_load_lds_dwordx4 v140, s[34:35]
	s_add_i32 m0, s44, 0xe000
	s_nop 0
	global_load_lds_dwordx4 v142, s[34:35]
	s_add_i32 s55, s55, s19
	s_add_u32 s98, s38, 0x80
	s_addc_u32 s99, s39, 0
	s_mov_b32 m0, s55
	s_waitcnt vmcnt(8)
	s_waitcnt lgkmcnt(0)
	s_barrier
	s_setprio 1
	v_mfma_f32_16x16x32_bf16 v[126:129], v[148:151], v[180:183], 0
	v_mfma_f32_16x16x32_bf16 v[122:125], v[156:159], v[180:183], 0
	v_mfma_f32_16x16x32_bf16 v[118:121], v[148:151], v[188:191], 0
	v_mfma_f32_16x16x32_bf16 v[110:113], v[156:159], v[188:191], 0
	v_mfma_f32_16x16x32_bf16 v[102:105], v[148:151], v[196:199], 0
	v_mfma_f32_16x16x32_bf16 v[94:97], v[156:159], v[196:199], 0
	v_mfma_f32_16x16x32_bf16 v[86:89], v[148:151], v[208:211], 0
	v_mfma_f32_16x16x32_bf16 v[78:81], v[156:159], v[208:211], 0
	v_mfma_f32_16x16x32_bf16 v[126:129], v[152:155], v[184:187], v[126:129]
	v_mfma_f32_16x16x32_bf16 v[122:125], v[160:163], v[184:187], v[122:125]
	v_mfma_f32_16x16x32_bf16 v[118:121], v[152:155], v[192:195], v[118:121]
	v_mfma_f32_16x16x32_bf16 v[110:113], v[160:163], v[192:195], v[110:113]
	v_mfma_f32_16x16x32_bf16 v[102:105], v[152:155], v[200:203], v[102:105]
	v_mfma_f32_16x16x32_bf16 v[94:97], v[160:163], v[200:203], v[94:97]
	v_mfma_f32_16x16x32_bf16 v[86:89], v[152:155], v[212:215], v[86:89]
	v_mfma_f32_16x16x32_bf16 v[78:81], v[160:163], v[212:215], v[78:81]
	s_setprio 0
	s_setprio 1
	v_mfma_f32_16x16x32_bf16 v[114:117], v[164:167], v[180:183], 0
	v_mfma_f32_16x16x32_bf16 v[106:109], v[172:175], v[180:183], 0
	v_mfma_f32_16x16x32_bf16 v[98:101], v[164:167], v[188:191], 0
	v_mfma_f32_16x16x32_bf16 v[90:93], v[172:175], v[188:191], 0
	v_mfma_f32_16x16x32_bf16 v[82:85], v[164:167], v[196:199], 0
	v_mfma_f32_16x16x32_bf16 v[74:77], v[172:175], v[196:199], 0
	v_mfma_f32_16x16x32_bf16 v[70:73], v[164:167], v[208:211], 0
	v_mfma_f32_16x16x32_bf16 v[66:69], v[172:175], v[208:211], 0
	v_mfma_f32_16x16x32_bf16 v[114:117], v[168:171], v[184:187], v[114:117]
	v_mfma_f32_16x16x32_bf16 v[106:109], v[176:179], v[184:187], v[106:109]
	v_mfma_f32_16x16x32_bf16 v[98:101], v[168:171], v[192:195], v[98:101]
	v_mfma_f32_16x16x32_bf16 v[90:93], v[176:179], v[192:195], v[90:93]
	v_mfma_f32_16x16x32_bf16 v[82:85], v[168:171], v[200:203], v[82:85]
	v_mfma_f32_16x16x32_bf16 v[74:77], v[176:179], v[200:203], v[74:77]
	v_mfma_f32_16x16x32_bf16 v[70:73], v[168:171], v[212:215], v[70:73]
	v_mfma_f32_16x16x32_bf16 v[66:69], v[176:179], v[212:215], v[66:69]
	s_setprio 0
	s_barrier
	ds_read_b128 v[180:183], v147 offset:16384
	ds_read_b128 v[184:187], v147 offset:17408
	ds_read_b128 v[188:191], v147 offset:18432
	ds_read_b128 v[192:195], v147 offset:19456
	ds_read_b128 v[196:199], v147 offset:20480
	ds_read_b128 v[200:203], v147 offset:21504
	ds_read_b128 v[208:211], v147 offset:22528
	ds_read_b128 v[212:215], v147 offset:23552
	global_load_lds_dwordx4 v132, s[38:39]
	s_add_i32 m0, s55, 0x2000
	s_add_u32 s56, s38, 0x80000
	s_addc_u32 s57, s39, 0
	s_add_i32 s55, s58, s19
	global_load_lds_dwordx4 v136, s[38:39]
	s_mov_b32 m0, s55
	s_add_u32 s100, s42, 0x80
	s_addc_u32 s101, s43, 0
	global_load_lds_dwordx4 v132, s[56:57]
	s_add_i32 m0, s55, 0x2000
	s_nop 0
	global_load_lds_dwordx4 v136, s[56:57]
	s_mov_b32 m0, s44
	s_nop 0
	global_load_lds_dwordx4 v130, s[42:43]
	s_add_i32 s55, 0, 0x18000
	s_add_i32 s56, 0, 0x1c000
	s_waitcnt vmcnt(7)
	s_waitcnt lgkmcnt(0)
	s_barrier
; #define PG8_STAGE(bufoff, gbase, voff) do { _Pragma("unroll") for (int _i = 0; _i < 2; ++_i) \
;         __builtin_amdgcn_global_load_lds((const unsigned*)((const char*)(gbase) + (voff)[_i]), (PG8_LAS unsigned*)(lds + (bufoff) + ldsw + _i * 8192), 16, 0, 0); } while (0)
; #define PG8_LDA(dst, b, h) do { _Pragma("unroll") for (int m = 0; m < 4; ++m) _Pragma("unroll") for (int k = 0; k < 2; ++k) dst[m][k] = *(const PG8_LAS bf16x8*)(lds + PG8_SA(b, h) + aoff + m * 2048 + k * 1024); } while (0)
; #define PG8_LDB(dst, b, h) do { _Pragma("unroll") for (int n = 0; n < 2; ++n) _Pragma("unroll") for (int k = 0; k < 2; ++k) dst[n][k] = *(const PG8_LAS bf16x8*)(lds + PG8_SB(b, h) + boff + n * 2048 + k * 1024); } while (0)
; #define PG8_MMA(ai, bj, At, Bt) do { __builtin_amdgcn_s_setprio(1); _Pragma("unroll") for (int m = 0; m < 4; ++m) _Pragma("unroll") for (int n = 0; n < 2; ++n) _Pragma("unroll") for (int k = 0; k < 2; ++k) \
;         acc[ai][bj][m][n] = __builtin_amdgcn_mfma_f32_16x16x32_bf16(Bt[n][k], At[m][k], acc[ai][bj][m][n], 0, 0, 0); __builtin_amdgcn_s_setprio(0); } while (0)
; #define PG8_WAIT_V(n) asm volatile("s_waitcnt vmcnt(" #n ")" ::: "memory")
; #define PG8_WAIT_L(n) asm volatile("s_waitcnt lgkmcnt(" #n ")" ::: "memory")
; #define PG8_BAR __builtin_amdgcn_s_barrier()
; #define PG8_SCHED __builtin_amdgcn_sched_barrier(0)
; template <class Epi, class Sched, bool ALIGN_EPI = false, bool SP2 = false>
; __device__ __forceinline__ void gemm_phase(PG8_LAS unsigned char* lds, const Gemm g, const Sched& S, const Epi& E, const int tid_in) {
;     ...
;             PG8_WAIT_V(8); PG8_WAIT_L(0); PG8_BAR; PG8_MMA(1, 0, At, B0); PG8_MMA(1, 1, At, B1); PG8_BAR; PG8_SCHED;
;             PG8_LDB(B0, 1, 0); PG8_LDB(B1, 1, 1); PG8_SCHED; PG8_LDA(At, 1, 0); PG8_STAGE(PG8_SA(0, 1), a2 + hstep, voffA);
;             PG8_WAIT_V(8); PG8_WAIT_L(0); PG8_BAR; PG8_MMA(0, 0, At, B0); PG8_MMA(0, 1, At, B1); PG8_BAR; PG8_SCHED;
	s_setprio 1
	v_mfma_f32_16x16x32_bf16 v[62:65], v[148:151], v[180:183], 0
	v_mfma_f32_16x16x32_bf16 v[58:61], v[156:159], v[180:183], 0
	v_mfma_f32_16x16x32_bf16 v[54:57], v[148:151], v[188:191], 0
	v_mfma_f32_16x16x32_bf16 v[46:49], v[156:159], v[188:191], 0
	v_mfma_f32_16x16x32_bf16 v[38:41], v[148:151], v[196:199], 0
	v_mfma_f32_16x16x32_bf16 v[30:33], v[156:159], v[196:199], 0
	v_mfma_f32_16x16x32_bf16 v[22:25], v[148:151], v[208:211], 0
	v_mfma_f32_16x16x32_bf16 v[12:15], v[156:159], v[208:211], 0
	v_mfma_f32_16x16x32_bf16 v[62:65], v[152:155], v[184:187], v[62:65]
	v_mfma_f32_16x16x32_bf16 v[58:61], v[160:163], v[184:187], v[58:61]
	v_mfma_f32_16x16x32_bf16 v[54:57], v[152:155], v[192:195], v[54:57]
	v_mfma_f32_16x16x32_bf16 v[46:49], v[160:163], v[192:195], v[46:49]
	v_mfma_f32_16x16x32_bf16 v[38:41], v[152:155], v[200:203], v[38:41]
	v_mfma_f32_16x16x32_bf16 v[30:33], v[160:163], v[200:203], v[30:33]
	v_mfma_f32_16x16x32_bf16 v[22:25], v[152:155], v[212:215], v[22:25]
	v_mfma_f32_16x16x32_bf16 v[12:15], v[160:163], v[212:215], v[12:15]
	s_setprio 0
	s_setprio 1
	v_mfma_f32_16x16x32_bf16 v[50:53], v[164:167], v[180:183], 0
	v_mfma_f32_16x16x32_bf16 v[42:45], v[172:175], v[180:183], 0
	v_mfma_f32_16x16x32_bf16 v[34:37], v[164:167], v[188:191], 0
	v_mfma_f32_16x16x32_bf16 v[26:29], v[172:175], v[188:191], 0
	v_mfma_f32_16x16x32_bf16 v[16:19], v[164:167], v[196:199], 0
	v_mfma_f32_16x16x32_bf16 v[8:11], v[172:175], v[196:199], 0
	v_mfma_f32_16x16x32_bf16 v[4:7], v[164:167], v[208:211], 0
	v_mfma_f32_16x16x32_bf16 v[0:3], v[172:175], v[208:211], 0
	v_mfma_f32_16x16x32_bf16 v[50:53], v[168:171], v[184:187], v[50:53]
	v_mfma_f32_16x16x32_bf16 v[42:45], v[176:179], v[184:187], v[42:45]
	v_mfma_f32_16x16x32_bf16 v[34:37], v[168:171], v[192:195], v[34:37]
	v_mfma_f32_16x16x32_bf16 v[26:29], v[176:179], v[192:195], v[26:29]
	v_mfma_f32_16x16x32_bf16 v[16:19], v[168:171], v[200:203], v[16:19]
	v_mfma_f32_16x16x32_bf16 v[8:11], v[176:179], v[200:203], v[8:11]
	v_mfma_f32_16x16x32_bf16 v[4:7], v[168:171], v[212:215], v[4:7]
	v_mfma_f32_16x16x32_bf16 v[0:3], v[176:179], v[212:215], v[0:3]
	s_setprio 0
	s_barrier
	ds_read_b128 v[148:151], v218
	ds_read_b128 v[152:155], v218 offset:1024
	ds_read_b128 v[156:159], v218 offset:2048
	ds_read_b128 v[160:163], v218 offset:3072
	ds_read_b128 v[164:167], v219
	ds_read_b128 v[168:171], v219 offset:1024
	ds_read_b128 v[172:175], v219 offset:2048
	ds_read_b128 v[176:179], v219 offset:3072
	s_mov_b32 m0, s45
	s_nop 0
	global_load_lds_dwordx4 v134, s[42:43]
	s_add_u32 s42, s42, 0x80000
	s_addc_u32 s43, s43, 0
	s_mov_b32 m0, s46
	ds_read_b128 v[180:183], v147 offset:32768
	ds_read_b128 v[184:187], v147 offset:33792
	ds_read_b128 v[188:191], v147 offset:34816
	ds_read_b128 v[192:195], v147 offset:35840
	ds_read_b128 v[196:199], v147 offset:36864
	ds_read_b128 v[200:203], v147 offset:37888
	ds_read_b128 v[208:211], v147 offset:38912
	ds_read_b128 v[212:215], v147 offset:39936
	global_load_lds_dwordx4 v130, s[42:43]
	s_mov_b32 m0, s47
	s_nop 0
	global_load_lds_dwordx4 v134, s[42:43]
	s_add_i32 s42, s55, s19
	s_mov_b32 m0, s42
	s_waitcnt vmcnt(8)
	s_waitcnt lgkmcnt(0)
	s_barrier
	s_setprio 1
	v_mfma_f32_16x16x32_bf16 v[126:129], v[148:151], v[180:183], v[126:129]
	v_mfma_f32_16x16x32_bf16 v[122:125], v[156:159], v[180:183], v[122:125]
	v_mfma_f32_16x16x32_bf16 v[118:121], v[148:151], v[188:191], v[118:121]
	v_mfma_f32_16x16x32_bf16 v[110:113], v[156:159], v[188:191], v[110:113]
	v_mfma_f32_16x16x32_bf16 v[102:105], v[148:151], v[196:199], v[102:105]
	v_mfma_f32_16x16x32_bf16 v[94:97], v[156:159], v[196:199], v[94:97]
	v_mfma_f32_16x16x32_bf16 v[86:89], v[148:151], v[208:211], v[86:89]
	v_mfma_f32_16x16x32_bf16 v[78:81], v[156:159], v[208:211], v[78:81]
	v_mfma_f32_16x16x32_bf16 v[126:129], v[152:155], v[184:187], v[126:129]
	v_mfma_f32_16x16x32_bf16 v[122:125], v[160:163], v[184:187], v[122:125]
	v_mfma_f32_16x16x32_bf16 v[118:121], v[152:155], v[192:195], v[118:121]
	v_mfma_f32_16x16x32_bf16 v[110:113], v[160:163], v[192:195], v[110:113]
	v_mfma_f32_16x16x32_bf16 v[102:105], v[152:155], v[200:203], v[102:105]
	v_mfma_f32_16x16x32_bf16 v[94:97], v[160:163], v[200:203], v[94:97]
	v_mfma_f32_16x16x32_bf16 v[86:89], v[152:155], v[212:215], v[86:89]
	v_mfma_f32_16x16x32_bf16 v[78:81], v[160:163], v[212:215], v[78:81]
	s_setprio 0
	s_setprio 1
	v_mfma_f32_16x16x32_bf16 v[114:117], v[164:167], v[180:183], v[114:117]
	v_mfma_f32_16x16x32_bf16 v[106:109], v[172:175], v[180:183], v[106:109]
	v_mfma_f32_16x16x32_bf16 v[98:101], v[164:167], v[188:191], v[98:101]
	v_mfma_f32_16x16x32_bf16 v[90:93], v[172:175], v[188:191], v[90:93]
	v_mfma_f32_16x16x32_bf16 v[82:85], v[164:167], v[196:199], v[82:85]
	v_mfma_f32_16x16x32_bf16 v[74:77], v[172:175], v[196:199], v[74:77]
	v_mfma_f32_16x16x32_bf16 v[70:73], v[164:167], v[208:211], v[70:73]
	v_mfma_f32_16x16x32_bf16 v[66:69], v[172:175], v[208:211], v[66:69]
	v_mfma_f32_16x16x32_bf16 v[114:117], v[168:171], v[184:187], v[114:117]
	v_mfma_f32_16x16x32_bf16 v[106:109], v[176:179], v[184:187], v[106:109]
	v_mfma_f32_16x16x32_bf16 v[98:101], v[168:171], v[192:195], v[98:101]
	v_mfma_f32_16x16x32_bf16 v[90:93], v[176:179], v[192:195], v[90:93]
	v_mfma_f32_16x16x32_bf16 v[82:85], v[168:171], v[200:203], v[82:85]
	v_mfma_f32_16x16x32_bf16 v[74:77], v[176:179], v[200:203], v[74:77]
	v_mfma_f32_16x16x32_bf16 v[70:73], v[168:171], v[212:215], v[70:73]
	v_mfma_f32_16x16x32_bf16 v[66:69], v[176:179], v[212:215], v[66:69]
	s_setprio 0
	s_barrier
; #define PG8_STAGE(bufoff, gbase, voff) do { _Pragma("unroll") for (int _i = 0; _i < 2; ++_i) \
;         __builtin_amdgcn_global_load_lds((const unsigned*)((const char*)(gbase) + (voff)[_i]), (PG8_LAS unsigned*)(lds + (bufoff) + ldsw + _i * 8192), 16, 0, 0); } while (0)
; #define PG8_LDA(dst, b, h) do { _Pragma("unroll") for (int m = 0; m < 4; ++m) _Pragma("unroll") for (int k = 0; k < 2; ++k) dst[m][k] = *(const PG8_LAS bf16x8*)(lds + PG8_SA(b, h) + aoff + m * 2048 + k * 1024); } while (0)
; #define PG8_LDB(dst, b, h) do { _Pragma("unroll") for (int n = 0; n < 2; ++n) _Pragma("unroll") for (int k = 0; k < 2; ++k) dst[n][k] = *(const PG8_LAS bf16x8*)(lds + PG8_SB(b, h) + boff + n * 2048 + k * 1024); } while (0)
; #define PG8_MMA(ai, bj, At, Bt) do { __builtin_amdgcn_s_setprio(1); _Pragma("unroll") for (int m = 0; m < 4; ++m) _Pragma("unroll") for (int n = 0; n < 2; ++n) _Pragma("unroll") for (int k = 0; k < 2; ++k) \
;         acc[ai][bj][m][n] = __builtin_amdgcn_mfma_f32_16x16x32_bf16(Bt[n][k], At[m][k], acc[ai][bj][m][n], 0, 0, 0); __builtin_amdgcn_s_setprio(0); } while (0)
; #define PG8_BAR __builtin_amdgcn_s_barrier()
; template <class Epi, class Sched, bool ALIGN_EPI = false, bool SP2 = false>
; __device__ __forceinline__ void gemm_phase(PG8_LAS unsigned char* lds, const Gemm g, const Sched& S, const Epi& E, const int tid_in) {
;     ...
;             PG8_LDB(B0, 0, 0); PG8_LDB(B1, 0, 1); PG8_SCHED; PG8_LDA(At, 0, 0); PG8_STAGE(PG8_SA(1, 1), a1 + hstep, voffA);
;             PG8_WAIT_V(8); PG8_WAIT_L(0); PG8_BAR; PG8_MMA(0, 0, At, B0); PG8_MMA(0, 1, At, B1); PG8_BAR; PG8_SCHED;
;             PG8_LDA(At, 0, 1); PG8_STAGE(PG8_SB(0, 0), b2, voffB); PG8_STAGE(PG8_SB(0, 1), b2 + hstep, voffB); PG8_STAGE(PG8_SA(0, 0), a2, voffA);
;             PG8_WAIT_V(8); PG8_WAIT_L(0); PG8_BAR; PG8_MMA(1, 0, At, B0); PG8_MMA(1, 1, At, B1); PG8_BAR; PG8_SCHED;
;             PG8_LDB(B0, 1, 0); PG8_LDB(B1, 1, 1); PG8_SCHED; PG8_LDA(At, 1, 0); PG8_STAGE(PG8_SA(0, 1), a2 + hstep, voffA);
;             PG8_WAIT_V(8); PG8_WAIT_L(0); PG8_BAR; PG8_MMA(0, 0, At, B0); PG8_MMA(0, 1, At, B1); PG8_BAR; PG8_SCHED;
;             PG8_LDA(At, 1, 1); PG8_STAGE(PG8_SB(1, 0), b3, voffB); PG8_STAGE(PG8_SB(1, 1), b3 + hstep, voffB); PG8_STAGE(PG8_SA(1, 0), a3, voffA);
;             PG8_WAIT_V(8); PG8_WAIT_L(0); PG8_BAR; PG8_MMA(1, 0, At, B0); PG8_MMA(1, 1, At, B1); PG8_BAR; PG8_SCHED;
	ds_read_b128 v[180:183], v147 offset:49152
	ds_read_b128 v[184:187], v147 offset:50176
	ds_read_b128 v[188:191], v147 offset:51200
	ds_read_b128 v[192:195], v147 offset:52224
	ds_read_b128 v[196:199], v147 offset:53248
	ds_read_b128 v[200:203], v147 offset:54272
	ds_read_b128 v[208:211], v147 offset:55296
	ds_read_b128 v[212:215], v147 offset:56320
	global_load_lds_dwordx4 v132, s[98:99]
	s_add_i32 m0, s42, 0x2000
	s_add_u32 s38, s38, 0x80080
	s_addc_u32 s39, s39, 0
	s_add_i32 s42, s56, s19
	global_load_lds_dwordx4 v136, s[98:99]
	s_mov_b32 m0, s42
	s_nop 0
	global_load_lds_dwordx4 v132, s[38:39]
	s_add_i32 m0, s42, 0x2000
	s_nop 0
	global_load_lds_dwordx4 v136, s[38:39]
	s_mov_b32 m0, s48
	s_nop 0
	global_load_lds_dwordx4 v130, s[100:101]
	s_add_i32 s54, s54, 2
	s_add_u32 s34, s34, 0x100
	s_addc_u32 s35, s35, 0
	s_add_u32 s52, s52, 0x100
	s_addc_u32 s53, s53, 0
	s_add_u32 s38, s34, 0xfff80080
	s_addc_u32 s39, s35, -1
	s_add_i32 s55, 0, 0x10000
	s_cmp_eq_u32 s54, 28
	s_cselect_b32 s43, s21, s39
	s_cselect_b32 s42, s25, s38
	s_cselect_b32 s39, s23, s53
	s_cselect_b32 s38, s51, s52
	s_add_i32 s58, 0, 0x14000
	s_cmp_gt_u32 s54, 29
	s_waitcnt vmcnt(7)
	s_waitcnt lgkmcnt(0)
	s_barrier
	s_setprio 1
	v_mfma_f32_16x16x32_bf16 v[62:65], v[148:151], v[180:183], v[62:65]
	v_mfma_f32_16x16x32_bf16 v[58:61], v[156:159], v[180:183], v[58:61]
	v_mfma_f32_16x16x32_bf16 v[54:57], v[148:151], v[188:191], v[54:57]
	v_mfma_f32_16x16x32_bf16 v[46:49], v[156:159], v[188:191], v[46:49]
	v_mfma_f32_16x16x32_bf16 v[38:41], v[148:151], v[196:199], v[38:41]
	v_mfma_f32_16x16x32_bf16 v[30:33], v[156:159], v[196:199], v[30:33]
	v_mfma_f32_16x16x32_bf16 v[22:25], v[148:151], v[208:211], v[22:25]
	v_mfma_f32_16x16x32_bf16 v[12:15], v[156:159], v[208:211], v[12:15]
	v_mfma_f32_16x16x32_bf16 v[62:65], v[152:155], v[184:187], v[62:65]
	v_mfma_f32_16x16x32_bf16 v[58:61], v[160:163], v[184:187], v[58:61]
	v_mfma_f32_16x16x32_bf16 v[54:57], v[152:155], v[192:195], v[54:57]
	v_mfma_f32_16x16x32_bf16 v[46:49], v[160:163], v[192:195], v[46:49]
	v_mfma_f32_16x16x32_bf16 v[38:41], v[152:155], v[200:203], v[38:41]
	v_mfma_f32_16x16x32_bf16 v[30:33], v[160:163], v[200:203], v[30:33]
	v_mfma_f32_16x16x32_bf16 v[22:25], v[152:155], v[212:215], v[22:25]
	v_mfma_f32_16x16x32_bf16 v[12:15], v[160:163], v[212:215], v[12:15]
	s_setprio 0
	s_setprio 1
	v_mfma_f32_16x16x32_bf16 v[50:53], v[164:167], v[180:183], v[50:53]
	v_mfma_f32_16x16x32_bf16 v[42:45], v[172:175], v[180:183], v[42:45]
	v_mfma_f32_16x16x32_bf16 v[34:37], v[164:167], v[188:191], v[34:37]
	v_mfma_f32_16x16x32_bf16 v[26:29], v[172:175], v[188:191], v[26:29]
	v_mfma_f32_16x16x32_bf16 v[16:19], v[164:167], v[196:199], v[16:19]
	v_mfma_f32_16x16x32_bf16 v[8:11], v[172:175], v[196:199], v[8:11]
	v_mfma_f32_16x16x32_bf16 v[4:7], v[164:167], v[208:211], v[4:7]
	v_mfma_f32_16x16x32_bf16 v[0:3], v[172:175], v[208:211], v[0:3]
	v_mfma_f32_16x16x32_bf16 v[50:53], v[168:171], v[184:187], v[50:53]
	v_mfma_f32_16x16x32_bf16 v[42:45], v[176:179], v[184:187], v[42:45]
	v_mfma_f32_16x16x32_bf16 v[34:37], v[168:171], v[192:195], v[34:37]
	v_mfma_f32_16x16x32_bf16 v[26:29], v[176:179], v[192:195], v[26:29]
	v_mfma_f32_16x16x32_bf16 v[16:19], v[168:171], v[200:203], v[16:19]
	v_mfma_f32_16x16x32_bf16 v[8:11], v[176:179], v[200:203], v[8:11]
	v_mfma_f32_16x16x32_bf16 v[4:7], v[168:171], v[212:215], v[4:7]
	v_mfma_f32_16x16x32_bf16 v[0:3], v[176:179], v[212:215], v[0:3]
	s_setprio 0
	s_barrier
.LBB0_374:
	s_mov_b32 m0, s49
	s_nop 0
	global_load_lds_dwordx4 v134, s[100:101]
	ds_read_b128 v[148:151], v216
	ds_read_b128 v[152:155], v216 offset:1024
	ds_read_b128 v[156:159], v216 offset:2048
	ds_read_b128 v[160:163], v216 offset:3072
	ds_read_b128 v[164:167], v217
	ds_read_b128 v[168:171], v217 offset:1024
	ds_read_b128 v[172:175], v217 offset:2048
	ds_read_b128 v[176:179], v217 offset:3072
	s_add_i32 m0, s44, 0xc000
	ds_read_b128 v[180:183], v147
	ds_read_b128 v[184:187], v147 offset:1024
	ds_read_b128 v[188:191], v147 offset:2048
	ds_read_b128 v[192:195], v147 offset:3072
	ds_read_b128 v[196:199], v147 offset:4096
	ds_read_b128 v[200:203], v147 offset:5120
	ds_read_b128 v[208:211], v147 offset:6144
	ds_read_b128 v[212:215], v147 offset:7168
	global_load_lds_dwordx4 v140, s[34:35]
	s_add_i32 m0, s44, 0xe000
	s_nop 0
	global_load_lds_dwordx4 v142, s[34:35]
	s_add_i32 s55, s55, s19
	s_add_u32 s98, s38, 0x80
	s_addc_u32 s99, s39, 0
	s_mov_b32 m0, s55
	s_waitcnt vmcnt(8)
	s_waitcnt lgkmcnt(0)
	s_barrier
	s_setprio 1
	v_mfma_f32_16x16x32_bf16 v[126:129], v[148:151], v[180:183], v[126:129]
	v_mfma_f32_16x16x32_bf16 v[122:125], v[156:159], v[180:183], v[122:125]
	v_mfma_f32_16x16x32_bf16 v[118:121], v[148:151], v[188:191], v[118:121]
	v_mfma_f32_16x16x32_bf16 v[110:113], v[156:159], v[188:191], v[110:113]
	v_mfma_f32_16x16x32_bf16 v[102:105], v[148:151], v[196:199], v[102:105]
	v_mfma_f32_16x16x32_bf16 v[94:97], v[156:159], v[196:199], v[94:97]
	v_mfma_f32_16x16x32_bf16 v[86:89], v[148:151], v[208:211], v[86:89]
	v_mfma_f32_16x16x32_bf16 v[78:81], v[156:159], v[208:211], v[78:81]
	v_mfma_f32_16x16x32_bf16 v[126:129], v[152:155], v[184:187], v[126:129]
	v_mfma_f32_16x16x32_bf16 v[122:125], v[160:163], v[184:187], v[122:125]
	v_mfma_f32_16x16x32_bf16 v[118:121], v[152:155], v[192:195], v[118:121]
	v_mfma_f32_16x16x32_bf16 v[110:113], v[160:163], v[192:195], v[110:113]
	v_mfma_f32_16x16x32_bf16 v[102:105], v[152:155], v[200:203], v[102:105]
	v_mfma_f32_16x16x32_bf16 v[94:97], v[160:163], v[200:203], v[94:97]
	v_mfma_f32_16x16x32_bf16 v[86:89], v[152:155], v[212:215], v[86:89]
	v_mfma_f32_16x16x32_bf16 v[78:81], v[160:163], v[212:215], v[78:81]
	s_setprio 0
	s_setprio 1
	v_mfma_f32_16x16x32_bf16 v[114:117], v[164:167], v[180:183], v[114:117]
	v_mfma_f32_16x16x32_bf16 v[106:109], v[172:175], v[180:183], v[106:109]
	v_mfma_f32_16x16x32_bf16 v[98:101], v[164:167], v[188:191], v[98:101]
	v_mfma_f32_16x16x32_bf16 v[90:93], v[172:175], v[188:191], v[90:93]
	v_mfma_f32_16x16x32_bf16 v[82:85], v[164:167], v[196:199], v[82:85]
	v_mfma_f32_16x16x32_bf16 v[74:77], v[172:175], v[196:199], v[74:77]
	v_mfma_f32_16x16x32_bf16 v[70:73], v[164:167], v[208:211], v[70:73]
	v_mfma_f32_16x16x32_bf16 v[66:69], v[172:175], v[208:211], v[66:69]
	v_mfma_f32_16x16x32_bf16 v[114:117], v[168:171], v[184:187], v[114:117]
	v_mfma_f32_16x16x32_bf16 v[106:109], v[176:179], v[184:187], v[106:109]
	v_mfma_f32_16x16x32_bf16 v[98:101], v[168:171], v[192:195], v[98:101]
	v_mfma_f32_16x16x32_bf16 v[90:93], v[176:179], v[192:195], v[90:93]
	v_mfma_f32_16x16x32_bf16 v[82:85], v[168:171], v[200:203], v[82:85]
	v_mfma_f32_16x16x32_bf16 v[74:77], v[176:179], v[200:203], v[74:77]
	v_mfma_f32_16x16x32_bf16 v[70:73], v[168:171], v[212:215], v[70:73]
	v_mfma_f32_16x16x32_bf16 v[66:69], v[176:179], v[212:215], v[66:69]
	s_setprio 0
	s_barrier
; #define PG8_STAGE(bufoff, gbase, voff) do { _Pragma("unroll") for (int _i = 0; _i < 2; ++_i) \
;         __builtin_amdgcn_global_load_lds((const unsigned*)((const char*)(gbase) + (voff)[_i]), (PG8_LAS unsigned*)(lds + (bufoff) + ldsw + _i * 8192), 16, 0, 0); } while (0)
; #define PG8_LDA(dst, b, h) do { _Pragma("unroll") for (int m = 0; m < 4; ++m) _Pragma("unroll") for (int k = 0; k < 2; ++k) dst[m][k] = *(const PG8_LAS bf16x8*)(lds + PG8_SA(b, h) + aoff + m * 2048 + k * 1024); } while (0)
; #define PG8_LDB(dst, b, h) do { _Pragma("unroll") for (int n = 0; n < 2; ++n) _Pragma("unroll") for (int k = 0; k < 2; ++k) dst[n][k] = *(const PG8_LAS bf16x8*)(lds + PG8_SB(b, h) + boff + n * 2048 + k * 1024); } while (0)
; #define PG8_MMA(ai, bj, At, Bt) do { __builtin_amdgcn_s_setprio(1); _Pragma("unroll") for (int m = 0; m < 4; ++m) _Pragma("unroll") for (int n = 0; n < 2; ++n) _Pragma("unroll") for (int k = 0; k < 2; ++k) \
;         acc[ai][bj][m][n] = __builtin_amdgcn_mfma_f32_16x16x32_bf16(Bt[n][k], At[m][k], acc[ai][bj][m][n], 0, 0, 0); __builtin_amdgcn_s_setprio(0); } while (0)
; #define PG8_WAIT_V(n) asm volatile("s_waitcnt vmcnt(" #n ")" ::: "memory")
; #define PG8_WAIT_L(n) asm volatile("s_waitcnt lgkmcnt(" #n ")" ::: "memory")
; #define PG8_BAR __builtin_amdgcn_s_barrier()
; #define PG8_SCHED __builtin_amdgcn_sched_barrier(0)
; template <class Epi, class Sched, bool ALIGN_EPI = false, bool SP2 = false>
; __device__ __forceinline__ void gemm_phase(PG8_LAS unsigned char* lds, const Gemm g, const Sched& S, const Epi& E, const int tid_in) {
;     ...
;             PG8_LDA(At, 0, 1); PG8_STAGE(PG8_SB(0, 0), b2, voffB); PG8_STAGE(PG8_SB(0, 1), b2 + hstep, voffB); PG8_STAGE(PG8_SA(0, 0), a2, voffA);
;             PG8_WAIT_V(8); PG8_WAIT_L(0); PG8_BAR; PG8_MMA(1, 0, At, B0); PG8_MMA(1, 1, At, B1); PG8_BAR; PG8_SCHED;
;             PG8_LDB(B0, 1, 0); PG8_LDB(B1, 1, 1); PG8_SCHED; PG8_LDA(At, 1, 0); PG8_STAGE(PG8_SA(0, 1), a2 + hstep, voffA);
;             PG8_WAIT_V(8); PG8_WAIT_L(0); PG8_BAR; PG8_MMA(0, 0, At, B0); PG8_MMA(0, 1, At, B1); PG8_BAR; PG8_SCHED;
;             PG8_LDA(At, 1, 1); PG8_STAGE(PG8_SB(1, 0), b3, voffB); PG8_STAGE(PG8_SB(1, 1), b3 + hstep, voffB); PG8_STAGE(PG8_SA(1, 0), a3, voffA);
	ds_read_b128 v[180:183], v147 offset:16384
	ds_read_b128 v[184:187], v147 offset:17408
	ds_read_b128 v[188:191], v147 offset:18432
	ds_read_b128 v[192:195], v147 offset:19456
	ds_read_b128 v[196:199], v147 offset:20480
	ds_read_b128 v[200:203], v147 offset:21504
	ds_read_b128 v[208:211], v147 offset:22528
	ds_read_b128 v[212:215], v147 offset:23552
	global_load_lds_dwordx4 v132, s[38:39]
	s_add_i32 m0, s55, 0x2000
	s_add_u32 s56, s38, 0x80000
	s_addc_u32 s57, s39, 0
	s_add_i32 s55, s58, s19
	global_load_lds_dwordx4 v136, s[38:39]
	s_mov_b32 m0, s55
	s_add_u32 s100, s42, 0x80
	s_addc_u32 s101, s43, 0
	global_load_lds_dwordx4 v132, s[56:57]
	s_add_i32 m0, s55, 0x2000
	s_nop 0
	global_load_lds_dwordx4 v136, s[56:57]
	s_mov_b32 m0, s44
	s_nop 0
	global_load_lds_dwordx4 v130, s[42:43]
	s_add_i32 s55, 0, 0x18000
	s_add_i32 s56, 0, 0x1c000
	s_waitcnt vmcnt(7)
	s_waitcnt lgkmcnt(0)
	s_barrier
	s_setprio 1
	v_mfma_f32_16x16x32_bf16 v[62:65], v[148:151], v[180:183], v[62:65]
	v_mfma_f32_16x16x32_bf16 v[58:61], v[156:159], v[180:183], v[58:61]
	v_mfma_f32_16x16x32_bf16 v[54:57], v[148:151], v[188:191], v[54:57]
	v_mfma_f32_16x16x32_bf16 v[46:49], v[156:159], v[188:191], v[46:49]
	v_mfma_f32_16x16x32_bf16 v[38:41], v[148:151], v[196:199], v[38:41]
	v_mfma_f32_16x16x32_bf16 v[30:33], v[156:159], v[196:199], v[30:33]
	v_mfma_f32_16x16x32_bf16 v[22:25], v[148:151], v[208:211], v[22:25]
	v_mfma_f32_16x16x32_bf16 v[12:15], v[156:159], v[208:211], v[12:15]
	v_mfma_f32_16x16x32_bf16 v[62:65], v[152:155], v[184:187], v[62:65]
	v_mfma_f32_16x16x32_bf16 v[58:61], v[160:163], v[184:187], v[58:61]
	v_mfma_f32_16x16x32_bf16 v[54:57], v[152:155], v[192:195], v[54:57]
	v_mfma_f32_16x16x32_bf16 v[46:49], v[160:163], v[192:195], v[46:49]
	v_mfma_f32_16x16x32_bf16 v[38:41], v[152:155], v[200:203], v[38:41]
	v_mfma_f32_16x16x32_bf16 v[30:33], v[160:163], v[200:203], v[30:33]
	v_mfma_f32_16x16x32_bf16 v[22:25], v[152:155], v[212:215], v[22:25]
	v_mfma_f32_16x16x32_bf16 v[12:15], v[160:163], v[212:215], v[12:15]
	s_setprio 0
	s_setprio 1
	v_mfma_f32_16x16x32_bf16 v[50:53], v[164:167], v[180:183], v[50:53]
	v_mfma_f32_16x16x32_bf16 v[42:45], v[172:175], v[180:183], v[42:45]
	v_mfma_f32_16x16x32_bf16 v[34:37], v[164:167], v[188:191], v[34:37]
	v_mfma_f32_16x16x32_bf16 v[26:29], v[172:175], v[188:191], v[26:29]
	v_mfma_f32_16x16x32_bf16 v[16:19], v[164:167], v[196:199], v[16:19]
	v_mfma_f32_16x16x32_bf16 v[8:11], v[172:175], v[196:199], v[8:11]
	v_mfma_f32_16x16x32_bf16 v[4:7], v[164:167], v[208:211], v[4:7]
	v_mfma_f32_16x16x32_bf16 v[0:3], v[172:175], v[208:211], v[0:3]
	v_mfma_f32_16x16x32_bf16 v[50:53], v[168:171], v[184:187], v[50:53]
	v_mfma_f32_16x16x32_bf16 v[42:45], v[176:179], v[184:187], v[42:45]
	v_mfma_f32_16x16x32_bf16 v[34:37], v[168:171], v[192:195], v[34:37]
	v_mfma_f32_16x16x32_bf16 v[26:29], v[176:179], v[192:195], v[26:29]
	v_mfma_f32_16x16x32_bf16 v[16:19], v[168:171], v[200:203], v[16:19]
	v_mfma_f32_16x16x32_bf16 v[8:11], v[176:179], v[200:203], v[8:11]
	v_mfma_f32_16x16x32_bf16 v[4:7], v[168:171], v[212:215], v[4:7]
	v_mfma_f32_16x16x32_bf16 v[0:3], v[176:179], v[212:215], v[0:3]
	s_setprio 0
	s_barrier
	ds_read_b128 v[148:151], v218
	ds_read_b128 v[152:155], v218 offset:1024
	ds_read_b128 v[156:159], v218 offset:2048
	ds_read_b128 v[160:163], v218 offset:3072
	ds_read_b128 v[164:167], v219
	ds_read_b128 v[168:171], v219 offset:1024
	ds_read_b128 v[172:175], v219 offset:2048
	ds_read_b128 v[176:179], v219 offset:3072
	s_mov_b32 m0, s45
	s_nop 0
	global_load_lds_dwordx4 v134, s[42:43]
	s_add_u32 s42, s42, 0x80000
	s_addc_u32 s43, s43, 0
	s_mov_b32 m0, s46
	ds_read_b128 v[180:183], v147 offset:32768
	ds_read_b128 v[184:187], v147 offset:33792
	ds_read_b128 v[188:191], v147 offset:34816
	ds_read_b128 v[192:195], v147 offset:35840
	ds_read_b128 v[196:199], v147 offset:36864
	ds_read_b128 v[200:203], v147 offset:37888
	ds_read_b128 v[208:211], v147 offset:38912
	ds_read_b128 v[212:215], v147 offset:39936
	global_load_lds_dwordx4 v130, s[42:43]
	s_mov_b32 m0, s47
	s_nop 0
	global_load_lds_dwordx4 v134, s[42:43]
	s_add_i32 s42, s55, s19
	s_mov_b32 m0, s42
	s_waitcnt vmcnt(8)
	s_waitcnt lgkmcnt(0)
	s_barrier
; #define PG8_STAGE(bufoff, gbase, voff) do { _Pragma("unroll") for (int _i = 0; _i < 2; ++_i) \
;         __builtin_amdgcn_global_load_lds((const unsigned*)((const char*)(gbase) + (voff)[_i]), (PG8_LAS unsigned*)(lds + (bufoff) + ldsw + _i * 8192), 16, 0, 0); } while (0)
; #define PG8_LDA(dst, b, h) do { _Pragma("unroll") for (int m = 0; m < 4; ++m) _Pragma("unroll") for (int k = 0; k < 2; ++k) dst[m][k] = *(const PG8_LAS bf16x8*)(lds + PG8_SA(b, h) + aoff + m * 2048 + k * 1024); } while (0)
; #define PG8_LDB(dst, b, h) do { _Pragma("unroll") for (int n = 0; n < 2; ++n) _Pragma("unroll") for (int k = 0; k < 2; ++k) dst[n][k] = *(const PG8_LAS bf16x8*)(lds + PG8_SB(b, h) + boff + n * 2048 + k * 1024); } while (0)
; #define PG8_MMA(ai, bj, At, Bt) do { __builtin_amdgcn_s_setprio(1); _Pragma("unroll") for (int m = 0; m < 4; ++m) _Pragma("unroll") for (int n = 0; n < 2; ++n) _Pragma("unroll") for (int k = 0; k < 2; ++k) \
;         acc[ai][bj][m][n] = __builtin_amdgcn_mfma_f32_16x16x32_bf16(Bt[n][k], At[m][k], acc[ai][bj][m][n], 0, 0, 0); __builtin_amdgcn_s_setprio(0); } while (0)
; #define PG8_WAIT_V(n) asm volatile("s_waitcnt vmcnt(" #n ")" ::: "memory")
; #define PG8_WAIT_L(n) asm volatile("s_waitcnt lgkmcnt(" #n ")" ::: "memory")
; #define PG8_BAR __builtin_amdgcn_s_barrier()
; #define PG8_SCHED __builtin_amdgcn_sched_barrier(0)
; template <class Epi, class Sched, bool ALIGN_EPI = false, bool SP2 = false>
; __device__ __forceinline__ void gemm_phase(PG8_LAS unsigned char* lds, const Gemm g, const Sched& S, const Epi& E, const int tid_in) {
;     ...
;             PG8_LDB(B0, 1, 0); PG8_LDB(B1, 1, 1); PG8_SCHED; PG8_LDA(At, 1, 0); PG8_STAGE(PG8_SA(0, 1), a2 + hstep, voffA);
;             PG8_WAIT_V(8); PG8_WAIT_L(0); PG8_BAR; PG8_MMA(0, 0, At, B0); PG8_MMA(0, 1, At, B1); PG8_BAR; PG8_SCHED;
;             PG8_LDA(At, 1, 1); PG8_STAGE(PG8_SB(1, 0), b3, voffB); PG8_STAGE(PG8_SB(1, 1), b3 + hstep, voffB); PG8_STAGE(PG8_SA(1, 0), a3, voffA);
;             PG8_WAIT_V(8); PG8_WAIT_L(0); PG8_BAR; PG8_MMA(1, 0, At, B0); PG8_MMA(1, 1, At, B1); PG8_BAR; PG8_SCHED;
	s_setprio 1
	v_mfma_f32_16x16x32_bf16 v[126:129], v[148:151], v[180:183], v[126:129]
	v_mfma_f32_16x16x32_bf16 v[122:125], v[156:159], v[180:183], v[122:125]
	v_mfma_f32_16x16x32_bf16 v[118:121], v[148:151], v[188:191], v[118:121]
	v_mfma_f32_16x16x32_bf16 v[110:113], v[156:159], v[188:191], v[110:113]
	v_mfma_f32_16x16x32_bf16 v[102:105], v[148:151], v[196:199], v[102:105]
	v_mfma_f32_16x16x32_bf16 v[94:97], v[156:159], v[196:199], v[94:97]
	v_mfma_f32_16x16x32_bf16 v[86:89], v[148:151], v[208:211], v[86:89]
	v_mfma_f32_16x16x32_bf16 v[78:81], v[156:159], v[208:211], v[78:81]
	v_mfma_f32_16x16x32_bf16 v[126:129], v[152:155], v[184:187], v[126:129]
	v_mfma_f32_16x16x32_bf16 v[122:125], v[160:163], v[184:187], v[122:125]
	v_mfma_f32_16x16x32_bf16 v[118:121], v[152:155], v[192:195], v[118:121]
	v_mfma_f32_16x16x32_bf16 v[110:113], v[160:163], v[192:195], v[110:113]
	v_mfma_f32_16x16x32_bf16 v[102:105], v[152:155], v[200:203], v[102:105]
	v_mfma_f32_16x16x32_bf16 v[94:97], v[160:163], v[200:203], v[94:97]
	v_mfma_f32_16x16x32_bf16 v[86:89], v[152:155], v[212:215], v[86:89]
	v_mfma_f32_16x16x32_bf16 v[78:81], v[160:163], v[212:215], v[78:81]
	s_setprio 0
	s_setprio 1
	v_mfma_f32_16x16x32_bf16 v[114:117], v[164:167], v[180:183], v[114:117]
	v_mfma_f32_16x16x32_bf16 v[106:109], v[172:175], v[180:183], v[106:109]
	v_mfma_f32_16x16x32_bf16 v[98:101], v[164:167], v[188:191], v[98:101]
	v_mfma_f32_16x16x32_bf16 v[90:93], v[172:175], v[188:191], v[90:93]
	v_mfma_f32_16x16x32_bf16 v[82:85], v[164:167], v[196:199], v[82:85]
	v_mfma_f32_16x16x32_bf16 v[74:77], v[172:175], v[196:199], v[74:77]
	v_mfma_f32_16x16x32_bf16 v[70:73], v[164:167], v[208:211], v[70:73]
	v_mfma_f32_16x16x32_bf16 v[66:69], v[172:175], v[208:211], v[66:69]
	v_mfma_f32_16x16x32_bf16 v[114:117], v[168:171], v[184:187], v[114:117]
	v_mfma_f32_16x16x32_bf16 v[106:109], v[176:179], v[184:187], v[106:109]
	v_mfma_f32_16x16x32_bf16 v[98:101], v[168:171], v[192:195], v[98:101]
	v_mfma_f32_16x16x32_bf16 v[90:93], v[176:179], v[192:195], v[90:93]
	v_mfma_f32_16x16x32_bf16 v[82:85], v[168:171], v[200:203], v[82:85]
	v_mfma_f32_16x16x32_bf16 v[74:77], v[176:179], v[200:203], v[74:77]
	v_mfma_f32_16x16x32_bf16 v[70:73], v[168:171], v[212:215], v[70:73]
	v_mfma_f32_16x16x32_bf16 v[66:69], v[176:179], v[212:215], v[66:69]
	s_setprio 0
	s_barrier
	ds_read_b128 v[180:183], v147 offset:49152
	ds_read_b128 v[184:187], v147 offset:50176
	ds_read_b128 v[188:191], v147 offset:51200
	ds_read_b128 v[192:195], v147 offset:52224
	ds_read_b128 v[196:199], v147 offset:53248
	ds_read_b128 v[200:203], v147 offset:54272
	ds_read_b128 v[208:211], v147 offset:55296
	ds_read_b128 v[212:215], v147 offset:56320
	global_load_lds_dwordx4 v132, s[98:99]
	s_add_i32 m0, s42, 0x2000
	s_add_u32 s38, s38, 0x80080
	s_addc_u32 s39, s39, 0
	s_add_i32 s42, s56, s19
	global_load_lds_dwordx4 v136, s[98:99]
	s_mov_b32 m0, s42
	s_nop 0
	global_load_lds_dwordx4 v132, s[38:39]
	s_add_i32 m0, s42, 0x2000
	s_nop 0
	global_load_lds_dwordx4 v136, s[38:39]
	s_mov_b32 m0, s48
	s_nop 0
	global_load_lds_dwordx4 v130, s[100:101]
	s_add_i32 s54, s54, 2
	s_add_u32 s34, s34, 0x100
	s_addc_u32 s35, s35, 0
	s_add_u32 s52, s52, 0x100
	s_addc_u32 s53, s53, 0
	s_add_u32 s38, s34, 0xfff80080
	s_addc_u32 s39, s35, -1
	s_add_i32 s55, 0, 0x10000
	s_cmp_eq_u32 s54, 28
	s_cselect_b32 s43, s21, s39
	s_cselect_b32 s42, s25, s38
	s_cselect_b32 s39, s23, s53
	s_cselect_b32 s38, s51, s52
	s_add_i32 s58, 0, 0x14000
	s_cmp_gt_u32 s54, 29
	s_waitcnt vmcnt(7)
	s_waitcnt lgkmcnt(0)
	s_barrier
	s_setprio 1
	v_mfma_f32_16x16x32_bf16 v[62:65], v[148:151], v[180:183], v[62:65]
	v_mfma_f32_16x16x32_bf16 v[58:61], v[156:159], v[180:183], v[58:61]
	v_mfma_f32_16x16x32_bf16 v[54:57], v[148:151], v[188:191], v[54:57]
	v_mfma_f32_16x16x32_bf16 v[46:49], v[156:159], v[188:191], v[46:49]
	v_mfma_f32_16x16x32_bf16 v[38:41], v[148:151], v[196:199], v[38:41]
	v_mfma_f32_16x16x32_bf16 v[30:33], v[156:159], v[196:199], v[30:33]
	v_mfma_f32_16x16x32_bf16 v[22:25], v[148:151], v[208:211], v[22:25]
	v_mfma_f32_16x16x32_bf16 v[12:15], v[156:159], v[208:211], v[12:15]
	v_mfma_f32_16x16x32_bf16 v[62:65], v[152:155], v[184:187], v[62:65]
	v_mfma_f32_16x16x32_bf16 v[58:61], v[160:163], v[184:187], v[58:61]
	v_mfma_f32_16x16x32_bf16 v[54:57], v[152:155], v[192:195], v[54:57]
	v_mfma_f32_16x16x32_bf16 v[46:49], v[160:163], v[192:195], v[46:49]
	v_mfma_f32_16x16x32_bf16 v[38:41], v[152:155], v[200:203], v[38:41]
	v_mfma_f32_16x16x32_bf16 v[30:33], v[160:163], v[200:203], v[30:33]
	v_mfma_f32_16x16x32_bf16 v[22:25], v[152:155], v[212:215], v[22:25]
	v_mfma_f32_16x16x32_bf16 v[12:15], v[160:163], v[212:215], v[12:15]
	s_setprio 0
	s_setprio 1
	v_mfma_f32_16x16x32_bf16 v[50:53], v[164:167], v[180:183], v[50:53]
	v_mfma_f32_16x16x32_bf16 v[42:45], v[172:175], v[180:183], v[42:45]
	v_mfma_f32_16x16x32_bf16 v[34:37], v[164:167], v[188:191], v[34:37]
	v_mfma_f32_16x16x32_bf16 v[26:29], v[172:175], v[188:191], v[26:29]
	v_mfma_f32_16x16x32_bf16 v[16:19], v[164:167], v[196:199], v[16:19]
	v_mfma_f32_16x16x32_bf16 v[8:11], v[172:175], v[196:199], v[8:11]
	v_mfma_f32_16x16x32_bf16 v[4:7], v[164:167], v[208:211], v[4:7]
	v_mfma_f32_16x16x32_bf16 v[0:3], v[172:175], v[208:211], v[0:3]
	v_mfma_f32_16x16x32_bf16 v[50:53], v[168:171], v[184:187], v[50:53]
	v_mfma_f32_16x16x32_bf16 v[42:45], v[176:179], v[184:187], v[42:45]
	v_mfma_f32_16x16x32_bf16 v[34:37], v[168:171], v[192:195], v[34:37]
	v_mfma_f32_16x16x32_bf16 v[26:29], v[176:179], v[192:195], v[26:29]
	v_mfma_f32_16x16x32_bf16 v[16:19], v[168:171], v[200:203], v[16:19]
	v_mfma_f32_16x16x32_bf16 v[8:11], v[176:179], v[200:203], v[8:11]
	v_mfma_f32_16x16x32_bf16 v[4:7], v[168:171], v[212:215], v[4:7]
	v_mfma_f32_16x16x32_bf16 v[0:3], v[176:179], v[212:215], v[0:3]
	s_setprio 0
	s_barrier
	s_cbranch_scc0 .LBB0_374
	s_and_b64 vcc, exec, s[6:7]
	v_readlane_b32 s52, v255, 9
	v_readlane_b32 s53, v255, 10
	s_cbranch_vccz .LBB0_377
	s_barrier

; #define PG8_STAGE(bufoff, gbase, voff) do { _Pragma("unroll") for (int _i = 0; _i < 2; ++_i) \
;         __builtin_amdgcn_global_load_lds((const unsigned*)((const char*)(gbase) + (voff)[_i]), (PG8_LAS unsigned*)(lds + (bufoff) + ldsw + _i * 8192), 16, 0, 0); } while (0)
; #define PG8_LDA(dst, b, h) do { _Pragma("unroll") for (int m = 0; m < 4; ++m) _Pragma("unroll") for (int k = 0; k < 2; ++k) dst[m][k] = *(const PG8_LAS bf16x8*)(lds + PG8_SA(b, h) + aoff + m * 2048 + k * 1024); } while (0)
; #define PG8_LDB(dst, b, h) do { _Pragma("unroll") for (int n = 0; n < 2; ++n) _Pragma("unroll") for (int k = 0; k < 2; ++k) dst[n][k] = *(const PG8_LAS bf16x8*)(lds + PG8_SB(b, h) + boff + n * 2048 + k * 1024); } while (0)
; #define PG8_WAIT_V(n) asm volatile("s_waitcnt vmcnt(" #n ")" ::: "memory")
; #define PG8_WAIT_L(n) asm volatile("s_waitcnt lgkmcnt(" #n ")" ::: "memory")
; #define PG8_BAR __builtin_amdgcn_s_barrier()
; #define PG8_SCHED __builtin_amdgcn_sched_barrier(0)
; template <class Epi, class Sched, bool ALIGN_EPI = false, bool SP2 = false>
; __device__ __forceinline__ void gemm_phase(PG8_LAS unsigned char* lds, const Gemm g, const Sched& S, const Epi& E, const int tid_in) {
;     ...
;         const bool has_next = S.next(ui + 1, nxt);
;         const char* nA = has_next ? (const char*)g.A + (size_t)nxt.pm * tstep : cA; const char* nB = has_next ? (const char*)g.Bt + (size_t)nxt.pn * tstep : cB;
;         for (int t = 0; t < nt; t += 2) {
;             if constexpr (Epi::KSPLIT > 0) { if (t == Epi::KSPLIT / BK) E.midk(acc, cur, wr, wc, fr, fq); }
;             const bool last = (t == nt - 2);
;             const char* a1 = cA + (size_t)(t + 1) * kstep;
;             const char* a2 = last ? nA : cA + (size_t)(t + 2) * kstep; const char* b2 = last ? nB : cB + (size_t)(t + 2) * kstep;
;             const char* a3 = a2 + kstep; const char* b3 = b2 + kstep;
;             if (last && has_next) S.a_ready(nxt);
;             if constexpr (SP2) {
;             PG8_LDB(B0, 0, 0); PG8_LDB(B1, 0, 1); PG8_SCHED; PG8_LDA(At, 0, 0); PG8_STAGE(PG8_SA(1, 1), a1 + hstep, voffA);
;             PG8_WAIT_V(8); PG8_WAIT_L(0); PG8_BAR; PG8_MMA(0, 0, At, B0); PG8_MMA(0, 1, At, B1); PG8_BAR; PG8_SCHED;
;             PG8_LDA(At, 0, 1); PG8_STAGE(PG8_SB(0, 0), b2, voffB); PG8_STAGE(PG8_SB(0, 1), b2 + hstep, voffB); PG8_STAGE(PG8_SA(0, 0), a2, voffA);
.LBB0_393:
	s_ashr_i32 s23, s22, 31
	s_lshl_b64 s[24:25], s[22:23], 20
	s_add_u32 s24, s1, s24
	s_addc_u32 s25, s5, s25
	s_and_b64 s[26:27], s[36:37], exec
	s_cselect_b32 s23, s25, s29
	s_cselect_b32 s49, s24, s28
	s_ashr_i32 s21, s20, 31
	s_lshl_b64 s[26:27], s[20:21], 20
	s_add_u32 s26, s8, s26
	s_addc_u32 s27, s10, s27
	s_and_b64 s[34:35], s[36:37], exec
	s_cselect_b32 s21, s27, s31
	s_cselect_b32 s50, s26, s30
	s_add_u32 s28, s28, 0x80080
	s_addc_u32 s29, s29, 0
	s_add_u32 s51, s30, 0x100
	v_mov_b32_e32 v0, 0
	s_addc_u32 s52, s31, 0
	s_mov_b32 s53, -2
	v_add_u32_e32 v216, 0x10000, v21
	v_add_u32_e32 v217, 0x14000, v21
	v_add_u32_e32 v218, 0x18000, v21
	v_add_u32_e32 v219, 0x1c000, v21
	s_add_u32 s30, s28, 0xfff80080
	s_addc_u32 s31, s29, -1
	s_add_i32 s54, 0, 0x10000
	s_cmp_eq_u32 s53, 28
	s_cselect_b32 s35, s23, s31
	s_cselect_b32 s34, s49, s30
	s_cselect_b32 s31, s21, s52
	s_cselect_b32 s30, s50, s51
	s_add_i32 s56, 0, 0x14000
	s_mov_b32 m0, s45
	s_nop 0
	global_load_lds_dwordx4 v132, s[100:101]
	ds_read_b128 v[148:151], v216
	ds_read_b128 v[152:155], v216 offset:1024
	ds_read_b128 v[156:159], v216 offset:2048
	ds_read_b128 v[160:163], v216 offset:3072
	ds_read_b128 v[164:167], v217
	ds_read_b128 v[168:171], v217 offset:1024
	ds_read_b128 v[172:175], v217 offset:2048
	ds_read_b128 v[176:179], v217 offset:3072
	s_add_i32 m0, s38, 0xc000
	ds_read_b128 v[180:183], v147
	ds_read_b128 v[184:187], v147 offset:1024
	ds_read_b128 v[188:191], v147 offset:2048
	ds_read_b128 v[192:195], v147 offset:3072
	ds_read_b128 v[196:199], v147 offset:4096
	ds_read_b128 v[200:203], v147 offset:5120
	ds_read_b128 v[208:211], v147 offset:6144
	ds_read_b128 v[212:215], v147 offset:7168
	global_load_lds_dwordx4 v140, s[28:29]
	s_add_i32 m0, s38, 0xe000
	s_nop 0
	global_load_lds_dwordx4 v142, s[28:29]
	s_add_i32 s54, s54, s19
	s_add_u32 s98, s30, 0x80
	s_addc_u32 s99, s31, 0
	s_mov_b32 m0, s54
	s_waitcnt vmcnt(8)
	s_waitcnt lgkmcnt(0)
	s_barrier
	s_setprio 1
	v_mfma_f32_16x16x32_bf16 v[126:129], v[148:151], v[180:183], 0
	v_mfma_f32_16x16x32_bf16 v[122:125], v[156:159], v[180:183], 0
	v_mfma_f32_16x16x32_bf16 v[118:121], v[148:151], v[188:191], 0
	v_mfma_f32_16x16x32_bf16 v[110:113], v[156:159], v[188:191], 0
	v_mfma_f32_16x16x32_bf16 v[102:105], v[148:151], v[196:199], 0
	v_mfma_f32_16x16x32_bf16 v[94:97], v[156:159], v[196:199], 0
	v_mfma_f32_16x16x32_bf16 v[86:89], v[148:151], v[208:211], 0
	v_mfma_f32_16x16x32_bf16 v[78:81], v[156:159], v[208:211], 0
	v_mfma_f32_16x16x32_bf16 v[126:129], v[152:155], v[184:187], v[126:129]
	v_mfma_f32_16x16x32_bf16 v[122:125], v[160:163], v[184:187], v[122:125]
	v_mfma_f32_16x16x32_bf16 v[118:121], v[152:155], v[192:195], v[118:121]
	v_mfma_f32_16x16x32_bf16 v[110:113], v[160:163], v[192:195], v[110:113]
	v_mfma_f32_16x16x32_bf16 v[102:105], v[152:155], v[200:203], v[102:105]
	v_mfma_f32_16x16x32_bf16 v[94:97], v[160:163], v[200:203], v[94:97]
	v_mfma_f32_16x16x32_bf16 v[86:89], v[152:155], v[212:215], v[86:89]
	v_mfma_f32_16x16x32_bf16 v[78:81], v[160:163], v[212:215], v[78:81]
	s_setprio 0
	s_setprio 1
	v_mfma_f32_16x16x32_bf16 v[114:117], v[164:167], v[180:183], 0
	v_mfma_f32_16x16x32_bf16 v[106:109], v[172:175], v[180:183], 0
	v_mfma_f32_16x16x32_bf16 v[98:101], v[164:167], v[188:191], 0
	v_mfma_f32_16x16x32_bf16 v[90:93], v[172:175], v[188:191], 0
	v_mfma_f32_16x16x32_bf16 v[82:85], v[164:167], v[196:199], 0
	v_mfma_f32_16x16x32_bf16 v[74:77], v[172:175], v[196:199], 0
	v_mfma_f32_16x16x32_bf16 v[70:73], v[164:167], v[208:211], 0
	v_mfma_f32_16x16x32_bf16 v[66:69], v[172:175], v[208:211], 0
	v_mfma_f32_16x16x32_bf16 v[114:117], v[168:171], v[184:187], v[114:117]
	v_mfma_f32_16x16x32_bf16 v[106:109], v[176:179], v[184:187], v[106:109]
	v_mfma_f32_16x16x32_bf16 v[98:101], v[168:171], v[192:195], v[98:101]
	v_mfma_f32_16x16x32_bf16 v[90:93], v[176:179], v[192:195], v[90:93]
	v_mfma_f32_16x16x32_bf16 v[82:85], v[168:171], v[200:203], v[82:85]
	v_mfma_f32_16x16x32_bf16 v[74:77], v[176:179], v[200:203], v[74:77]
	v_mfma_f32_16x16x32_bf16 v[70:73], v[168:171], v[212:215], v[70:73]
	v_mfma_f32_16x16x32_bf16 v[66:69], v[176:179], v[212:215], v[66:69]
	s_setprio 0
	s_barrier
	ds_read_b128 v[180:183], v147 offset:16384
	ds_read_b128 v[184:187], v147 offset:17408
	ds_read_b128 v[188:191], v147 offset:18432
	ds_read_b128 v[192:195], v147 offset:19456
	ds_read_b128 v[196:199], v147 offset:20480
	ds_read_b128 v[200:203], v147 offset:21504
	ds_read_b128 v[208:211], v147 offset:22528
	ds_read_b128 v[212:215], v147 offset:23552
	global_load_lds_dwordx4 v134, s[30:31]
	s_add_i32 m0, s54, 0x2000
	s_add_u32 s54, s30, 0x80000
	s_addc_u32 s55, s31, 0
	s_add_i32 s56, s56, s19
	global_load_lds_dwordx4 v130, s[30:31]
	s_mov_b32 m0, s56
	s_add_u32 s100, s34, 0x80
	s_addc_u32 s101, s35, 0
	global_load_lds_dwordx4 v134, s[54:55]
	s_add_i32 m0, s56, 0x2000
	s_nop 0
	global_load_lds_dwordx4 v130, s[54:55]
	s_mov_b32 m0, s38
	s_nop 0
	global_load_lds_dwordx4 v136, s[34:35]
	s_add_i32 s54, 0, 0x18000
	s_add_i32 s55, 0, 0x1c000
	s_waitcnt vmcnt(7)
	s_waitcnt lgkmcnt(0)
	s_barrier
; #define PG8_STAGE(bufoff, gbase, voff) do { _Pragma("unroll") for (int _i = 0; _i < 2; ++_i) \
;         __builtin_amdgcn_global_load_lds((const unsigned*)((const char*)(gbase) + (voff)[_i]), (PG8_LAS unsigned*)(lds + (bufoff) + ldsw + _i * 8192), 16, 0, 0); } while (0)
; #define PG8_LDA(dst, b, h) do { _Pragma("unroll") for (int m = 0; m < 4; ++m) _Pragma("unroll") for (int k = 0; k < 2; ++k) dst[m][k] = *(const PG8_LAS bf16x8*)(lds + PG8_SA(b, h) + aoff + m * 2048 + k * 1024); } while (0)
; #define PG8_LDB(dst, b, h) do { _Pragma("unroll") for (int n = 0; n < 2; ++n) _Pragma("unroll") for (int k = 0; k < 2; ++k) dst[n][k] = *(const PG8_LAS bf16x8*)(lds + PG8_SB(b, h) + boff + n * 2048 + k * 1024); } while (0)
; #define PG8_MMA(ai, bj, At, Bt) do { __builtin_amdgcn_s_setprio(1); _Pragma("unroll") for (int m = 0; m < 4; ++m) _Pragma("unroll") for (int n = 0; n < 2; ++n) _Pragma("unroll") for (int k = 0; k < 2; ++k) \
;         acc[ai][bj][m][n] = __builtin_amdgcn_mfma_f32_16x16x32_bf16(Bt[n][k], At[m][k], acc[ai][bj][m][n], 0, 0, 0); __builtin_amdgcn_s_setprio(0); } while (0)
; #define PG8_WAIT_V(n) asm volatile("s_waitcnt vmcnt(" #n ")" ::: "memory")
; #define PG8_WAIT_L(n) asm volatile("s_waitcnt lgkmcnt(" #n ")" ::: "memory")
; #define PG8_BAR __builtin_amdgcn_s_barrier()
; #define PG8_SCHED __builtin_amdgcn_sched_barrier(0)
; template <class Epi, class Sched, bool ALIGN_EPI = false, bool SP2 = false>
; __device__ __forceinline__ void gemm_phase(PG8_LAS unsigned char* lds, const Gemm g, const Sched& S, const Epi& E, const int tid_in) {
;     ...
;             PG8_WAIT_V(8); PG8_WAIT_L(0); PG8_BAR; PG8_MMA(0, 0, At, B0); PG8_MMA(0, 1, At, B1); PG8_BAR; PG8_SCHED;
;             PG8_LDA(At, 0, 1); PG8_STAGE(PG8_SB(0, 0), b2, voffB); PG8_STAGE(PG8_SB(0, 1), b2 + hstep, voffB); PG8_STAGE(PG8_SA(0, 0), a2, voffA);
;             PG8_WAIT_V(8); PG8_WAIT_L(0); PG8_BAR; PG8_MMA(1, 0, At, B0); PG8_MMA(1, 1, At, B1); PG8_BAR; PG8_SCHED;
;             PG8_LDB(B0, 1, 0); PG8_LDB(B1, 1, 1); PG8_SCHED; PG8_LDA(At, 1, 0); PG8_STAGE(PG8_SA(0, 1), a2 + hstep, voffA);
;             PG8_WAIT_V(8); PG8_WAIT_L(0); PG8_BAR; PG8_MMA(0, 0, At, B0); PG8_MMA(0, 1, At, B1); PG8_BAR; PG8_SCHED;
	s_setprio 1
	v_mfma_f32_16x16x32_bf16 v[62:65], v[148:151], v[180:183], 0
	v_mfma_f32_16x16x32_bf16 v[58:61], v[156:159], v[180:183], 0
	v_mfma_f32_16x16x32_bf16 v[54:57], v[148:151], v[188:191], 0
	v_mfma_f32_16x16x32_bf16 v[46:49], v[156:159], v[188:191], 0
	v_mfma_f32_16x16x32_bf16 v[38:41], v[148:151], v[196:199], 0
	v_mfma_f32_16x16x32_bf16 v[30:33], v[156:159], v[196:199], 0
	v_mfma_f32_16x16x32_bf16 v[22:25], v[148:151], v[208:211], 0
	v_mfma_f32_16x16x32_bf16 v[12:15], v[156:159], v[208:211], 0
	v_mfma_f32_16x16x32_bf16 v[62:65], v[152:155], v[184:187], v[62:65]
	v_mfma_f32_16x16x32_bf16 v[58:61], v[160:163], v[184:187], v[58:61]
	v_mfma_f32_16x16x32_bf16 v[54:57], v[152:155], v[192:195], v[54:57]
	v_mfma_f32_16x16x32_bf16 v[46:49], v[160:163], v[192:195], v[46:49]
	v_mfma_f32_16x16x32_bf16 v[38:41], v[152:155], v[200:203], v[38:41]
	v_mfma_f32_16x16x32_bf16 v[30:33], v[160:163], v[200:203], v[30:33]
	v_mfma_f32_16x16x32_bf16 v[22:25], v[152:155], v[212:215], v[22:25]
	v_mfma_f32_16x16x32_bf16 v[12:15], v[160:163], v[212:215], v[12:15]
	s_setprio 0
	s_setprio 1
	v_mfma_f32_16x16x32_bf16 v[50:53], v[164:167], v[180:183], 0
	v_mfma_f32_16x16x32_bf16 v[42:45], v[172:175], v[180:183], 0
	v_mfma_f32_16x16x32_bf16 v[34:37], v[164:167], v[188:191], 0
	v_mfma_f32_16x16x32_bf16 v[26:29], v[172:175], v[188:191], 0
	v_mfma_f32_16x16x32_bf16 v[16:19], v[164:167], v[196:199], 0
	v_mfma_f32_16x16x32_bf16 v[8:11], v[172:175], v[196:199], 0
	v_mfma_f32_16x16x32_bf16 v[4:7], v[164:167], v[208:211], 0
	v_mfma_f32_16x16x32_bf16 v[0:3], v[172:175], v[208:211], 0
	v_mfma_f32_16x16x32_bf16 v[50:53], v[168:171], v[184:187], v[50:53]
	v_mfma_f32_16x16x32_bf16 v[42:45], v[176:179], v[184:187], v[42:45]
	v_mfma_f32_16x16x32_bf16 v[34:37], v[168:171], v[192:195], v[34:37]
	v_mfma_f32_16x16x32_bf16 v[26:29], v[176:179], v[192:195], v[26:29]
	v_mfma_f32_16x16x32_bf16 v[16:19], v[168:171], v[200:203], v[16:19]
	v_mfma_f32_16x16x32_bf16 v[8:11], v[176:179], v[200:203], v[8:11]
	v_mfma_f32_16x16x32_bf16 v[4:7], v[168:171], v[212:215], v[4:7]
	v_mfma_f32_16x16x32_bf16 v[0:3], v[176:179], v[212:215], v[0:3]
	s_setprio 0
	s_barrier
	ds_read_b128 v[148:151], v218
	ds_read_b128 v[152:155], v218 offset:1024
	ds_read_b128 v[156:159], v218 offset:2048
	ds_read_b128 v[160:163], v218 offset:3072
	ds_read_b128 v[164:167], v219
	ds_read_b128 v[168:171], v219 offset:1024
	ds_read_b128 v[172:175], v219 offset:2048
	ds_read_b128 v[176:179], v219 offset:3072
	s_mov_b32 m0, s39
	s_nop 0
	global_load_lds_dwordx4 v132, s[34:35]
	s_add_u32 s34, s34, 0x80000
	s_addc_u32 s35, s35, 0
	s_mov_b32 m0, s42
	ds_read_b128 v[180:183], v147 offset:32768
	ds_read_b128 v[184:187], v147 offset:33792
	ds_read_b128 v[188:191], v147 offset:34816
	ds_read_b128 v[192:195], v147 offset:35840
	ds_read_b128 v[196:199], v147 offset:36864
	ds_read_b128 v[200:203], v147 offset:37888
	ds_read_b128 v[208:211], v147 offset:38912
	ds_read_b128 v[212:215], v147 offset:39936
	global_load_lds_dwordx4 v136, s[34:35]
	s_mov_b32 m0, s43
	s_nop 0
	global_load_lds_dwordx4 v132, s[34:35]
	s_add_i32 s34, s54, s19
	s_mov_b32 m0, s34
	s_waitcnt vmcnt(8)
	s_waitcnt lgkmcnt(0)
	s_barrier
	s_setprio 1
	v_mfma_f32_16x16x32_bf16 v[126:129], v[148:151], v[180:183], v[126:129]
	v_mfma_f32_16x16x32_bf16 v[122:125], v[156:159], v[180:183], v[122:125]
	v_mfma_f32_16x16x32_bf16 v[118:121], v[148:151], v[188:191], v[118:121]
	v_mfma_f32_16x16x32_bf16 v[110:113], v[156:159], v[188:191], v[110:113]
	v_mfma_f32_16x16x32_bf16 v[102:105], v[148:151], v[196:199], v[102:105]
	v_mfma_f32_16x16x32_bf16 v[94:97], v[156:159], v[196:199], v[94:97]
	v_mfma_f32_16x16x32_bf16 v[86:89], v[148:151], v[208:211], v[86:89]
	v_mfma_f32_16x16x32_bf16 v[78:81], v[156:159], v[208:211], v[78:81]
	v_mfma_f32_16x16x32_bf16 v[126:129], v[152:155], v[184:187], v[126:129]
	v_mfma_f32_16x16x32_bf16 v[122:125], v[160:163], v[184:187], v[122:125]
	v_mfma_f32_16x16x32_bf16 v[118:121], v[152:155], v[192:195], v[118:121]
	v_mfma_f32_16x16x32_bf16 v[110:113], v[160:163], v[192:195], v[110:113]
	v_mfma_f32_16x16x32_bf16 v[102:105], v[152:155], v[200:203], v[102:105]
	v_mfma_f32_16x16x32_bf16 v[94:97], v[160:163], v[200:203], v[94:97]
	v_mfma_f32_16x16x32_bf16 v[86:89], v[152:155], v[212:215], v[86:89]
	v_mfma_f32_16x16x32_bf16 v[78:81], v[160:163], v[212:215], v[78:81]
	s_setprio 0
	s_setprio 1
	v_mfma_f32_16x16x32_bf16 v[114:117], v[164:167], v[180:183], v[114:117]
	v_mfma_f32_16x16x32_bf16 v[106:109], v[172:175], v[180:183], v[106:109]
	v_mfma_f32_16x16x32_bf16 v[98:101], v[164:167], v[188:191], v[98:101]
	v_mfma_f32_16x16x32_bf16 v[90:93], v[172:175], v[188:191], v[90:93]
	v_mfma_f32_16x16x32_bf16 v[82:85], v[164:167], v[196:199], v[82:85]
	v_mfma_f32_16x16x32_bf16 v[74:77], v[172:175], v[196:199], v[74:77]
	v_mfma_f32_16x16x32_bf16 v[70:73], v[164:167], v[208:211], v[70:73]
	v_mfma_f32_16x16x32_bf16 v[66:69], v[172:175], v[208:211], v[66:69]
	v_mfma_f32_16x16x32_bf16 v[114:117], v[168:171], v[184:187], v[114:117]
	v_mfma_f32_16x16x32_bf16 v[106:109], v[176:179], v[184:187], v[106:109]
	v_mfma_f32_16x16x32_bf16 v[98:101], v[168:171], v[192:195], v[98:101]
	v_mfma_f32_16x16x32_bf16 v[90:93], v[176:179], v[192:195], v[90:93]
	v_mfma_f32_16x16x32_bf16 v[82:85], v[168:171], v[200:203], v[82:85]
	v_mfma_f32_16x16x32_bf16 v[74:77], v[176:179], v[200:203], v[74:77]
	v_mfma_f32_16x16x32_bf16 v[70:73], v[168:171], v[212:215], v[70:73]
	v_mfma_f32_16x16x32_bf16 v[66:69], v[176:179], v[212:215], v[66:69]
	s_setprio 0
	s_barrier
; #define PG8_STAGE(bufoff, gbase, voff) do { _Pragma("unroll") for (int _i = 0; _i < 2; ++_i) \
;         __builtin_amdgcn_global_load_lds((const unsigned*)((const char*)(gbase) + (voff)[_i]), (PG8_LAS unsigned*)(lds + (bufoff) + ldsw + _i * 8192), 16, 0, 0); } while (0)
; #define PG8_LDA(dst, b, h) do { _Pragma("unroll") for (int m = 0; m < 4; ++m) _Pragma("unroll") for (int k = 0; k < 2; ++k) dst[m][k] = *(const PG8_LAS bf16x8*)(lds + PG8_SA(b, h) + aoff + m * 2048 + k * 1024); } while (0)
; #define PG8_LDB(dst, b, h) do { _Pragma("unroll") for (int n = 0; n < 2; ++n) _Pragma("unroll") for (int k = 0; k < 2; ++k) dst[n][k] = *(const PG8_LAS bf16x8*)(lds + PG8_SB(b, h) + boff + n * 2048 + k * 1024); } while (0)
; #define PG8_MMA(ai, bj, At, Bt) do { __builtin_amdgcn_s_setprio(1); _Pragma("unroll") for (int m = 0; m < 4; ++m) _Pragma("unroll") for (int n = 0; n < 2; ++n) _Pragma("unroll") for (int k = 0; k < 2; ++k) \
;         acc[ai][bj][m][n] = __builtin_amdgcn_mfma_f32_16x16x32_bf16(Bt[n][k], At[m][k], acc[ai][bj][m][n], 0, 0, 0); __builtin_amdgcn_s_setprio(0); } while (0)
; #define PG8_BAR __builtin_amdgcn_s_barrier()
; template <class Epi, class Sched, bool ALIGN_EPI = false, bool SP2 = false>
; __device__ __forceinline__ void gemm_phase(PG8_LAS unsigned char* lds, const Gemm g, const Sched& S, const Epi& E, const int tid_in) {
;     ...
;             PG8_LDB(B0, 0, 0); PG8_LDB(B1, 0, 1); PG8_SCHED; PG8_LDA(At, 0, 0); PG8_STAGE(PG8_SA(1, 1), a1 + hstep, voffA);
;             PG8_WAIT_V(8); PG8_WAIT_L(0); PG8_BAR; PG8_MMA(0, 0, At, B0); PG8_MMA(0, 1, At, B1); PG8_BAR; PG8_SCHED;
;             PG8_LDA(At, 0, 1); PG8_STAGE(PG8_SB(0, 0), b2, voffB); PG8_STAGE(PG8_SB(0, 1), b2 + hstep, voffB); PG8_STAGE(PG8_SA(0, 0), a2, voffA);
;             PG8_WAIT_V(8); PG8_WAIT_L(0); PG8_BAR; PG8_MMA(1, 0, At, B0); PG8_MMA(1, 1, At, B1); PG8_BAR; PG8_SCHED;
;             PG8_LDB(B0, 1, 0); PG8_LDB(B1, 1, 1); PG8_SCHED; PG8_LDA(At, 1, 0); PG8_STAGE(PG8_SA(0, 1), a2 + hstep, voffA);
;             PG8_WAIT_V(8); PG8_WAIT_L(0); PG8_BAR; PG8_MMA(0, 0, At, B0); PG8_MMA(0, 1, At, B1); PG8_BAR; PG8_SCHED;
;             PG8_LDA(At, 1, 1); PG8_STAGE(PG8_SB(1, 0), b3, voffB); PG8_STAGE(PG8_SB(1, 1), b3 + hstep, voffB); PG8_STAGE(PG8_SA(1, 0), a3, voffA);
;             PG8_WAIT_V(8); PG8_WAIT_L(0); PG8_BAR; PG8_MMA(1, 0, At, B0); PG8_MMA(1, 1, At, B1); PG8_BAR; PG8_SCHED;
	ds_read_b128 v[180:183], v147 offset:49152
	ds_read_b128 v[184:187], v147 offset:50176
	ds_read_b128 v[188:191], v147 offset:51200
	ds_read_b128 v[192:195], v147 offset:52224
	ds_read_b128 v[196:199], v147 offset:53248
	ds_read_b128 v[200:203], v147 offset:54272
	ds_read_b128 v[208:211], v147 offset:55296
	ds_read_b128 v[212:215], v147 offset:56320
	global_load_lds_dwordx4 v134, s[98:99]
	s_add_i32 m0, s34, 0x2000
	s_add_u32 s30, s30, 0x80080
	s_addc_u32 s31, s31, 0
	s_add_i32 s34, s55, s19
	global_load_lds_dwordx4 v130, s[98:99]
	s_mov_b32 m0, s34
	s_nop 0
	global_load_lds_dwordx4 v134, s[30:31]
	s_add_i32 m0, s34, 0x2000
	s_nop 0
	global_load_lds_dwordx4 v130, s[30:31]
	s_mov_b32 m0, s44
	s_nop 0
	global_load_lds_dwordx4 v136, s[100:101]
	s_add_i32 s53, s53, 2
	s_add_u32 s28, s28, 0x100
	s_addc_u32 s29, s29, 0
	s_add_u32 s51, s51, 0x100
	s_addc_u32 s52, s52, 0
	s_add_u32 s30, s28, 0xfff80080
	s_addc_u32 s31, s29, -1
	s_add_i32 s54, 0, 0x10000
	s_cmp_eq_u32 s53, 28
	s_cselect_b32 s35, s23, s31
	s_cselect_b32 s34, s49, s30
	s_cselect_b32 s31, s21, s52
	s_cselect_b32 s30, s50, s51
	s_add_i32 s56, 0, 0x14000
	s_cmp_gt_u32 s53, 29
	s_waitcnt vmcnt(7)
	s_waitcnt lgkmcnt(0)
	s_barrier
	s_setprio 1
	v_mfma_f32_16x16x32_bf16 v[62:65], v[148:151], v[180:183], v[62:65]
	v_mfma_f32_16x16x32_bf16 v[58:61], v[156:159], v[180:183], v[58:61]
	v_mfma_f32_16x16x32_bf16 v[54:57], v[148:151], v[188:191], v[54:57]
	v_mfma_f32_16x16x32_bf16 v[46:49], v[156:159], v[188:191], v[46:49]
	v_mfma_f32_16x16x32_bf16 v[38:41], v[148:151], v[196:199], v[38:41]
	v_mfma_f32_16x16x32_bf16 v[30:33], v[156:159], v[196:199], v[30:33]
	v_mfma_f32_16x16x32_bf16 v[22:25], v[148:151], v[208:211], v[22:25]
	v_mfma_f32_16x16x32_bf16 v[12:15], v[156:159], v[208:211], v[12:15]
	v_mfma_f32_16x16x32_bf16 v[62:65], v[152:155], v[184:187], v[62:65]
	v_mfma_f32_16x16x32_bf16 v[58:61], v[160:163], v[184:187], v[58:61]
	v_mfma_f32_16x16x32_bf16 v[54:57], v[152:155], v[192:195], v[54:57]
	v_mfma_f32_16x16x32_bf16 v[46:49], v[160:163], v[192:195], v[46:49]
	v_mfma_f32_16x16x32_bf16 v[38:41], v[152:155], v[200:203], v[38:41]
	v_mfma_f32_16x16x32_bf16 v[30:33], v[160:163], v[200:203], v[30:33]
	v_mfma_f32_16x16x32_bf16 v[22:25], v[152:155], v[212:215], v[22:25]
	v_mfma_f32_16x16x32_bf16 v[12:15], v[160:163], v[212:215], v[12:15]
	s_setprio 0
	s_setprio 1
	v_mfma_f32_16x16x32_bf16 v[50:53], v[164:167], v[180:183], v[50:53]
	v_mfma_f32_16x16x32_bf16 v[42:45], v[172:175], v[180:183], v[42:45]
	v_mfma_f32_16x16x32_bf16 v[34:37], v[164:167], v[188:191], v[34:37]
	v_mfma_f32_16x16x32_bf16 v[26:29], v[172:175], v[188:191], v[26:29]
	v_mfma_f32_16x16x32_bf16 v[16:19], v[164:167], v[196:199], v[16:19]
	v_mfma_f32_16x16x32_bf16 v[8:11], v[172:175], v[196:199], v[8:11]
	v_mfma_f32_16x16x32_bf16 v[4:7], v[164:167], v[208:211], v[4:7]
	v_mfma_f32_16x16x32_bf16 v[0:3], v[172:175], v[208:211], v[0:3]
	v_mfma_f32_16x16x32_bf16 v[50:53], v[168:171], v[184:187], v[50:53]
	v_mfma_f32_16x16x32_bf16 v[42:45], v[176:179], v[184:187], v[42:45]
	v_mfma_f32_16x16x32_bf16 v[34:37], v[168:171], v[192:195], v[34:37]
	v_mfma_f32_16x16x32_bf16 v[26:29], v[176:179], v[192:195], v[26:29]
	v_mfma_f32_16x16x32_bf16 v[16:19], v[168:171], v[200:203], v[16:19]
	v_mfma_f32_16x16x32_bf16 v[8:11], v[176:179], v[200:203], v[8:11]
	v_mfma_f32_16x16x32_bf16 v[4:7], v[168:171], v[212:215], v[4:7]
	v_mfma_f32_16x16x32_bf16 v[0:3], v[176:179], v[212:215], v[0:3]
	s_setprio 0
	s_barrier
.LBB0_394:
	s_mov_b32 m0, s45
	s_nop 0
	global_load_lds_dwordx4 v132, s[100:101]
	ds_read_b128 v[148:151], v216
	ds_read_b128 v[152:155], v216 offset:1024
	ds_read_b128 v[156:159], v216 offset:2048
	ds_read_b128 v[160:163], v216 offset:3072
	ds_read_b128 v[164:167], v217
	ds_read_b128 v[168:171], v217 offset:1024
	ds_read_b128 v[172:175], v217 offset:2048
	ds_read_b128 v[176:179], v217 offset:3072
	s_add_i32 m0, s38, 0xc000
	ds_read_b128 v[180:183], v147
	ds_read_b128 v[184:187], v147 offset:1024
	ds_read_b128 v[188:191], v147 offset:2048
	ds_read_b128 v[192:195], v147 offset:3072
	ds_read_b128 v[196:199], v147 offset:4096
	ds_read_b128 v[200:203], v147 offset:5120
	ds_read_b128 v[208:211], v147 offset:6144
	ds_read_b128 v[212:215], v147 offset:7168
	global_load_lds_dwordx4 v140, s[28:29]
	s_add_i32 m0, s38, 0xe000
	s_nop 0
	global_load_lds_dwordx4 v142, s[28:29]
	s_add_i32 s54, s54, s19
	s_add_u32 s98, s30, 0x80
	s_addc_u32 s99, s31, 0
	s_mov_b32 m0, s54
	s_waitcnt vmcnt(8)
	s_waitcnt lgkmcnt(0)
	s_barrier
	s_setprio 1
	v_mfma_f32_16x16x32_bf16 v[126:129], v[148:151], v[180:183], v[126:129]
	v_mfma_f32_16x16x32_bf16 v[122:125], v[156:159], v[180:183], v[122:125]
	v_mfma_f32_16x16x32_bf16 v[118:121], v[148:151], v[188:191], v[118:121]
	v_mfma_f32_16x16x32_bf16 v[110:113], v[156:159], v[188:191], v[110:113]
	v_mfma_f32_16x16x32_bf16 v[102:105], v[148:151], v[196:199], v[102:105]
	v_mfma_f32_16x16x32_bf16 v[94:97], v[156:159], v[196:199], v[94:97]
	v_mfma_f32_16x16x32_bf16 v[86:89], v[148:151], v[208:211], v[86:89]
	v_mfma_f32_16x16x32_bf16 v[78:81], v[156:159], v[208:211], v[78:81]
	v_mfma_f32_16x16x32_bf16 v[126:129], v[152:155], v[184:187], v[126:129]
	v_mfma_f32_16x16x32_bf16 v[122:125], v[160:163], v[184:187], v[122:125]
	v_mfma_f32_16x16x32_bf16 v[118:121], v[152:155], v[192:195], v[118:121]
	v_mfma_f32_16x16x32_bf16 v[110:113], v[160:163], v[192:195], v[110:113]
	v_mfma_f32_16x16x32_bf16 v[102:105], v[152:155], v[200:203], v[102:105]
	v_mfma_f32_16x16x32_bf16 v[94:97], v[160:163], v[200:203], v[94:97]
	v_mfma_f32_16x16x32_bf16 v[86:89], v[152:155], v[212:215], v[86:89]
	v_mfma_f32_16x16x32_bf16 v[78:81], v[160:163], v[212:215], v[78:81]
	s_setprio 0
	s_setprio 1
	v_mfma_f32_16x16x32_bf16 v[114:117], v[164:167], v[180:183], v[114:117]
	v_mfma_f32_16x16x32_bf16 v[106:109], v[172:175], v[180:183], v[106:109]
	v_mfma_f32_16x16x32_bf16 v[98:101], v[164:167], v[188:191], v[98:101]
	v_mfma_f32_16x16x32_bf16 v[90:93], v[172:175], v[188:191], v[90:93]
	v_mfma_f32_16x16x32_bf16 v[82:85], v[164:167], v[196:199], v[82:85]
	v_mfma_f32_16x16x32_bf16 v[74:77], v[172:175], v[196:199], v[74:77]
	v_mfma_f32_16x16x32_bf16 v[70:73], v[164:167], v[208:211], v[70:73]
	v_mfma_f32_16x16x32_bf16 v[66:69], v[172:175], v[208:211], v[66:69]
	v_mfma_f32_16x16x32_bf16 v[114:117], v[168:171], v[184:187], v[114:117]
	v_mfma_f32_16x16x32_bf16 v[106:109], v[176:179], v[184:187], v[106:109]
	v_mfma_f32_16x16x32_bf16 v[98:101], v[168:171], v[192:195], v[98:101]
	v_mfma_f32_16x16x32_bf16 v[90:93], v[176:179], v[192:195], v[90:93]
	v_mfma_f32_16x16x32_bf16 v[82:85], v[168:171], v[200:203], v[82:85]
	v_mfma_f32_16x16x32_bf16 v[74:77], v[176:179], v[200:203], v[74:77]
	v_mfma_f32_16x16x32_bf16 v[70:73], v[168:171], v[212:215], v[70:73]
	v_mfma_f32_16x16x32_bf16 v[66:69], v[176:179], v[212:215], v[66:69]
	s_setprio 0
	s_barrier
; #define PG8_STAGE(bufoff, gbase, voff) do { _Pragma("unroll") for (int _i = 0; _i < 2; ++_i) \
;         __builtin_amdgcn_global_load_lds((const unsigned*)((const char*)(gbase) + (voff)[_i]), (PG8_LAS unsigned*)(lds + (bufoff) + ldsw + _i * 8192), 16, 0, 0); } while (0)
; #define PG8_LDA(dst, b, h) do { _Pragma("unroll") for (int m = 0; m < 4; ++m) _Pragma("unroll") for (int k = 0; k < 2; ++k) dst[m][k] = *(const PG8_LAS bf16x8*)(lds + PG8_SA(b, h) + aoff + m * 2048 + k * 1024); } while (0)
; #define PG8_LDB(dst, b, h) do { _Pragma("unroll") for (int n = 0; n < 2; ++n) _Pragma("unroll") for (int k = 0; k < 2; ++k) dst[n][k] = *(const PG8_LAS bf16x8*)(lds + PG8_SB(b, h) + boff + n * 2048 + k * 1024); } while (0)
; #define PG8_MMA(ai, bj, At, Bt) do { __builtin_amdgcn_s_setprio(1); _Pragma("unroll") for (int m = 0; m < 4; ++m) _Pragma("unroll") for (int n = 0; n < 2; ++n) _Pragma("unroll") for (int k = 0; k < 2; ++k) \
;         acc[ai][bj][m][n] = __builtin_amdgcn_mfma_f32_16x16x32_bf16(Bt[n][k], At[m][k], acc[ai][bj][m][n], 0, 0, 0); __builtin_amdgcn_s_setprio(0); } while (0)
; #define PG8_WAIT_V(n) asm volatile("s_waitcnt vmcnt(" #n ")" ::: "memory")
; #define PG8_WAIT_L(n) asm volatile("s_waitcnt lgkmcnt(" #n ")" ::: "memory")
; #define PG8_BAR __builtin_amdgcn_s_barrier()
; #define PG8_SCHED __builtin_amdgcn_sched_barrier(0)
; template <class Epi, class Sched, bool ALIGN_EPI = false, bool SP2 = false>
; __device__ __forceinline__ void gemm_phase(PG8_LAS unsigned char* lds, const Gemm g, const Sched& S, const Epi& E, const int tid_in) {
;     ...
;             PG8_LDA(At, 0, 1); PG8_STAGE(PG8_SB(0, 0), b2, voffB); PG8_STAGE(PG8_SB(0, 1), b2 + hstep, voffB); PG8_STAGE(PG8_SA(0, 0), a2, voffA);
;             PG8_WAIT_V(8); PG8_WAIT_L(0); PG8_BAR; PG8_MMA(1, 0, At, B0); PG8_MMA(1, 1, At, B1); PG8_BAR; PG8_SCHED;
;             PG8_LDB(B0, 1, 0); PG8_LDB(B1, 1, 1); PG8_SCHED; PG8_LDA(At, 1, 0); PG8_STAGE(PG8_SA(0, 1), a2 + hstep, voffA);
;             PG8_WAIT_V(8); PG8_WAIT_L(0); PG8_BAR; PG8_MMA(0, 0, At, B0); PG8_MMA(0, 1, At, B1); PG8_BAR; PG8_SCHED;
;             PG8_LDA(At, 1, 1); PG8_STAGE(PG8_SB(1, 0), b3, voffB); PG8_STAGE(PG8_SB(1, 1), b3 + hstep, voffB); PG8_STAGE(PG8_SA(1, 0), a3, voffA);
	ds_read_b128 v[180:183], v147 offset:16384
	ds_read_b128 v[184:187], v147 offset:17408
	ds_read_b128 v[188:191], v147 offset:18432
	ds_read_b128 v[192:195], v147 offset:19456
	ds_read_b128 v[196:199], v147 offset:20480
	ds_read_b128 v[200:203], v147 offset:21504
	ds_read_b128 v[208:211], v147 offset:22528
	ds_read_b128 v[212:215], v147 offset:23552
	global_load_lds_dwordx4 v134, s[30:31]
	s_add_i32 m0, s54, 0x2000
	s_add_u32 s54, s30, 0x80000
	s_addc_u32 s55, s31, 0
	s_add_i32 s56, s56, s19
	global_load_lds_dwordx4 v130, s[30:31]
	s_mov_b32 m0, s56
	s_add_u32 s100, s34, 0x80
	s_addc_u32 s101, s35, 0
	global_load_lds_dwordx4 v134, s[54:55]
	s_add_i32 m0, s56, 0x2000
	s_nop 0
	global_load_lds_dwordx4 v130, s[54:55]
	s_mov_b32 m0, s38
	s_nop 0
	global_load_lds_dwordx4 v136, s[34:35]
	s_add_i32 s54, 0, 0x18000
	s_add_i32 s55, 0, 0x1c000
	s_waitcnt vmcnt(7)
	s_waitcnt lgkmcnt(0)
	s_barrier
	s_setprio 1
	v_mfma_f32_16x16x32_bf16 v[62:65], v[148:151], v[180:183], v[62:65]
	v_mfma_f32_16x16x32_bf16 v[58:61], v[156:159], v[180:183], v[58:61]
	v_mfma_f32_16x16x32_bf16 v[54:57], v[148:151], v[188:191], v[54:57]
	v_mfma_f32_16x16x32_bf16 v[46:49], v[156:159], v[188:191], v[46:49]
	v_mfma_f32_16x16x32_bf16 v[38:41], v[148:151], v[196:199], v[38:41]
	v_mfma_f32_16x16x32_bf16 v[30:33], v[156:159], v[196:199], v[30:33]
	v_mfma_f32_16x16x32_bf16 v[22:25], v[148:151], v[208:211], v[22:25]
	v_mfma_f32_16x16x32_bf16 v[12:15], v[156:159], v[208:211], v[12:15]
	v_mfma_f32_16x16x32_bf16 v[62:65], v[152:155], v[184:187], v[62:65]
	v_mfma_f32_16x16x32_bf16 v[58:61], v[160:163], v[184:187], v[58:61]
	v_mfma_f32_16x16x32_bf16 v[54:57], v[152:155], v[192:195], v[54:57]
	v_mfma_f32_16x16x32_bf16 v[46:49], v[160:163], v[192:195], v[46:49]
	v_mfma_f32_16x16x32_bf16 v[38:41], v[152:155], v[200:203], v[38:41]
	v_mfma_f32_16x16x32_bf16 v[30:33], v[160:163], v[200:203], v[30:33]
	v_mfma_f32_16x16x32_bf16 v[22:25], v[152:155], v[212:215], v[22:25]
	v_mfma_f32_16x16x32_bf16 v[12:15], v[160:163], v[212:215], v[12:15]
	s_setprio 0
	s_setprio 1
	v_mfma_f32_16x16x32_bf16 v[50:53], v[164:167], v[180:183], v[50:53]
	v_mfma_f32_16x16x32_bf16 v[42:45], v[172:175], v[180:183], v[42:45]
	v_mfma_f32_16x16x32_bf16 v[34:37], v[164:167], v[188:191], v[34:37]
	v_mfma_f32_16x16x32_bf16 v[26:29], v[172:175], v[188:191], v[26:29]
	v_mfma_f32_16x16x32_bf16 v[16:19], v[164:167], v[196:199], v[16:19]
	v_mfma_f32_16x16x32_bf16 v[8:11], v[172:175], v[196:199], v[8:11]
	v_mfma_f32_16x16x32_bf16 v[4:7], v[164:167], v[208:211], v[4:7]
	v_mfma_f32_16x16x32_bf16 v[0:3], v[172:175], v[208:211], v[0:3]
	v_mfma_f32_16x16x32_bf16 v[50:53], v[168:171], v[184:187], v[50:53]
	v_mfma_f32_16x16x32_bf16 v[42:45], v[176:179], v[184:187], v[42:45]
	v_mfma_f32_16x16x32_bf16 v[34:37], v[168:171], v[192:195], v[34:37]
	v_mfma_f32_16x16x32_bf16 v[26:29], v[176:179], v[192:195], v[26:29]
	v_mfma_f32_16x16x32_bf16 v[16:19], v[168:171], v[200:203], v[16:19]
	v_mfma_f32_16x16x32_bf16 v[8:11], v[176:179], v[200:203], v[8:11]
	v_mfma_f32_16x16x32_bf16 v[4:7], v[168:171], v[212:215], v[4:7]
	v_mfma_f32_16x16x32_bf16 v[0:3], v[176:179], v[212:215], v[0:3]
	s_setprio 0
	s_barrier
	ds_read_b128 v[148:151], v218
	ds_read_b128 v[152:155], v218 offset:1024
	ds_read_b128 v[156:159], v218 offset:2048
	ds_read_b128 v[160:163], v218 offset:3072
	ds_read_b128 v[164:167], v219
	ds_read_b128 v[168:171], v219 offset:1024
	ds_read_b128 v[172:175], v219 offset:2048
	ds_read_b128 v[176:179], v219 offset:3072
	s_mov_b32 m0, s39
	s_nop 0
	global_load_lds_dwordx4 v132, s[34:35]
	s_add_u32 s34, s34, 0x80000
	s_addc_u32 s35, s35, 0
	s_mov_b32 m0, s42
	ds_read_b128 v[180:183], v147 offset:32768
	ds_read_b128 v[184:187], v147 offset:33792
	ds_read_b128 v[188:191], v147 offset:34816
	ds_read_b128 v[192:195], v147 offset:35840
	ds_read_b128 v[196:199], v147 offset:36864
	ds_read_b128 v[200:203], v147 offset:37888
	ds_read_b128 v[208:211], v147 offset:38912
	ds_read_b128 v[212:215], v147 offset:39936
	global_load_lds_dwordx4 v136, s[34:35]
	s_mov_b32 m0, s43
	s_nop 0
	global_load_lds_dwordx4 v132, s[34:35]
	s_add_i32 s34, s54, s19
	s_mov_b32 m0, s34
	s_waitcnt vmcnt(8)
	s_waitcnt lgkmcnt(0)
	s_barrier
; #define PG8_STAGE(bufoff, gbase, voff) do { _Pragma("unroll") for (int _i = 0; _i < 2; ++_i) \
;         __builtin_amdgcn_global_load_lds((const unsigned*)((const char*)(gbase) + (voff)[_i]), (PG8_LAS unsigned*)(lds + (bufoff) + ldsw + _i * 8192), 16, 0, 0); } while (0)
; #define PG8_LDA(dst, b, h) do { _Pragma("unroll") for (int m = 0; m < 4; ++m) _Pragma("unroll") for (int k = 0; k < 2; ++k) dst[m][k] = *(const PG8_LAS bf16x8*)(lds + PG8_SA(b, h) + aoff + m * 2048 + k * 1024); } while (0)
; #define PG8_LDB(dst, b, h) do { _Pragma("unroll") for (int n = 0; n < 2; ++n) _Pragma("unroll") for (int k = 0; k < 2; ++k) dst[n][k] = *(const PG8_LAS bf16x8*)(lds + PG8_SB(b, h) + boff + n * 2048 + k * 1024); } while (0)
; #define PG8_MMA(ai, bj, At, Bt) do { __builtin_amdgcn_s_setprio(1); _Pragma("unroll") for (int m = 0; m < 4; ++m) _Pragma("unroll") for (int n = 0; n < 2; ++n) _Pragma("unroll") for (int k = 0; k < 2; ++k) \
;         acc[ai][bj][m][n] = __builtin_amdgcn_mfma_f32_16x16x32_bf16(Bt[n][k], At[m][k], acc[ai][bj][m][n], 0, 0, 0); __builtin_amdgcn_s_setprio(0); } while (0)
; #define PG8_WAIT_V(n) asm volatile("s_waitcnt vmcnt(" #n ")" ::: "memory")
; #define PG8_WAIT_L(n) asm volatile("s_waitcnt lgkmcnt(" #n ")" ::: "memory")
; #define PG8_BAR __builtin_amdgcn_s_barrier()
; #define PG8_SCHED __builtin_amdgcn_sched_barrier(0)
; template <class Epi, class Sched, bool ALIGN_EPI = false, bool SP2 = false>
; __device__ __forceinline__ void gemm_phase(PG8_LAS unsigned char* lds, const Gemm g, const Sched& S, const Epi& E, const int tid_in) {
;     ...
;             PG8_LDB(B0, 1, 0); PG8_LDB(B1, 1, 1); PG8_SCHED; PG8_LDA(At, 1, 0); PG8_STAGE(PG8_SA(0, 1), a2 + hstep, voffA);
;             PG8_WAIT_V(8); PG8_WAIT_L(0); PG8_BAR; PG8_MMA(0, 0, At, B0); PG8_MMA(0, 1, At, B1); PG8_BAR; PG8_SCHED;
;             PG8_LDA(At, 1, 1); PG8_STAGE(PG8_SB(1, 0), b3, voffB); PG8_STAGE(PG8_SB(1, 1), b3 + hstep, voffB); PG8_STAGE(PG8_SA(1, 0), a3, voffA);
;             PG8_WAIT_V(8); PG8_WAIT_L(0); PG8_BAR; PG8_MMA(1, 0, At, B0); PG8_MMA(1, 1, At, B1); PG8_BAR; PG8_SCHED;
	s_setprio 1
	v_mfma_f32_16x16x32_bf16 v[126:129], v[148:151], v[180:183], v[126:129]
	v_mfma_f32_16x16x32_bf16 v[122:125], v[156:159], v[180:183], v[122:125]
	v_mfma_f32_16x16x32_bf16 v[118:121], v[148:151], v[188:191], v[118:121]
	v_mfma_f32_16x16x32_bf16 v[110:113], v[156:159], v[188:191], v[110:113]
	v_mfma_f32_16x16x32_bf16 v[102:105], v[148:151], v[196:199], v[102:105]
	v_mfma_f32_16x16x32_bf16 v[94:97], v[156:159], v[196:199], v[94:97]
	v_mfma_f32_16x16x32_bf16 v[86:89], v[148:151], v[208:211], v[86:89]
	v_mfma_f32_16x16x32_bf16 v[78:81], v[156:159], v[208:211], v[78:81]
	v_mfma_f32_16x16x32_bf16 v[126:129], v[152:155], v[184:187], v[126:129]
	v_mfma_f32_16x16x32_bf16 v[122:125], v[160:163], v[184:187], v[122:125]
	v_mfma_f32_16x16x32_bf16 v[118:121], v[152:155], v[192:195], v[118:121]
	v_mfma_f32_16x16x32_bf16 v[110:113], v[160:163], v[192:195], v[110:113]
	v_mfma_f32_16x16x32_bf16 v[102:105], v[152:155], v[200:203], v[102:105]
	v_mfma_f32_16x16x32_bf16 v[94:97], v[160:163], v[200:203], v[94:97]
	v_mfma_f32_16x16x32_bf16 v[86:89], v[152:155], v[212:215], v[86:89]
	v_mfma_f32_16x16x32_bf16 v[78:81], v[160:163], v[212:215], v[78:81]
	s_setprio 0
	s_setprio 1
	v_mfma_f32_16x16x32_bf16 v[114:117], v[164:167], v[180:183], v[114:117]
	v_mfma_f32_16x16x32_bf16 v[106:109], v[172:175], v[180:183], v[106:109]
	v_mfma_f32_16x16x32_bf16 v[98:101], v[164:167], v[188:191], v[98:101]
	v_mfma_f32_16x16x32_bf16 v[90:93], v[172:175], v[188:191], v[90:93]
	v_mfma_f32_16x16x32_bf16 v[82:85], v[164:167], v[196:199], v[82:85]
	v_mfma_f32_16x16x32_bf16 v[74:77], v[172:175], v[196:199], v[74:77]
	v_mfma_f32_16x16x32_bf16 v[70:73], v[164:167], v[208:211], v[70:73]
	v_mfma_f32_16x16x32_bf16 v[66:69], v[172:175], v[208:211], v[66:69]
	v_mfma_f32_16x16x32_bf16 v[114:117], v[168:171], v[184:187], v[114:117]
	v_mfma_f32_16x16x32_bf16 v[106:109], v[176:179], v[184:187], v[106:109]
	v_mfma_f32_16x16x32_bf16 v[98:101], v[168:171], v[192:195], v[98:101]
	v_mfma_f32_16x16x32_bf16 v[90:93], v[176:179], v[192:195], v[90:93]
	v_mfma_f32_16x16x32_bf16 v[82:85], v[168:171], v[200:203], v[82:85]
	v_mfma_f32_16x16x32_bf16 v[74:77], v[176:179], v[200:203], v[74:77]
	v_mfma_f32_16x16x32_bf16 v[70:73], v[168:171], v[212:215], v[70:73]
	v_mfma_f32_16x16x32_bf16 v[66:69], v[176:179], v[212:215], v[66:69]
	s_setprio 0
	s_barrier
	ds_read_b128 v[180:183], v147 offset:49152
	ds_read_b128 v[184:187], v147 offset:50176
	ds_read_b128 v[188:191], v147 offset:51200
	ds_read_b128 v[192:195], v147 offset:52224
	ds_read_b128 v[196:199], v147 offset:53248
	ds_read_b128 v[200:203], v147 offset:54272
	ds_read_b128 v[208:211], v147 offset:55296
	ds_read_b128 v[212:215], v147 offset:56320
	global_load_lds_dwordx4 v134, s[98:99]
	s_add_i32 m0, s34, 0x2000
	s_add_u32 s30, s30, 0x80080
	s_addc_u32 s31, s31, 0
	s_add_i32 s34, s55, s19
	global_load_lds_dwordx4 v130, s[98:99]
	s_mov_b32 m0, s34
	s_nop 0
	global_load_lds_dwordx4 v134, s[30:31]
	s_add_i32 m0, s34, 0x2000
	s_nop 0
	global_load_lds_dwordx4 v130, s[30:31]
	s_mov_b32 m0, s44
	s_nop 0
	global_load_lds_dwordx4 v136, s[100:101]
	s_add_i32 s53, s53, 2
	s_add_u32 s28, s28, 0x100
	s_addc_u32 s29, s29, 0
	s_add_u32 s51, s51, 0x100
	s_addc_u32 s52, s52, 0
	s_add_u32 s30, s28, 0xfff80080
	s_addc_u32 s31, s29, -1
	s_add_i32 s54, 0, 0x10000
	s_cmp_eq_u32 s53, 28
	s_cselect_b32 s35, s23, s31
	s_cselect_b32 s34, s49, s30
	s_cselect_b32 s31, s21, s52
	s_cselect_b32 s30, s50, s51
	s_add_i32 s56, 0, 0x14000
	s_cmp_gt_u32 s53, 29
	s_waitcnt vmcnt(7)
	s_waitcnt lgkmcnt(0)
	s_barrier
	s_setprio 1
	v_mfma_f32_16x16x32_bf16 v[62:65], v[148:151], v[180:183], v[62:65]
	v_mfma_f32_16x16x32_bf16 v[58:61], v[156:159], v[180:183], v[58:61]
	v_mfma_f32_16x16x32_bf16 v[54:57], v[148:151], v[188:191], v[54:57]
	v_mfma_f32_16x16x32_bf16 v[46:49], v[156:159], v[188:191], v[46:49]
	v_mfma_f32_16x16x32_bf16 v[38:41], v[148:151], v[196:199], v[38:41]
	v_mfma_f32_16x16x32_bf16 v[30:33], v[156:159], v[196:199], v[30:33]
	v_mfma_f32_16x16x32_bf16 v[22:25], v[148:151], v[208:211], v[22:25]
	v_mfma_f32_16x16x32_bf16 v[12:15], v[156:159], v[208:211], v[12:15]
	v_mfma_f32_16x16x32_bf16 v[62:65], v[152:155], v[184:187], v[62:65]
	v_mfma_f32_16x16x32_bf16 v[58:61], v[160:163], v[184:187], v[58:61]
	v_mfma_f32_16x16x32_bf16 v[54:57], v[152:155], v[192:195], v[54:57]
	v_mfma_f32_16x16x32_bf16 v[46:49], v[160:163], v[192:195], v[46:49]
	v_mfma_f32_16x16x32_bf16 v[38:41], v[152:155], v[200:203], v[38:41]
	v_mfma_f32_16x16x32_bf16 v[30:33], v[160:163], v[200:203], v[30:33]
	v_mfma_f32_16x16x32_bf16 v[22:25], v[152:155], v[212:215], v[22:25]
	v_mfma_f32_16x16x32_bf16 v[12:15], v[160:163], v[212:215], v[12:15]
	s_setprio 0
	s_setprio 1
	v_mfma_f32_16x16x32_bf16 v[50:53], v[164:167], v[180:183], v[50:53]
	v_mfma_f32_16x16x32_bf16 v[42:45], v[172:175], v[180:183], v[42:45]
	v_mfma_f32_16x16x32_bf16 v[34:37], v[164:167], v[188:191], v[34:37]
	v_mfma_f32_16x16x32_bf16 v[26:29], v[172:175], v[188:191], v[26:29]
	v_mfma_f32_16x16x32_bf16 v[16:19], v[164:167], v[196:199], v[16:19]
	v_mfma_f32_16x16x32_bf16 v[8:11], v[172:175], v[196:199], v[8:11]
	v_mfma_f32_16x16x32_bf16 v[4:7], v[164:167], v[208:211], v[4:7]
	v_mfma_f32_16x16x32_bf16 v[0:3], v[172:175], v[208:211], v[0:3]
	v_mfma_f32_16x16x32_bf16 v[50:53], v[168:171], v[184:187], v[50:53]
	v_mfma_f32_16x16x32_bf16 v[42:45], v[176:179], v[184:187], v[42:45]
	v_mfma_f32_16x16x32_bf16 v[34:37], v[168:171], v[192:195], v[34:37]
	v_mfma_f32_16x16x32_bf16 v[26:29], v[176:179], v[192:195], v[26:29]
	v_mfma_f32_16x16x32_bf16 v[16:19], v[168:171], v[200:203], v[16:19]
	v_mfma_f32_16x16x32_bf16 v[8:11], v[176:179], v[200:203], v[8:11]
	v_mfma_f32_16x16x32_bf16 v[4:7], v[168:171], v[212:215], v[4:7]
	v_mfma_f32_16x16x32_bf16 v[0:3], v[176:179], v[212:215], v[0:3]
	s_setprio 0
	s_barrier
	s_cbranch_scc0 .LBB0_394
	s_and_b64 vcc, exec, s[6:7]
	v_readlane_b32 s52, v255, 9
	v_readlane_b32 s53, v255, 10
	s_cbranch_vccz .LBB0_397
	s_barrier

; #define PG8_STAGE(bufoff, gbase, voff) do { _Pragma("unroll") for (int _i = 0; _i < 2; ++_i) \
;         __builtin_amdgcn_global_load_lds((const unsigned*)((const char*)(gbase) + (voff)[_i]), (PG8_LAS unsigned*)(lds + (bufoff) + ldsw + _i * 8192), 16, 0, 0); } while (0)
; #define PG8_LDA(dst, b, h) do { _Pragma("unroll") for (int m = 0; m < 4; ++m) _Pragma("unroll") for (int k = 0; k < 2; ++k) dst[m][k] = *(const PG8_LAS bf16x8*)(lds + PG8_SA(b, h) + aoff + m * 2048 + k * 1024); } while (0)
; #define PG8_LDB(dst, b, h) do { _Pragma("unroll") for (int n = 0; n < 2; ++n) _Pragma("unroll") for (int k = 0; k < 2; ++k) dst[n][k] = *(const PG8_LAS bf16x8*)(lds + PG8_SB(b, h) + boff + n * 2048 + k * 1024); } while (0)
; #define PG8_WAIT_V(n) asm volatile("s_waitcnt vmcnt(" #n ")" ::: "memory")
; #define PG8_WAIT_L(n) asm volatile("s_waitcnt lgkmcnt(" #n ")" ::: "memory")
; #define PG8_BAR __builtin_amdgcn_s_barrier()
; #define PG8_SCHED __builtin_amdgcn_sched_barrier(0)
; template <class Epi, class Sched, bool ALIGN_EPI = false, bool SP2 = false>
; __device__ __forceinline__ void gemm_phase(PG8_LAS unsigned char* lds, const Gemm g, const Sched& S, const Epi& E, const int tid_in) {
;     ...
;         const bool has_next = S.next(ui + 1, nxt);
;         const char* nA = has_next ? (const char*)g.A + (size_t)nxt.pm * tstep : cA; const char* nB = has_next ? (const char*)g.Bt + (size_t)nxt.pn * tstep : cB;
;         for (int t = 0; t < nt; t += 2) {
;             if constexpr (Epi::KSPLIT > 0) { if (t == Epi::KSPLIT / BK) E.midk(acc, cur, wr, wc, fr, fq); }
;             const bool last = (t == nt - 2);
;             const char* a1 = cA + (size_t)(t + 1) * kstep;
;             const char* a2 = last ? nA : cA + (size_t)(t + 2) * kstep; const char* b2 = last ? nB : cB + (size_t)(t + 2) * kstep;
;             const char* a3 = a2 + kstep; const char* b3 = b2 + kstep;
;             if (last && has_next) S.a_ready(nxt);
;             if constexpr (SP2) {
;             PG8_LDB(B0, 0, 0); PG8_LDB(B1, 0, 1); PG8_SCHED; PG8_LDA(At, 0, 0); PG8_STAGE(PG8_SA(1, 1), a1 + hstep, voffA);
;             PG8_WAIT_V(8); PG8_WAIT_L(0); PG8_BAR; PG8_MMA(0, 0, At, B0); PG8_MMA(0, 1, At, B1); PG8_BAR; PG8_SCHED;
;             PG8_LDA(At, 0, 1); PG8_STAGE(PG8_SB(0, 0), b2, voffB); PG8_STAGE(PG8_SB(0, 1), b2 + hstep, voffB); PG8_STAGE(PG8_SA(0, 0), a2, voffA);
.LBB0_411:
	s_ashr_i32 s27, s26, 31
	s_lshl_b64 s[28:29], s[26:27], 20
	s_add_u32 s28, s1, s28
	s_addc_u32 s29, s5, s29
	s_and_b64 s[30:31], s[36:37], exec
	s_cselect_b32 s27, s29, s35
	s_cselect_b32 s54, s28, s34
	s_ashr_i32 s7, s6, 31
	s_lshl_b64 s[30:31], s[6:7], 20
	s_add_u32 s30, s8, s30
	s_addc_u32 s31, s10, s31
	s_and_b64 s[42:43], s[36:37], exec
	s_cselect_b32 s7, s31, s39
	s_cselect_b32 s55, s30, s38
	s_add_u32 s34, s34, 0x80080
	s_addc_u32 s35, s35, 0
	s_add_u32 s56, s38, 0x100
	v_mov_b32_e32 v0, 0
	s_addc_u32 s57, s39, 0
	s_mov_b32 s58, -2
	v_add_u32_e32 v216, 0x10000, v162
	v_add_u32_e32 v217, 0x14000, v162
	v_add_u32_e32 v218, 0x18000, v162
	v_add_u32_e32 v219, 0x1c000, v162
	s_add_u32 s38, s34, 0xfff80080
	s_addc_u32 s39, s35, -1
	s_add_i32 s59, 0, 0x10000
	s_cmp_eq_u32 s58, 28
	s_cselect_b32 s43, s27, s39
	s_cselect_b32 s42, s54, s38
	s_cselect_b32 s39, s7, s57
	s_cselect_b32 s38, s55, s56
	s_add_i32 s62, 0, 0x14000
	s_mov_b32 m0, s49
	s_nop 0
	global_load_lds_dwordx4 v150, s[100:101]
	ds_read_b128 v[66:69], v216
	ds_read_b128 v[70:73], v216 offset:1024
	ds_read_b128 v[74:77], v216 offset:2048
	ds_read_b128 v[78:81], v216 offset:3072
	ds_read_b128 v[166:169], v217
	ds_read_b128 v[170:173], v217 offset:1024
	ds_read_b128 v[174:177], v217 offset:2048
	ds_read_b128 v[178:181], v217 offset:3072
	s_add_i32 m0, s44, 0xc000
	ds_read_b128 v[182:185], v165
	ds_read_b128 v[186:189], v165 offset:1024
	ds_read_b128 v[190:193], v165 offset:2048
	ds_read_b128 v[194:197], v165 offset:3072
	ds_read_b128 v[198:201], v165 offset:4096
	ds_read_b128 v[202:205], v165 offset:5120
	ds_read_b128 v[208:211], v165 offset:6144
	ds_read_b128 v[212:215], v165 offset:7168
	global_load_lds_dwordx4 v156, s[34:35]
	s_add_i32 m0, s44, 0xe000
	s_nop 0
	global_load_lds_dwordx4 v158, s[34:35]
	s_add_i32 s59, s59, s19
	s_add_u32 s98, s38, 0x80
	s_addc_u32 s99, s39, 0
	s_mov_b32 m0, s59
	s_waitcnt vmcnt(8)
	s_waitcnt lgkmcnt(0)
	s_barrier
	s_setprio 1
	v_mfma_f32_16x16x32_bf16 v[142:145], v[66:69], v[182:185], 0
	v_mfma_f32_16x16x32_bf16 v[138:141], v[74:77], v[182:185], 0
	v_mfma_f32_16x16x32_bf16 v[126:129], v[66:69], v[190:193], 0
	v_mfma_f32_16x16x32_bf16 v[122:125], v[74:77], v[190:193], 0
	v_mfma_f32_16x16x32_bf16 v[110:113], v[66:69], v[198:201], 0
	v_mfma_f32_16x16x32_bf16 v[106:109], v[74:77], v[198:201], 0
	v_mfma_f32_16x16x32_bf16 v[94:97], v[66:69], v[208:211], 0
	v_mfma_f32_16x16x32_bf16 v[90:93], v[74:77], v[208:211], 0
	v_mfma_f32_16x16x32_bf16 v[142:145], v[70:73], v[186:189], v[142:145]
	v_mfma_f32_16x16x32_bf16 v[138:141], v[78:81], v[186:189], v[138:141]
	v_mfma_f32_16x16x32_bf16 v[126:129], v[70:73], v[194:197], v[126:129]
	v_mfma_f32_16x16x32_bf16 v[122:125], v[78:81], v[194:197], v[122:125]
	v_mfma_f32_16x16x32_bf16 v[110:113], v[70:73], v[202:205], v[110:113]
	v_mfma_f32_16x16x32_bf16 v[106:109], v[78:81], v[202:205], v[106:109]
	v_mfma_f32_16x16x32_bf16 v[94:97], v[70:73], v[212:215], v[94:97]
	v_mfma_f32_16x16x32_bf16 v[90:93], v[78:81], v[212:215], v[90:93]
	s_setprio 0
	s_setprio 1
	v_mfma_f32_16x16x32_bf16 v[134:137], v[166:169], v[182:185], 0
	v_mfma_f32_16x16x32_bf16 v[130:133], v[174:177], v[182:185], 0
	v_mfma_f32_16x16x32_bf16 v[118:121], v[166:169], v[190:193], 0
	v_mfma_f32_16x16x32_bf16 v[114:117], v[174:177], v[190:193], 0
	v_mfma_f32_16x16x32_bf16 v[102:105], v[166:169], v[198:201], 0
	v_mfma_f32_16x16x32_bf16 v[98:101], v[174:177], v[198:201], 0
	v_mfma_f32_16x16x32_bf16 v[86:89], v[166:169], v[208:211], 0
	v_mfma_f32_16x16x32_bf16 v[82:85], v[174:177], v[208:211], 0
	v_mfma_f32_16x16x32_bf16 v[134:137], v[170:173], v[186:189], v[134:137]
	v_mfma_f32_16x16x32_bf16 v[130:133], v[178:181], v[186:189], v[130:133]
	v_mfma_f32_16x16x32_bf16 v[118:121], v[170:173], v[194:197], v[118:121]
	v_mfma_f32_16x16x32_bf16 v[114:117], v[178:181], v[194:197], v[114:117]
	v_mfma_f32_16x16x32_bf16 v[102:105], v[170:173], v[202:205], v[102:105]
	v_mfma_f32_16x16x32_bf16 v[98:101], v[178:181], v[202:205], v[98:101]
	v_mfma_f32_16x16x32_bf16 v[86:89], v[170:173], v[212:215], v[86:89]
	v_mfma_f32_16x16x32_bf16 v[82:85], v[178:181], v[212:215], v[82:85]
	s_setprio 0
	s_barrier
	ds_read_b128 v[182:185], v165 offset:16384
	ds_read_b128 v[186:189], v165 offset:17408
	ds_read_b128 v[190:193], v165 offset:18432
	ds_read_b128 v[194:197], v165 offset:19456
	ds_read_b128 v[198:201], v165 offset:20480
	ds_read_b128 v[202:205], v165 offset:21504
	ds_read_b128 v[208:211], v165 offset:22528
	ds_read_b128 v[212:215], v165 offset:23552
	global_load_lds_dwordx4 v148, s[38:39]
	s_add_i32 m0, s59, 0x2000
	s_add_u32 s60, s38, 0x80000
	s_addc_u32 s61, s39, 0
	s_add_i32 s59, s62, s19
	global_load_lds_dwordx4 v152, s[38:39]
	s_mov_b32 m0, s59
	s_add_u32 s100, s42, 0x80
	s_addc_u32 s101, s43, 0
	global_load_lds_dwordx4 v148, s[60:61]
	s_add_i32 m0, s59, 0x2000
	s_nop 0
	global_load_lds_dwordx4 v152, s[60:61]
	s_mov_b32 m0, s44
	s_nop 0
	global_load_lds_dwordx4 v146, s[42:43]
	s_add_i32 s59, 0, 0x18000
	s_add_i32 s60, 0, 0x1c000
	s_waitcnt vmcnt(7)
	s_waitcnt lgkmcnt(0)
	s_barrier
; #define PG8_STAGE(bufoff, gbase, voff) do { _Pragma("unroll") for (int _i = 0; _i < 2; ++_i) \
;         __builtin_amdgcn_global_load_lds((const unsigned*)((const char*)(gbase) + (voff)[_i]), (PG8_LAS unsigned*)(lds + (bufoff) + ldsw + _i * 8192), 16, 0, 0); } while (0)
; #define PG8_LDA(dst, b, h) do { _Pragma("unroll") for (int m = 0; m < 4; ++m) _Pragma("unroll") for (int k = 0; k < 2; ++k) dst[m][k] = *(const PG8_LAS bf16x8*)(lds + PG8_SA(b, h) + aoff + m * 2048 + k * 1024); } while (0)
; #define PG8_LDB(dst, b, h) do { _Pragma("unroll") for (int n = 0; n < 2; ++n) _Pragma("unroll") for (int k = 0; k < 2; ++k) dst[n][k] = *(const PG8_LAS bf16x8*)(lds + PG8_SB(b, h) + boff + n * 2048 + k * 1024); } while (0)
; #define PG8_MMA(ai, bj, At, Bt) do { __builtin_amdgcn_s_setprio(1); _Pragma("unroll") for (int m = 0; m < 4; ++m) _Pragma("unroll") for (int n = 0; n < 2; ++n) _Pragma("unroll") for (int k = 0; k < 2; ++k) \
;         acc[ai][bj][m][n] = __builtin_amdgcn_mfma_f32_16x16x32_bf16(Bt[n][k], At[m][k], acc[ai][bj][m][n], 0, 0, 0); __builtin_amdgcn_s_setprio(0); } while (0)
; #define PG8_WAIT_V(n) asm volatile("s_waitcnt vmcnt(" #n ")" ::: "memory")
; #define PG8_WAIT_L(n) asm volatile("s_waitcnt lgkmcnt(" #n ")" ::: "memory")
; #define PG8_BAR __builtin_amdgcn_s_barrier()
; #define PG8_SCHED __builtin_amdgcn_sched_barrier(0)
; template <class Epi, class Sched, bool ALIGN_EPI = false, bool SP2 = false>
; __device__ __forceinline__ void gemm_phase(PG8_LAS unsigned char* lds, const Gemm g, const Sched& S, const Epi& E, const int tid_in) {
;     ...
;             PG8_WAIT_V(8); PG8_WAIT_L(0); PG8_BAR; PG8_MMA(0, 0, At, B0); PG8_MMA(0, 1, At, B1); PG8_BAR; PG8_SCHED;
;             PG8_LDA(At, 0, 1); PG8_STAGE(PG8_SB(0, 0), b2, voffB); PG8_STAGE(PG8_SB(0, 1), b2 + hstep, voffB); PG8_STAGE(PG8_SA(0, 0), a2, voffA);
;             PG8_WAIT_V(8); PG8_WAIT_L(0); PG8_BAR; PG8_MMA(1, 0, At, B0); PG8_MMA(1, 1, At, B1); PG8_BAR; PG8_SCHED;
;             PG8_LDB(B0, 1, 0); PG8_LDB(B1, 1, 1); PG8_SCHED; PG8_LDA(At, 1, 0); PG8_STAGE(PG8_SA(0, 1), a2 + hstep, voffA);
;             PG8_WAIT_V(8); PG8_WAIT_L(0); PG8_BAR; PG8_MMA(0, 0, At, B0); PG8_MMA(0, 1, At, B1); PG8_BAR; PG8_SCHED;
	s_setprio 1
	v_mfma_f32_16x16x32_bf16 v[62:65], v[66:69], v[182:185], 0
	v_mfma_f32_16x16x32_bf16 v[58:61], v[74:77], v[182:185], 0
	v_mfma_f32_16x16x32_bf16 v[46:49], v[66:69], v[190:193], 0
	v_mfma_f32_16x16x32_bf16 v[42:45], v[74:77], v[190:193], 0
	v_mfma_f32_16x16x32_bf16 v[30:33], v[66:69], v[198:201], 0
	v_mfma_f32_16x16x32_bf16 v[26:29], v[74:77], v[198:201], 0
	v_mfma_f32_16x16x32_bf16 v[12:15], v[66:69], v[208:211], 0
	v_mfma_f32_16x16x32_bf16 v[8:11], v[74:77], v[208:211], 0
	v_mfma_f32_16x16x32_bf16 v[62:65], v[70:73], v[186:189], v[62:65]
	v_mfma_f32_16x16x32_bf16 v[58:61], v[78:81], v[186:189], v[58:61]
	v_mfma_f32_16x16x32_bf16 v[46:49], v[70:73], v[194:197], v[46:49]
	v_mfma_f32_16x16x32_bf16 v[42:45], v[78:81], v[194:197], v[42:45]
	v_mfma_f32_16x16x32_bf16 v[30:33], v[70:73], v[202:205], v[30:33]
	v_mfma_f32_16x16x32_bf16 v[26:29], v[78:81], v[202:205], v[26:29]
	v_mfma_f32_16x16x32_bf16 v[12:15], v[70:73], v[212:215], v[12:15]
	v_mfma_f32_16x16x32_bf16 v[8:11], v[78:81], v[212:215], v[8:11]
	s_setprio 0
	s_setprio 1
	v_mfma_f32_16x16x32_bf16 v[54:57], v[166:169], v[182:185], 0
	v_mfma_f32_16x16x32_bf16 v[50:53], v[174:177], v[182:185], 0
	v_mfma_f32_16x16x32_bf16 v[38:41], v[166:169], v[190:193], 0
	v_mfma_f32_16x16x32_bf16 v[34:37], v[174:177], v[190:193], 0
	v_mfma_f32_16x16x32_bf16 v[22:25], v[166:169], v[198:201], 0
	v_mfma_f32_16x16x32_bf16 v[16:19], v[174:177], v[198:201], 0
	v_mfma_f32_16x16x32_bf16 v[4:7], v[166:169], v[208:211], 0
	v_mfma_f32_16x16x32_bf16 v[0:3], v[174:177], v[208:211], 0
	v_mfma_f32_16x16x32_bf16 v[54:57], v[170:173], v[186:189], v[54:57]
	v_mfma_f32_16x16x32_bf16 v[50:53], v[178:181], v[186:189], v[50:53]
	v_mfma_f32_16x16x32_bf16 v[38:41], v[170:173], v[194:197], v[38:41]
	v_mfma_f32_16x16x32_bf16 v[34:37], v[178:181], v[194:197], v[34:37]
	v_mfma_f32_16x16x32_bf16 v[22:25], v[170:173], v[202:205], v[22:25]
	v_mfma_f32_16x16x32_bf16 v[16:19], v[178:181], v[202:205], v[16:19]
	v_mfma_f32_16x16x32_bf16 v[4:7], v[170:173], v[212:215], v[4:7]
	v_mfma_f32_16x16x32_bf16 v[0:3], v[178:181], v[212:215], v[0:3]
	s_setprio 0
	s_barrier
	ds_read_b128 v[66:69], v218
	ds_read_b128 v[70:73], v218 offset:1024
	ds_read_b128 v[74:77], v218 offset:2048
	ds_read_b128 v[78:81], v218 offset:3072
	ds_read_b128 v[166:169], v219
	ds_read_b128 v[170:173], v219 offset:1024
	ds_read_b128 v[174:177], v219 offset:2048
	ds_read_b128 v[178:181], v219 offset:3072
	s_mov_b32 m0, s45
	s_nop 0
	global_load_lds_dwordx4 v150, s[42:43]
	s_add_u32 s42, s42, 0x80000
	s_addc_u32 s43, s43, 0
	s_mov_b32 m0, s46
	ds_read_b128 v[182:185], v165 offset:32768
	ds_read_b128 v[186:189], v165 offset:33792
	ds_read_b128 v[190:193], v165 offset:34816
	ds_read_b128 v[194:197], v165 offset:35840
	ds_read_b128 v[198:201], v165 offset:36864
	ds_read_b128 v[202:205], v165 offset:37888
	ds_read_b128 v[208:211], v165 offset:38912
	ds_read_b128 v[212:215], v165 offset:39936
	global_load_lds_dwordx4 v146, s[42:43]
	s_mov_b32 m0, s47
	s_nop 0
	global_load_lds_dwordx4 v150, s[42:43]
	s_add_i32 s42, s59, s19
	s_mov_b32 m0, s42
	s_waitcnt vmcnt(8)
	s_waitcnt lgkmcnt(0)
	s_barrier
	s_setprio 1
	v_mfma_f32_16x16x32_bf16 v[142:145], v[66:69], v[182:185], v[142:145]
	v_mfma_f32_16x16x32_bf16 v[138:141], v[74:77], v[182:185], v[138:141]
	v_mfma_f32_16x16x32_bf16 v[126:129], v[66:69], v[190:193], v[126:129]
	v_mfma_f32_16x16x32_bf16 v[122:125], v[74:77], v[190:193], v[122:125]
	v_mfma_f32_16x16x32_bf16 v[110:113], v[66:69], v[198:201], v[110:113]
	v_mfma_f32_16x16x32_bf16 v[106:109], v[74:77], v[198:201], v[106:109]
	v_mfma_f32_16x16x32_bf16 v[94:97], v[66:69], v[208:211], v[94:97]
	v_mfma_f32_16x16x32_bf16 v[90:93], v[74:77], v[208:211], v[90:93]
	v_mfma_f32_16x16x32_bf16 v[142:145], v[70:73], v[186:189], v[142:145]
	v_mfma_f32_16x16x32_bf16 v[138:141], v[78:81], v[186:189], v[138:141]
	v_mfma_f32_16x16x32_bf16 v[126:129], v[70:73], v[194:197], v[126:129]
	v_mfma_f32_16x16x32_bf16 v[122:125], v[78:81], v[194:197], v[122:125]
	v_mfma_f32_16x16x32_bf16 v[110:113], v[70:73], v[202:205], v[110:113]
	v_mfma_f32_16x16x32_bf16 v[106:109], v[78:81], v[202:205], v[106:109]
	v_mfma_f32_16x16x32_bf16 v[94:97], v[70:73], v[212:215], v[94:97]
	v_mfma_f32_16x16x32_bf16 v[90:93], v[78:81], v[212:215], v[90:93]
	s_setprio 0
	s_setprio 1
	v_mfma_f32_16x16x32_bf16 v[134:137], v[166:169], v[182:185], v[134:137]
	v_mfma_f32_16x16x32_bf16 v[130:133], v[174:177], v[182:185], v[130:133]
	v_mfma_f32_16x16x32_bf16 v[118:121], v[166:169], v[190:193], v[118:121]
	v_mfma_f32_16x16x32_bf16 v[114:117], v[174:177], v[190:193], v[114:117]
	v_mfma_f32_16x16x32_bf16 v[102:105], v[166:169], v[198:201], v[102:105]
	v_mfma_f32_16x16x32_bf16 v[98:101], v[174:177], v[198:201], v[98:101]
	v_mfma_f32_16x16x32_bf16 v[86:89], v[166:169], v[208:211], v[86:89]
	v_mfma_f32_16x16x32_bf16 v[82:85], v[174:177], v[208:211], v[82:85]
	v_mfma_f32_16x16x32_bf16 v[134:137], v[170:173], v[186:189], v[134:137]
	v_mfma_f32_16x16x32_bf16 v[130:133], v[178:181], v[186:189], v[130:133]
	v_mfma_f32_16x16x32_bf16 v[118:121], v[170:173], v[194:197], v[118:121]
	v_mfma_f32_16x16x32_bf16 v[114:117], v[178:181], v[194:197], v[114:117]
	v_mfma_f32_16x16x32_bf16 v[102:105], v[170:173], v[202:205], v[102:105]
	v_mfma_f32_16x16x32_bf16 v[98:101], v[178:181], v[202:205], v[98:101]
	v_mfma_f32_16x16x32_bf16 v[86:89], v[170:173], v[212:215], v[86:89]
	v_mfma_f32_16x16x32_bf16 v[82:85], v[178:181], v[212:215], v[82:85]
	s_setprio 0
	s_barrier
; #define PG8_STAGE(bufoff, gbase, voff) do { _Pragma("unroll") for (int _i = 0; _i < 2; ++_i) \
;         __builtin_amdgcn_global_load_lds((const unsigned*)((const char*)(gbase) + (voff)[_i]), (PG8_LAS unsigned*)(lds + (bufoff) + ldsw + _i * 8192), 16, 0, 0); } while (0)
; #define PG8_LDA(dst, b, h) do { _Pragma("unroll") for (int m = 0; m < 4; ++m) _Pragma("unroll") for (int k = 0; k < 2; ++k) dst[m][k] = *(const PG8_LAS bf16x8*)(lds + PG8_SA(b, h) + aoff + m * 2048 + k * 1024); } while (0)
; #define PG8_LDB(dst, b, h) do { _Pragma("unroll") for (int n = 0; n < 2; ++n) _Pragma("unroll") for (int k = 0; k < 2; ++k) dst[n][k] = *(const PG8_LAS bf16x8*)(lds + PG8_SB(b, h) + boff + n * 2048 + k * 1024); } while (0)
; #define PG8_MMA(ai, bj, At, Bt) do { __builtin_amdgcn_s_setprio(1); _Pragma("unroll") for (int m = 0; m < 4; ++m) _Pragma("unroll") for (int n = 0; n < 2; ++n) _Pragma("unroll") for (int k = 0; k < 2; ++k) \
;         acc[ai][bj][m][n] = __builtin_amdgcn_mfma_f32_16x16x32_bf16(Bt[n][k], At[m][k], acc[ai][bj][m][n], 0, 0, 0); __builtin_amdgcn_s_setprio(0); } while (0)
; #define PG8_BAR __builtin_amdgcn_s_barrier()
; template <class Epi, class Sched, bool ALIGN_EPI = false, bool SP2 = false>
; __device__ __forceinline__ void gemm_phase(PG8_LAS unsigned char* lds, const Gemm g, const Sched& S, const Epi& E, const int tid_in) {
;     ...
;             PG8_LDB(B0, 0, 0); PG8_LDB(B1, 0, 1); PG8_SCHED; PG8_LDA(At, 0, 0); PG8_STAGE(PG8_SA(1, 1), a1 + hstep, voffA);
;             PG8_WAIT_V(8); PG8_WAIT_L(0); PG8_BAR; PG8_MMA(0, 0, At, B0); PG8_MMA(0, 1, At, B1); PG8_BAR; PG8_SCHED;
;             PG8_LDA(At, 0, 1); PG8_STAGE(PG8_SB(0, 0), b2, voffB); PG8_STAGE(PG8_SB(0, 1), b2 + hstep, voffB); PG8_STAGE(PG8_SA(0, 0), a2, voffA);
;             PG8_WAIT_V(8); PG8_WAIT_L(0); PG8_BAR; PG8_MMA(1, 0, At, B0); PG8_MMA(1, 1, At, B1); PG8_BAR; PG8_SCHED;
;             PG8_LDB(B0, 1, 0); PG8_LDB(B1, 1, 1); PG8_SCHED; PG8_LDA(At, 1, 0); PG8_STAGE(PG8_SA(0, 1), a2 + hstep, voffA);
;             PG8_WAIT_V(8); PG8_WAIT_L(0); PG8_BAR; PG8_MMA(0, 0, At, B0); PG8_MMA(0, 1, At, B1); PG8_BAR; PG8_SCHED;
;             PG8_LDA(At, 1, 1); PG8_STAGE(PG8_SB(1, 0), b3, voffB); PG8_STAGE(PG8_SB(1, 1), b3 + hstep, voffB); PG8_STAGE(PG8_SA(1, 0), a3, voffA);
;             PG8_WAIT_V(8); PG8_WAIT_L(0); PG8_BAR; PG8_MMA(1, 0, At, B0); PG8_MMA(1, 1, At, B1); PG8_BAR; PG8_SCHED;
	ds_read_b128 v[182:185], v165 offset:49152
	ds_read_b128 v[186:189], v165 offset:50176
	ds_read_b128 v[190:193], v165 offset:51200
	ds_read_b128 v[194:197], v165 offset:52224
	ds_read_b128 v[198:201], v165 offset:53248
	ds_read_b128 v[202:205], v165 offset:54272
	ds_read_b128 v[208:211], v165 offset:55296
	ds_read_b128 v[212:215], v165 offset:56320
	global_load_lds_dwordx4 v148, s[98:99]
	s_add_i32 m0, s42, 0x2000
	s_add_u32 s38, s38, 0x80080
	s_addc_u32 s39, s39, 0
	s_add_i32 s42, s60, s19
	global_load_lds_dwordx4 v152, s[98:99]
	s_mov_b32 m0, s42
	s_nop 0
	global_load_lds_dwordx4 v148, s[38:39]
	s_add_i32 m0, s42, 0x2000
	s_nop 0
	global_load_lds_dwordx4 v152, s[38:39]
	s_mov_b32 m0, s48
	s_nop 0
	global_load_lds_dwordx4 v146, s[100:101]
	s_add_i32 s58, s58, 2
	s_add_u32 s34, s34, 0x100
	s_addc_u32 s35, s35, 0
	s_add_u32 s56, s56, 0x100
	s_addc_u32 s57, s57, 0
	s_add_u32 s38, s34, 0xfff80080
	s_addc_u32 s39, s35, -1
	s_add_i32 s59, 0, 0x10000
	s_cmp_eq_u32 s58, 28
	s_cselect_b32 s43, s27, s39
	s_cselect_b32 s42, s54, s38
	s_cselect_b32 s39, s7, s57
	s_cselect_b32 s38, s55, s56
	s_add_i32 s62, 0, 0x14000
	s_cmp_gt_u32 s58, 29
	s_waitcnt vmcnt(7)
	s_waitcnt lgkmcnt(0)
	s_barrier
	s_setprio 1
	v_mfma_f32_16x16x32_bf16 v[62:65], v[66:69], v[182:185], v[62:65]
	v_mfma_f32_16x16x32_bf16 v[58:61], v[74:77], v[182:185], v[58:61]
	v_mfma_f32_16x16x32_bf16 v[46:49], v[66:69], v[190:193], v[46:49]
	v_mfma_f32_16x16x32_bf16 v[42:45], v[74:77], v[190:193], v[42:45]
	v_mfma_f32_16x16x32_bf16 v[30:33], v[66:69], v[198:201], v[30:33]
	v_mfma_f32_16x16x32_bf16 v[26:29], v[74:77], v[198:201], v[26:29]
	v_mfma_f32_16x16x32_bf16 v[12:15], v[66:69], v[208:211], v[12:15]
	v_mfma_f32_16x16x32_bf16 v[8:11], v[74:77], v[208:211], v[8:11]
	v_mfma_f32_16x16x32_bf16 v[62:65], v[70:73], v[186:189], v[62:65]
	v_mfma_f32_16x16x32_bf16 v[58:61], v[78:81], v[186:189], v[58:61]
	v_mfma_f32_16x16x32_bf16 v[46:49], v[70:73], v[194:197], v[46:49]
	v_mfma_f32_16x16x32_bf16 v[42:45], v[78:81], v[194:197], v[42:45]
	v_mfma_f32_16x16x32_bf16 v[30:33], v[70:73], v[202:205], v[30:33]
	v_mfma_f32_16x16x32_bf16 v[26:29], v[78:81], v[202:205], v[26:29]
	v_mfma_f32_16x16x32_bf16 v[12:15], v[70:73], v[212:215], v[12:15]
	v_mfma_f32_16x16x32_bf16 v[8:11], v[78:81], v[212:215], v[8:11]
	s_setprio 0
	s_setprio 1
	v_mfma_f32_16x16x32_bf16 v[54:57], v[166:169], v[182:185], v[54:57]
	v_mfma_f32_16x16x32_bf16 v[50:53], v[174:177], v[182:185], v[50:53]
	v_mfma_f32_16x16x32_bf16 v[38:41], v[166:169], v[190:193], v[38:41]
	v_mfma_f32_16x16x32_bf16 v[34:37], v[174:177], v[190:193], v[34:37]
	v_mfma_f32_16x16x32_bf16 v[22:25], v[166:169], v[198:201], v[22:25]
	v_mfma_f32_16x16x32_bf16 v[16:19], v[174:177], v[198:201], v[16:19]
	v_mfma_f32_16x16x32_bf16 v[4:7], v[166:169], v[208:211], v[4:7]
	v_mfma_f32_16x16x32_bf16 v[0:3], v[174:177], v[208:211], v[0:3]
	v_mfma_f32_16x16x32_bf16 v[54:57], v[170:173], v[186:189], v[54:57]
	v_mfma_f32_16x16x32_bf16 v[50:53], v[178:181], v[186:189], v[50:53]
	v_mfma_f32_16x16x32_bf16 v[38:41], v[170:173], v[194:197], v[38:41]
	v_mfma_f32_16x16x32_bf16 v[34:37], v[178:181], v[194:197], v[34:37]
	v_mfma_f32_16x16x32_bf16 v[22:25], v[170:173], v[202:205], v[22:25]
	v_mfma_f32_16x16x32_bf16 v[16:19], v[178:181], v[202:205], v[16:19]
	v_mfma_f32_16x16x32_bf16 v[4:7], v[170:173], v[212:215], v[4:7]
	v_mfma_f32_16x16x32_bf16 v[0:3], v[178:181], v[212:215], v[0:3]
	s_setprio 0
	s_barrier
.LBB0_412:
	s_mov_b32 m0, s49
	s_nop 0
	global_load_lds_dwordx4 v150, s[100:101]
	ds_read_b128 v[66:69], v216
	ds_read_b128 v[70:73], v216 offset:1024
	ds_read_b128 v[74:77], v216 offset:2048
	ds_read_b128 v[78:81], v216 offset:3072
	ds_read_b128 v[166:169], v217
	ds_read_b128 v[170:173], v217 offset:1024
	ds_read_b128 v[174:177], v217 offset:2048
	ds_read_b128 v[178:181], v217 offset:3072
	s_add_i32 m0, s44, 0xc000
	ds_read_b128 v[182:185], v165
	ds_read_b128 v[186:189], v165 offset:1024
	ds_read_b128 v[190:193], v165 offset:2048
	ds_read_b128 v[194:197], v165 offset:3072
	ds_read_b128 v[198:201], v165 offset:4096
	ds_read_b128 v[202:205], v165 offset:5120
	ds_read_b128 v[208:211], v165 offset:6144
	ds_read_b128 v[212:215], v165 offset:7168
	global_load_lds_dwordx4 v156, s[34:35]
	s_add_i32 m0, s44, 0xe000
	s_nop 0
	global_load_lds_dwordx4 v158, s[34:35]
	s_add_i32 s59, s59, s19
	s_add_u32 s98, s38, 0x80
	s_addc_u32 s99, s39, 0
	s_mov_b32 m0, s59
	s_waitcnt vmcnt(8)
	s_waitcnt lgkmcnt(0)
	s_barrier
	s_setprio 1
	v_mfma_f32_16x16x32_bf16 v[142:145], v[66:69], v[182:185], v[142:145]
	v_mfma_f32_16x16x32_bf16 v[138:141], v[74:77], v[182:185], v[138:141]
	v_mfma_f32_16x16x32_bf16 v[126:129], v[66:69], v[190:193], v[126:129]
	v_mfma_f32_16x16x32_bf16 v[122:125], v[74:77], v[190:193], v[122:125]
	v_mfma_f32_16x16x32_bf16 v[110:113], v[66:69], v[198:201], v[110:113]
	v_mfma_f32_16x16x32_bf16 v[106:109], v[74:77], v[198:201], v[106:109]
	v_mfma_f32_16x16x32_bf16 v[94:97], v[66:69], v[208:211], v[94:97]
	v_mfma_f32_16x16x32_bf16 v[90:93], v[74:77], v[208:211], v[90:93]
	v_mfma_f32_16x16x32_bf16 v[142:145], v[70:73], v[186:189], v[142:145]
	v_mfma_f32_16x16x32_bf16 v[138:141], v[78:81], v[186:189], v[138:141]
	v_mfma_f32_16x16x32_bf16 v[126:129], v[70:73], v[194:197], v[126:129]
	v_mfma_f32_16x16x32_bf16 v[122:125], v[78:81], v[194:197], v[122:125]
	v_mfma_f32_16x16x32_bf16 v[110:113], v[70:73], v[202:205], v[110:113]
	v_mfma_f32_16x16x32_bf16 v[106:109], v[78:81], v[202:205], v[106:109]
	v_mfma_f32_16x16x32_bf16 v[94:97], v[70:73], v[212:215], v[94:97]
	v_mfma_f32_16x16x32_bf16 v[90:93], v[78:81], v[212:215], v[90:93]
	s_setprio 0
	s_setprio 1
	v_mfma_f32_16x16x32_bf16 v[134:137], v[166:169], v[182:185], v[134:137]
	v_mfma_f32_16x16x32_bf16 v[130:133], v[174:177], v[182:185], v[130:133]
	v_mfma_f32_16x16x32_bf16 v[118:121], v[166:169], v[190:193], v[118:121]
	v_mfma_f32_16x16x32_bf16 v[114:117], v[174:177], v[190:193], v[114:117]
	v_mfma_f32_16x16x32_bf16 v[102:105], v[166:169], v[198:201], v[102:105]
	v_mfma_f32_16x16x32_bf16 v[98:101], v[174:177], v[198:201], v[98:101]
	v_mfma_f32_16x16x32_bf16 v[86:89], v[166:169], v[208:211], v[86:89]
	v_mfma_f32_16x16x32_bf16 v[82:85], v[174:177], v[208:211], v[82:85]
	v_mfma_f32_16x16x32_bf16 v[134:137], v[170:173], v[186:189], v[134:137]
	v_mfma_f32_16x16x32_bf16 v[130:133], v[178:181], v[186:189], v[130:133]
	v_mfma_f32_16x16x32_bf16 v[118:121], v[170:173], v[194:197], v[118:121]
	v_mfma_f32_16x16x32_bf16 v[114:117], v[178:181], v[194:197], v[114:117]
	v_mfma_f32_16x16x32_bf16 v[102:105], v[170:173], v[202:205], v[102:105]
	v_mfma_f32_16x16x32_bf16 v[98:101], v[178:181], v[202:205], v[98:101]
	v_mfma_f32_16x16x32_bf16 v[86:89], v[170:173], v[212:215], v[86:89]
	v_mfma_f32_16x16x32_bf16 v[82:85], v[178:181], v[212:215], v[82:85]
	s_setprio 0
	s_barrier
; #define PG8_STAGE(bufoff, gbase, voff) do { _Pragma("unroll") for (int _i = 0; _i < 2; ++_i) \
;         __builtin_amdgcn_global_load_lds((const unsigned*)((const char*)(gbase) + (voff)[_i]), (PG8_LAS unsigned*)(lds + (bufoff) + ldsw + _i * 8192), 16, 0, 0); } while (0)
; #define PG8_LDA(dst, b, h) do { _Pragma("unroll") for (int m = 0; m < 4; ++m) _Pragma("unroll") for (int k = 0; k < 2; ++k) dst[m][k] = *(const PG8_LAS bf16x8*)(lds + PG8_SA(b, h) + aoff + m * 2048 + k * 1024); } while (0)
; #define PG8_LDB(dst, b, h) do { _Pragma("unroll") for (int n = 0; n < 2; ++n) _Pragma("unroll") for (int k = 0; k < 2; ++k) dst[n][k] = *(const PG8_LAS bf16x8*)(lds + PG8_SB(b, h) + boff + n * 2048 + k * 1024); } while (0)
; #define PG8_MMA(ai, bj, At, Bt) do { __builtin_amdgcn_s_setprio(1); _Pragma("unroll") for (int m = 0; m < 4; ++m) _Pragma("unroll") for (int n = 0; n < 2; ++n) _Pragma("unroll") for (int k = 0; k < 2; ++k) \
;         acc[ai][bj][m][n] = __builtin_amdgcn_mfma_f32_16x16x32_bf16(Bt[n][k], At[m][k], acc[ai][bj][m][n], 0, 0, 0); __builtin_amdgcn_s_setprio(0); } while (0)
; #define PG8_WAIT_V(n) asm volatile("s_waitcnt vmcnt(" #n ")" ::: "memory")
; #define PG8_WAIT_L(n) asm volatile("s_waitcnt lgkmcnt(" #n ")" ::: "memory")
; #define PG8_BAR __builtin_amdgcn_s_barrier()
; #define PG8_SCHED __builtin_amdgcn_sched_barrier(0)
; template <class Epi, class Sched, bool ALIGN_EPI = false, bool SP2 = false>
; __device__ __forceinline__ void gemm_phase(PG8_LAS unsigned char* lds, const Gemm g, const Sched& S, const Epi& E, const int tid_in) {
;     ...
;             PG8_LDA(At, 0, 1); PG8_STAGE(PG8_SB(0, 0), b2, voffB); PG8_STAGE(PG8_SB(0, 1), b2 + hstep, voffB); PG8_STAGE(PG8_SA(0, 0), a2, voffA);
;             PG8_WAIT_V(8); PG8_WAIT_L(0); PG8_BAR; PG8_MMA(1, 0, At, B0); PG8_MMA(1, 1, At, B1); PG8_BAR; PG8_SCHED;
;             PG8_LDB(B0, 1, 0); PG8_LDB(B1, 1, 1); PG8_SCHED; PG8_LDA(At, 1, 0); PG8_STAGE(PG8_SA(0, 1), a2 + hstep, voffA);
;             PG8_WAIT_V(8); PG8_WAIT_L(0); PG8_BAR; PG8_MMA(0, 0, At, B0); PG8_MMA(0, 1, At, B1); PG8_BAR; PG8_SCHED;
;             PG8_LDA(At, 1, 1); PG8_STAGE(PG8_SB(1, 0), b3, voffB); PG8_STAGE(PG8_SB(1, 1), b3 + hstep, voffB); PG8_STAGE(PG8_SA(1, 0), a3, voffA);
	ds_read_b128 v[182:185], v165 offset:16384
	ds_read_b128 v[186:189], v165 offset:17408
	ds_read_b128 v[190:193], v165 offset:18432
	ds_read_b128 v[194:197], v165 offset:19456
	ds_read_b128 v[198:201], v165 offset:20480
	ds_read_b128 v[202:205], v165 offset:21504
	ds_read_b128 v[208:211], v165 offset:22528
	ds_read_b128 v[212:215], v165 offset:23552
	global_load_lds_dwordx4 v148, s[38:39]
	s_add_i32 m0, s59, 0x2000
	s_add_u32 s60, s38, 0x80000
	s_addc_u32 s61, s39, 0
	s_add_i32 s59, s62, s19
	global_load_lds_dwordx4 v152, s[38:39]
	s_mov_b32 m0, s59
	s_add_u32 s100, s42, 0x80
	s_addc_u32 s101, s43, 0
	global_load_lds_dwordx4 v148, s[60:61]
	s_add_i32 m0, s59, 0x2000
	s_nop 0
	global_load_lds_dwordx4 v152, s[60:61]
	s_mov_b32 m0, s44
	s_nop 0
	global_load_lds_dwordx4 v146, s[42:43]
	s_add_i32 s59, 0, 0x18000
	s_add_i32 s60, 0, 0x1c000
	s_waitcnt vmcnt(7)
	s_waitcnt lgkmcnt(0)
	s_barrier
	s_setprio 1
	v_mfma_f32_16x16x32_bf16 v[62:65], v[66:69], v[182:185], v[62:65]
	v_mfma_f32_16x16x32_bf16 v[58:61], v[74:77], v[182:185], v[58:61]
	v_mfma_f32_16x16x32_bf16 v[46:49], v[66:69], v[190:193], v[46:49]
	v_mfma_f32_16x16x32_bf16 v[42:45], v[74:77], v[190:193], v[42:45]
	v_mfma_f32_16x16x32_bf16 v[30:33], v[66:69], v[198:201], v[30:33]
	v_mfma_f32_16x16x32_bf16 v[26:29], v[74:77], v[198:201], v[26:29]
	v_mfma_f32_16x16x32_bf16 v[12:15], v[66:69], v[208:211], v[12:15]
	v_mfma_f32_16x16x32_bf16 v[8:11], v[74:77], v[208:211], v[8:11]
	v_mfma_f32_16x16x32_bf16 v[62:65], v[70:73], v[186:189], v[62:65]
	v_mfma_f32_16x16x32_bf16 v[58:61], v[78:81], v[186:189], v[58:61]
	v_mfma_f32_16x16x32_bf16 v[46:49], v[70:73], v[194:197], v[46:49]
	v_mfma_f32_16x16x32_bf16 v[42:45], v[78:81], v[194:197], v[42:45]
	v_mfma_f32_16x16x32_bf16 v[30:33], v[70:73], v[202:205], v[30:33]
	v_mfma_f32_16x16x32_bf16 v[26:29], v[78:81], v[202:205], v[26:29]
	v_mfma_f32_16x16x32_bf16 v[12:15], v[70:73], v[212:215], v[12:15]
	v_mfma_f32_16x16x32_bf16 v[8:11], v[78:81], v[212:215], v[8:11]
	s_setprio 0
	s_setprio 1
	v_mfma_f32_16x16x32_bf16 v[54:57], v[166:169], v[182:185], v[54:57]
	v_mfma_f32_16x16x32_bf16 v[50:53], v[174:177], v[182:185], v[50:53]
	v_mfma_f32_16x16x32_bf16 v[38:41], v[166:169], v[190:193], v[38:41]
	v_mfma_f32_16x16x32_bf16 v[34:37], v[174:177], v[190:193], v[34:37]
	v_mfma_f32_16x16x32_bf16 v[22:25], v[166:169], v[198:201], v[22:25]
	v_mfma_f32_16x16x32_bf16 v[16:19], v[174:177], v[198:201], v[16:19]
	v_mfma_f32_16x16x32_bf16 v[4:7], v[166:169], v[208:211], v[4:7]
	v_mfma_f32_16x16x32_bf16 v[0:3], v[174:177], v[208:211], v[0:3]
	v_mfma_f32_16x16x32_bf16 v[54:57], v[170:173], v[186:189], v[54:57]
	v_mfma_f32_16x16x32_bf16 v[50:53], v[178:181], v[186:189], v[50:53]
	v_mfma_f32_16x16x32_bf16 v[38:41], v[170:173], v[194:197], v[38:41]
	v_mfma_f32_16x16x32_bf16 v[34:37], v[178:181], v[194:197], v[34:37]
	v_mfma_f32_16x16x32_bf16 v[22:25], v[170:173], v[202:205], v[22:25]
	v_mfma_f32_16x16x32_bf16 v[16:19], v[178:181], v[202:205], v[16:19]
	v_mfma_f32_16x16x32_bf16 v[4:7], v[170:173], v[212:215], v[4:7]
	v_mfma_f32_16x16x32_bf16 v[0:3], v[178:181], v[212:215], v[0:3]
	s_setprio 0
	s_barrier
	ds_read_b128 v[66:69], v218
	ds_read_b128 v[70:73], v218 offset:1024
	ds_read_b128 v[74:77], v218 offset:2048
	ds_read_b128 v[78:81], v218 offset:3072
	ds_read_b128 v[166:169], v219
	ds_read_b128 v[170:173], v219 offset:1024
	ds_read_b128 v[174:177], v219 offset:2048
	ds_read_b128 v[178:181], v219 offset:3072
	s_mov_b32 m0, s45
	s_nop 0
	global_load_lds_dwordx4 v150, s[42:43]
	s_add_u32 s42, s42, 0x80000
	s_addc_u32 s43, s43, 0
	s_mov_b32 m0, s46
	ds_read_b128 v[182:185], v165 offset:32768
	ds_read_b128 v[186:189], v165 offset:33792
	ds_read_b128 v[190:193], v165 offset:34816
	ds_read_b128 v[194:197], v165 offset:35840
	ds_read_b128 v[198:201], v165 offset:36864
	ds_read_b128 v[202:205], v165 offset:37888
	ds_read_b128 v[208:211], v165 offset:38912
	ds_read_b128 v[212:215], v165 offset:39936
	global_load_lds_dwordx4 v146, s[42:43]
	s_mov_b32 m0, s47
	s_nop 0
	global_load_lds_dwordx4 v150, s[42:43]
	s_add_i32 s42, s59, s19
	s_mov_b32 m0, s42
	s_waitcnt vmcnt(8)
	s_waitcnt lgkmcnt(0)
	s_barrier
; #define PG8_STAGE(bufoff, gbase, voff) do { _Pragma("unroll") for (int _i = 0; _i < 2; ++_i) \
;         __builtin_amdgcn_global_load_lds((const unsigned*)((const char*)(gbase) + (voff)[_i]), (PG8_LAS unsigned*)(lds + (bufoff) + ldsw + _i * 8192), 16, 0, 0); } while (0)
; #define PG8_LDA(dst, b, h) do { _Pragma("unroll") for (int m = 0; m < 4; ++m) _Pragma("unroll") for (int k = 0; k < 2; ++k) dst[m][k] = *(const PG8_LAS bf16x8*)(lds + PG8_SA(b, h) + aoff + m * 2048 + k * 1024); } while (0)
; #define PG8_LDB(dst, b, h) do { _Pragma("unroll") for (int n = 0; n < 2; ++n) _Pragma("unroll") for (int k = 0; k < 2; ++k) dst[n][k] = *(const PG8_LAS bf16x8*)(lds + PG8_SB(b, h) + boff + n * 2048 + k * 1024); } while (0)
; #define PG8_MMA(ai, bj, At, Bt) do { __builtin_amdgcn_s_setprio(1); _Pragma("unroll") for (int m = 0; m < 4; ++m) _Pragma("unroll") for (int n = 0; n < 2; ++n) _Pragma("unroll") for (int k = 0; k < 2; ++k) \
;         acc[ai][bj][m][n] = __builtin_amdgcn_mfma_f32_16x16x32_bf16(Bt[n][k], At[m][k], acc[ai][bj][m][n], 0, 0, 0); __builtin_amdgcn_s_setprio(0); } while (0)
; #define PG8_WAIT_V(n) asm volatile("s_waitcnt vmcnt(" #n ")" ::: "memory")
; #define PG8_WAIT_L(n) asm volatile("s_waitcnt lgkmcnt(" #n ")" ::: "memory")
; #define PG8_BAR __builtin_amdgcn_s_barrier()
; #define PG8_SCHED __builtin_amdgcn_sched_barrier(0)
; template <class Epi, class Sched, bool ALIGN_EPI = false, bool SP2 = false>
; __device__ __forceinline__ void gemm_phase(PG8_LAS unsigned char* lds, const Gemm g, const Sched& S, const Epi& E, const int tid_in) {
;     ...
;             PG8_LDB(B0, 1, 0); PG8_LDB(B1, 1, 1); PG8_SCHED; PG8_LDA(At, 1, 0); PG8_STAGE(PG8_SA(0, 1), a2 + hstep, voffA);
;             PG8_WAIT_V(8); PG8_WAIT_L(0); PG8_BAR; PG8_MMA(0, 0, At, B0); PG8_MMA(0, 1, At, B1); PG8_BAR; PG8_SCHED;
;             PG8_LDA(At, 1, 1); PG8_STAGE(PG8_SB(1, 0), b3, voffB); PG8_STAGE(PG8_SB(1, 1), b3 + hstep, voffB); PG8_STAGE(PG8_SA(1, 0), a3, voffA);
;             PG8_WAIT_V(8); PG8_WAIT_L(0); PG8_BAR; PG8_MMA(1, 0, At, B0); PG8_MMA(1, 1, At, B1); PG8_BAR; PG8_SCHED;
	s_setprio 1
	v_mfma_f32_16x16x32_bf16 v[142:145], v[66:69], v[182:185], v[142:145]
	v_mfma_f32_16x16x32_bf16 v[138:141], v[74:77], v[182:185], v[138:141]
	v_mfma_f32_16x16x32_bf16 v[126:129], v[66:69], v[190:193], v[126:129]
	v_mfma_f32_16x16x32_bf16 v[122:125], v[74:77], v[190:193], v[122:125]
	v_mfma_f32_16x16x32_bf16 v[110:113], v[66:69], v[198:201], v[110:113]
	v_mfma_f32_16x16x32_bf16 v[106:109], v[74:77], v[198:201], v[106:109]
	v_mfma_f32_16x16x32_bf16 v[94:97], v[66:69], v[208:211], v[94:97]
	v_mfma_f32_16x16x32_bf16 v[90:93], v[74:77], v[208:211], v[90:93]
	v_mfma_f32_16x16x32_bf16 v[142:145], v[70:73], v[186:189], v[142:145]
	v_mfma_f32_16x16x32_bf16 v[138:141], v[78:81], v[186:189], v[138:141]
	v_mfma_f32_16x16x32_bf16 v[126:129], v[70:73], v[194:197], v[126:129]
	v_mfma_f32_16x16x32_bf16 v[122:125], v[78:81], v[194:197], v[122:125]
	v_mfma_f32_16x16x32_bf16 v[110:113], v[70:73], v[202:205], v[110:113]
	v_mfma_f32_16x16x32_bf16 v[106:109], v[78:81], v[202:205], v[106:109]
	v_mfma_f32_16x16x32_bf16 v[94:97], v[70:73], v[212:215], v[94:97]
	v_mfma_f32_16x16x32_bf16 v[90:93], v[78:81], v[212:215], v[90:93]
	s_setprio 0
	s_setprio 1
	v_mfma_f32_16x16x32_bf16 v[134:137], v[166:169], v[182:185], v[134:137]
	v_mfma_f32_16x16x32_bf16 v[130:133], v[174:177], v[182:185], v[130:133]
	v_mfma_f32_16x16x32_bf16 v[118:121], v[166:169], v[190:193], v[118:121]
	v_mfma_f32_16x16x32_bf16 v[114:117], v[174:177], v[190:193], v[114:117]
	v_mfma_f32_16x16x32_bf16 v[102:105], v[166:169], v[198:201], v[102:105]
	v_mfma_f32_16x16x32_bf16 v[98:101], v[174:177], v[198:201], v[98:101]
	v_mfma_f32_16x16x32_bf16 v[86:89], v[166:169], v[208:211], v[86:89]
	v_mfma_f32_16x16x32_bf16 v[82:85], v[174:177], v[208:211], v[82:85]
	v_mfma_f32_16x16x32_bf16 v[134:137], v[170:173], v[186:189], v[134:137]
	v_mfma_f32_16x16x32_bf16 v[130:133], v[178:181], v[186:189], v[130:133]
	v_mfma_f32_16x16x32_bf16 v[118:121], v[170:173], v[194:197], v[118:121]
	v_mfma_f32_16x16x32_bf16 v[114:117], v[178:181], v[194:197], v[114:117]
	v_mfma_f32_16x16x32_bf16 v[102:105], v[170:173], v[202:205], v[102:105]
	v_mfma_f32_16x16x32_bf16 v[98:101], v[178:181], v[202:205], v[98:101]
	v_mfma_f32_16x16x32_bf16 v[86:89], v[170:173], v[212:215], v[86:89]
	v_mfma_f32_16x16x32_bf16 v[82:85], v[178:181], v[212:215], v[82:85]
	s_setprio 0
	s_barrier
	ds_read_b128 v[182:185], v165 offset:49152
	ds_read_b128 v[186:189], v165 offset:50176
	ds_read_b128 v[190:193], v165 offset:51200
	ds_read_b128 v[194:197], v165 offset:52224
	ds_read_b128 v[198:201], v165 offset:53248
	ds_read_b128 v[202:205], v165 offset:54272
	ds_read_b128 v[208:211], v165 offset:55296
	ds_read_b128 v[212:215], v165 offset:56320
	global_load_lds_dwordx4 v148, s[98:99]
	s_add_i32 m0, s42, 0x2000
	s_add_u32 s38, s38, 0x80080
	s_addc_u32 s39, s39, 0
	s_add_i32 s42, s60, s19
	global_load_lds_dwordx4 v152, s[98:99]
	s_mov_b32 m0, s42
	s_nop 0
	global_load_lds_dwordx4 v148, s[38:39]
	s_add_i32 m0, s42, 0x2000
	s_nop 0
	global_load_lds_dwordx4 v152, s[38:39]
	s_mov_b32 m0, s48
	s_nop 0
	global_load_lds_dwordx4 v146, s[100:101]
	s_add_i32 s58, s58, 2
	s_add_u32 s34, s34, 0x100
	s_addc_u32 s35, s35, 0
	s_add_u32 s56, s56, 0x100
	s_addc_u32 s57, s57, 0
	s_add_u32 s38, s34, 0xfff80080
	s_addc_u32 s39, s35, -1
	s_add_i32 s59, 0, 0x10000
	s_cmp_eq_u32 s58, 28
	s_cselect_b32 s43, s27, s39
	s_cselect_b32 s42, s54, s38
	s_cselect_b32 s39, s7, s57
	s_cselect_b32 s38, s55, s56
	s_add_i32 s62, 0, 0x14000
	s_cmp_gt_u32 s58, 29
	s_waitcnt vmcnt(7)
	s_waitcnt lgkmcnt(0)
	s_barrier
	s_setprio 1
	v_mfma_f32_16x16x32_bf16 v[62:65], v[66:69], v[182:185], v[62:65]
	v_mfma_f32_16x16x32_bf16 v[58:61], v[74:77], v[182:185], v[58:61]
	v_mfma_f32_16x16x32_bf16 v[46:49], v[66:69], v[190:193], v[46:49]
	v_mfma_f32_16x16x32_bf16 v[42:45], v[74:77], v[190:193], v[42:45]
	v_mfma_f32_16x16x32_bf16 v[30:33], v[66:69], v[198:201], v[30:33]
	v_mfma_f32_16x16x32_bf16 v[26:29], v[74:77], v[198:201], v[26:29]
	v_mfma_f32_16x16x32_bf16 v[12:15], v[66:69], v[208:211], v[12:15]
	v_mfma_f32_16x16x32_bf16 v[8:11], v[74:77], v[208:211], v[8:11]
	v_mfma_f32_16x16x32_bf16 v[62:65], v[70:73], v[186:189], v[62:65]
	v_mfma_f32_16x16x32_bf16 v[58:61], v[78:81], v[186:189], v[58:61]
	v_mfma_f32_16x16x32_bf16 v[46:49], v[70:73], v[194:197], v[46:49]
	v_mfma_f32_16x16x32_bf16 v[42:45], v[78:81], v[194:197], v[42:45]
	v_mfma_f32_16x16x32_bf16 v[30:33], v[70:73], v[202:205], v[30:33]
	v_mfma_f32_16x16x32_bf16 v[26:29], v[78:81], v[202:205], v[26:29]
	v_mfma_f32_16x16x32_bf16 v[12:15], v[70:73], v[212:215], v[12:15]
	v_mfma_f32_16x16x32_bf16 v[8:11], v[78:81], v[212:215], v[8:11]
	s_setprio 0
	s_setprio 1
	v_mfma_f32_16x16x32_bf16 v[54:57], v[166:169], v[182:185], v[54:57]
	v_mfma_f32_16x16x32_bf16 v[50:53], v[174:177], v[182:185], v[50:53]
	v_mfma_f32_16x16x32_bf16 v[38:41], v[166:169], v[190:193], v[38:41]
	v_mfma_f32_16x16x32_bf16 v[34:37], v[174:177], v[190:193], v[34:37]
	v_mfma_f32_16x16x32_bf16 v[22:25], v[166:169], v[198:201], v[22:25]
	v_mfma_f32_16x16x32_bf16 v[16:19], v[174:177], v[198:201], v[16:19]
	v_mfma_f32_16x16x32_bf16 v[4:7], v[166:169], v[208:211], v[4:7]
	v_mfma_f32_16x16x32_bf16 v[0:3], v[174:177], v[208:211], v[0:3]
	v_mfma_f32_16x16x32_bf16 v[54:57], v[170:173], v[186:189], v[54:57]
	v_mfma_f32_16x16x32_bf16 v[50:53], v[178:181], v[186:189], v[50:53]
	v_mfma_f32_16x16x32_bf16 v[38:41], v[170:173], v[194:197], v[38:41]
	v_mfma_f32_16x16x32_bf16 v[34:37], v[178:181], v[194:197], v[34:37]
	v_mfma_f32_16x16x32_bf16 v[22:25], v[170:173], v[202:205], v[22:25]
	v_mfma_f32_16x16x32_bf16 v[16:19], v[178:181], v[202:205], v[16:19]
	v_mfma_f32_16x16x32_bf16 v[4:7], v[170:173], v[212:215], v[4:7]
	v_mfma_f32_16x16x32_bf16 v[0:3], v[178:181], v[212:215], v[0:3]
	s_setprio 0
	s_barrier
	s_cbranch_scc0 .LBB0_412
	s_and_b64 vcc, exec, s[2:3]
	s_cbranch_vccz .LBB0_415
	s_barrier

; #define PG8_STAGE(bufoff, gbase, voff) do { _Pragma("unroll") for (int _i = 0; _i < 2; ++_i) \
;         __builtin_amdgcn_global_load_lds((const unsigned*)((const char*)(gbase) + (voff)[_i]), (PG8_LAS unsigned*)(lds + (bufoff) + ldsw + _i * 8192), 16, 0, 0); } while (0)
; #define PG8_LDA(dst, b, h) do { _Pragma("unroll") for (int m = 0; m < 4; ++m) _Pragma("unroll") for (int k = 0; k < 2; ++k) dst[m][k] = *(const PG8_LAS bf16x8*)(lds + PG8_SA(b, h) + aoff + m * 2048 + k * 1024); } while (0)
; #define PG8_LDB(dst, b, h) do { _Pragma("unroll") for (int n = 0; n < 2; ++n) _Pragma("unroll") for (int k = 0; k < 2; ++k) dst[n][k] = *(const PG8_LAS bf16x8*)(lds + PG8_SB(b, h) + boff + n * 2048 + k * 1024); } while (0)
; #define PG8_WAIT_V(n) asm volatile("s_waitcnt vmcnt(" #n ")" ::: "memory")
; #define PG8_WAIT_L(n) asm volatile("s_waitcnt lgkmcnt(" #n ")" ::: "memory")
; template <class Epi, class Sched, bool ALIGN_EPI = false, bool SP2 = false>
; __device__ __forceinline__ void gemm_phase(PG8_LAS unsigned char* lds, const Gemm g, const Sched& S, const Epi& E, const int tid_in) {
;     ...
;         const char* nA = has_next ? (const char*)g.A + (size_t)nxt.pm * tstep : cA; const char* nB = has_next ? (const char*)g.Bt + (size_t)nxt.pn * tstep : cB;
;         for (int t = 0; t < nt; t += 2) {
;             if constexpr (Epi::KSPLIT > 0) { if (t == Epi::KSPLIT / BK) E.midk(acc, cur, wr, wc, fr, fq); }
;             const bool last = (t == nt - 2);
;             const char* a1 = cA + (size_t)(t + 1) * kstep;
;             const char* a2 = last ? nA : cA + (size_t)(t + 2) * kstep; const char* b2 = last ? nB : cB + (size_t)(t + 2) * kstep;
;             const char* a3 = a2 + kstep; const char* b3 = b2 + kstep;
;             if (last && has_next) S.a_ready(nxt);
;             if constexpr (SP2) {
;             PG8_LDB(B0, 0, 0); PG8_LDB(B1, 0, 1); PG8_SCHED; PG8_LDA(At, 0, 0); PG8_STAGE(PG8_SA(1, 1), a1 + hstep, voffA);
;             PG8_WAIT_V(8); PG8_WAIT_L(0); PG8_BAR; PG8_MMA(0, 0, At, B0); PG8_MMA(0, 1, At, B1); PG8_BAR; PG8_SCHED;
;     ...
; #pragma unroll
;         for (int a = 0; a < 2; ++a)
; #pragma unroll
;             for (int b = 0; b < 2; ++b)
; #pragma unroll
;                 for (int m = 0; m < 4; ++m)
; #pragma unroll
;                     for (int n = 0; n < 2; ++n) acc[a][b][m][n] = (f32x4){0.f, 0.f, 0.f, 0.f};
;         cur = nxt; cA = nA; cB = nB; ++ui;
.LBB0_959:
	s_lshl_b32 s54, s36, 8
	s_lshl_b32 s55, s53, 9
	s_add_i32 s56, s54, s46
	s_add_i32 s57, s49, s55
	s_add_u32 s36, s30, 0x60080
	s_addc_u32 s37, s31, 0
	s_add_u32 s58, s34, 0x100
	v_mov_b32_e32 v0, 0
	v_lshl_add_u64 v[182:183], s[36:37], 0, v[202:203]
	v_lshl_add_u64 v[184:185], s[36:37], 0, v[204:205]
	s_addc_u32 s59, s35, 0
	s_mov_b32 s60, -2
	s_mov_b64 s[34:35], 0
	v_mov_b32_e32 v1, v0
	v_mov_b32_e32 v2, v0
	v_mov_b32_e32 v3, v0
	v_mov_b32_e32 v4, v0
	v_mov_b32_e32 v5, v0
	v_mov_b32_e32 v6, v0
	v_mov_b32_e32 v7, v0
	v_mov_b32_e32 v8, v0
	v_mov_b32_e32 v9, v0
	v_mov_b32_e32 v10, v0
	v_mov_b32_e32 v11, v0
	v_mov_b32_e32 v16, v0
	v_mov_b32_e32 v17, v0
	v_mov_b32_e32 v18, v0
	v_mov_b32_e32 v19, v0
	v_mov_b32_e32 v26, v0
	v_mov_b32_e32 v27, v0
	v_mov_b32_e32 v28, v0
	v_mov_b32_e32 v29, v0
	v_mov_b32_e32 v34, v0
	v_mov_b32_e32 v35, v0
	v_mov_b32_e32 v36, v0
	v_mov_b32_e32 v37, v0
	v_mov_b32_e32 v42, v0
	v_mov_b32_e32 v43, v0
	v_mov_b32_e32 v44, v0
	v_mov_b32_e32 v45, v0
	v_mov_b32_e32 v50, v0
	v_mov_b32_e32 v51, v0
	v_mov_b32_e32 v52, v0
	v_mov_b32_e32 v53, v0
	v_mov_b32_e32 v12, v0
	v_mov_b32_e32 v13, v0
	v_mov_b32_e32 v14, v0
	v_mov_b32_e32 v15, v0
	v_mov_b32_e32 v22, v0
	v_mov_b32_e32 v23, v0
	v_mov_b32_e32 v24, v0
	v_mov_b32_e32 v25, v0
	v_mov_b32_e32 v30, v0
	v_mov_b32_e32 v31, v0
	v_mov_b32_e32 v32, v0
	v_mov_b32_e32 v33, v0
	v_mov_b32_e32 v38, v0
	v_mov_b32_e32 v39, v0
	v_mov_b32_e32 v40, v0
	v_mov_b32_e32 v41, v0
	v_mov_b32_e32 v46, v0
	v_mov_b32_e32 v47, v0
	v_mov_b32_e32 v48, v0
	v_mov_b32_e32 v49, v0
	v_mov_b32_e32 v54, v0
	v_mov_b32_e32 v55, v0
	v_mov_b32_e32 v56, v0
	v_mov_b32_e32 v57, v0
	v_mov_b32_e32 v58, v0
	v_mov_b32_e32 v59, v0
	v_mov_b32_e32 v60, v0
	v_mov_b32_e32 v61, v0
	v_mov_b32_e32 v62, v0
	v_mov_b32_e32 v63, v0
	v_mov_b32_e32 v64, v0
	v_mov_b32_e32 v65, v0
	v_mov_b32_e32 v66, v0
	v_mov_b32_e32 v67, v0
	v_mov_b32_e32 v68, v0
	v_mov_b32_e32 v69, v0
	v_mov_b32_e32 v70, v0
	v_mov_b32_e32 v71, v0
	v_mov_b32_e32 v72, v0
	v_mov_b32_e32 v73, v0
	v_mov_b32_e32 v74, v0
	v_mov_b32_e32 v75, v0
	v_mov_b32_e32 v76, v0
	v_mov_b32_e32 v77, v0
	v_mov_b32_e32 v82, v0
	v_mov_b32_e32 v83, v0
	v_mov_b32_e32 v84, v0
	v_mov_b32_e32 v85, v0
	v_mov_b32_e32 v90, v0
	v_mov_b32_e32 v91, v0
	v_mov_b32_e32 v92, v0
	v_mov_b32_e32 v93, v0
	v_mov_b32_e32 v98, v0
	v_mov_b32_e32 v99, v0
	v_mov_b32_e32 v100, v0
	v_mov_b32_e32 v101, v0
	v_mov_b32_e32 v114, v0
	v_mov_b32_e32 v115, v0
	v_mov_b32_e32 v116, v0
	v_mov_b32_e32 v117, v0
	v_mov_b32_e32 v118, v0
	v_mov_b32_e32 v119, v0
	v_mov_b32_e32 v120, v0
	v_mov_b32_e32 v121, v0
	v_mov_b32_e32 v78, v0
	v_mov_b32_e32 v79, v0
	v_mov_b32_e32 v80, v0
	v_mov_b32_e32 v81, v0
	v_mov_b32_e32 v86, v0
	v_mov_b32_e32 v87, v0
	v_mov_b32_e32 v88, v0
	v_mov_b32_e32 v89, v0
	v_mov_b32_e32 v94, v0
	v_mov_b32_e32 v95, v0
	v_mov_b32_e32 v96, v0
	v_mov_b32_e32 v97, v0
	v_mov_b32_e32 v102, v0
	v_mov_b32_e32 v103, v0
	v_mov_b32_e32 v104, v0
	v_mov_b32_e32 v105, v0
	v_mov_b32_e32 v106, v0
	v_mov_b32_e32 v107, v0
	v_mov_b32_e32 v108, v0
	v_mov_b32_e32 v109, v0
	v_mov_b32_e32 v110, v0
	v_mov_b32_e32 v111, v0
	v_mov_b32_e32 v112, v0
	v_mov_b32_e32 v113, v0
	v_mov_b32_e32 v122, v0
	v_mov_b32_e32 v123, v0
	v_mov_b32_e32 v124, v0
	v_mov_b32_e32 v125, v0
	v_mov_b32_e32 v126, v0
	v_mov_b32_e32 v127, v0
	v_mov_b32_e32 v128, v0
	v_mov_b32_e32 v129, v0
	v_add_u32_e32 v216, 0x10000, v230
	v_add_u32_e32 v217, 0x14000, v230
	v_add_u32_e32 v218, 0x18000, v230
	v_add_u32_e32 v219, 0x1c000, v230
	s_branch .LBB0_961
.LBB0_960:
	s_mov_b32 m0, s48
	s_nop 0
	global_load_lds_dwordx4 v196, s[100:101]
	s_add_u32 s36, s30, s34
	s_addc_u32 s37, s31, s35
	s_add_u32 s36, s36, 0x100
	s_addc_u32 s37, s37, 0
	s_add_u32 s61, s58, s34
	s_addc_u32 s62, s59, s35
	s_add_i32 s63, 0, 0x10000
	s_cmpk_eq_i32 s34, 0xb00
	s_cselect_b32 s41, s27, s37
	s_cselect_b32 s40, s26, s36
	s_cselect_b32 s37, s29, s62
	s_cselect_b32 s36, s28, s61
	s_add_i32 s61, 0, 0x14000
	ds_read_b128 v[130:133], v216
	ds_read_b128 v[134:137], v216 offset:1024
	ds_read_b128 v[138:141], v216 offset:2048
	ds_read_b128 v[142:145], v216 offset:3072
	ds_read_b128 v[146:149], v217
	ds_read_b128 v[150:153], v217 offset:1024
	ds_read_b128 v[154:157], v217 offset:2048
	ds_read_b128 v[158:161], v217 offset:3072
	v_lshl_add_u64 v[214:215], v[182:183], 0, s[34:35]
	s_add_i32 m0, s42, 0xc000
	ds_read_b128 v[162:165], v233
	ds_read_b128 v[166:169], v233 offset:1024
	ds_read_b128 v[170:173], v233 offset:2048
	ds_read_b128 v[174:177], v233 offset:3072
	ds_read_b128 v[178:181], v233 offset:4096
	ds_read_b128 v[186:189], v233 offset:5120
	ds_read_b128 v[190:193], v233 offset:6144
	ds_read_b128 v[210:213], v233 offset:7168
	global_load_lds_dwordx4 v[214:215], off
	v_lshl_add_u64 v[214:215], v[184:185], 0, s[34:35]
	s_add_i32 m0, s42, 0xe000
	s_nop 0
	global_load_lds_dwordx4 v[214:215], off
	s_add_i32 s62, s63, s19
	s_add_u32 s98, s36, 0x80
	s_addc_u32 s99, s37, 0
	s_mov_b32 m0, s62
	s_waitcnt vmcnt(8)
	s_waitcnt lgkmcnt(0)
	s_barrier
; #define PG8_STAGE(bufoff, gbase, voff) do { _Pragma("unroll") for (int _i = 0; _i < 2; ++_i) \
;         __builtin_amdgcn_global_load_lds((const unsigned*)((const char*)(gbase) + (voff)[_i]), (PG8_LAS unsigned*)(lds + (bufoff) + ldsw + _i * 8192), 16, 0, 0); } while (0)
; #define PG8_LDA(dst, b, h) do { _Pragma("unroll") for (int m = 0; m < 4; ++m) _Pragma("unroll") for (int k = 0; k < 2; ++k) dst[m][k] = *(const PG8_LAS bf16x8*)(lds + PG8_SA(b, h) + aoff + m * 2048 + k * 1024); } while (0)
; #define PG8_MMA(ai, bj, At, Bt) do { __builtin_amdgcn_s_setprio(1); _Pragma("unroll") for (int m = 0; m < 4; ++m) _Pragma("unroll") for (int n = 0; n < 2; ++n) _Pragma("unroll") for (int k = 0; k < 2; ++k) \
;         acc[ai][bj][m][n] = __builtin_amdgcn_mfma_f32_16x16x32_bf16(Bt[n][k], At[m][k], acc[ai][bj][m][n], 0, 0, 0); __builtin_amdgcn_s_setprio(0); } while (0)
; #define PG8_WAIT_V(n) asm volatile("s_waitcnt vmcnt(" #n ")" ::: "memory")
; #define PG8_WAIT_L(n) asm volatile("s_waitcnt lgkmcnt(" #n ")" ::: "memory")
; #define PG8_BAR __builtin_amdgcn_s_barrier()
; #define PG8_SCHED __builtin_amdgcn_sched_barrier(0)
; template <class Epi, class Sched, bool ALIGN_EPI = false, bool SP2 = false>
; __device__ __forceinline__ void gemm_phase(PG8_LAS unsigned char* lds, const Gemm g, const Sched& S, const Epi& E, const int tid_in) {
;     ...
;             PG8_WAIT_V(8); PG8_WAIT_L(0); PG8_BAR; PG8_MMA(0, 0, At, B0); PG8_MMA(0, 1, At, B1); PG8_BAR; PG8_SCHED;
;             PG8_LDA(At, 0, 1); PG8_STAGE(PG8_SB(0, 0), b2, voffB); PG8_STAGE(PG8_SB(0, 1), b2 + hstep, voffB); PG8_STAGE(PG8_SA(0, 0), a2, voffA);
;             PG8_WAIT_V(8); PG8_WAIT_L(0); PG8_BAR; PG8_MMA(1, 0, At, B0); PG8_MMA(1, 1, At, B1); PG8_BAR; PG8_SCHED;
	s_setprio 1
	v_mfma_f32_16x16x32_bf16 v[126:129], v[130:133], v[162:165], v[126:129]
	v_mfma_f32_16x16x32_bf16 v[122:125], v[138:141], v[162:165], v[122:125]
	v_mfma_f32_16x16x32_bf16 v[110:113], v[130:133], v[170:173], v[110:113]
	v_mfma_f32_16x16x32_bf16 v[106:109], v[138:141], v[170:173], v[106:109]
	v_mfma_f32_16x16x32_bf16 v[102:105], v[130:133], v[178:181], v[102:105]
	v_mfma_f32_16x16x32_bf16 v[94:97], v[138:141], v[178:181], v[94:97]
	v_mfma_f32_16x16x32_bf16 v[86:89], v[130:133], v[190:193], v[86:89]
	v_mfma_f32_16x16x32_bf16 v[78:81], v[138:141], v[190:193], v[78:81]
	v_mfma_f32_16x16x32_bf16 v[126:129], v[134:137], v[166:169], v[126:129]
	v_mfma_f32_16x16x32_bf16 v[122:125], v[142:145], v[166:169], v[122:125]
	v_mfma_f32_16x16x32_bf16 v[110:113], v[134:137], v[174:177], v[110:113]
	v_mfma_f32_16x16x32_bf16 v[106:109], v[142:145], v[174:177], v[106:109]
	v_mfma_f32_16x16x32_bf16 v[102:105], v[134:137], v[186:189], v[102:105]
	v_mfma_f32_16x16x32_bf16 v[94:97], v[142:145], v[186:189], v[94:97]
	v_mfma_f32_16x16x32_bf16 v[86:89], v[134:137], v[210:213], v[86:89]
	v_mfma_f32_16x16x32_bf16 v[78:81], v[142:145], v[210:213], v[78:81]
	s_setprio 0
	s_setprio 1
	v_mfma_f32_16x16x32_bf16 v[118:121], v[146:149], v[162:165], v[118:121]
	v_mfma_f32_16x16x32_bf16 v[114:117], v[154:157], v[162:165], v[114:117]
	v_mfma_f32_16x16x32_bf16 v[98:101], v[146:149], v[170:173], v[98:101]
	v_mfma_f32_16x16x32_bf16 v[90:93], v[154:157], v[170:173], v[90:93]
	v_mfma_f32_16x16x32_bf16 v[82:85], v[146:149], v[178:181], v[82:85]
	v_mfma_f32_16x16x32_bf16 v[74:77], v[154:157], v[178:181], v[74:77]
	v_mfma_f32_16x16x32_bf16 v[70:73], v[146:149], v[190:193], v[70:73]
	v_mfma_f32_16x16x32_bf16 v[66:69], v[154:157], v[190:193], v[66:69]
	v_mfma_f32_16x16x32_bf16 v[118:121], v[150:153], v[166:169], v[118:121]
	v_mfma_f32_16x16x32_bf16 v[114:117], v[158:161], v[166:169], v[114:117]
	v_mfma_f32_16x16x32_bf16 v[98:101], v[150:153], v[174:177], v[98:101]
	v_mfma_f32_16x16x32_bf16 v[90:93], v[158:161], v[174:177], v[90:93]
	v_mfma_f32_16x16x32_bf16 v[82:85], v[150:153], v[186:189], v[82:85]
	v_mfma_f32_16x16x32_bf16 v[74:77], v[158:161], v[186:189], v[74:77]
	v_mfma_f32_16x16x32_bf16 v[70:73], v[150:153], v[210:213], v[70:73]
	v_mfma_f32_16x16x32_bf16 v[66:69], v[158:161], v[210:213], v[66:69]
	s_setprio 0
	s_barrier
	ds_read_b128 v[162:165], v233 offset:16384
	ds_read_b128 v[166:169], v233 offset:17408
	ds_read_b128 v[170:173], v233 offset:18432
	ds_read_b128 v[174:177], v233 offset:19456
	ds_read_b128 v[178:181], v233 offset:20480
	ds_read_b128 v[186:189], v233 offset:21504
	ds_read_b128 v[190:193], v233 offset:22528
	ds_read_b128 v[210:213], v233 offset:23552
	global_load_lds_dwordx4 v198, s[36:37]
	s_add_i32 m0, s62, 0x2000
	s_add_u32 s62, s36, 0x60000
	s_addc_u32 s63, s37, 0
	s_add_i32 s61, s61, s19
	global_load_lds_dwordx4 v194, s[36:37]
	s_mov_b32 m0, s61
	s_add_u32 s100, s40, 0x80
	s_addc_u32 s101, s41, 0
	global_load_lds_dwordx4 v198, s[62:63]
	s_add_i32 m0, s61, 0x2000
	s_nop 0
	global_load_lds_dwordx4 v194, s[62:63]
	s_mov_b32 m0, s42
	s_nop 0
	global_load_lds_dwordx4 v200, s[40:41]
	s_add_i32 s61, 0, 0x18000
	s_add_i32 s62, 0, 0x1c000
	s_waitcnt vmcnt(7)
	s_waitcnt lgkmcnt(0)
	s_barrier
	s_setprio 1
	v_mfma_f32_16x16x32_bf16 v[62:65], v[130:133], v[162:165], v[62:65]
	v_mfma_f32_16x16x32_bf16 v[58:61], v[138:141], v[162:165], v[58:61]
	v_mfma_f32_16x16x32_bf16 v[54:57], v[130:133], v[170:173], v[54:57]
	v_mfma_f32_16x16x32_bf16 v[46:49], v[138:141], v[170:173], v[46:49]
	v_mfma_f32_16x16x32_bf16 v[38:41], v[130:133], v[178:181], v[38:41]
	v_mfma_f32_16x16x32_bf16 v[30:33], v[138:141], v[178:181], v[30:33]
	v_mfma_f32_16x16x32_bf16 v[22:25], v[130:133], v[190:193], v[22:25]
	v_mfma_f32_16x16x32_bf16 v[12:15], v[138:141], v[190:193], v[12:15]
	v_mfma_f32_16x16x32_bf16 v[62:65], v[134:137], v[166:169], v[62:65]
	v_mfma_f32_16x16x32_bf16 v[58:61], v[142:145], v[166:169], v[58:61]
	v_mfma_f32_16x16x32_bf16 v[54:57], v[134:137], v[174:177], v[54:57]
	v_mfma_f32_16x16x32_bf16 v[46:49], v[142:145], v[174:177], v[46:49]
	v_mfma_f32_16x16x32_bf16 v[38:41], v[134:137], v[186:189], v[38:41]
	v_mfma_f32_16x16x32_bf16 v[30:33], v[142:145], v[186:189], v[30:33]
	v_mfma_f32_16x16x32_bf16 v[22:25], v[134:137], v[210:213], v[22:25]
	v_mfma_f32_16x16x32_bf16 v[12:15], v[142:145], v[210:213], v[12:15]
	s_setprio 0
	s_setprio 1
	v_mfma_f32_16x16x32_bf16 v[50:53], v[146:149], v[162:165], v[50:53]
	v_mfma_f32_16x16x32_bf16 v[42:45], v[154:157], v[162:165], v[42:45]
	v_mfma_f32_16x16x32_bf16 v[34:37], v[146:149], v[170:173], v[34:37]
	v_mfma_f32_16x16x32_bf16 v[26:29], v[154:157], v[170:173], v[26:29]
	v_mfma_f32_16x16x32_bf16 v[16:19], v[146:149], v[178:181], v[16:19]
	v_mfma_f32_16x16x32_bf16 v[8:11], v[154:157], v[178:181], v[8:11]
	v_mfma_f32_16x16x32_bf16 v[4:7], v[146:149], v[190:193], v[4:7]
	v_mfma_f32_16x16x32_bf16 v[0:3], v[154:157], v[190:193], v[0:3]
	v_mfma_f32_16x16x32_bf16 v[50:53], v[150:153], v[166:169], v[50:53]
	v_mfma_f32_16x16x32_bf16 v[42:45], v[158:161], v[166:169], v[42:45]
	v_mfma_f32_16x16x32_bf16 v[34:37], v[150:153], v[174:177], v[34:37]
	v_mfma_f32_16x16x32_bf16 v[26:29], v[158:161], v[174:177], v[26:29]
	v_mfma_f32_16x16x32_bf16 v[16:19], v[150:153], v[186:189], v[16:19]
	v_mfma_f32_16x16x32_bf16 v[8:11], v[158:161], v[186:189], v[8:11]
	v_mfma_f32_16x16x32_bf16 v[4:7], v[150:153], v[210:213], v[4:7]
	v_mfma_f32_16x16x32_bf16 v[0:3], v[158:161], v[210:213], v[0:3]
	s_setprio 0
	s_barrier
; #define PG8_STAGE(bufoff, gbase, voff) do { _Pragma("unroll") for (int _i = 0; _i < 2; ++_i) \
;         __builtin_amdgcn_global_load_lds((const unsigned*)((const char*)(gbase) + (voff)[_i]), (PG8_LAS unsigned*)(lds + (bufoff) + ldsw + _i * 8192), 16, 0, 0); } while (0)
; #define PG8_LDA(dst, b, h) do { _Pragma("unroll") for (int m = 0; m < 4; ++m) _Pragma("unroll") for (int k = 0; k < 2; ++k) dst[m][k] = *(const PG8_LAS bf16x8*)(lds + PG8_SA(b, h) + aoff + m * 2048 + k * 1024); } while (0)
; #define PG8_LDB(dst, b, h) do { _Pragma("unroll") for (int n = 0; n < 2; ++n) _Pragma("unroll") for (int k = 0; k < 2; ++k) dst[n][k] = *(const PG8_LAS bf16x8*)(lds + PG8_SB(b, h) + boff + n * 2048 + k * 1024); } while (0)
; #define PG8_MMA(ai, bj, At, Bt) do { __builtin_amdgcn_s_setprio(1); _Pragma("unroll") for (int m = 0; m < 4; ++m) _Pragma("unroll") for (int n = 0; n < 2; ++n) _Pragma("unroll") for (int k = 0; k < 2; ++k) \
;         acc[ai][bj][m][n] = __builtin_amdgcn_mfma_f32_16x16x32_bf16(Bt[n][k], At[m][k], acc[ai][bj][m][n], 0, 0, 0); __builtin_amdgcn_s_setprio(0); } while (0)
; #define PG8_WAIT_V(n) asm volatile("s_waitcnt vmcnt(" #n ")" ::: "memory")
; #define PG8_WAIT_L(n) asm volatile("s_waitcnt lgkmcnt(" #n ")" ::: "memory")
; #define PG8_BAR __builtin_amdgcn_s_barrier()
; #define PG8_SCHED __builtin_amdgcn_sched_barrier(0)
; template <class Epi, class Sched, bool ALIGN_EPI = false, bool SP2 = false>
; __device__ __forceinline__ void gemm_phase(PG8_LAS unsigned char* lds, const Gemm g, const Sched& S, const Epi& E, const int tid_in) {
;     ...
;         for (int t = 0; t < nt; t += 2) {
;     ...
;             PG8_LDB(B0, 1, 0); PG8_LDB(B1, 1, 1); PG8_SCHED; PG8_LDA(At, 1, 0); PG8_STAGE(PG8_SA(0, 1), a2 + hstep, voffA);
;             PG8_WAIT_V(8); PG8_WAIT_L(0); PG8_BAR; PG8_MMA(0, 0, At, B0); PG8_MMA(0, 1, At, B1); PG8_BAR; PG8_SCHED;
;             PG8_LDA(At, 1, 1); PG8_STAGE(PG8_SB(1, 0), b3, voffB); PG8_STAGE(PG8_SB(1, 1), b3 + hstep, voffB); PG8_STAGE(PG8_SA(1, 0), a3, voffA);
;             PG8_WAIT_V(8); PG8_WAIT_L(0); PG8_BAR; PG8_MMA(1, 0, At, B0); PG8_MMA(1, 1, At, B1); PG8_BAR; PG8_SCHED;
	ds_read_b128 v[130:133], v218
	ds_read_b128 v[134:137], v218 offset:1024
	ds_read_b128 v[138:141], v218 offset:2048
	ds_read_b128 v[142:145], v218 offset:3072
	ds_read_b128 v[146:149], v219
	ds_read_b128 v[150:153], v219 offset:1024
	ds_read_b128 v[154:157], v219 offset:2048
	ds_read_b128 v[158:161], v219 offset:3072
	s_mov_b32 m0, s43
	s_nop 0
	global_load_lds_dwordx4 v196, s[40:41]
	s_add_u32 s40, s40, 0x60000
	s_addc_u32 s41, s41, 0
	s_mov_b32 m0, s44
	ds_read_b128 v[162:165], v233 offset:32768
	ds_read_b128 v[166:169], v233 offset:33792
	ds_read_b128 v[170:173], v233 offset:34816
	ds_read_b128 v[174:177], v233 offset:35840
	ds_read_b128 v[178:181], v233 offset:36864
	ds_read_b128 v[186:189], v233 offset:37888
	ds_read_b128 v[190:193], v233 offset:38912
	ds_read_b128 v[210:213], v233 offset:39936
	global_load_lds_dwordx4 v200, s[40:41]
	s_mov_b32 m0, s45
	s_nop 0
	global_load_lds_dwordx4 v196, s[40:41]
	s_add_i32 s40, s61, s19
	s_mov_b32 m0, s40
	s_waitcnt vmcnt(8)
	s_waitcnt lgkmcnt(0)
	s_barrier
	s_setprio 1
	v_mfma_f32_16x16x32_bf16 v[126:129], v[130:133], v[162:165], v[126:129]
	v_mfma_f32_16x16x32_bf16 v[122:125], v[138:141], v[162:165], v[122:125]
	v_mfma_f32_16x16x32_bf16 v[110:113], v[130:133], v[170:173], v[110:113]
	v_mfma_f32_16x16x32_bf16 v[106:109], v[138:141], v[170:173], v[106:109]
	v_mfma_f32_16x16x32_bf16 v[102:105], v[130:133], v[178:181], v[102:105]
	v_mfma_f32_16x16x32_bf16 v[94:97], v[138:141], v[178:181], v[94:97]
	v_mfma_f32_16x16x32_bf16 v[86:89], v[130:133], v[190:193], v[86:89]
	v_mfma_f32_16x16x32_bf16 v[78:81], v[138:141], v[190:193], v[78:81]
	v_mfma_f32_16x16x32_bf16 v[126:129], v[134:137], v[166:169], v[126:129]
	v_mfma_f32_16x16x32_bf16 v[122:125], v[142:145], v[166:169], v[122:125]
	v_mfma_f32_16x16x32_bf16 v[110:113], v[134:137], v[174:177], v[110:113]
	v_mfma_f32_16x16x32_bf16 v[106:109], v[142:145], v[174:177], v[106:109]
	v_mfma_f32_16x16x32_bf16 v[102:105], v[134:137], v[186:189], v[102:105]
	v_mfma_f32_16x16x32_bf16 v[94:97], v[142:145], v[186:189], v[94:97]
	v_mfma_f32_16x16x32_bf16 v[86:89], v[134:137], v[210:213], v[86:89]
	v_mfma_f32_16x16x32_bf16 v[78:81], v[142:145], v[210:213], v[78:81]
	s_setprio 0
	s_setprio 1
	v_mfma_f32_16x16x32_bf16 v[118:121], v[146:149], v[162:165], v[118:121]
	v_mfma_f32_16x16x32_bf16 v[114:117], v[154:157], v[162:165], v[114:117]
	v_mfma_f32_16x16x32_bf16 v[98:101], v[146:149], v[170:173], v[98:101]
	v_mfma_f32_16x16x32_bf16 v[90:93], v[154:157], v[170:173], v[90:93]
	v_mfma_f32_16x16x32_bf16 v[82:85], v[146:149], v[178:181], v[82:85]
	v_mfma_f32_16x16x32_bf16 v[74:77], v[154:157], v[178:181], v[74:77]
	v_mfma_f32_16x16x32_bf16 v[70:73], v[146:149], v[190:193], v[70:73]
	v_mfma_f32_16x16x32_bf16 v[66:69], v[154:157], v[190:193], v[66:69]
	v_mfma_f32_16x16x32_bf16 v[118:121], v[150:153], v[166:169], v[118:121]
	v_mfma_f32_16x16x32_bf16 v[114:117], v[158:161], v[166:169], v[114:117]
	v_mfma_f32_16x16x32_bf16 v[98:101], v[150:153], v[174:177], v[98:101]
	v_mfma_f32_16x16x32_bf16 v[90:93], v[158:161], v[174:177], v[90:93]
	v_mfma_f32_16x16x32_bf16 v[82:85], v[150:153], v[186:189], v[82:85]
	v_mfma_f32_16x16x32_bf16 v[74:77], v[158:161], v[186:189], v[74:77]
	v_mfma_f32_16x16x32_bf16 v[70:73], v[150:153], v[210:213], v[70:73]
	v_mfma_f32_16x16x32_bf16 v[66:69], v[158:161], v[210:213], v[66:69]
	s_setprio 0
	s_barrier
	ds_read_b128 v[162:165], v233 offset:49152
	ds_read_b128 v[166:169], v233 offset:50176
	ds_read_b128 v[170:173], v233 offset:51200
	ds_read_b128 v[174:177], v233 offset:52224
	ds_read_b128 v[178:181], v233 offset:53248
	ds_read_b128 v[186:189], v233 offset:54272
	ds_read_b128 v[190:193], v233 offset:55296
	ds_read_b128 v[210:213], v233 offset:56320
	global_load_lds_dwordx4 v198, s[98:99]
	s_add_i32 m0, s40, 0x2000
	s_add_u32 s36, s36, 0x60080
	s_addc_u32 s37, s37, 0
	s_add_i32 s40, s62, s19
	global_load_lds_dwordx4 v194, s[98:99]
	s_mov_b32 m0, s40
	s_nop 0
	global_load_lds_dwordx4 v198, s[36:37]
	s_add_i32 m0, s40, 0x2000
	s_nop 0
	global_load_lds_dwordx4 v194, s[36:37]
	s_mov_b32 m0, s47
	s_nop 0
	global_load_lds_dwordx4 v200, s[100:101]
	s_waitcnt vmcnt(7)
	s_waitcnt lgkmcnt(0)
	s_barrier
	s_setprio 1
	v_mfma_f32_16x16x32_bf16 v[62:65], v[130:133], v[162:165], v[62:65]
	v_mfma_f32_16x16x32_bf16 v[58:61], v[138:141], v[162:165], v[58:61]
	v_mfma_f32_16x16x32_bf16 v[54:57], v[130:133], v[170:173], v[54:57]
	v_mfma_f32_16x16x32_bf16 v[46:49], v[138:141], v[170:173], v[46:49]
	v_mfma_f32_16x16x32_bf16 v[38:41], v[130:133], v[178:181], v[38:41]
	v_mfma_f32_16x16x32_bf16 v[30:33], v[138:141], v[178:181], v[30:33]
	v_mfma_f32_16x16x32_bf16 v[22:25], v[130:133], v[190:193], v[22:25]
	v_mfma_f32_16x16x32_bf16 v[12:15], v[138:141], v[190:193], v[12:15]
	v_mfma_f32_16x16x32_bf16 v[62:65], v[134:137], v[166:169], v[62:65]
	v_mfma_f32_16x16x32_bf16 v[58:61], v[142:145], v[166:169], v[58:61]
	v_mfma_f32_16x16x32_bf16 v[54:57], v[134:137], v[174:177], v[54:57]
	v_mfma_f32_16x16x32_bf16 v[46:49], v[142:145], v[174:177], v[46:49]
	v_mfma_f32_16x16x32_bf16 v[38:41], v[134:137], v[186:189], v[38:41]
	v_mfma_f32_16x16x32_bf16 v[30:33], v[142:145], v[186:189], v[30:33]
	v_mfma_f32_16x16x32_bf16 v[22:25], v[134:137], v[210:213], v[22:25]
	v_mfma_f32_16x16x32_bf16 v[12:15], v[142:145], v[210:213], v[12:15]
	s_setprio 0
	s_setprio 1
	v_mfma_f32_16x16x32_bf16 v[50:53], v[146:149], v[162:165], v[50:53]
	v_mfma_f32_16x16x32_bf16 v[42:45], v[154:157], v[162:165], v[42:45]
	v_mfma_f32_16x16x32_bf16 v[34:37], v[146:149], v[170:173], v[34:37]
	v_mfma_f32_16x16x32_bf16 v[26:29], v[154:157], v[170:173], v[26:29]
	v_mfma_f32_16x16x32_bf16 v[16:19], v[146:149], v[178:181], v[16:19]
	v_mfma_f32_16x16x32_bf16 v[8:11], v[154:157], v[178:181], v[8:11]
	v_mfma_f32_16x16x32_bf16 v[4:7], v[146:149], v[190:193], v[4:7]
	v_mfma_f32_16x16x32_bf16 v[0:3], v[154:157], v[190:193], v[0:3]
	v_mfma_f32_16x16x32_bf16 v[50:53], v[150:153], v[166:169], v[50:53]
	v_mfma_f32_16x16x32_bf16 v[42:45], v[158:161], v[166:169], v[42:45]
	v_mfma_f32_16x16x32_bf16 v[34:37], v[150:153], v[174:177], v[34:37]
	v_mfma_f32_16x16x32_bf16 v[26:29], v[158:161], v[174:177], v[26:29]
	v_mfma_f32_16x16x32_bf16 v[16:19], v[150:153], v[186:189], v[16:19]
	v_mfma_f32_16x16x32_bf16 v[8:11], v[158:161], v[186:189], v[8:11]
	v_mfma_f32_16x16x32_bf16 v[4:7], v[150:153], v[210:213], v[4:7]
	v_mfma_f32_16x16x32_bf16 v[0:3], v[158:161], v[210:213], v[0:3]
	s_setprio 0
	s_barrier
	s_add_i32 s60, s60, 2
	s_add_u32 s34, s34, 0x100
	s_addc_u32 s35, s35, 0
	s_cmp_gt_u32 s60, 21
	s_cbranch_scc1 .LBB0_963

; #define PG8_STAGE(bufoff, gbase, voff) do { _Pragma("unroll") for (int _i = 0; _i < 2; ++_i) \
;         __builtin_amdgcn_global_load_lds((const unsigned*)((const char*)(gbase) + (voff)[_i]), (PG8_LAS unsigned*)(lds + (bufoff) + ldsw + _i * 8192), 16, 0, 0); } while (0)
; #define PG8_LDA(dst, b, h) do { _Pragma("unroll") for (int m = 0; m < 4; ++m) _Pragma("unroll") for (int k = 0; k < 2; ++k) dst[m][k] = *(const PG8_LAS bf16x8*)(lds + PG8_SA(b, h) + aoff + m * 2048 + k * 1024); } while (0)
; #define PG8_LDB(dst, b, h) do { _Pragma("unroll") for (int n = 0; n < 2; ++n) _Pragma("unroll") for (int k = 0; k < 2; ++k) dst[n][k] = *(const PG8_LAS bf16x8*)(lds + PG8_SB(b, h) + boff + n * 2048 + k * 1024); } while (0)
; #define PG8_WAIT_V(n) asm volatile("s_waitcnt vmcnt(" #n ")" ::: "memory")
; #define PG8_WAIT_L(n) asm volatile("s_waitcnt lgkmcnt(" #n ")" ::: "memory")
; #define PG8_BAR __builtin_amdgcn_s_barrier()
; #define PG8_SCHED __builtin_amdgcn_sched_barrier(0)
; template <class Epi, class Sched, bool ALIGN_EPI = false, bool SP2 = false>
; __device__ __forceinline__ void gemm_phase(PG8_LAS unsigned char* lds, const Gemm g, const Sched& S, const Epi& E, const int tid_in) {
;     ...
;         const bool has_next = S.next(ui + 1, nxt);
;         const char* nA = has_next ? (const char*)g.A + (size_t)nxt.pm * tstep : cA; const char* nB = has_next ? (const char*)g.Bt + (size_t)nxt.pn * tstep : cB;
;         for (int t = 0; t < nt; t += 2) {
;             if constexpr (Epi::KSPLIT > 0) { if (t == Epi::KSPLIT / BK) E.midk(acc, cur, wr, wc, fr, fq); }
;             const bool last = (t == nt - 2);
;             const char* a1 = cA + (size_t)(t + 1) * kstep;
;             const char* a2 = last ? nA : cA + (size_t)(t + 2) * kstep; const char* b2 = last ? nB : cB + (size_t)(t + 2) * kstep;
;             const char* a3 = a2 + kstep; const char* b3 = b2 + kstep;
;             if (last && has_next) S.a_ready(nxt);
;             if constexpr (SP2) {
;             PG8_LDB(B0, 0, 0); PG8_LDB(B1, 0, 1); PG8_SCHED; PG8_LDA(At, 0, 0); PG8_STAGE(PG8_SA(1, 1), a1 + hstep, voffA);
;             PG8_WAIT_V(8); PG8_WAIT_L(0); PG8_BAR; PG8_MMA(0, 0, At, B0); PG8_MMA(0, 1, At, B1); PG8_BAR; PG8_SCHED;
;             PG8_LDA(At, 0, 1); PG8_STAGE(PG8_SB(0, 0), b2, voffB); PG8_STAGE(PG8_SB(0, 1), b2 + hstep, voffB); PG8_STAGE(PG8_SA(0, 0), a2, voffA);
.LBB0_1036:
	s_ashr_i32 s57, s56, 31
	s_lshl_b64 s[34:35], s[56:57], 20
	s_add_u32 s36, s10, s34
	s_addc_u32 s37, s19, s35
	s_and_b64 s[34:35], exec, s[6:7]
	v_readlane_b32 s34, v254, 36
	v_readlane_b32 s35, v254, 37
	s_cselect_b32 s38, s29, s37
	s_cselect_b32 s39, s28, s36
	s_mov_b32 s40, s34
	s_ashr_i32 s41, s34, 31
	v_writelane_b32 v254, s34, 36
	v_mov_b32_e32 v0, 0
	s_mov_b32 vcc_lo, -2
	v_writelane_b32 v254, s35, 37
	s_lshl_b64 s[34:35], s[40:41], 20
	s_add_u32 s60, s62, s34
	s_addc_u32 s61, s63, s35
	s_and_b64 s[34:35], exec, s[6:7]
	s_cselect_b32 s40, s31, s61
	s_cselect_b32 s41, s30, s60
	s_add_u32 s28, s28, 0x80080
	s_addc_u32 s29, s29, 0
	s_add_u32 s57, s30, 0x100
	s_addc_u32 s92, s31, 0
	v_add_u32_e32 v194, 0x10000, v21
	v_add_u32_e32 v195, 0x14000, v21
	v_add_u32_e32 v196, 0x18000, v21
	v_add_u32_e32 v197, 0x1c000, v21
	s_add_u32 s30, s28, 0xfff80080
	s_addc_u32 s31, s29, -1
	s_add_i32 s46, 0, 0x10000
	s_cmp_eq_u32 vcc_lo, 28
	s_cselect_b32 s35, s38, s31
	s_cselect_b32 s34, s39, s30
	s_cselect_b32 s31, s40, s92
	s_cselect_b32 s30, s41, s57
	s_add_i32 vcc_hi, 0, 0x14000
	s_mov_b32 m0, s76
	s_nop 0
	global_load_lds_dwordx4 v214, s[100:101]
	ds_read_b128 v[130:133], v194
	ds_read_b128 v[134:137], v194 offset:1024
	ds_read_b128 v[138:141], v194 offset:2048
	ds_read_b128 v[142:145], v194 offset:3072
	ds_read_b128 v[146:149], v195
	ds_read_b128 v[150:153], v195 offset:1024
	ds_read_b128 v[154:157], v195 offset:2048
	ds_read_b128 v[158:161], v195 offset:3072
	s_add_i32 m0, s64, 0xc000
	ds_read_b128 v[162:165], v208
	ds_read_b128 v[166:169], v208 offset:1024
	ds_read_b128 v[170:173], v208 offset:2048
	ds_read_b128 v[174:177], v208 offset:3072
	ds_read_b128 v[178:181], v208 offset:4096
	ds_read_b128 v[182:185], v208 offset:5120
	ds_read_b128 v[186:189], v208 offset:6144
	ds_read_b128 v[190:193], v208 offset:7168
	global_load_lds_dwordx4 v218, s[28:29]
	s_add_i32 m0, s64, 0xe000
	s_nop 0
	global_load_lds_dwordx4 v220, s[28:29]
	s_add_i32 s46, s46, s8
	s_add_u32 s98, s30, 0x80
	s_addc_u32 s99, s31, 0
	s_mov_b32 m0, s46
	s_waitcnt vmcnt(8)
	s_waitcnt lgkmcnt(0)
	s_barrier
	s_setprio 1
	v_mfma_f32_16x16x32_bf16 v[126:129], v[130:133], v[162:165], 0
	v_mfma_f32_16x16x32_bf16 v[122:125], v[138:141], v[162:165], 0
	v_mfma_f32_16x16x32_bf16 v[110:113], v[130:133], v[170:173], 0
	v_mfma_f32_16x16x32_bf16 v[106:109], v[138:141], v[170:173], 0
	v_mfma_f32_16x16x32_bf16 v[94:97], v[130:133], v[178:181], 0
	v_mfma_f32_16x16x32_bf16 v[90:93], v[138:141], v[178:181], 0
	v_mfma_f32_16x16x32_bf16 v[78:81], v[130:133], v[186:189], 0
	v_mfma_f32_16x16x32_bf16 v[74:77], v[138:141], v[186:189], 0
	v_mfma_f32_16x16x32_bf16 v[126:129], v[134:137], v[166:169], v[126:129]
	v_mfma_f32_16x16x32_bf16 v[122:125], v[142:145], v[166:169], v[122:125]
	v_mfma_f32_16x16x32_bf16 v[110:113], v[134:137], v[174:177], v[110:113]
	v_mfma_f32_16x16x32_bf16 v[106:109], v[142:145], v[174:177], v[106:109]
	v_mfma_f32_16x16x32_bf16 v[94:97], v[134:137], v[182:185], v[94:97]
	v_mfma_f32_16x16x32_bf16 v[90:93], v[142:145], v[182:185], v[90:93]
	v_mfma_f32_16x16x32_bf16 v[78:81], v[134:137], v[190:193], v[78:81]
	v_mfma_f32_16x16x32_bf16 v[74:77], v[142:145], v[190:193], v[74:77]
	s_setprio 0
	s_setprio 1
	v_mfma_f32_16x16x32_bf16 v[118:121], v[146:149], v[162:165], 0
	v_mfma_f32_16x16x32_bf16 v[114:117], v[154:157], v[162:165], 0
	v_mfma_f32_16x16x32_bf16 v[102:105], v[146:149], v[170:173], 0
	v_mfma_f32_16x16x32_bf16 v[98:101], v[154:157], v[170:173], 0
	v_mfma_f32_16x16x32_bf16 v[86:89], v[146:149], v[178:181], 0
	v_mfma_f32_16x16x32_bf16 v[82:85], v[154:157], v[178:181], 0
	v_mfma_f32_16x16x32_bf16 v[70:73], v[146:149], v[186:189], 0
	v_mfma_f32_16x16x32_bf16 v[66:69], v[154:157], v[186:189], 0
	v_mfma_f32_16x16x32_bf16 v[118:121], v[150:153], v[166:169], v[118:121]
	v_mfma_f32_16x16x32_bf16 v[114:117], v[158:161], v[166:169], v[114:117]
	v_mfma_f32_16x16x32_bf16 v[102:105], v[150:153], v[174:177], v[102:105]
	v_mfma_f32_16x16x32_bf16 v[98:101], v[158:161], v[174:177], v[98:101]
	v_mfma_f32_16x16x32_bf16 v[86:89], v[150:153], v[182:185], v[86:89]
	v_mfma_f32_16x16x32_bf16 v[82:85], v[158:161], v[182:185], v[82:85]
	v_mfma_f32_16x16x32_bf16 v[70:73], v[150:153], v[190:193], v[70:73]
	v_mfma_f32_16x16x32_bf16 v[66:69], v[158:161], v[190:193], v[66:69]
	s_setprio 0
	s_barrier
	ds_read_b128 v[162:165], v208 offset:16384
	ds_read_b128 v[166:169], v208 offset:17408
	ds_read_b128 v[170:173], v208 offset:18432
	ds_read_b128 v[174:177], v208 offset:19456
	ds_read_b128 v[178:181], v208 offset:20480
	ds_read_b128 v[182:185], v208 offset:21504
	ds_read_b128 v[186:189], v208 offset:22528
	ds_read_b128 v[190:193], v208 offset:23552
	global_load_lds_dwordx4 v204, s[30:31]
	s_add_i32 m0, s46, 0x2000
	s_add_u32 s46, s30, 0x80000
	s_addc_u32 s47, s31, 0
	s_add_i32 vcc_hi, vcc_hi, s8
	global_load_lds_dwordx4 v216, s[30:31]
	s_mov_b32 m0, vcc_hi
	s_add_u32 s100, s34, 0x80
	s_addc_u32 s101, s35, 0
	global_load_lds_dwordx4 v204, s[46:47]
	s_add_i32 m0, vcc_hi, 0x2000
	s_nop 0
	global_load_lds_dwordx4 v216, s[46:47]
	s_mov_b32 m0, s64
	s_nop 0
	global_load_lds_dwordx4 v202, s[34:35]
	s_add_i32 s46, 0, 0x18000
	s_add_i32 s47, 0, 0x1c000
	s_waitcnt vmcnt(7)
	s_waitcnt lgkmcnt(0)
	s_barrier
; #define PG8_STAGE(bufoff, gbase, voff) do { _Pragma("unroll") for (int _i = 0; _i < 2; ++_i) \
;         __builtin_amdgcn_global_load_lds((const unsigned*)((const char*)(gbase) + (voff)[_i]), (PG8_LAS unsigned*)(lds + (bufoff) + ldsw + _i * 8192), 16, 0, 0); } while (0)
; #define PG8_LDA(dst, b, h) do { _Pragma("unroll") for (int m = 0; m < 4; ++m) _Pragma("unroll") for (int k = 0; k < 2; ++k) dst[m][k] = *(const PG8_LAS bf16x8*)(lds + PG8_SA(b, h) + aoff + m * 2048 + k * 1024); } while (0)
; #define PG8_LDB(dst, b, h) do { _Pragma("unroll") for (int n = 0; n < 2; ++n) _Pragma("unroll") for (int k = 0; k < 2; ++k) dst[n][k] = *(const PG8_LAS bf16x8*)(lds + PG8_SB(b, h) + boff + n * 2048 + k * 1024); } while (0)
; #define PG8_MMA(ai, bj, At, Bt) do { __builtin_amdgcn_s_setprio(1); _Pragma("unroll") for (int m = 0; m < 4; ++m) _Pragma("unroll") for (int n = 0; n < 2; ++n) _Pragma("unroll") for (int k = 0; k < 2; ++k) \
;         acc[ai][bj][m][n] = __builtin_amdgcn_mfma_f32_16x16x32_bf16(Bt[n][k], At[m][k], acc[ai][bj][m][n], 0, 0, 0); __builtin_amdgcn_s_setprio(0); } while (0)
; #define PG8_WAIT_V(n) asm volatile("s_waitcnt vmcnt(" #n ")" ::: "memory")
; #define PG8_WAIT_L(n) asm volatile("s_waitcnt lgkmcnt(" #n ")" ::: "memory")
; #define PG8_BAR __builtin_amdgcn_s_barrier()
; #define PG8_SCHED __builtin_amdgcn_sched_barrier(0)
; template <class Epi, class Sched, bool ALIGN_EPI = false, bool SP2 = false>
; __device__ __forceinline__ void gemm_phase(PG8_LAS unsigned char* lds, const Gemm g, const Sched& S, const Epi& E, const int tid_in) {
;     ...
;             PG8_WAIT_V(8); PG8_WAIT_L(0); PG8_BAR; PG8_MMA(1, 0, At, B0); PG8_MMA(1, 1, At, B1); PG8_BAR; PG8_SCHED;
;             PG8_LDB(B0, 1, 0); PG8_LDB(B1, 1, 1); PG8_SCHED; PG8_LDA(At, 1, 0); PG8_STAGE(PG8_SA(0, 1), a2 + hstep, voffA);
;             PG8_WAIT_V(8); PG8_WAIT_L(0); PG8_BAR; PG8_MMA(0, 0, At, B0); PG8_MMA(0, 1, At, B1); PG8_BAR; PG8_SCHED;
	s_setprio 1
	v_mfma_f32_16x16x32_bf16 v[62:65], v[130:133], v[162:165], 0
	v_mfma_f32_16x16x32_bf16 v[58:61], v[138:141], v[162:165], 0
	v_mfma_f32_16x16x32_bf16 v[46:49], v[130:133], v[170:173], 0
	v_mfma_f32_16x16x32_bf16 v[42:45], v[138:141], v[170:173], 0
	v_mfma_f32_16x16x32_bf16 v[30:33], v[130:133], v[178:181], 0
	v_mfma_f32_16x16x32_bf16 v[26:29], v[138:141], v[178:181], 0
	v_mfma_f32_16x16x32_bf16 v[12:15], v[130:133], v[186:189], 0
	v_mfma_f32_16x16x32_bf16 v[8:11], v[138:141], v[186:189], 0
	v_mfma_f32_16x16x32_bf16 v[62:65], v[134:137], v[166:169], v[62:65]
	v_mfma_f32_16x16x32_bf16 v[58:61], v[142:145], v[166:169], v[58:61]
	v_mfma_f32_16x16x32_bf16 v[46:49], v[134:137], v[174:177], v[46:49]
	v_mfma_f32_16x16x32_bf16 v[42:45], v[142:145], v[174:177], v[42:45]
	v_mfma_f32_16x16x32_bf16 v[30:33], v[134:137], v[182:185], v[30:33]
	v_mfma_f32_16x16x32_bf16 v[26:29], v[142:145], v[182:185], v[26:29]
	v_mfma_f32_16x16x32_bf16 v[12:15], v[134:137], v[190:193], v[12:15]
	v_mfma_f32_16x16x32_bf16 v[8:11], v[142:145], v[190:193], v[8:11]
	s_setprio 0
	s_setprio 1
	v_mfma_f32_16x16x32_bf16 v[54:57], v[146:149], v[162:165], 0
	v_mfma_f32_16x16x32_bf16 v[50:53], v[154:157], v[162:165], 0
	v_mfma_f32_16x16x32_bf16 v[38:41], v[146:149], v[170:173], 0
	v_mfma_f32_16x16x32_bf16 v[34:37], v[154:157], v[170:173], 0
	v_mfma_f32_16x16x32_bf16 v[22:25], v[146:149], v[178:181], 0
	v_mfma_f32_16x16x32_bf16 v[16:19], v[154:157], v[178:181], 0
	v_mfma_f32_16x16x32_bf16 v[4:7], v[146:149], v[186:189], 0
	v_mfma_f32_16x16x32_bf16 v[0:3], v[154:157], v[186:189], 0
	v_mfma_f32_16x16x32_bf16 v[54:57], v[150:153], v[166:169], v[54:57]
	v_mfma_f32_16x16x32_bf16 v[50:53], v[158:161], v[166:169], v[50:53]
	v_mfma_f32_16x16x32_bf16 v[38:41], v[150:153], v[174:177], v[38:41]
	v_mfma_f32_16x16x32_bf16 v[34:37], v[158:161], v[174:177], v[34:37]
	v_mfma_f32_16x16x32_bf16 v[22:25], v[150:153], v[182:185], v[22:25]
	v_mfma_f32_16x16x32_bf16 v[16:19], v[158:161], v[182:185], v[16:19]
	v_mfma_f32_16x16x32_bf16 v[4:7], v[150:153], v[190:193], v[4:7]
	v_mfma_f32_16x16x32_bf16 v[0:3], v[158:161], v[190:193], v[0:3]
	s_setprio 0
	s_barrier
	ds_read_b128 v[130:133], v196
	ds_read_b128 v[134:137], v196 offset:1024
	ds_read_b128 v[138:141], v196 offset:2048
	ds_read_b128 v[142:145], v196 offset:3072
	ds_read_b128 v[146:149], v197
	ds_read_b128 v[150:153], v197 offset:1024
	ds_read_b128 v[154:157], v197 offset:2048
	ds_read_b128 v[158:161], v197 offset:3072
	s_mov_b32 m0, s65
	s_nop 0
	global_load_lds_dwordx4 v214, s[34:35]
	s_add_u32 s34, s34, 0x80000
	s_addc_u32 s35, s35, 0
	s_mov_b32 m0, s66
	ds_read_b128 v[162:165], v208 offset:32768
	ds_read_b128 v[166:169], v208 offset:33792
	ds_read_b128 v[170:173], v208 offset:34816
	ds_read_b128 v[174:177], v208 offset:35840
	ds_read_b128 v[178:181], v208 offset:36864
	ds_read_b128 v[182:185], v208 offset:37888
	ds_read_b128 v[186:189], v208 offset:38912
	ds_read_b128 v[190:193], v208 offset:39936
	global_load_lds_dwordx4 v202, s[34:35]
	s_mov_b32 m0, s67
	s_nop 0
	global_load_lds_dwordx4 v214, s[34:35]
	s_add_i32 s34, s46, s8
	s_mov_b32 m0, s34
	s_waitcnt vmcnt(8)
	s_waitcnt lgkmcnt(0)
	s_barrier
	s_setprio 1
	v_mfma_f32_16x16x32_bf16 v[126:129], v[130:133], v[162:165], v[126:129]
	v_mfma_f32_16x16x32_bf16 v[122:125], v[138:141], v[162:165], v[122:125]
	v_mfma_f32_16x16x32_bf16 v[110:113], v[130:133], v[170:173], v[110:113]
	v_mfma_f32_16x16x32_bf16 v[106:109], v[138:141], v[170:173], v[106:109]
	v_mfma_f32_16x16x32_bf16 v[94:97], v[130:133], v[178:181], v[94:97]
	v_mfma_f32_16x16x32_bf16 v[90:93], v[138:141], v[178:181], v[90:93]
	v_mfma_f32_16x16x32_bf16 v[78:81], v[130:133], v[186:189], v[78:81]
	v_mfma_f32_16x16x32_bf16 v[74:77], v[138:141], v[186:189], v[74:77]
	v_mfma_f32_16x16x32_bf16 v[126:129], v[134:137], v[166:169], v[126:129]
	v_mfma_f32_16x16x32_bf16 v[122:125], v[142:145], v[166:169], v[122:125]
	v_mfma_f32_16x16x32_bf16 v[110:113], v[134:137], v[174:177], v[110:113]
	v_mfma_f32_16x16x32_bf16 v[106:109], v[142:145], v[174:177], v[106:109]
	v_mfma_f32_16x16x32_bf16 v[94:97], v[134:137], v[182:185], v[94:97]
	v_mfma_f32_16x16x32_bf16 v[90:93], v[142:145], v[182:185], v[90:93]
	v_mfma_f32_16x16x32_bf16 v[78:81], v[134:137], v[190:193], v[78:81]
	v_mfma_f32_16x16x32_bf16 v[74:77], v[142:145], v[190:193], v[74:77]
	s_setprio 0
	s_setprio 1
	v_mfma_f32_16x16x32_bf16 v[118:121], v[146:149], v[162:165], v[118:121]
	v_mfma_f32_16x16x32_bf16 v[114:117], v[154:157], v[162:165], v[114:117]
	v_mfma_f32_16x16x32_bf16 v[102:105], v[146:149], v[170:173], v[102:105]
	v_mfma_f32_16x16x32_bf16 v[98:101], v[154:157], v[170:173], v[98:101]
	v_mfma_f32_16x16x32_bf16 v[86:89], v[146:149], v[178:181], v[86:89]
	v_mfma_f32_16x16x32_bf16 v[82:85], v[154:157], v[178:181], v[82:85]
	v_mfma_f32_16x16x32_bf16 v[70:73], v[146:149], v[186:189], v[70:73]
	v_mfma_f32_16x16x32_bf16 v[66:69], v[154:157], v[186:189], v[66:69]
	v_mfma_f32_16x16x32_bf16 v[118:121], v[150:153], v[166:169], v[118:121]
	v_mfma_f32_16x16x32_bf16 v[114:117], v[158:161], v[166:169], v[114:117]
	v_mfma_f32_16x16x32_bf16 v[102:105], v[150:153], v[174:177], v[102:105]
	v_mfma_f32_16x16x32_bf16 v[98:101], v[158:161], v[174:177], v[98:101]
	v_mfma_f32_16x16x32_bf16 v[86:89], v[150:153], v[182:185], v[86:89]
	v_mfma_f32_16x16x32_bf16 v[82:85], v[158:161], v[182:185], v[82:85]
	v_mfma_f32_16x16x32_bf16 v[70:73], v[150:153], v[190:193], v[70:73]
	v_mfma_f32_16x16x32_bf16 v[66:69], v[158:161], v[190:193], v[66:69]
	s_setprio 0
	s_barrier
; #define PG8_STAGE(bufoff, gbase, voff) do { _Pragma("unroll") for (int _i = 0; _i < 2; ++_i) \
;         __builtin_amdgcn_global_load_lds((const unsigned*)((const char*)(gbase) + (voff)[_i]), (PG8_LAS unsigned*)(lds + (bufoff) + ldsw + _i * 8192), 16, 0, 0); } while (0)
; #define PG8_LDA(dst, b, h) do { _Pragma("unroll") for (int m = 0; m < 4; ++m) _Pragma("unroll") for (int k = 0; k < 2; ++k) dst[m][k] = *(const PG8_LAS bf16x8*)(lds + PG8_SA(b, h) + aoff + m * 2048 + k * 1024); } while (0)
; #define PG8_LDB(dst, b, h) do { _Pragma("unroll") for (int n = 0; n < 2; ++n) _Pragma("unroll") for (int k = 0; k < 2; ++k) dst[n][k] = *(const PG8_LAS bf16x8*)(lds + PG8_SB(b, h) + boff + n * 2048 + k * 1024); } while (0)
; #define PG8_MMA(ai, bj, At, Bt) do { __builtin_amdgcn_s_setprio(1); _Pragma("unroll") for (int m = 0; m < 4; ++m) _Pragma("unroll") for (int n = 0; n < 2; ++n) _Pragma("unroll") for (int k = 0; k < 2; ++k) \
;         acc[ai][bj][m][n] = __builtin_amdgcn_mfma_f32_16x16x32_bf16(Bt[n][k], At[m][k], acc[ai][bj][m][n], 0, 0, 0); __builtin_amdgcn_s_setprio(0); } while (0)
; #define PG8_WAIT_V(n) asm volatile("s_waitcnt vmcnt(" #n ")" ::: "memory")
; #define PG8_WAIT_L(n) asm volatile("s_waitcnt lgkmcnt(" #n ")" ::: "memory")
; #define PG8_BAR __builtin_amdgcn_s_barrier()
; #define PG8_SCHED __builtin_amdgcn_sched_barrier(0)
; template <class Epi, class Sched, bool ALIGN_EPI = false, bool SP2 = false>
; __device__ __forceinline__ void gemm_phase(PG8_LAS unsigned char* lds, const Gemm g, const Sched& S, const Epi& E, const int tid_in) {
;     ...
;             PG8_LDB(B0, 0, 0); PG8_LDB(B1, 0, 1); PG8_SCHED; PG8_LDA(At, 0, 0); PG8_STAGE(PG8_SA(1, 1), a1 + hstep, voffA);
;             PG8_WAIT_V(8); PG8_WAIT_L(0); PG8_BAR; PG8_MMA(0, 0, At, B0); PG8_MMA(0, 1, At, B1); PG8_BAR; PG8_SCHED;
;     ...
;             PG8_LDA(At, 1, 1); PG8_STAGE(PG8_SB(1, 0), b3, voffB); PG8_STAGE(PG8_SB(1, 1), b3 + hstep, voffB); PG8_STAGE(PG8_SA(1, 0), a3, voffA);
;             PG8_WAIT_V(8); PG8_WAIT_L(0); PG8_BAR; PG8_MMA(1, 0, At, B0); PG8_MMA(1, 1, At, B1); PG8_BAR; PG8_SCHED;
	ds_read_b128 v[162:165], v208 offset:49152
	ds_read_b128 v[166:169], v208 offset:50176
	ds_read_b128 v[170:173], v208 offset:51200
	ds_read_b128 v[174:177], v208 offset:52224
	ds_read_b128 v[178:181], v208 offset:53248
	ds_read_b128 v[182:185], v208 offset:54272
	ds_read_b128 v[186:189], v208 offset:55296
	ds_read_b128 v[190:193], v208 offset:56320
	global_load_lds_dwordx4 v204, s[98:99]
	s_add_i32 m0, s34, 0x2000
	s_add_u32 s30, s30, 0x80080
	s_addc_u32 s31, s31, 0
	s_add_i32 s34, s47, s8
	global_load_lds_dwordx4 v216, s[98:99]
	s_mov_b32 m0, s34
	s_nop 0
	global_load_lds_dwordx4 v204, s[30:31]
	s_add_i32 m0, s34, 0x2000
	s_nop 0
	global_load_lds_dwordx4 v216, s[30:31]
	s_mov_b32 m0, s75
	s_nop 0
	global_load_lds_dwordx4 v202, s[100:101]
	s_add_i32 vcc_lo, vcc_lo, 2
	s_add_u32 s28, s28, 0x100
	s_addc_u32 s29, s29, 0
	s_add_u32 s57, s57, 0x100
	s_addc_u32 s92, s92, 0
	s_add_u32 s30, s28, 0xfff80080
	s_addc_u32 s31, s29, -1
	s_add_i32 s46, 0, 0x10000
	s_cmp_eq_u32 vcc_lo, 28
	s_cselect_b32 s35, s38, s31
	s_cselect_b32 s34, s39, s30
	s_cselect_b32 s31, s40, s92
	s_cselect_b32 s30, s41, s57
	s_add_i32 vcc_hi, 0, 0x14000
	s_cmp_gt_u32 vcc_lo, 29
	s_waitcnt vmcnt(7)
	s_waitcnt lgkmcnt(0)
	s_barrier
	s_setprio 1
	v_mfma_f32_16x16x32_bf16 v[62:65], v[130:133], v[162:165], v[62:65]
	v_mfma_f32_16x16x32_bf16 v[58:61], v[138:141], v[162:165], v[58:61]
	v_mfma_f32_16x16x32_bf16 v[46:49], v[130:133], v[170:173], v[46:49]
	v_mfma_f32_16x16x32_bf16 v[42:45], v[138:141], v[170:173], v[42:45]
	v_mfma_f32_16x16x32_bf16 v[30:33], v[130:133], v[178:181], v[30:33]
	v_mfma_f32_16x16x32_bf16 v[26:29], v[138:141], v[178:181], v[26:29]
	v_mfma_f32_16x16x32_bf16 v[12:15], v[130:133], v[186:189], v[12:15]
	v_mfma_f32_16x16x32_bf16 v[8:11], v[138:141], v[186:189], v[8:11]
	v_mfma_f32_16x16x32_bf16 v[62:65], v[134:137], v[166:169], v[62:65]
	v_mfma_f32_16x16x32_bf16 v[58:61], v[142:145], v[166:169], v[58:61]
	v_mfma_f32_16x16x32_bf16 v[46:49], v[134:137], v[174:177], v[46:49]
	v_mfma_f32_16x16x32_bf16 v[42:45], v[142:145], v[174:177], v[42:45]
	v_mfma_f32_16x16x32_bf16 v[30:33], v[134:137], v[182:185], v[30:33]
	v_mfma_f32_16x16x32_bf16 v[26:29], v[142:145], v[182:185], v[26:29]
	v_mfma_f32_16x16x32_bf16 v[12:15], v[134:137], v[190:193], v[12:15]
	v_mfma_f32_16x16x32_bf16 v[8:11], v[142:145], v[190:193], v[8:11]
	s_setprio 0
	s_setprio 1
	v_mfma_f32_16x16x32_bf16 v[54:57], v[146:149], v[162:165], v[54:57]
	v_mfma_f32_16x16x32_bf16 v[50:53], v[154:157], v[162:165], v[50:53]
	v_mfma_f32_16x16x32_bf16 v[38:41], v[146:149], v[170:173], v[38:41]
	v_mfma_f32_16x16x32_bf16 v[34:37], v[154:157], v[170:173], v[34:37]
	v_mfma_f32_16x16x32_bf16 v[22:25], v[146:149], v[178:181], v[22:25]
	v_mfma_f32_16x16x32_bf16 v[16:19], v[154:157], v[178:181], v[16:19]
	v_mfma_f32_16x16x32_bf16 v[4:7], v[146:149], v[186:189], v[4:7]
	v_mfma_f32_16x16x32_bf16 v[0:3], v[154:157], v[186:189], v[0:3]
	v_mfma_f32_16x16x32_bf16 v[54:57], v[150:153], v[166:169], v[54:57]
	v_mfma_f32_16x16x32_bf16 v[50:53], v[158:161], v[166:169], v[50:53]
	v_mfma_f32_16x16x32_bf16 v[38:41], v[150:153], v[174:177], v[38:41]
	v_mfma_f32_16x16x32_bf16 v[34:37], v[158:161], v[174:177], v[34:37]
	v_mfma_f32_16x16x32_bf16 v[22:25], v[150:153], v[182:185], v[22:25]
	v_mfma_f32_16x16x32_bf16 v[16:19], v[158:161], v[182:185], v[16:19]
	v_mfma_f32_16x16x32_bf16 v[4:7], v[150:153], v[190:193], v[4:7]
	v_mfma_f32_16x16x32_bf16 v[0:3], v[158:161], v[190:193], v[0:3]
	s_setprio 0
	s_barrier
.LBB0_1037:
	s_mov_b32 m0, s76
	s_nop 0
	global_load_lds_dwordx4 v214, s[100:101]
	ds_read_b128 v[130:133], v194
	ds_read_b128 v[134:137], v194 offset:1024
	ds_read_b128 v[138:141], v194 offset:2048
	ds_read_b128 v[142:145], v194 offset:3072
	ds_read_b128 v[146:149], v195
	ds_read_b128 v[150:153], v195 offset:1024
	ds_read_b128 v[154:157], v195 offset:2048
	ds_read_b128 v[158:161], v195 offset:3072
	s_add_i32 m0, s64, 0xc000
	ds_read_b128 v[162:165], v208
	ds_read_b128 v[166:169], v208 offset:1024
	ds_read_b128 v[170:173], v208 offset:2048
	ds_read_b128 v[174:177], v208 offset:3072
	ds_read_b128 v[178:181], v208 offset:4096
	ds_read_b128 v[182:185], v208 offset:5120
	ds_read_b128 v[186:189], v208 offset:6144
	ds_read_b128 v[190:193], v208 offset:7168
	global_load_lds_dwordx4 v218, s[28:29]
	s_add_i32 m0, s64, 0xe000
	s_nop 0
	global_load_lds_dwordx4 v220, s[28:29]
	s_add_i32 s46, s46, s8
	s_add_u32 s98, s30, 0x80
	s_addc_u32 s99, s31, 0
	s_mov_b32 m0, s46
	s_waitcnt vmcnt(8)
	s_waitcnt lgkmcnt(0)
	s_barrier
; #define PG8_STAGE(bufoff, gbase, voff) do { _Pragma("unroll") for (int _i = 0; _i < 2; ++_i) \
;         __builtin_amdgcn_global_load_lds((const unsigned*)((const char*)(gbase) + (voff)[_i]), (PG8_LAS unsigned*)(lds + (bufoff) + ldsw + _i * 8192), 16, 0, 0); } while (0)
; #define PG8_LDA(dst, b, h) do { _Pragma("unroll") for (int m = 0; m < 4; ++m) _Pragma("unroll") for (int k = 0; k < 2; ++k) dst[m][k] = *(const PG8_LAS bf16x8*)(lds + PG8_SA(b, h) + aoff + m * 2048 + k * 1024); } while (0)
; #define PG8_MMA(ai, bj, At, Bt) do { __builtin_amdgcn_s_setprio(1); _Pragma("unroll") for (int m = 0; m < 4; ++m) _Pragma("unroll") for (int n = 0; n < 2; ++n) _Pragma("unroll") for (int k = 0; k < 2; ++k) \
;         acc[ai][bj][m][n] = __builtin_amdgcn_mfma_f32_16x16x32_bf16(Bt[n][k], At[m][k], acc[ai][bj][m][n], 0, 0, 0); __builtin_amdgcn_s_setprio(0); } while (0)
; #define PG8_WAIT_V(n) asm volatile("s_waitcnt vmcnt(" #n ")" ::: "memory")
; #define PG8_WAIT_L(n) asm volatile("s_waitcnt lgkmcnt(" #n ")" ::: "memory")
; #define PG8_BAR __builtin_amdgcn_s_barrier()
; #define PG8_SCHED __builtin_amdgcn_sched_barrier(0)
; template <class Epi, class Sched, bool ALIGN_EPI = false, bool SP2 = false>
; __device__ __forceinline__ void gemm_phase(PG8_LAS unsigned char* lds, const Gemm g, const Sched& S, const Epi& E, const int tid_in) {
;     ...
;             PG8_WAIT_V(8); PG8_WAIT_L(0); PG8_BAR; PG8_MMA(0, 0, At, B0); PG8_MMA(0, 1, At, B1); PG8_BAR; PG8_SCHED;
;             PG8_LDA(At, 0, 1); PG8_STAGE(PG8_SB(0, 0), b2, voffB); PG8_STAGE(PG8_SB(0, 1), b2 + hstep, voffB); PG8_STAGE(PG8_SA(0, 0), a2, voffA);
;             PG8_WAIT_V(8); PG8_WAIT_L(0); PG8_BAR; PG8_MMA(1, 0, At, B0); PG8_MMA(1, 1, At, B1); PG8_BAR; PG8_SCHED;
	s_setprio 1
	v_mfma_f32_16x16x32_bf16 v[126:129], v[130:133], v[162:165], v[126:129]
	v_mfma_f32_16x16x32_bf16 v[122:125], v[138:141], v[162:165], v[122:125]
	v_mfma_f32_16x16x32_bf16 v[110:113], v[130:133], v[170:173], v[110:113]
	v_mfma_f32_16x16x32_bf16 v[106:109], v[138:141], v[170:173], v[106:109]
	v_mfma_f32_16x16x32_bf16 v[94:97], v[130:133], v[178:181], v[94:97]
	v_mfma_f32_16x16x32_bf16 v[90:93], v[138:141], v[178:181], v[90:93]
	v_mfma_f32_16x16x32_bf16 v[78:81], v[130:133], v[186:189], v[78:81]
	v_mfma_f32_16x16x32_bf16 v[74:77], v[138:141], v[186:189], v[74:77]
	v_mfma_f32_16x16x32_bf16 v[126:129], v[134:137], v[166:169], v[126:129]
	v_mfma_f32_16x16x32_bf16 v[122:125], v[142:145], v[166:169], v[122:125]
	v_mfma_f32_16x16x32_bf16 v[110:113], v[134:137], v[174:177], v[110:113]
	v_mfma_f32_16x16x32_bf16 v[106:109], v[142:145], v[174:177], v[106:109]
	v_mfma_f32_16x16x32_bf16 v[94:97], v[134:137], v[182:185], v[94:97]
	v_mfma_f32_16x16x32_bf16 v[90:93], v[142:145], v[182:185], v[90:93]
	v_mfma_f32_16x16x32_bf16 v[78:81], v[134:137], v[190:193], v[78:81]
	v_mfma_f32_16x16x32_bf16 v[74:77], v[142:145], v[190:193], v[74:77]
	s_setprio 0
	s_setprio 1
	v_mfma_f32_16x16x32_bf16 v[118:121], v[146:149], v[162:165], v[118:121]
	v_mfma_f32_16x16x32_bf16 v[114:117], v[154:157], v[162:165], v[114:117]
	v_mfma_f32_16x16x32_bf16 v[102:105], v[146:149], v[170:173], v[102:105]
	v_mfma_f32_16x16x32_bf16 v[98:101], v[154:157], v[170:173], v[98:101]
	v_mfma_f32_16x16x32_bf16 v[86:89], v[146:149], v[178:181], v[86:89]
	v_mfma_f32_16x16x32_bf16 v[82:85], v[154:157], v[178:181], v[82:85]
	v_mfma_f32_16x16x32_bf16 v[70:73], v[146:149], v[186:189], v[70:73]
	v_mfma_f32_16x16x32_bf16 v[66:69], v[154:157], v[186:189], v[66:69]
	v_mfma_f32_16x16x32_bf16 v[118:121], v[150:153], v[166:169], v[118:121]
	v_mfma_f32_16x16x32_bf16 v[114:117], v[158:161], v[166:169], v[114:117]
	v_mfma_f32_16x16x32_bf16 v[102:105], v[150:153], v[174:177], v[102:105]
	v_mfma_f32_16x16x32_bf16 v[98:101], v[158:161], v[174:177], v[98:101]
	v_mfma_f32_16x16x32_bf16 v[86:89], v[150:153], v[182:185], v[86:89]
	v_mfma_f32_16x16x32_bf16 v[82:85], v[158:161], v[182:185], v[82:85]
	v_mfma_f32_16x16x32_bf16 v[70:73], v[150:153], v[190:193], v[70:73]
	v_mfma_f32_16x16x32_bf16 v[66:69], v[158:161], v[190:193], v[66:69]
	s_setprio 0
	s_barrier
	ds_read_b128 v[162:165], v208 offset:16384
	ds_read_b128 v[166:169], v208 offset:17408
	ds_read_b128 v[170:173], v208 offset:18432
	ds_read_b128 v[174:177], v208 offset:19456
	ds_read_b128 v[178:181], v208 offset:20480
	ds_read_b128 v[182:185], v208 offset:21504
	ds_read_b128 v[186:189], v208 offset:22528
	ds_read_b128 v[190:193], v208 offset:23552
	global_load_lds_dwordx4 v204, s[30:31]
	s_add_i32 m0, s46, 0x2000
	s_add_u32 s46, s30, 0x80000
	s_addc_u32 s47, s31, 0
	s_add_i32 vcc_hi, vcc_hi, s8
	global_load_lds_dwordx4 v216, s[30:31]
	s_mov_b32 m0, vcc_hi
	s_add_u32 s100, s34, 0x80
	s_addc_u32 s101, s35, 0
	global_load_lds_dwordx4 v204, s[46:47]
	s_add_i32 m0, vcc_hi, 0x2000
	s_nop 0
	global_load_lds_dwordx4 v216, s[46:47]
	s_mov_b32 m0, s64
	s_nop 0
	global_load_lds_dwordx4 v202, s[34:35]
	s_add_i32 s46, 0, 0x18000
	s_add_i32 s47, 0, 0x1c000
	s_waitcnt vmcnt(7)
	s_waitcnt lgkmcnt(0)
	s_barrier
	s_setprio 1
	v_mfma_f32_16x16x32_bf16 v[62:65], v[130:133], v[162:165], v[62:65]
	v_mfma_f32_16x16x32_bf16 v[58:61], v[138:141], v[162:165], v[58:61]
	v_mfma_f32_16x16x32_bf16 v[46:49], v[130:133], v[170:173], v[46:49]
	v_mfma_f32_16x16x32_bf16 v[42:45], v[138:141], v[170:173], v[42:45]
	v_mfma_f32_16x16x32_bf16 v[30:33], v[130:133], v[178:181], v[30:33]
	v_mfma_f32_16x16x32_bf16 v[26:29], v[138:141], v[178:181], v[26:29]
	v_mfma_f32_16x16x32_bf16 v[12:15], v[130:133], v[186:189], v[12:15]
	v_mfma_f32_16x16x32_bf16 v[8:11], v[138:141], v[186:189], v[8:11]
	v_mfma_f32_16x16x32_bf16 v[62:65], v[134:137], v[166:169], v[62:65]
	v_mfma_f32_16x16x32_bf16 v[58:61], v[142:145], v[166:169], v[58:61]
	v_mfma_f32_16x16x32_bf16 v[46:49], v[134:137], v[174:177], v[46:49]
	v_mfma_f32_16x16x32_bf16 v[42:45], v[142:145], v[174:177], v[42:45]
	v_mfma_f32_16x16x32_bf16 v[30:33], v[134:137], v[182:185], v[30:33]
	v_mfma_f32_16x16x32_bf16 v[26:29], v[142:145], v[182:185], v[26:29]
	v_mfma_f32_16x16x32_bf16 v[12:15], v[134:137], v[190:193], v[12:15]
	v_mfma_f32_16x16x32_bf16 v[8:11], v[142:145], v[190:193], v[8:11]
	s_setprio 0
	s_setprio 1
	v_mfma_f32_16x16x32_bf16 v[54:57], v[146:149], v[162:165], v[54:57]
	v_mfma_f32_16x16x32_bf16 v[50:53], v[154:157], v[162:165], v[50:53]
	v_mfma_f32_16x16x32_bf16 v[38:41], v[146:149], v[170:173], v[38:41]
	v_mfma_f32_16x16x32_bf16 v[34:37], v[154:157], v[170:173], v[34:37]
	v_mfma_f32_16x16x32_bf16 v[22:25], v[146:149], v[178:181], v[22:25]
	v_mfma_f32_16x16x32_bf16 v[16:19], v[154:157], v[178:181], v[16:19]
	v_mfma_f32_16x16x32_bf16 v[4:7], v[146:149], v[186:189], v[4:7]
	v_mfma_f32_16x16x32_bf16 v[0:3], v[154:157], v[186:189], v[0:3]
	v_mfma_f32_16x16x32_bf16 v[54:57], v[150:153], v[166:169], v[54:57]
	v_mfma_f32_16x16x32_bf16 v[50:53], v[158:161], v[166:169], v[50:53]
	v_mfma_f32_16x16x32_bf16 v[38:41], v[150:153], v[174:177], v[38:41]
	v_mfma_f32_16x16x32_bf16 v[34:37], v[158:161], v[174:177], v[34:37]
	v_mfma_f32_16x16x32_bf16 v[22:25], v[150:153], v[182:185], v[22:25]
	v_mfma_f32_16x16x32_bf16 v[16:19], v[158:161], v[182:185], v[16:19]
	v_mfma_f32_16x16x32_bf16 v[4:7], v[150:153], v[190:193], v[4:7]
	v_mfma_f32_16x16x32_bf16 v[0:3], v[158:161], v[190:193], v[0:3]
	s_setprio 0
	s_barrier
; #define PG8_STAGE(bufoff, gbase, voff) do { _Pragma("unroll") for (int _i = 0; _i < 2; ++_i) \
;         __builtin_amdgcn_global_load_lds((const unsigned*)((const char*)(gbase) + (voff)[_i]), (PG8_LAS unsigned*)(lds + (bufoff) + ldsw + _i * 8192), 16, 0, 0); } while (0)
; #define PG8_LDA(dst, b, h) do { _Pragma("unroll") for (int m = 0; m < 4; ++m) _Pragma("unroll") for (int k = 0; k < 2; ++k) dst[m][k] = *(const PG8_LAS bf16x8*)(lds + PG8_SA(b, h) + aoff + m * 2048 + k * 1024); } while (0)
; #define PG8_WAIT_V(n) asm volatile("s_waitcnt vmcnt(" #n ")" ::: "memory")
; template <class Epi, class Sched, bool ALIGN_EPI = false, bool SP2 = false>
; __device__ __forceinline__ void gemm_phase(PG8_LAS unsigned char* lds, const Gemm g, const Sched& S, const Epi& E, const int tid_in) {
;     ...
;         for (int t = 0; t < nt; t += 2) {
;             if constexpr (Epi::KSPLIT > 0) { if (t == Epi::KSPLIT / BK) E.midk(acc, cur, wr, wc, fr, fq); }
;             const bool last = (t == nt - 2);
;             const char* a1 = cA + (size_t)(t + 1) * kstep;
;             const char* a2 = last ? nA : cA + (size_t)(t + 2) * kstep; const char* b2 = last ? nB : cB + (size_t)(t + 2) * kstep;
;             const char* a3 = a2 + kstep; const char* b3 = b2 + kstep;
;             if (last && has_next) S.a_ready(nxt);
;             if constexpr (SP2) {
;             PG8_LDB(B0, 0, 0); PG8_LDB(B1, 0, 1); PG8_SCHED; PG8_LDA(At, 0, 0); PG8_STAGE(PG8_SA(1, 1), a1 + hstep, voffA);
;             PG8_WAIT_V(8); PG8_WAIT_L(0); PG8_BAR; PG8_MMA(0, 0, At, B0); PG8_MMA(0, 1, At, B1); PG8_BAR; PG8_SCHED;
;             PG8_LDA(At, 0, 1); PG8_STAGE(PG8_SB(0, 0), b2, voffB); PG8_STAGE(PG8_SB(0, 1), b2 + hstep, voffB); PG8_STAGE(PG8_SA(0, 0), a2, voffA);
;             PG8_WAIT_V(8); PG8_WAIT_L(0); PG8_BAR; PG8_MMA(1, 0, At, B0); PG8_MMA(1, 1, At, B1); PG8_BAR; PG8_SCHED;
;             PG8_LDB(B0, 1, 0); PG8_LDB(B1, 1, 1); PG8_SCHED; PG8_LDA(At, 1, 0); PG8_STAGE(PG8_SA(0, 1), a2 + hstep, voffA);
;             PG8_WAIT_V(8); PG8_WAIT_L(0); PG8_BAR; PG8_MMA(0, 0, At, B0); PG8_MMA(0, 1, At, B1); PG8_BAR; PG8_SCHED;
;             PG8_LDA(At, 1, 1); PG8_STAGE(PG8_SB(1, 0), b3, voffB); PG8_STAGE(PG8_SB(1, 1), b3 + hstep, voffB); PG8_STAGE(PG8_SA(1, 0), a3, voffA);
;             PG8_WAIT_V(8); PG8_WAIT_L(0); PG8_BAR; PG8_MMA(1, 0, At, B0); PG8_MMA(1, 1, At, B1); PG8_BAR; PG8_SCHED;
	ds_read_b128 v[130:133], v196
	ds_read_b128 v[134:137], v196 offset:1024
	ds_read_b128 v[138:141], v196 offset:2048
	ds_read_b128 v[142:145], v196 offset:3072
	ds_read_b128 v[146:149], v197
	ds_read_b128 v[150:153], v197 offset:1024
	ds_read_b128 v[154:157], v197 offset:2048
	ds_read_b128 v[158:161], v197 offset:3072
	s_mov_b32 m0, s65
	s_nop 0
	global_load_lds_dwordx4 v214, s[34:35]
	s_add_u32 s34, s34, 0x80000
	s_addc_u32 s35, s35, 0
	s_mov_b32 m0, s66
	ds_read_b128 v[162:165], v208 offset:32768
	ds_read_b128 v[166:169], v208 offset:33792
	ds_read_b128 v[170:173], v208 offset:34816
	ds_read_b128 v[174:177], v208 offset:35840
	ds_read_b128 v[178:181], v208 offset:36864
	ds_read_b128 v[182:185], v208 offset:37888
	ds_read_b128 v[186:189], v208 offset:38912
	ds_read_b128 v[190:193], v208 offset:39936
	global_load_lds_dwordx4 v202, s[34:35]
	s_mov_b32 m0, s67
	s_nop 0
	global_load_lds_dwordx4 v214, s[34:35]
	s_add_i32 s34, s46, s8
	s_mov_b32 m0, s34
	s_waitcnt vmcnt(8)
	s_waitcnt lgkmcnt(0)
	s_barrier
	s_setprio 1
	v_mfma_f32_16x16x32_bf16 v[126:129], v[130:133], v[162:165], v[126:129]
	v_mfma_f32_16x16x32_bf16 v[122:125], v[138:141], v[162:165], v[122:125]
	v_mfma_f32_16x16x32_bf16 v[110:113], v[130:133], v[170:173], v[110:113]
	v_mfma_f32_16x16x32_bf16 v[106:109], v[138:141], v[170:173], v[106:109]
	v_mfma_f32_16x16x32_bf16 v[94:97], v[130:133], v[178:181], v[94:97]
	v_mfma_f32_16x16x32_bf16 v[90:93], v[138:141], v[178:181], v[90:93]
	v_mfma_f32_16x16x32_bf16 v[78:81], v[130:133], v[186:189], v[78:81]
	v_mfma_f32_16x16x32_bf16 v[74:77], v[138:141], v[186:189], v[74:77]
	v_mfma_f32_16x16x32_bf16 v[126:129], v[134:137], v[166:169], v[126:129]
	v_mfma_f32_16x16x32_bf16 v[122:125], v[142:145], v[166:169], v[122:125]
	v_mfma_f32_16x16x32_bf16 v[110:113], v[134:137], v[174:177], v[110:113]
	v_mfma_f32_16x16x32_bf16 v[106:109], v[142:145], v[174:177], v[106:109]
	v_mfma_f32_16x16x32_bf16 v[94:97], v[134:137], v[182:185], v[94:97]
	v_mfma_f32_16x16x32_bf16 v[90:93], v[142:145], v[182:185], v[90:93]
	v_mfma_f32_16x16x32_bf16 v[78:81], v[134:137], v[190:193], v[78:81]
	v_mfma_f32_16x16x32_bf16 v[74:77], v[142:145], v[190:193], v[74:77]
	s_setprio 0
	s_setprio 1
	v_mfma_f32_16x16x32_bf16 v[118:121], v[146:149], v[162:165], v[118:121]
	v_mfma_f32_16x16x32_bf16 v[114:117], v[154:157], v[162:165], v[114:117]
	v_mfma_f32_16x16x32_bf16 v[102:105], v[146:149], v[170:173], v[102:105]
	v_mfma_f32_16x16x32_bf16 v[98:101], v[154:157], v[170:173], v[98:101]
	v_mfma_f32_16x16x32_bf16 v[86:89], v[146:149], v[178:181], v[86:89]
	v_mfma_f32_16x16x32_bf16 v[82:85], v[154:157], v[178:181], v[82:85]
	v_mfma_f32_16x16x32_bf16 v[70:73], v[146:149], v[186:189], v[70:73]
	v_mfma_f32_16x16x32_bf16 v[66:69], v[154:157], v[186:189], v[66:69]
	v_mfma_f32_16x16x32_bf16 v[118:121], v[150:153], v[166:169], v[118:121]
	v_mfma_f32_16x16x32_bf16 v[114:117], v[158:161], v[166:169], v[114:117]
	v_mfma_f32_16x16x32_bf16 v[102:105], v[150:153], v[174:177], v[102:105]
	v_mfma_f32_16x16x32_bf16 v[98:101], v[158:161], v[174:177], v[98:101]
	v_mfma_f32_16x16x32_bf16 v[86:89], v[150:153], v[182:185], v[86:89]
	v_mfma_f32_16x16x32_bf16 v[82:85], v[158:161], v[182:185], v[82:85]
	v_mfma_f32_16x16x32_bf16 v[70:73], v[150:153], v[190:193], v[70:73]
	v_mfma_f32_16x16x32_bf16 v[66:69], v[158:161], v[190:193], v[66:69]
	s_setprio 0
	s_barrier
	ds_read_b128 v[162:165], v208 offset:49152
	ds_read_b128 v[166:169], v208 offset:50176
	ds_read_b128 v[170:173], v208 offset:51200
	ds_read_b128 v[174:177], v208 offset:52224
	ds_read_b128 v[178:181], v208 offset:53248
	ds_read_b128 v[182:185], v208 offset:54272
	ds_read_b128 v[186:189], v208 offset:55296
	ds_read_b128 v[190:193], v208 offset:56320
	global_load_lds_dwordx4 v204, s[98:99]
	s_add_i32 m0, s34, 0x2000
	s_add_u32 s30, s30, 0x80080
	s_addc_u32 s31, s31, 0
	s_add_i32 s34, s47, s8
	global_load_lds_dwordx4 v216, s[98:99]
	s_mov_b32 m0, s34
	s_nop 0
	global_load_lds_dwordx4 v204, s[30:31]
	s_add_i32 m0, s34, 0x2000
	s_nop 0
	global_load_lds_dwordx4 v216, s[30:31]
	s_mov_b32 m0, s75
	s_nop 0
	global_load_lds_dwordx4 v202, s[100:101]
	s_add_i32 vcc_lo, vcc_lo, 2
	s_add_u32 s28, s28, 0x100
	s_addc_u32 s29, s29, 0
	s_add_u32 s57, s57, 0x100
	s_addc_u32 s92, s92, 0
	s_add_u32 s30, s28, 0xfff80080
	s_addc_u32 s31, s29, -1
	s_add_i32 s46, 0, 0x10000
	s_cmp_eq_u32 vcc_lo, 28
	s_cselect_b32 s35, s38, s31
	s_cselect_b32 s34, s39, s30
	s_cselect_b32 s31, s40, s92
	s_cselect_b32 s30, s41, s57
	s_add_i32 vcc_hi, 0, 0x14000
	s_cmp_gt_u32 vcc_lo, 29
	s_waitcnt vmcnt(7)
	s_waitcnt lgkmcnt(0)
	s_barrier
	s_setprio 1
	v_mfma_f32_16x16x32_bf16 v[62:65], v[130:133], v[162:165], v[62:65]
	v_mfma_f32_16x16x32_bf16 v[58:61], v[138:141], v[162:165], v[58:61]
	v_mfma_f32_16x16x32_bf16 v[46:49], v[130:133], v[170:173], v[46:49]
	v_mfma_f32_16x16x32_bf16 v[42:45], v[138:141], v[170:173], v[42:45]
	v_mfma_f32_16x16x32_bf16 v[30:33], v[130:133], v[178:181], v[30:33]
	v_mfma_f32_16x16x32_bf16 v[26:29], v[138:141], v[178:181], v[26:29]
	v_mfma_f32_16x16x32_bf16 v[12:15], v[130:133], v[186:189], v[12:15]
	v_mfma_f32_16x16x32_bf16 v[8:11], v[138:141], v[186:189], v[8:11]
	v_mfma_f32_16x16x32_bf16 v[62:65], v[134:137], v[166:169], v[62:65]
	v_mfma_f32_16x16x32_bf16 v[58:61], v[142:145], v[166:169], v[58:61]
	v_mfma_f32_16x16x32_bf16 v[46:49], v[134:137], v[174:177], v[46:49]
	v_mfma_f32_16x16x32_bf16 v[42:45], v[142:145], v[174:177], v[42:45]
	v_mfma_f32_16x16x32_bf16 v[30:33], v[134:137], v[182:185], v[30:33]
	v_mfma_f32_16x16x32_bf16 v[26:29], v[142:145], v[182:185], v[26:29]
	v_mfma_f32_16x16x32_bf16 v[12:15], v[134:137], v[190:193], v[12:15]
	v_mfma_f32_16x16x32_bf16 v[8:11], v[142:145], v[190:193], v[8:11]
	s_setprio 0
	s_setprio 1
	v_mfma_f32_16x16x32_bf16 v[54:57], v[146:149], v[162:165], v[54:57]
	v_mfma_f32_16x16x32_bf16 v[50:53], v[154:157], v[162:165], v[50:53]
	v_mfma_f32_16x16x32_bf16 v[38:41], v[146:149], v[170:173], v[38:41]
	v_mfma_f32_16x16x32_bf16 v[34:37], v[154:157], v[170:173], v[34:37]
	v_mfma_f32_16x16x32_bf16 v[22:25], v[146:149], v[178:181], v[22:25]
	v_mfma_f32_16x16x32_bf16 v[16:19], v[154:157], v[178:181], v[16:19]
	v_mfma_f32_16x16x32_bf16 v[4:7], v[146:149], v[186:189], v[4:7]
	v_mfma_f32_16x16x32_bf16 v[0:3], v[154:157], v[186:189], v[0:3]
	v_mfma_f32_16x16x32_bf16 v[54:57], v[150:153], v[166:169], v[54:57]
	v_mfma_f32_16x16x32_bf16 v[50:53], v[158:161], v[166:169], v[50:53]
	v_mfma_f32_16x16x32_bf16 v[38:41], v[150:153], v[174:177], v[38:41]
	v_mfma_f32_16x16x32_bf16 v[34:37], v[158:161], v[174:177], v[34:37]
	v_mfma_f32_16x16x32_bf16 v[22:25], v[150:153], v[182:185], v[22:25]
	v_mfma_f32_16x16x32_bf16 v[16:19], v[158:161], v[182:185], v[16:19]
	v_mfma_f32_16x16x32_bf16 v[4:7], v[150:153], v[190:193], v[4:7]
	v_mfma_f32_16x16x32_bf16 v[0:3], v[158:161], v[190:193], v[0:3]
	s_setprio 0
	s_barrier
	s_cbranch_scc0 .LBB0_1037
	s_and_b64 vcc, exec, s[48:49]
	s_cbranch_vccz .LBB0_1040
	s_barrier

; #define PG8_STAGE(bufoff, gbase, voff) do { _Pragma("unroll") for (int _i = 0; _i < 2; ++_i) \
;         __builtin_amdgcn_global_load_lds((const unsigned*)((const char*)(gbase) + (voff)[_i]), (PG8_LAS unsigned*)(lds + (bufoff) + ldsw + _i * 8192), 16, 0, 0); } while (0)
; #define PG8_WAIT_V(n) asm volatile("s_waitcnt vmcnt(" #n ")" ::: "memory")
; template <class Epi, class Sched, bool ALIGN_EPI = false, bool SP2 = false>
; __device__ __forceinline__ void gemm_phase(PG8_LAS unsigned char* lds, const Gemm g, const Sched& S, const Epi& E, const int tid_in) {
;     ...
;     for (;;) {
;         const bool has_next = S.next(ui + 1, nxt);
;         const char* nA = has_next ? (const char*)g.A + (size_t)nxt.pm * tstep : cA; const char* nB = has_next ? (const char*)g.Bt + (size_t)nxt.pn * tstep : cB;
;         for (int t = 0; t < nt; t += 2) {
;             if constexpr (Epi::KSPLIT > 0) { if (t == Epi::KSPLIT / BK) E.midk(acc, cur, wr, wc, fr, fq); }
;             const bool last = (t == nt - 2);
;             const char* a1 = cA + (size_t)(t + 1) * kstep;
;             const char* a2 = last ? nA : cA + (size_t)(t + 2) * kstep; const char* b2 = last ? nB : cB + (size_t)(t + 2) * kstep;
;             const char* a3 = a2 + kstep; const char* b3 = b2 + kstep;
;             if (last && has_next) S.a_ready(nxt);
;             if constexpr (SP2) {
;             PG8_LDB(B0, 0, 0); PG8_LDB(B1, 0, 1); PG8_SCHED; PG8_LDA(At, 0, 0); PG8_STAGE(PG8_SA(1, 1), a1 + hstep, voffA);
;             PG8_WAIT_V(8); PG8_WAIT_L(0); PG8_BAR; PG8_MMA(0, 0, At, B0); PG8_MMA(0, 1, At, B1); PG8_BAR; PG8_SCHED;
;             PG8_LDA(At, 0, 1); PG8_STAGE(PG8_SB(0, 0), b2, voffB); PG8_STAGE(PG8_SB(0, 1), b2 + hstep, voffB); PG8_STAGE(PG8_SA(0, 0), a2, voffA);
;             PG8_WAIT_V(8); PG8_WAIT_L(0); PG8_BAR; PG8_MMA(1, 0, At, B0); PG8_MMA(1, 1, At, B1); PG8_BAR; PG8_SCHED;
;             PG8_LDB(B0, 1, 0); PG8_LDB(B1, 1, 1); PG8_SCHED; PG8_LDA(At, 1, 0); PG8_STAGE(PG8_SA(0, 1), a2 + hstep, voffA);
;             PG8_WAIT_V(8); PG8_WAIT_L(0); PG8_BAR; PG8_MMA(0, 0, At, B0); PG8_MMA(0, 1, At, B1); PG8_BAR; PG8_SCHED;
;             PG8_LDA(At, 1, 1); PG8_STAGE(PG8_SB(1, 0), b3, voffB); PG8_STAGE(PG8_SB(1, 1), b3 + hstep, voffB); PG8_STAGE(PG8_SA(1, 0), a3, voffA);
;             PG8_WAIT_V(8); PG8_WAIT_L(0); PG8_BAR; PG8_MMA(1, 0, At, B0); PG8_MMA(1, 1, At, B1); PG8_BAR; PG8_SCHED;
.LBB0_1156:
	s_ashr_i32 s35, s34, 31
	s_lshl_b64 s[6:7], s[34:35], 20
	s_add_u32 s6, s5, s6
	s_addc_u32 s7, s8, s7
	s_and_b64 s[20:21], exec, s[48:49]
	s_cselect_b32 s35, s51, s7
	s_cselect_b32 s58, s50, s6
	s_ashr_i32 s31, s30, 31
	s_lshl_b64 s[20:21], s[30:31], 20
	s_add_u32 s20, s10, s20
	s_addc_u32 s21, s19, s21
	s_and_b64 s[54:55], exec, s[48:49]
	s_cselect_b32 s31, s53, s21
	s_cselect_b32 s59, s52, s20
	s_add_u32 s50, s50, 0x80080
	s_addc_u32 s51, s51, 0
	s_add_u32 s60, s52, 0x100
	v_mov_b32_e32 v0, 0
	s_addc_u32 s61, s53, 0
	s_mov_b32 s62, -2
	v_add_u32_e32 v224, 0x10000, v177
	v_add_u32_e32 v225, 0x14000, v177
	v_add_u32_e32 v226, 0x18000, v177
	v_add_u32_e32 v227, 0x1c000, v177
	s_add_u32 s52, s50, 0xfff80080
	s_addc_u32 s53, s51, -1
	s_add_i32 s63, 0, 0x10000
	s_cmp_eq_u32 s62, 28
	s_cselect_b32 s55, s35, s53
	s_cselect_b32 s54, s58, s52
	s_cselect_b32 s53, s31, s61
	s_cselect_b32 s52, s59, s60
	s_add_i32 s66, 0, 0x14000
	s_mov_b32 m0, s25
	s_nop 0
	global_load_lds_dwordx4 v166, s[100:101]
	ds_read_b128 v[66:69], v224
	ds_read_b128 v[70:73], v224 offset:1024
	ds_read_b128 v[74:77], v224 offset:2048
	ds_read_b128 v[78:81], v224 offset:3072
	ds_read_b128 v[122:125], v225
	ds_read_b128 v[126:129], v225 offset:1024
	ds_read_b128 v[130:133], v225 offset:2048
	ds_read_b128 v[134:137], v225 offset:3072
	s_add_i32 m0, s89, 0xc000
	ds_read_b128 v[188:191], v193
	ds_read_b128 v[194:197], v193 offset:1024
	ds_read_b128 v[198:201], v193 offset:2048
	ds_read_b128 v[202:205], v193 offset:3072
	ds_read_b128 v[208:211], v193 offset:4096
	ds_read_b128 v[212:215], v193 offset:5120
	ds_read_b128 v[216:219], v193 offset:6144
	ds_read_b128 v[220:223], v193 offset:7168
	global_load_lds_dwordx4 v184, s[50:51]
	s_add_i32 m0, s89, 0xe000
	s_nop 0
	global_load_lds_dwordx4 v186, s[50:51]
	s_add_i32 s63, s63, s1
	s_add_u32 s98, s52, 0x80
	s_addc_u32 s99, s53, 0
	s_mov_b32 m0, s63
	s_waitcnt vmcnt(8)
	s_waitcnt lgkmcnt(0)
	s_barrier
	s_setprio 1
	v_mfma_f32_16x16x32_bf16 v[150:153], v[66:69], v[188:191], 0
	v_mfma_f32_16x16x32_bf16 v[110:113], v[74:77], v[188:191], 0
	v_mfma_f32_16x16x32_bf16 v[146:149], v[66:69], v[198:201], 0
	v_mfma_f32_16x16x32_bf16 v[106:109], v[74:77], v[198:201], 0
	v_mfma_f32_16x16x32_bf16 v[142:145], v[66:69], v[208:211], 0
	v_mfma_f32_16x16x32_bf16 v[102:105], v[74:77], v[208:211], 0
	v_mfma_f32_16x16x32_bf16 v[138:141], v[66:69], v[216:219], 0
	v_mfma_f32_16x16x32_bf16 v[98:101], v[74:77], v[216:219], 0
	v_mfma_f32_16x16x32_bf16 v[150:153], v[70:73], v[194:197], v[150:153]
	v_mfma_f32_16x16x32_bf16 v[110:113], v[78:81], v[194:197], v[110:113]
	v_mfma_f32_16x16x32_bf16 v[146:149], v[70:73], v[202:205], v[146:149]
	v_mfma_f32_16x16x32_bf16 v[106:109], v[78:81], v[202:205], v[106:109]
	v_mfma_f32_16x16x32_bf16 v[142:145], v[70:73], v[212:215], v[142:145]
	v_mfma_f32_16x16x32_bf16 v[102:105], v[78:81], v[212:215], v[102:105]
	v_mfma_f32_16x16x32_bf16 v[138:141], v[70:73], v[220:223], v[138:141]
	v_mfma_f32_16x16x32_bf16 v[98:101], v[78:81], v[220:223], v[98:101]
	s_setprio 0
	s_setprio 1
	v_mfma_f32_16x16x32_bf16 v[94:97], v[122:125], v[188:191], 0
	v_mfma_f32_16x16x32_bf16 v[90:93], v[130:133], v[188:191], 0
	v_mfma_f32_16x16x32_bf16 v[158:161], v[122:125], v[198:201], 0
	v_mfma_f32_16x16x32_bf16 v[118:121], v[130:133], v[198:201], 0
	v_mfma_f32_16x16x32_bf16 v[154:157], v[122:125], v[208:211], 0
	v_mfma_f32_16x16x32_bf16 v[114:117], v[130:133], v[208:211], 0
	v_mfma_f32_16x16x32_bf16 v[86:89], v[122:125], v[216:219], 0
	v_mfma_f32_16x16x32_bf16 v[82:85], v[130:133], v[216:219], 0
	v_mfma_f32_16x16x32_bf16 v[94:97], v[126:129], v[194:197], v[94:97]
	v_mfma_f32_16x16x32_bf16 v[90:93], v[134:137], v[194:197], v[90:93]
	v_mfma_f32_16x16x32_bf16 v[158:161], v[126:129], v[202:205], v[158:161]
	v_mfma_f32_16x16x32_bf16 v[118:121], v[134:137], v[202:205], v[118:121]
	v_mfma_f32_16x16x32_bf16 v[154:157], v[126:129], v[212:215], v[154:157]
	v_mfma_f32_16x16x32_bf16 v[114:117], v[134:137], v[212:215], v[114:117]
	v_mfma_f32_16x16x32_bf16 v[86:89], v[126:129], v[220:223], v[86:89]
	v_mfma_f32_16x16x32_bf16 v[82:85], v[134:137], v[220:223], v[82:85]
	s_setprio 0
	s_barrier
	ds_read_b128 v[188:191], v193 offset:16384
	ds_read_b128 v[194:197], v193 offset:17408
	ds_read_b128 v[198:201], v193 offset:18432
	ds_read_b128 v[202:205], v193 offset:19456
	ds_read_b128 v[208:211], v193 offset:20480
	ds_read_b128 v[212:215], v193 offset:21504
	ds_read_b128 v[216:219], v193 offset:22528
	ds_read_b128 v[220:223], v193 offset:23552
	global_load_lds_dwordx4 v164, s[52:53]
	s_add_i32 m0, s63, 0x2000
	s_add_u32 s64, s52, 0x80000
	s_addc_u32 s65, s53, 0
	s_add_i32 s63, s66, s1
	global_load_lds_dwordx4 v168, s[52:53]
	s_mov_b32 m0, s63
	s_add_u32 s100, s54, 0x80
	s_addc_u32 s101, s55, 0
	global_load_lds_dwordx4 v164, s[64:65]
	s_add_i32 m0, s63, 0x2000
	s_nop 0
	global_load_lds_dwordx4 v168, s[64:65]
	s_mov_b32 m0, s89
	s_nop 0
	global_load_lds_dwordx4 v162, s[54:55]
	s_add_i32 s63, 0, 0x18000
	s_add_i32 s64, 0, 0x1c000
	s_waitcnt vmcnt(7)
	s_waitcnt lgkmcnt(0)
	s_barrier
; #define PG8_STAGE(bufoff, gbase, voff) do { _Pragma("unroll") for (int _i = 0; _i < 2; ++_i) \
;         __builtin_amdgcn_global_load_lds((const unsigned*)((const char*)(gbase) + (voff)[_i]), (PG8_LAS unsigned*)(lds + (bufoff) + ldsw + _i * 8192), 16, 0, 0); } while (0)
; #define PG8_LDA(dst, b, h) do { _Pragma("unroll") for (int m = 0; m < 4; ++m) _Pragma("unroll") for (int k = 0; k < 2; ++k) dst[m][k] = *(const PG8_LAS bf16x8*)(lds + PG8_SA(b, h) + aoff + m * 2048 + k * 1024); } while (0)
; #define PG8_LDB(dst, b, h) do { _Pragma("unroll") for (int n = 0; n < 2; ++n) _Pragma("unroll") for (int k = 0; k < 2; ++k) dst[n][k] = *(const PG8_LAS bf16x8*)(lds + PG8_SB(b, h) + boff + n * 2048 + k * 1024); } while (0)
; #define PG8_MMA(ai, bj, At, Bt) do { __builtin_amdgcn_s_setprio(1); _Pragma("unroll") for (int m = 0; m < 4; ++m) _Pragma("unroll") for (int n = 0; n < 2; ++n) _Pragma("unroll") for (int k = 0; k < 2; ++k) \
;         acc[ai][bj][m][n] = __builtin_amdgcn_mfma_f32_16x16x32_bf16(Bt[n][k], At[m][k], acc[ai][bj][m][n], 0, 0, 0); __builtin_amdgcn_s_setprio(0); } while (0)
; template <class Epi, class Sched, bool ALIGN_EPI = false, bool SP2 = false>
; __device__ __forceinline__ void gemm_phase(PG8_LAS unsigned char* lds, const Gemm g, const Sched& S, const Epi& E, const int tid_in) {
;     ...
;             if constexpr (SP2) {
;             PG8_LDB(B0, 0, 0); PG8_LDB(B1, 0, 1); PG8_SCHED; PG8_LDA(At, 0, 0); PG8_STAGE(PG8_SA(1, 1), a1 + hstep, voffA);
;             PG8_WAIT_V(8); PG8_WAIT_L(0); PG8_BAR; PG8_MMA(0, 0, At, B0); PG8_MMA(0, 1, At, B1); PG8_BAR; PG8_SCHED;
;             PG8_LDA(At, 0, 1); PG8_STAGE(PG8_SB(0, 0), b2, voffB); PG8_STAGE(PG8_SB(0, 1), b2 + hstep, voffB); PG8_STAGE(PG8_SA(0, 0), a2, voffA);
;             PG8_WAIT_V(8); PG8_WAIT_L(0); PG8_BAR; PG8_MMA(1, 0, At, B0); PG8_MMA(1, 1, At, B1); PG8_BAR; PG8_SCHED;
;             PG8_LDB(B0, 1, 0); PG8_LDB(B1, 1, 1); PG8_SCHED; PG8_LDA(At, 1, 0); PG8_STAGE(PG8_SA(0, 1), a2 + hstep, voffA);
;             PG8_WAIT_V(8); PG8_WAIT_L(0); PG8_BAR; PG8_MMA(0, 0, At, B0); PG8_MMA(0, 1, At, B1); PG8_BAR; PG8_SCHED;
;             PG8_LDA(At, 1, 1); PG8_STAGE(PG8_SB(1, 0), b3, voffB); PG8_STAGE(PG8_SB(1, 1), b3 + hstep, voffB); PG8_STAGE(PG8_SA(1, 0), a3, voffA);
;             PG8_WAIT_V(8); PG8_WAIT_L(0); PG8_BAR; PG8_MMA(1, 0, At, B0); PG8_MMA(1, 1, At, B1); PG8_BAR; PG8_SCHED;
	s_setprio 1
	v_mfma_f32_16x16x32_bf16 v[54:57], v[66:69], v[188:191], 0
	v_mfma_f32_16x16x32_bf16 v[30:33], v[74:77], v[188:191], 0
	v_mfma_f32_16x16x32_bf16 v[50:53], v[66:69], v[198:201], 0
	v_mfma_f32_16x16x32_bf16 v[26:29], v[74:77], v[198:201], 0
	v_mfma_f32_16x16x32_bf16 v[46:49], v[66:69], v[208:211], 0
	v_mfma_f32_16x16x32_bf16 v[22:25], v[74:77], v[208:211], 0
	v_mfma_f32_16x16x32_bf16 v[42:45], v[66:69], v[216:219], 0
	v_mfma_f32_16x16x32_bf16 v[16:19], v[74:77], v[216:219], 0
	v_mfma_f32_16x16x32_bf16 v[54:57], v[70:73], v[194:197], v[54:57]
	v_mfma_f32_16x16x32_bf16 v[30:33], v[78:81], v[194:197], v[30:33]
	v_mfma_f32_16x16x32_bf16 v[50:53], v[70:73], v[202:205], v[50:53]
	v_mfma_f32_16x16x32_bf16 v[26:29], v[78:81], v[202:205], v[26:29]
	v_mfma_f32_16x16x32_bf16 v[46:49], v[70:73], v[212:215], v[46:49]
	v_mfma_f32_16x16x32_bf16 v[22:25], v[78:81], v[212:215], v[22:25]
	v_mfma_f32_16x16x32_bf16 v[42:45], v[70:73], v[220:223], v[42:45]
	v_mfma_f32_16x16x32_bf16 v[16:19], v[78:81], v[220:223], v[16:19]
	s_setprio 0
	s_setprio 1
	v_mfma_f32_16x16x32_bf16 v[12:15], v[122:125], v[188:191], 0
	v_mfma_f32_16x16x32_bf16 v[8:11], v[130:133], v[188:191], 0
	v_mfma_f32_16x16x32_bf16 v[62:65], v[122:125], v[198:201], 0
	v_mfma_f32_16x16x32_bf16 v[38:41], v[130:133], v[198:201], 0
	v_mfma_f32_16x16x32_bf16 v[58:61], v[122:125], v[208:211], 0
	v_mfma_f32_16x16x32_bf16 v[34:37], v[130:133], v[208:211], 0
	v_mfma_f32_16x16x32_bf16 v[4:7], v[122:125], v[216:219], 0
	v_mfma_f32_16x16x32_bf16 v[0:3], v[130:133], v[216:219], 0
	v_mfma_f32_16x16x32_bf16 v[12:15], v[126:129], v[194:197], v[12:15]
	v_mfma_f32_16x16x32_bf16 v[8:11], v[134:137], v[194:197], v[8:11]
	v_mfma_f32_16x16x32_bf16 v[62:65], v[126:129], v[202:205], v[62:65]
	v_mfma_f32_16x16x32_bf16 v[38:41], v[134:137], v[202:205], v[38:41]
	v_mfma_f32_16x16x32_bf16 v[58:61], v[126:129], v[212:215], v[58:61]
	v_mfma_f32_16x16x32_bf16 v[34:37], v[134:137], v[212:215], v[34:37]
	v_mfma_f32_16x16x32_bf16 v[4:7], v[126:129], v[220:223], v[4:7]
	v_mfma_f32_16x16x32_bf16 v[0:3], v[134:137], v[220:223], v[0:3]
	s_setprio 0
	s_barrier
	ds_read_b128 v[66:69], v226
	ds_read_b128 v[70:73], v226 offset:1024
	ds_read_b128 v[74:77], v226 offset:2048
	ds_read_b128 v[78:81], v226 offset:3072
	ds_read_b128 v[122:125], v227
	ds_read_b128 v[126:129], v227 offset:1024
	ds_read_b128 v[130:133], v227 offset:2048
	ds_read_b128 v[134:137], v227 offset:3072
	s_mov_b32 m0, s92
	s_nop 0
	global_load_lds_dwordx4 v166, s[54:55]
	s_add_u32 s54, s54, 0x80000
	s_addc_u32 s55, s55, 0
	s_mov_b32 m0, s2
	ds_read_b128 v[188:191], v193 offset:32768
	ds_read_b128 v[194:197], v193 offset:33792
	ds_read_b128 v[198:201], v193 offset:34816
	ds_read_b128 v[202:205], v193 offset:35840
	ds_read_b128 v[208:211], v193 offset:36864
	ds_read_b128 v[212:215], v193 offset:37888
	ds_read_b128 v[216:219], v193 offset:38912
	ds_read_b128 v[220:223], v193 offset:39936
	global_load_lds_dwordx4 v162, s[54:55]
	s_mov_b32 m0, s3
	s_nop 0
	global_load_lds_dwordx4 v166, s[54:55]
	s_add_i32 s54, s63, s1
	s_mov_b32 m0, s54
	s_waitcnt vmcnt(8)
	s_waitcnt lgkmcnt(0)
	s_barrier
	s_setprio 1
	v_mfma_f32_16x16x32_bf16 v[150:153], v[66:69], v[188:191], v[150:153]
	v_mfma_f32_16x16x32_bf16 v[110:113], v[74:77], v[188:191], v[110:113]
	v_mfma_f32_16x16x32_bf16 v[146:149], v[66:69], v[198:201], v[146:149]
	v_mfma_f32_16x16x32_bf16 v[106:109], v[74:77], v[198:201], v[106:109]
	v_mfma_f32_16x16x32_bf16 v[142:145], v[66:69], v[208:211], v[142:145]
	v_mfma_f32_16x16x32_bf16 v[102:105], v[74:77], v[208:211], v[102:105]
	v_mfma_f32_16x16x32_bf16 v[138:141], v[66:69], v[216:219], v[138:141]
	v_mfma_f32_16x16x32_bf16 v[98:101], v[74:77], v[216:219], v[98:101]
	v_mfma_f32_16x16x32_bf16 v[150:153], v[70:73], v[194:197], v[150:153]
	v_mfma_f32_16x16x32_bf16 v[110:113], v[78:81], v[194:197], v[110:113]
	v_mfma_f32_16x16x32_bf16 v[146:149], v[70:73], v[202:205], v[146:149]
	v_mfma_f32_16x16x32_bf16 v[106:109], v[78:81], v[202:205], v[106:109]
	v_mfma_f32_16x16x32_bf16 v[142:145], v[70:73], v[212:215], v[142:145]
	v_mfma_f32_16x16x32_bf16 v[102:105], v[78:81], v[212:215], v[102:105]
	v_mfma_f32_16x16x32_bf16 v[138:141], v[70:73], v[220:223], v[138:141]
	v_mfma_f32_16x16x32_bf16 v[98:101], v[78:81], v[220:223], v[98:101]
	s_setprio 0
	s_setprio 1
	v_mfma_f32_16x16x32_bf16 v[94:97], v[122:125], v[188:191], v[94:97]
	v_mfma_f32_16x16x32_bf16 v[90:93], v[130:133], v[188:191], v[90:93]
	v_mfma_f32_16x16x32_bf16 v[158:161], v[122:125], v[198:201], v[158:161]
	v_mfma_f32_16x16x32_bf16 v[118:121], v[130:133], v[198:201], v[118:121]
	v_mfma_f32_16x16x32_bf16 v[154:157], v[122:125], v[208:211], v[154:157]
	v_mfma_f32_16x16x32_bf16 v[114:117], v[130:133], v[208:211], v[114:117]
	v_mfma_f32_16x16x32_bf16 v[86:89], v[122:125], v[216:219], v[86:89]
	v_mfma_f32_16x16x32_bf16 v[82:85], v[130:133], v[216:219], v[82:85]
	v_mfma_f32_16x16x32_bf16 v[94:97], v[126:129], v[194:197], v[94:97]
	v_mfma_f32_16x16x32_bf16 v[90:93], v[134:137], v[194:197], v[90:93]
	v_mfma_f32_16x16x32_bf16 v[158:161], v[126:129], v[202:205], v[158:161]
	v_mfma_f32_16x16x32_bf16 v[118:121], v[134:137], v[202:205], v[118:121]
	v_mfma_f32_16x16x32_bf16 v[154:157], v[126:129], v[212:215], v[154:157]
	v_mfma_f32_16x16x32_bf16 v[114:117], v[134:137], v[212:215], v[114:117]
	v_mfma_f32_16x16x32_bf16 v[86:89], v[126:129], v[220:223], v[86:89]
	v_mfma_f32_16x16x32_bf16 v[82:85], v[134:137], v[220:223], v[82:85]
	s_setprio 0
	s_barrier
; #define PG8_STAGE(bufoff, gbase, voff) do { _Pragma("unroll") for (int _i = 0; _i < 2; ++_i) \
;         __builtin_amdgcn_global_load_lds((const unsigned*)((const char*)(gbase) + (voff)[_i]), (PG8_LAS unsigned*)(lds + (bufoff) + ldsw + _i * 8192), 16, 0, 0); } while (0)
; #define PG8_LDA(dst, b, h) do { _Pragma("unroll") for (int m = 0; m < 4; ++m) _Pragma("unroll") for (int k = 0; k < 2; ++k) dst[m][k] = *(const PG8_LAS bf16x8*)(lds + PG8_SA(b, h) + aoff + m * 2048 + k * 1024); } while (0)
; #define PG8_WAIT_V(n) asm volatile("s_waitcnt vmcnt(" #n ")" ::: "memory")
; template <class Epi, class Sched, bool ALIGN_EPI = false, bool SP2 = false>
; __device__ __forceinline__ void gemm_phase(PG8_LAS unsigned char* lds, const Gemm g, const Sched& S, const Epi& E, const int tid_in) {
;     ...
;         for (int t = 0; t < nt; t += 2) {
;             if constexpr (Epi::KSPLIT > 0) { if (t == Epi::KSPLIT / BK) E.midk(acc, cur, wr, wc, fr, fq); }
;             const bool last = (t == nt - 2);
;             const char* a1 = cA + (size_t)(t + 1) * kstep;
;             const char* a2 = last ? nA : cA + (size_t)(t + 2) * kstep; const char* b2 = last ? nB : cB + (size_t)(t + 2) * kstep;
;             const char* a3 = a2 + kstep; const char* b3 = b2 + kstep;
;             if (last && has_next) S.a_ready(nxt);
;             if constexpr (SP2) {
;             PG8_LDB(B0, 0, 0); PG8_LDB(B1, 0, 1); PG8_SCHED; PG8_LDA(At, 0, 0); PG8_STAGE(PG8_SA(1, 1), a1 + hstep, voffA);
;             PG8_WAIT_V(8); PG8_WAIT_L(0); PG8_BAR; PG8_MMA(0, 0, At, B0); PG8_MMA(0, 1, At, B1); PG8_BAR; PG8_SCHED;
;             PG8_LDA(At, 0, 1); PG8_STAGE(PG8_SB(0, 0), b2, voffB); PG8_STAGE(PG8_SB(0, 1), b2 + hstep, voffB); PG8_STAGE(PG8_SA(0, 0), a2, voffA);
;             PG8_WAIT_V(8); PG8_WAIT_L(0); PG8_BAR; PG8_MMA(1, 0, At, B0); PG8_MMA(1, 1, At, B1); PG8_BAR; PG8_SCHED;
;             PG8_LDB(B0, 1, 0); PG8_LDB(B1, 1, 1); PG8_SCHED; PG8_LDA(At, 1, 0); PG8_STAGE(PG8_SA(0, 1), a2 + hstep, voffA);
;             PG8_WAIT_V(8); PG8_WAIT_L(0); PG8_BAR; PG8_MMA(0, 0, At, B0); PG8_MMA(0, 1, At, B1); PG8_BAR; PG8_SCHED;
;             PG8_LDA(At, 1, 1); PG8_STAGE(PG8_SB(1, 0), b3, voffB); PG8_STAGE(PG8_SB(1, 1), b3 + hstep, voffB); PG8_STAGE(PG8_SA(1, 0), a3, voffA);
;             PG8_WAIT_V(8); PG8_WAIT_L(0); PG8_BAR; PG8_MMA(1, 0, At, B0); PG8_MMA(1, 1, At, B1); PG8_BAR; PG8_SCHED;
	ds_read_b128 v[188:191], v193 offset:49152
	ds_read_b128 v[194:197], v193 offset:50176
	ds_read_b128 v[198:201], v193 offset:51200
	ds_read_b128 v[202:205], v193 offset:52224
	ds_read_b128 v[208:211], v193 offset:53248
	ds_read_b128 v[212:215], v193 offset:54272
	ds_read_b128 v[216:219], v193 offset:55296
	ds_read_b128 v[220:223], v193 offset:56320
	global_load_lds_dwordx4 v164, s[98:99]
	s_add_i32 m0, s54, 0x2000
	s_add_u32 s52, s52, 0x80080
	s_addc_u32 s53, s53, 0
	s_add_i32 s54, s64, s1
	global_load_lds_dwordx4 v168, s[98:99]
	s_mov_b32 m0, s54
	s_nop 0
	global_load_lds_dwordx4 v164, s[52:53]
	s_add_i32 m0, s54, 0x2000
	s_nop 0
	global_load_lds_dwordx4 v168, s[52:53]
	s_mov_b32 m0, s24
	s_nop 0
	global_load_lds_dwordx4 v162, s[100:101]
	s_add_i32 s62, s62, 2
	s_add_u32 s50, s50, 0x100
	s_addc_u32 s51, s51, 0
	s_add_u32 s60, s60, 0x100
	s_addc_u32 s61, s61, 0
	s_add_u32 s52, s50, 0xfff80080
	s_addc_u32 s53, s51, -1
	s_add_i32 s63, 0, 0x10000
	s_cmp_eq_u32 s62, 28
	s_cselect_b32 s55, s35, s53
	s_cselect_b32 s54, s58, s52
	s_cselect_b32 s53, s31, s61
	s_cselect_b32 s52, s59, s60
	s_add_i32 s66, 0, 0x14000
	s_cmp_gt_u32 s62, 29
	s_waitcnt vmcnt(7)
	s_waitcnt lgkmcnt(0)
	s_barrier
	s_setprio 1
	v_mfma_f32_16x16x32_bf16 v[54:57], v[66:69], v[188:191], v[54:57]
	v_mfma_f32_16x16x32_bf16 v[30:33], v[74:77], v[188:191], v[30:33]
	v_mfma_f32_16x16x32_bf16 v[50:53], v[66:69], v[198:201], v[50:53]
	v_mfma_f32_16x16x32_bf16 v[26:29], v[74:77], v[198:201], v[26:29]
	v_mfma_f32_16x16x32_bf16 v[46:49], v[66:69], v[208:211], v[46:49]
	v_mfma_f32_16x16x32_bf16 v[22:25], v[74:77], v[208:211], v[22:25]
	v_mfma_f32_16x16x32_bf16 v[42:45], v[66:69], v[216:219], v[42:45]
	v_mfma_f32_16x16x32_bf16 v[16:19], v[74:77], v[216:219], v[16:19]
	v_mfma_f32_16x16x32_bf16 v[54:57], v[70:73], v[194:197], v[54:57]
	v_mfma_f32_16x16x32_bf16 v[30:33], v[78:81], v[194:197], v[30:33]
	v_mfma_f32_16x16x32_bf16 v[50:53], v[70:73], v[202:205], v[50:53]
	v_mfma_f32_16x16x32_bf16 v[26:29], v[78:81], v[202:205], v[26:29]
	v_mfma_f32_16x16x32_bf16 v[46:49], v[70:73], v[212:215], v[46:49]
	v_mfma_f32_16x16x32_bf16 v[22:25], v[78:81], v[212:215], v[22:25]
	v_mfma_f32_16x16x32_bf16 v[42:45], v[70:73], v[220:223], v[42:45]
	v_mfma_f32_16x16x32_bf16 v[16:19], v[78:81], v[220:223], v[16:19]
	s_setprio 0
	s_setprio 1
	v_mfma_f32_16x16x32_bf16 v[12:15], v[122:125], v[188:191], v[12:15]
	v_mfma_f32_16x16x32_bf16 v[8:11], v[130:133], v[188:191], v[8:11]
	v_mfma_f32_16x16x32_bf16 v[62:65], v[122:125], v[198:201], v[62:65]
	v_mfma_f32_16x16x32_bf16 v[38:41], v[130:133], v[198:201], v[38:41]
	v_mfma_f32_16x16x32_bf16 v[58:61], v[122:125], v[208:211], v[58:61]
	v_mfma_f32_16x16x32_bf16 v[34:37], v[130:133], v[208:211], v[34:37]
	v_mfma_f32_16x16x32_bf16 v[4:7], v[122:125], v[216:219], v[4:7]
	v_mfma_f32_16x16x32_bf16 v[0:3], v[130:133], v[216:219], v[0:3]
	v_mfma_f32_16x16x32_bf16 v[12:15], v[126:129], v[194:197], v[12:15]
	v_mfma_f32_16x16x32_bf16 v[8:11], v[134:137], v[194:197], v[8:11]
	v_mfma_f32_16x16x32_bf16 v[62:65], v[126:129], v[202:205], v[62:65]
	v_mfma_f32_16x16x32_bf16 v[38:41], v[134:137], v[202:205], v[38:41]
	v_mfma_f32_16x16x32_bf16 v[58:61], v[126:129], v[212:215], v[58:61]
	v_mfma_f32_16x16x32_bf16 v[34:37], v[134:137], v[212:215], v[34:37]
	v_mfma_f32_16x16x32_bf16 v[4:7], v[126:129], v[220:223], v[4:7]
	v_mfma_f32_16x16x32_bf16 v[0:3], v[134:137], v[220:223], v[0:3]
	s_setprio 0
	s_barrier
.LBB0_1157:
	s_mov_b32 m0, s25
	s_nop 0
	global_load_lds_dwordx4 v166, s[100:101]
	ds_read_b128 v[66:69], v224
	ds_read_b128 v[70:73], v224 offset:1024
	ds_read_b128 v[74:77], v224 offset:2048
	ds_read_b128 v[78:81], v224 offset:3072
	ds_read_b128 v[122:125], v225
	ds_read_b128 v[126:129], v225 offset:1024
	ds_read_b128 v[130:133], v225 offset:2048
	ds_read_b128 v[134:137], v225 offset:3072
	s_add_i32 m0, s89, 0xc000
	ds_read_b128 v[188:191], v193
	ds_read_b128 v[194:197], v193 offset:1024
	ds_read_b128 v[198:201], v193 offset:2048
	ds_read_b128 v[202:205], v193 offset:3072
	ds_read_b128 v[208:211], v193 offset:4096
	ds_read_b128 v[212:215], v193 offset:5120
	ds_read_b128 v[216:219], v193 offset:6144
	ds_read_b128 v[220:223], v193 offset:7168
	global_load_lds_dwordx4 v184, s[50:51]
	s_add_i32 m0, s89, 0xe000
	s_nop 0
	global_load_lds_dwordx4 v186, s[50:51]
	s_add_i32 s63, s63, s1
	s_add_u32 s98, s52, 0x80
	s_addc_u32 s99, s53, 0
	s_mov_b32 m0, s63
	s_waitcnt vmcnt(8)
	s_waitcnt lgkmcnt(0)
	s_barrier
	s_setprio 1
	v_mfma_f32_16x16x32_bf16 v[150:153], v[66:69], v[188:191], v[150:153]
	v_mfma_f32_16x16x32_bf16 v[110:113], v[74:77], v[188:191], v[110:113]
	v_mfma_f32_16x16x32_bf16 v[146:149], v[66:69], v[198:201], v[146:149]
	v_mfma_f32_16x16x32_bf16 v[106:109], v[74:77], v[198:201], v[106:109]
	v_mfma_f32_16x16x32_bf16 v[142:145], v[66:69], v[208:211], v[142:145]
	v_mfma_f32_16x16x32_bf16 v[102:105], v[74:77], v[208:211], v[102:105]
	v_mfma_f32_16x16x32_bf16 v[138:141], v[66:69], v[216:219], v[138:141]
	v_mfma_f32_16x16x32_bf16 v[98:101], v[74:77], v[216:219], v[98:101]
	v_mfma_f32_16x16x32_bf16 v[150:153], v[70:73], v[194:197], v[150:153]
	v_mfma_f32_16x16x32_bf16 v[110:113], v[78:81], v[194:197], v[110:113]
	v_mfma_f32_16x16x32_bf16 v[146:149], v[70:73], v[202:205], v[146:149]
	v_mfma_f32_16x16x32_bf16 v[106:109], v[78:81], v[202:205], v[106:109]
	v_mfma_f32_16x16x32_bf16 v[142:145], v[70:73], v[212:215], v[142:145]
	v_mfma_f32_16x16x32_bf16 v[102:105], v[78:81], v[212:215], v[102:105]
	v_mfma_f32_16x16x32_bf16 v[138:141], v[70:73], v[220:223], v[138:141]
	v_mfma_f32_16x16x32_bf16 v[98:101], v[78:81], v[220:223], v[98:101]
	s_setprio 0
	s_setprio 1
	v_mfma_f32_16x16x32_bf16 v[94:97], v[122:125], v[188:191], v[94:97]
	v_mfma_f32_16x16x32_bf16 v[90:93], v[130:133], v[188:191], v[90:93]
	v_mfma_f32_16x16x32_bf16 v[158:161], v[122:125], v[198:201], v[158:161]
	v_mfma_f32_16x16x32_bf16 v[118:121], v[130:133], v[198:201], v[118:121]
	v_mfma_f32_16x16x32_bf16 v[154:157], v[122:125], v[208:211], v[154:157]
	v_mfma_f32_16x16x32_bf16 v[114:117], v[130:133], v[208:211], v[114:117]
	v_mfma_f32_16x16x32_bf16 v[86:89], v[122:125], v[216:219], v[86:89]
	v_mfma_f32_16x16x32_bf16 v[82:85], v[130:133], v[216:219], v[82:85]
	v_mfma_f32_16x16x32_bf16 v[94:97], v[126:129], v[194:197], v[94:97]
	v_mfma_f32_16x16x32_bf16 v[90:93], v[134:137], v[194:197], v[90:93]
	v_mfma_f32_16x16x32_bf16 v[158:161], v[126:129], v[202:205], v[158:161]
	v_mfma_f32_16x16x32_bf16 v[118:121], v[134:137], v[202:205], v[118:121]
	v_mfma_f32_16x16x32_bf16 v[154:157], v[126:129], v[212:215], v[154:157]
	v_mfma_f32_16x16x32_bf16 v[114:117], v[134:137], v[212:215], v[114:117]
	v_mfma_f32_16x16x32_bf16 v[86:89], v[126:129], v[220:223], v[86:89]
	v_mfma_f32_16x16x32_bf16 v[82:85], v[134:137], v[220:223], v[82:85]
	s_setprio 0
	s_barrier
; #define PG8_STAGE(bufoff, gbase, voff) do { _Pragma("unroll") for (int _i = 0; _i < 2; ++_i) \
;         __builtin_amdgcn_global_load_lds((const unsigned*)((const char*)(gbase) + (voff)[_i]), (PG8_LAS unsigned*)(lds + (bufoff) + ldsw + _i * 8192), 16, 0, 0); } while (0)
; #define PG8_LDA(dst, b, h) do { _Pragma("unroll") for (int m = 0; m < 4; ++m) _Pragma("unroll") for (int k = 0; k < 2; ++k) dst[m][k] = *(const PG8_LAS bf16x8*)(lds + PG8_SA(b, h) + aoff + m * 2048 + k * 1024); } while (0)
; #define PG8_LDB(dst, b, h) do { _Pragma("unroll") for (int n = 0; n < 2; ++n) _Pragma("unroll") for (int k = 0; k < 2; ++k) dst[n][k] = *(const PG8_LAS bf16x8*)(lds + PG8_SB(b, h) + boff + n * 2048 + k * 1024); } while (0)
; #define PG8_MMA(ai, bj, At, Bt) do { __builtin_amdgcn_s_setprio(1); _Pragma("unroll") for (int m = 0; m < 4; ++m) _Pragma("unroll") for (int n = 0; n < 2; ++n) _Pragma("unroll") for (int k = 0; k < 2; ++k) \
;         acc[ai][bj][m][n] = __builtin_amdgcn_mfma_f32_16x16x32_bf16(Bt[n][k], At[m][k], acc[ai][bj][m][n], 0, 0, 0); __builtin_amdgcn_s_setprio(0); } while (0)
; template <class Epi, class Sched, bool ALIGN_EPI = false, bool SP2 = false>
; __device__ __forceinline__ void gemm_phase(PG8_LAS unsigned char* lds, const Gemm g, const Sched& S, const Epi& E, const int tid_in) {
;     ...
;             if constexpr (SP2) {
;             PG8_LDB(B0, 0, 0); PG8_LDB(B1, 0, 1); PG8_SCHED; PG8_LDA(At, 0, 0); PG8_STAGE(PG8_SA(1, 1), a1 + hstep, voffA);
;             PG8_WAIT_V(8); PG8_WAIT_L(0); PG8_BAR; PG8_MMA(0, 0, At, B0); PG8_MMA(0, 1, At, B1); PG8_BAR; PG8_SCHED;
;             PG8_LDA(At, 0, 1); PG8_STAGE(PG8_SB(0, 0), b2, voffB); PG8_STAGE(PG8_SB(0, 1), b2 + hstep, voffB); PG8_STAGE(PG8_SA(0, 0), a2, voffA);
;             PG8_WAIT_V(8); PG8_WAIT_L(0); PG8_BAR; PG8_MMA(1, 0, At, B0); PG8_MMA(1, 1, At, B1); PG8_BAR; PG8_SCHED;
;             PG8_LDB(B0, 1, 0); PG8_LDB(B1, 1, 1); PG8_SCHED; PG8_LDA(At, 1, 0); PG8_STAGE(PG8_SA(0, 1), a2 + hstep, voffA);
;             PG8_WAIT_V(8); PG8_WAIT_L(0); PG8_BAR; PG8_MMA(0, 0, At, B0); PG8_MMA(0, 1, At, B1); PG8_BAR; PG8_SCHED;
;             PG8_LDA(At, 1, 1); PG8_STAGE(PG8_SB(1, 0), b3, voffB); PG8_STAGE(PG8_SB(1, 1), b3 + hstep, voffB); PG8_STAGE(PG8_SA(1, 0), a3, voffA);
;             PG8_WAIT_V(8); PG8_WAIT_L(0); PG8_BAR; PG8_MMA(1, 0, At, B0); PG8_MMA(1, 1, At, B1); PG8_BAR; PG8_SCHED;
	ds_read_b128 v[188:191], v193 offset:16384
	ds_read_b128 v[194:197], v193 offset:17408
	ds_read_b128 v[198:201], v193 offset:18432
	ds_read_b128 v[202:205], v193 offset:19456
	ds_read_b128 v[208:211], v193 offset:20480
	ds_read_b128 v[212:215], v193 offset:21504
	ds_read_b128 v[216:219], v193 offset:22528
	ds_read_b128 v[220:223], v193 offset:23552
	global_load_lds_dwordx4 v164, s[52:53]
	s_add_i32 m0, s63, 0x2000
	s_add_u32 s64, s52, 0x80000
	s_addc_u32 s65, s53, 0
	s_add_i32 s63, s66, s1
	global_load_lds_dwordx4 v168, s[52:53]
	s_mov_b32 m0, s63
	s_add_u32 s100, s54, 0x80
	s_addc_u32 s101, s55, 0
	global_load_lds_dwordx4 v164, s[64:65]
	s_add_i32 m0, s63, 0x2000
	s_nop 0
	global_load_lds_dwordx4 v168, s[64:65]
	s_mov_b32 m0, s89
	s_nop 0
	global_load_lds_dwordx4 v162, s[54:55]
	s_add_i32 s63, 0, 0x18000
	s_add_i32 s64, 0, 0x1c000
	s_waitcnt vmcnt(7)
	s_waitcnt lgkmcnt(0)
	s_barrier
	s_setprio 1
	v_mfma_f32_16x16x32_bf16 v[54:57], v[66:69], v[188:191], v[54:57]
	v_mfma_f32_16x16x32_bf16 v[30:33], v[74:77], v[188:191], v[30:33]
	v_mfma_f32_16x16x32_bf16 v[50:53], v[66:69], v[198:201], v[50:53]
	v_mfma_f32_16x16x32_bf16 v[26:29], v[74:77], v[198:201], v[26:29]
	v_mfma_f32_16x16x32_bf16 v[46:49], v[66:69], v[208:211], v[46:49]
	v_mfma_f32_16x16x32_bf16 v[22:25], v[74:77], v[208:211], v[22:25]
	v_mfma_f32_16x16x32_bf16 v[42:45], v[66:69], v[216:219], v[42:45]
	v_mfma_f32_16x16x32_bf16 v[16:19], v[74:77], v[216:219], v[16:19]
	v_mfma_f32_16x16x32_bf16 v[54:57], v[70:73], v[194:197], v[54:57]
	v_mfma_f32_16x16x32_bf16 v[30:33], v[78:81], v[194:197], v[30:33]
	v_mfma_f32_16x16x32_bf16 v[50:53], v[70:73], v[202:205], v[50:53]
	v_mfma_f32_16x16x32_bf16 v[26:29], v[78:81], v[202:205], v[26:29]
	v_mfma_f32_16x16x32_bf16 v[46:49], v[70:73], v[212:215], v[46:49]
	v_mfma_f32_16x16x32_bf16 v[22:25], v[78:81], v[212:215], v[22:25]
	v_mfma_f32_16x16x32_bf16 v[42:45], v[70:73], v[220:223], v[42:45]
	v_mfma_f32_16x16x32_bf16 v[16:19], v[78:81], v[220:223], v[16:19]
	s_setprio 0
	s_setprio 1
	v_mfma_f32_16x16x32_bf16 v[12:15], v[122:125], v[188:191], v[12:15]
	v_mfma_f32_16x16x32_bf16 v[8:11], v[130:133], v[188:191], v[8:11]
	v_mfma_f32_16x16x32_bf16 v[62:65], v[122:125], v[198:201], v[62:65]
	v_mfma_f32_16x16x32_bf16 v[38:41], v[130:133], v[198:201], v[38:41]
	v_mfma_f32_16x16x32_bf16 v[58:61], v[122:125], v[208:211], v[58:61]
	v_mfma_f32_16x16x32_bf16 v[34:37], v[130:133], v[208:211], v[34:37]
	v_mfma_f32_16x16x32_bf16 v[4:7], v[122:125], v[216:219], v[4:7]
	v_mfma_f32_16x16x32_bf16 v[0:3], v[130:133], v[216:219], v[0:3]
	v_mfma_f32_16x16x32_bf16 v[12:15], v[126:129], v[194:197], v[12:15]
	v_mfma_f32_16x16x32_bf16 v[8:11], v[134:137], v[194:197], v[8:11]
	v_mfma_f32_16x16x32_bf16 v[62:65], v[126:129], v[202:205], v[62:65]
	v_mfma_f32_16x16x32_bf16 v[38:41], v[134:137], v[202:205], v[38:41]
	v_mfma_f32_16x16x32_bf16 v[58:61], v[126:129], v[212:215], v[58:61]
	v_mfma_f32_16x16x32_bf16 v[34:37], v[134:137], v[212:215], v[34:37]
	v_mfma_f32_16x16x32_bf16 v[4:7], v[126:129], v[220:223], v[4:7]
	v_mfma_f32_16x16x32_bf16 v[0:3], v[134:137], v[220:223], v[0:3]
	s_setprio 0
	s_barrier
	ds_read_b128 v[66:69], v226
	ds_read_b128 v[70:73], v226 offset:1024
	ds_read_b128 v[74:77], v226 offset:2048
	ds_read_b128 v[78:81], v226 offset:3072
	ds_read_b128 v[122:125], v227
	ds_read_b128 v[126:129], v227 offset:1024
	ds_read_b128 v[130:133], v227 offset:2048
	ds_read_b128 v[134:137], v227 offset:3072
	s_mov_b32 m0, s92
	s_nop 0
	global_load_lds_dwordx4 v166, s[54:55]
	s_add_u32 s54, s54, 0x80000
	s_addc_u32 s55, s55, 0
	s_mov_b32 m0, s2
	ds_read_b128 v[188:191], v193 offset:32768
	ds_read_b128 v[194:197], v193 offset:33792
	ds_read_b128 v[198:201], v193 offset:34816
	ds_read_b128 v[202:205], v193 offset:35840
	ds_read_b128 v[208:211], v193 offset:36864
	ds_read_b128 v[212:215], v193 offset:37888
	ds_read_b128 v[216:219], v193 offset:38912
	ds_read_b128 v[220:223], v193 offset:39936
	global_load_lds_dwordx4 v162, s[54:55]
	s_mov_b32 m0, s3
	s_nop 0
	global_load_lds_dwordx4 v166, s[54:55]
	s_add_i32 s54, s63, s1
	s_mov_b32 m0, s54
	s_waitcnt vmcnt(8)
	s_waitcnt lgkmcnt(0)
	s_barrier
; #define PG8_STAGE(bufoff, gbase, voff) do { _Pragma("unroll") for (int _i = 0; _i < 2; ++_i) \
;         __builtin_amdgcn_global_load_lds((const unsigned*)((const char*)(gbase) + (voff)[_i]), (PG8_LAS unsigned*)(lds + (bufoff) + ldsw + _i * 8192), 16, 0, 0); } while (0)
; #define PG8_LDA(dst, b, h) do { _Pragma("unroll") for (int m = 0; m < 4; ++m) _Pragma("unroll") for (int k = 0; k < 2; ++k) dst[m][k] = *(const PG8_LAS bf16x8*)(lds + PG8_SA(b, h) + aoff + m * 2048 + k * 1024); } while (0)
; #define PG8_WAIT_V(n) asm volatile("s_waitcnt vmcnt(" #n ")" ::: "memory")
; template <class Epi, class Sched, bool ALIGN_EPI = false, bool SP2 = false>
; __device__ __forceinline__ void gemm_phase(PG8_LAS unsigned char* lds, const Gemm g, const Sched& S, const Epi& E, const int tid_in) {
;     ...
;         for (int t = 0; t < nt; t += 2) {
;             if constexpr (Epi::KSPLIT > 0) { if (t == Epi::KSPLIT / BK) E.midk(acc, cur, wr, wc, fr, fq); }
;             const bool last = (t == nt - 2);
;             const char* a1 = cA + (size_t)(t + 1) * kstep;
;             const char* a2 = last ? nA : cA + (size_t)(t + 2) * kstep; const char* b2 = last ? nB : cB + (size_t)(t + 2) * kstep;
;             const char* a3 = a2 + kstep; const char* b3 = b2 + kstep;
;             if (last && has_next) S.a_ready(nxt);
;             if constexpr (SP2) {
;             PG8_LDB(B0, 0, 0); PG8_LDB(B1, 0, 1); PG8_SCHED; PG8_LDA(At, 0, 0); PG8_STAGE(PG8_SA(1, 1), a1 + hstep, voffA);
;             PG8_WAIT_V(8); PG8_WAIT_L(0); PG8_BAR; PG8_MMA(0, 0, At, B0); PG8_MMA(0, 1, At, B1); PG8_BAR; PG8_SCHED;
;             PG8_LDA(At, 0, 1); PG8_STAGE(PG8_SB(0, 0), b2, voffB); PG8_STAGE(PG8_SB(0, 1), b2 + hstep, voffB); PG8_STAGE(PG8_SA(0, 0), a2, voffA);
;             PG8_WAIT_V(8); PG8_WAIT_L(0); PG8_BAR; PG8_MMA(1, 0, At, B0); PG8_MMA(1, 1, At, B1); PG8_BAR; PG8_SCHED;
;             PG8_LDB(B0, 1, 0); PG8_LDB(B1, 1, 1); PG8_SCHED; PG8_LDA(At, 1, 0); PG8_STAGE(PG8_SA(0, 1), a2 + hstep, voffA);
;             PG8_WAIT_V(8); PG8_WAIT_L(0); PG8_BAR; PG8_MMA(0, 0, At, B0); PG8_MMA(0, 1, At, B1); PG8_BAR; PG8_SCHED;
;             PG8_LDA(At, 1, 1); PG8_STAGE(PG8_SB(1, 0), b3, voffB); PG8_STAGE(PG8_SB(1, 1), b3 + hstep, voffB); PG8_STAGE(PG8_SA(1, 0), a3, voffA);
;             PG8_WAIT_V(8); PG8_WAIT_L(0); PG8_BAR; PG8_MMA(1, 0, At, B0); PG8_MMA(1, 1, At, B1); PG8_BAR; PG8_SCHED;
	s_setprio 1
	v_mfma_f32_16x16x32_bf16 v[150:153], v[66:69], v[188:191], v[150:153]
	v_mfma_f32_16x16x32_bf16 v[110:113], v[74:77], v[188:191], v[110:113]
	v_mfma_f32_16x16x32_bf16 v[146:149], v[66:69], v[198:201], v[146:149]
	v_mfma_f32_16x16x32_bf16 v[106:109], v[74:77], v[198:201], v[106:109]
	v_mfma_f32_16x16x32_bf16 v[142:145], v[66:69], v[208:211], v[142:145]
	v_mfma_f32_16x16x32_bf16 v[102:105], v[74:77], v[208:211], v[102:105]
	v_mfma_f32_16x16x32_bf16 v[138:141], v[66:69], v[216:219], v[138:141]
	v_mfma_f32_16x16x32_bf16 v[98:101], v[74:77], v[216:219], v[98:101]
	v_mfma_f32_16x16x32_bf16 v[150:153], v[70:73], v[194:197], v[150:153]
	v_mfma_f32_16x16x32_bf16 v[110:113], v[78:81], v[194:197], v[110:113]
	v_mfma_f32_16x16x32_bf16 v[146:149], v[70:73], v[202:205], v[146:149]
	v_mfma_f32_16x16x32_bf16 v[106:109], v[78:81], v[202:205], v[106:109]
	v_mfma_f32_16x16x32_bf16 v[142:145], v[70:73], v[212:215], v[142:145]
	v_mfma_f32_16x16x32_bf16 v[102:105], v[78:81], v[212:215], v[102:105]
	v_mfma_f32_16x16x32_bf16 v[138:141], v[70:73], v[220:223], v[138:141]
	v_mfma_f32_16x16x32_bf16 v[98:101], v[78:81], v[220:223], v[98:101]
	s_setprio 0
	s_setprio 1
	v_mfma_f32_16x16x32_bf16 v[94:97], v[122:125], v[188:191], v[94:97]
	v_mfma_f32_16x16x32_bf16 v[90:93], v[130:133], v[188:191], v[90:93]
	v_mfma_f32_16x16x32_bf16 v[158:161], v[122:125], v[198:201], v[158:161]
	v_mfma_f32_16x16x32_bf16 v[118:121], v[130:133], v[198:201], v[118:121]
	v_mfma_f32_16x16x32_bf16 v[154:157], v[122:125], v[208:211], v[154:157]
	v_mfma_f32_16x16x32_bf16 v[114:117], v[130:133], v[208:211], v[114:117]
	v_mfma_f32_16x16x32_bf16 v[86:89], v[122:125], v[216:219], v[86:89]
	v_mfma_f32_16x16x32_bf16 v[82:85], v[130:133], v[216:219], v[82:85]
	v_mfma_f32_16x16x32_bf16 v[94:97], v[126:129], v[194:197], v[94:97]
	v_mfma_f32_16x16x32_bf16 v[90:93], v[134:137], v[194:197], v[90:93]
	v_mfma_f32_16x16x32_bf16 v[158:161], v[126:129], v[202:205], v[158:161]
	v_mfma_f32_16x16x32_bf16 v[118:121], v[134:137], v[202:205], v[118:121]
	v_mfma_f32_16x16x32_bf16 v[154:157], v[126:129], v[212:215], v[154:157]
	v_mfma_f32_16x16x32_bf16 v[114:117], v[134:137], v[212:215], v[114:117]
	v_mfma_f32_16x16x32_bf16 v[86:89], v[126:129], v[220:223], v[86:89]
	v_mfma_f32_16x16x32_bf16 v[82:85], v[134:137], v[220:223], v[82:85]
	s_setprio 0
	s_barrier
	ds_read_b128 v[188:191], v193 offset:49152
	ds_read_b128 v[194:197], v193 offset:50176
	ds_read_b128 v[198:201], v193 offset:51200
	ds_read_b128 v[202:205], v193 offset:52224
	ds_read_b128 v[208:211], v193 offset:53248
	ds_read_b128 v[212:215], v193 offset:54272
	ds_read_b128 v[216:219], v193 offset:55296
	ds_read_b128 v[220:223], v193 offset:56320
	global_load_lds_dwordx4 v164, s[98:99]
	s_add_i32 m0, s54, 0x2000
	s_add_u32 s52, s52, 0x80080
	s_addc_u32 s53, s53, 0
	s_add_i32 s54, s64, s1
	global_load_lds_dwordx4 v168, s[98:99]
	s_mov_b32 m0, s54
	s_nop 0
	global_load_lds_dwordx4 v164, s[52:53]
	s_add_i32 m0, s54, 0x2000
	s_nop 0
	global_load_lds_dwordx4 v168, s[52:53]
	s_mov_b32 m0, s24
	s_nop 0
	global_load_lds_dwordx4 v162, s[100:101]
	s_add_i32 s62, s62, 2
	s_add_u32 s50, s50, 0x100
	s_addc_u32 s51, s51, 0
	s_add_u32 s60, s60, 0x100
	s_addc_u32 s61, s61, 0
	s_add_u32 s52, s50, 0xfff80080
	s_addc_u32 s53, s51, -1
	s_add_i32 s63, 0, 0x10000
	s_cmp_eq_u32 s62, 28
	s_cselect_b32 s55, s35, s53
	s_cselect_b32 s54, s58, s52
	s_cselect_b32 s53, s31, s61
	s_cselect_b32 s52, s59, s60
	s_add_i32 s66, 0, 0x14000
	s_cmp_gt_u32 s62, 29
	s_waitcnt vmcnt(7)
	s_waitcnt lgkmcnt(0)
	s_barrier
	s_setprio 1
	v_mfma_f32_16x16x32_bf16 v[54:57], v[66:69], v[188:191], v[54:57]
	v_mfma_f32_16x16x32_bf16 v[30:33], v[74:77], v[188:191], v[30:33]
	v_mfma_f32_16x16x32_bf16 v[50:53], v[66:69], v[198:201], v[50:53]
	v_mfma_f32_16x16x32_bf16 v[26:29], v[74:77], v[198:201], v[26:29]
	v_mfma_f32_16x16x32_bf16 v[46:49], v[66:69], v[208:211], v[46:49]
	v_mfma_f32_16x16x32_bf16 v[22:25], v[74:77], v[208:211], v[22:25]
	v_mfma_f32_16x16x32_bf16 v[42:45], v[66:69], v[216:219], v[42:45]
	v_mfma_f32_16x16x32_bf16 v[16:19], v[74:77], v[216:219], v[16:19]
	v_mfma_f32_16x16x32_bf16 v[54:57], v[70:73], v[194:197], v[54:57]
	v_mfma_f32_16x16x32_bf16 v[30:33], v[78:81], v[194:197], v[30:33]
	v_mfma_f32_16x16x32_bf16 v[50:53], v[70:73], v[202:205], v[50:53]
	v_mfma_f32_16x16x32_bf16 v[26:29], v[78:81], v[202:205], v[26:29]
	v_mfma_f32_16x16x32_bf16 v[46:49], v[70:73], v[212:215], v[46:49]
	v_mfma_f32_16x16x32_bf16 v[22:25], v[78:81], v[212:215], v[22:25]
	v_mfma_f32_16x16x32_bf16 v[42:45], v[70:73], v[220:223], v[42:45]
	v_mfma_f32_16x16x32_bf16 v[16:19], v[78:81], v[220:223], v[16:19]
	s_setprio 0
	s_setprio 1
	v_mfma_f32_16x16x32_bf16 v[12:15], v[122:125], v[188:191], v[12:15]
	v_mfma_f32_16x16x32_bf16 v[8:11], v[130:133], v[188:191], v[8:11]
	v_mfma_f32_16x16x32_bf16 v[62:65], v[122:125], v[198:201], v[62:65]
	v_mfma_f32_16x16x32_bf16 v[38:41], v[130:133], v[198:201], v[38:41]
	v_mfma_f32_16x16x32_bf16 v[58:61], v[122:125], v[208:211], v[58:61]
	v_mfma_f32_16x16x32_bf16 v[34:37], v[130:133], v[208:211], v[34:37]
	v_mfma_f32_16x16x32_bf16 v[4:7], v[122:125], v[216:219], v[4:7]
	v_mfma_f32_16x16x32_bf16 v[0:3], v[130:133], v[216:219], v[0:3]
	v_mfma_f32_16x16x32_bf16 v[12:15], v[126:129], v[194:197], v[12:15]
	v_mfma_f32_16x16x32_bf16 v[8:11], v[134:137], v[194:197], v[8:11]
	v_mfma_f32_16x16x32_bf16 v[62:65], v[126:129], v[202:205], v[62:65]
	v_mfma_f32_16x16x32_bf16 v[38:41], v[134:137], v[202:205], v[38:41]
	v_mfma_f32_16x16x32_bf16 v[58:61], v[126:129], v[212:215], v[58:61]
	v_mfma_f32_16x16x32_bf16 v[34:37], v[134:137], v[212:215], v[34:37]
	v_mfma_f32_16x16x32_bf16 v[4:7], v[126:129], v[220:223], v[4:7]
	v_mfma_f32_16x16x32_bf16 v[0:3], v[134:137], v[220:223], v[0:3]
	s_setprio 0
	s_barrier
	s_cbranch_scc0 .LBB0_1157
	s_and_b64 vcc, exec, s[28:29]
	s_cbranch_vccz .LBB0_1160
	s_barrier

; #define PG8_STAGE(bufoff, gbase, voff) do { _Pragma("unroll") for (int _i = 0; _i < 2; ++_i) \
;         __builtin_amdgcn_global_load_lds((const unsigned*)((const char*)(gbase) + (voff)[_i]), (PG8_LAS unsigned*)(lds + (bufoff) + ldsw + _i * 8192), 16, 0, 0); } while (0)
; #define PG8_WAIT_V(n) asm volatile("s_waitcnt vmcnt(" #n ")" ::: "memory")
; template <class Epi, class Sched, bool ALIGN_EPI = false, bool SP2 = false>
; __device__ __forceinline__ void gemm_phase(PG8_LAS unsigned char* lds, const Gemm g, const Sched& S, const Epi& E, const int tid_in) {
;     ...
;     for (;;) {
;         const bool has_next = S.next(ui + 1, nxt);
;         const char* nA = has_next ? (const char*)g.A + (size_t)nxt.pm * tstep : cA; const char* nB = has_next ? (const char*)g.Bt + (size_t)nxt.pn * tstep : cB;
;         for (int t = 0; t < nt; t += 2) {
;             if constexpr (Epi::KSPLIT > 0) { if (t == Epi::KSPLIT / BK) E.midk(acc, cur, wr, wc, fr, fq); }
;             const bool last = (t == nt - 2);
;             const char* a1 = cA + (size_t)(t + 1) * kstep;
;             const char* a2 = last ? nA : cA + (size_t)(t + 2) * kstep; const char* b2 = last ? nB : cB + (size_t)(t + 2) * kstep;
;             const char* a3 = a2 + kstep; const char* b3 = b2 + kstep;
;             if (last && has_next) S.a_ready(nxt);
;             if constexpr (SP2) {
;             PG8_LDB(B0, 0, 0); PG8_LDB(B1, 0, 1); PG8_SCHED; PG8_LDA(At, 0, 0); PG8_STAGE(PG8_SA(1, 1), a1 + hstep, voffA);
;             PG8_WAIT_V(8); PG8_WAIT_L(0); PG8_BAR; PG8_MMA(0, 0, At, B0); PG8_MMA(0, 1, At, B1); PG8_BAR; PG8_SCHED;
;             PG8_LDA(At, 0, 1); PG8_STAGE(PG8_SB(0, 0), b2, voffB); PG8_STAGE(PG8_SB(0, 1), b2 + hstep, voffB); PG8_STAGE(PG8_SA(0, 0), a2, voffA);
;             PG8_WAIT_V(8); PG8_WAIT_L(0); PG8_BAR; PG8_MMA(1, 0, At, B0); PG8_MMA(1, 1, At, B1); PG8_BAR; PG8_SCHED;
;             PG8_LDB(B0, 1, 0); PG8_LDB(B1, 1, 1); PG8_SCHED; PG8_LDA(At, 1, 0); PG8_STAGE(PG8_SA(0, 1), a2 + hstep, voffA);
;             PG8_WAIT_V(8); PG8_WAIT_L(0); PG8_BAR; PG8_MMA(0, 0, At, B0); PG8_MMA(0, 1, At, B1); PG8_BAR; PG8_SCHED;
;             PG8_LDA(At, 1, 1); PG8_STAGE(PG8_SB(1, 0), b3, voffB); PG8_STAGE(PG8_SB(1, 1), b3 + hstep, voffB); PG8_STAGE(PG8_SA(1, 0), a3, voffA);
;             PG8_WAIT_V(8); PG8_WAIT_L(0); PG8_BAR; PG8_MMA(1, 0, At, B0); PG8_MMA(1, 1, At, B1); PG8_BAR; PG8_SCHED;
.LBB0_1304:
	s_add_u32 s54, s30, 0x100
	v_mov_b32_e32 v0, 0
	s_addc_u32 s55, s31, 0
	s_mov_b32 s56, -2
	v_add_u32_e32 v196, 0x10000, v208
	v_add_u32_e32 v197, 0x14000, v208
	v_add_u32_e32 v198, 0x18000, v208
	v_add_u32_e32 v199, 0x1c000, v208
	s_add_u32 s30, s28, 0x100
	s_addc_u32 s31, s29, 0
	s_add_i32 s57, 0, 0x10000
	s_cmpk_eq_i32 s56, 0x54
	s_cselect_b32 s39, s25, s31
	s_cselect_b32 s38, s24, s30
	s_cselect_b32 s35, s27, s55
	s_cselect_b32 s34, s26, s54
	s_add_i32 s58, 0, 0x14000
	s_mov_b32 m0, s47
	s_nop 0
	global_load_lds_dwordx4 v216, s[100:101]
	ds_read_b128 v[78:81], v196
	ds_read_b128 v[86:89], v196 offset:1024
	ds_read_b128 v[94:97], v196 offset:2048
	ds_read_b128 v[102:105], v196 offset:3072
	ds_read_b128 v[118:121], v197
	ds_read_b128 v[126:129], v197 offset:1024
	ds_read_b128 v[134:137], v197 offset:2048
	ds_read_b128 v[142:145], v197 offset:3072
	v_lshl_add_u64 v[194:195], s[28:29], 0, v[222:223]
	s_add_i32 m0, s40, 0xc000
	ds_read_b128 v[154:157], v244
	ds_read_b128 v[158:161], v244 offset:1024
	ds_read_b128 v[162:165], v244 offset:2048
	ds_read_b128 v[166:169], v244 offset:3072
	ds_read_b128 v[170:173], v244 offset:4096
	ds_read_b128 v[182:185], v244 offset:5120
	ds_read_b128 v[186:189], v244 offset:6144
	ds_read_b128 v[190:193], v244 offset:7168
	global_load_lds_dwordx4 v[194:195], off
	v_lshl_add_u64 v[194:195], s[28:29], 0, v[224:225]
	s_add_i32 m0, s40, 0xe000
	s_nop 0
	global_load_lds_dwordx4 v[194:195], off
	s_add_i32 s28, s57, s19
	s_add_u32 s98, s34, 0x80
	s_addc_u32 s99, s35, 0
	s_mov_b32 m0, s28
	s_waitcnt vmcnt(8)
	s_waitcnt lgkmcnt(0)
	s_barrier
	s_setprio 1
	v_mfma_f32_16x16x32_bf16 v[178:181], v[78:81], v[154:157], 0
	v_mfma_f32_16x16x32_bf16 v[174:177], v[94:97], v[154:157], 0
	v_mfma_f32_16x16x32_bf16 v[138:141], v[78:81], v[162:165], 0
	v_mfma_f32_16x16x32_bf16 v[130:133], v[94:97], v[162:165], 0
	v_mfma_f32_16x16x32_bf16 v[110:113], v[78:81], v[170:173], 0
	v_mfma_f32_16x16x32_bf16 v[106:109], v[94:97], v[170:173], 0
	v_mfma_f32_16x16x32_bf16 v[82:85], v[78:81], v[186:189], 0
	v_mfma_f32_16x16x32_bf16 v[74:77], v[94:97], v[186:189], 0
	v_mfma_f32_16x16x32_bf16 v[178:181], v[86:89], v[158:161], v[178:181]
	v_mfma_f32_16x16x32_bf16 v[174:177], v[102:105], v[158:161], v[174:177]
	v_mfma_f32_16x16x32_bf16 v[138:141], v[86:89], v[166:169], v[138:141]
	v_mfma_f32_16x16x32_bf16 v[130:133], v[102:105], v[166:169], v[130:133]
	v_mfma_f32_16x16x32_bf16 v[110:113], v[86:89], v[182:185], v[110:113]
	v_mfma_f32_16x16x32_bf16 v[106:109], v[102:105], v[182:185], v[106:109]
	v_mfma_f32_16x16x32_bf16 v[82:85], v[86:89], v[190:193], v[82:85]
	v_mfma_f32_16x16x32_bf16 v[74:77], v[102:105], v[190:193], v[74:77]
	s_setprio 0
	s_setprio 1
	v_mfma_f32_16x16x32_bf16 v[150:153], v[118:121], v[154:157], 0
	v_mfma_f32_16x16x32_bf16 v[146:149], v[134:137], v[154:157], 0
	v_mfma_f32_16x16x32_bf16 v[122:125], v[118:121], v[162:165], 0
	v_mfma_f32_16x16x32_bf16 v[114:117], v[134:137], v[162:165], 0
	v_mfma_f32_16x16x32_bf16 v[98:101], v[118:121], v[170:173], 0
	v_mfma_f32_16x16x32_bf16 v[90:93], v[134:137], v[170:173], 0
	v_mfma_f32_16x16x32_bf16 v[70:73], v[118:121], v[186:189], 0
	v_mfma_f32_16x16x32_bf16 v[66:69], v[134:137], v[186:189], 0
	v_mfma_f32_16x16x32_bf16 v[150:153], v[126:129], v[158:161], v[150:153]
	v_mfma_f32_16x16x32_bf16 v[146:149], v[142:145], v[158:161], v[146:149]
	v_mfma_f32_16x16x32_bf16 v[122:125], v[126:129], v[166:169], v[122:125]
	v_mfma_f32_16x16x32_bf16 v[114:117], v[142:145], v[166:169], v[114:117]
	v_mfma_f32_16x16x32_bf16 v[98:101], v[126:129], v[182:185], v[98:101]
	v_mfma_f32_16x16x32_bf16 v[90:93], v[142:145], v[182:185], v[90:93]
	v_mfma_f32_16x16x32_bf16 v[70:73], v[126:129], v[190:193], v[70:73]
	v_mfma_f32_16x16x32_bf16 v[66:69], v[142:145], v[190:193], v[66:69]
	s_setprio 0
	s_barrier
	ds_read_b128 v[154:157], v244 offset:16384
	ds_read_b128 v[158:161], v244 offset:17408
	ds_read_b128 v[162:165], v244 offset:18432
	ds_read_b128 v[166:169], v244 offset:19456
	ds_read_b128 v[170:173], v244 offset:20480
	ds_read_b128 v[182:185], v244 offset:21504
	ds_read_b128 v[186:189], v244 offset:22528
	ds_read_b128 v[190:193], v244 offset:23552
	global_load_lds_dwordx4 v218, s[34:35]
	s_add_i32 m0, s28, 0x2000
	s_add_u32 s28, s34, 0x160000
	s_addc_u32 s29, s35, 0
	s_add_i32 s57, s58, s19
	global_load_lds_dwordx4 v214, s[34:35]
	s_mov_b32 m0, s57
	s_add_u32 s100, s38, 0x80
	s_addc_u32 s101, s39, 0
	global_load_lds_dwordx4 v218, s[28:29]
	s_add_i32 m0, s57, 0x2000
	s_nop 0
	global_load_lds_dwordx4 v214, s[28:29]
	s_mov_b32 m0, s40
	s_nop 0
	global_load_lds_dwordx4 v220, s[38:39]
	s_add_i32 s57, 0, 0x18000
	s_add_i32 s58, 0, 0x1c000
	s_waitcnt vmcnt(7)
	s_waitcnt lgkmcnt(0)
	s_barrier
; #define PG8_STAGE(bufoff, gbase, voff) do { _Pragma("unroll") for (int _i = 0; _i < 2; ++_i) \
;         __builtin_amdgcn_global_load_lds((const unsigned*)((const char*)(gbase) + (voff)[_i]), (PG8_LAS unsigned*)(lds + (bufoff) + ldsw + _i * 8192), 16, 0, 0); } while (0)
; #define PG8_LDA(dst, b, h) do { _Pragma("unroll") for (int m = 0; m < 4; ++m) _Pragma("unroll") for (int k = 0; k < 2; ++k) dst[m][k] = *(const PG8_LAS bf16x8*)(lds + PG8_SA(b, h) + aoff + m * 2048 + k * 1024); } while (0)
; #define PG8_LDB(dst, b, h) do { _Pragma("unroll") for (int n = 0; n < 2; ++n) _Pragma("unroll") for (int k = 0; k < 2; ++k) dst[n][k] = *(const PG8_LAS bf16x8*)(lds + PG8_SB(b, h) + boff + n * 2048 + k * 1024); } while (0)
; #define PG8_MMA(ai, bj, At, Bt) do { __builtin_amdgcn_s_setprio(1); _Pragma("unroll") for (int m = 0; m < 4; ++m) _Pragma("unroll") for (int n = 0; n < 2; ++n) _Pragma("unroll") for (int k = 0; k < 2; ++k) \
;         acc[ai][bj][m][n] = __builtin_amdgcn_mfma_f32_16x16x32_bf16(Bt[n][k], At[m][k], acc[ai][bj][m][n], 0, 0, 0); __builtin_amdgcn_s_setprio(0); } while (0)
; template <class Epi, class Sched, bool ALIGN_EPI = false, bool SP2 = false>
; __device__ __forceinline__ void gemm_phase(PG8_LAS unsigned char* lds, const Gemm g, const Sched& S, const Epi& E, const int tid_in) {
;     ...
;             if constexpr (SP2) {
;             PG8_LDB(B0, 0, 0); PG8_LDB(B1, 0, 1); PG8_SCHED; PG8_LDA(At, 0, 0); PG8_STAGE(PG8_SA(1, 1), a1 + hstep, voffA);
;             PG8_WAIT_V(8); PG8_WAIT_L(0); PG8_BAR; PG8_MMA(0, 0, At, B0); PG8_MMA(0, 1, At, B1); PG8_BAR; PG8_SCHED;
;             PG8_LDA(At, 0, 1); PG8_STAGE(PG8_SB(0, 0), b2, voffB); PG8_STAGE(PG8_SB(0, 1), b2 + hstep, voffB); PG8_STAGE(PG8_SA(0, 0), a2, voffA);
;             PG8_WAIT_V(8); PG8_WAIT_L(0); PG8_BAR; PG8_MMA(1, 0, At, B0); PG8_MMA(1, 1, At, B1); PG8_BAR; PG8_SCHED;
;             PG8_LDB(B0, 1, 0); PG8_LDB(B1, 1, 1); PG8_SCHED; PG8_LDA(At, 1, 0); PG8_STAGE(PG8_SA(0, 1), a2 + hstep, voffA);
;             PG8_WAIT_V(8); PG8_WAIT_L(0); PG8_BAR; PG8_MMA(0, 0, At, B0); PG8_MMA(0, 1, At, B1); PG8_BAR; PG8_SCHED;
;             PG8_LDA(At, 1, 1); PG8_STAGE(PG8_SB(1, 0), b3, voffB); PG8_STAGE(PG8_SB(1, 1), b3 + hstep, voffB); PG8_STAGE(PG8_SA(1, 0), a3, voffA);
;             PG8_WAIT_V(8); PG8_WAIT_L(0); PG8_BAR; PG8_MMA(1, 0, At, B0); PG8_MMA(1, 1, At, B1); PG8_BAR; PG8_SCHED;
	s_setprio 1
	v_mfma_f32_16x16x32_bf16 v[62:65], v[78:81], v[154:157], 0
	v_mfma_f32_16x16x32_bf16 v[58:61], v[94:97], v[154:157], 0
	v_mfma_f32_16x16x32_bf16 v[46:49], v[78:81], v[162:165], 0
	v_mfma_f32_16x16x32_bf16 v[42:45], v[94:97], v[162:165], 0
	v_mfma_f32_16x16x32_bf16 v[30:33], v[78:81], v[170:173], 0
	v_mfma_f32_16x16x32_bf16 v[26:29], v[94:97], v[170:173], 0
	v_mfma_f32_16x16x32_bf16 v[12:15], v[78:81], v[186:189], 0
	v_mfma_f32_16x16x32_bf16 v[8:11], v[94:97], v[186:189], 0
	v_mfma_f32_16x16x32_bf16 v[62:65], v[86:89], v[158:161], v[62:65]
	v_mfma_f32_16x16x32_bf16 v[58:61], v[102:105], v[158:161], v[58:61]
	v_mfma_f32_16x16x32_bf16 v[46:49], v[86:89], v[166:169], v[46:49]
	v_mfma_f32_16x16x32_bf16 v[42:45], v[102:105], v[166:169], v[42:45]
	v_mfma_f32_16x16x32_bf16 v[30:33], v[86:89], v[182:185], v[30:33]
	v_mfma_f32_16x16x32_bf16 v[26:29], v[102:105], v[182:185], v[26:29]
	v_mfma_f32_16x16x32_bf16 v[12:15], v[86:89], v[190:193], v[12:15]
	v_mfma_f32_16x16x32_bf16 v[8:11], v[102:105], v[190:193], v[8:11]
	s_setprio 0
	s_setprio 1
	v_mfma_f32_16x16x32_bf16 v[54:57], v[118:121], v[154:157], 0
	v_mfma_f32_16x16x32_bf16 v[50:53], v[134:137], v[154:157], 0
	v_mfma_f32_16x16x32_bf16 v[38:41], v[118:121], v[162:165], 0
	v_mfma_f32_16x16x32_bf16 v[34:37], v[134:137], v[162:165], 0
	v_mfma_f32_16x16x32_bf16 v[22:25], v[118:121], v[170:173], 0
	v_mfma_f32_16x16x32_bf16 v[16:19], v[134:137], v[170:173], 0
	v_mfma_f32_16x16x32_bf16 v[4:7], v[118:121], v[186:189], 0
	v_mfma_f32_16x16x32_bf16 v[0:3], v[134:137], v[186:189], 0
	v_mfma_f32_16x16x32_bf16 v[54:57], v[126:129], v[158:161], v[54:57]
	v_mfma_f32_16x16x32_bf16 v[50:53], v[142:145], v[158:161], v[50:53]
	v_mfma_f32_16x16x32_bf16 v[38:41], v[126:129], v[166:169], v[38:41]
	v_mfma_f32_16x16x32_bf16 v[34:37], v[142:145], v[166:169], v[34:37]
	v_mfma_f32_16x16x32_bf16 v[22:25], v[126:129], v[182:185], v[22:25]
	v_mfma_f32_16x16x32_bf16 v[16:19], v[142:145], v[182:185], v[16:19]
	v_mfma_f32_16x16x32_bf16 v[4:7], v[126:129], v[190:193], v[4:7]
	v_mfma_f32_16x16x32_bf16 v[0:3], v[142:145], v[190:193], v[0:3]
	s_setprio 0
	s_barrier
	ds_read_b128 v[78:81], v198
	ds_read_b128 v[86:89], v198 offset:1024
	ds_read_b128 v[94:97], v198 offset:2048
	ds_read_b128 v[102:105], v198 offset:3072
	ds_read_b128 v[118:121], v199
	ds_read_b128 v[126:129], v199 offset:1024
	ds_read_b128 v[134:137], v199 offset:2048
	ds_read_b128 v[142:145], v199 offset:3072
	s_add_u32 s28, s38, 0x160000
	s_addc_u32 s29, s39, 0
	s_mov_b32 m0, s41
	s_nop 0
	global_load_lds_dwordx4 v216, s[38:39]
	s_mov_b32 m0, s42
	ds_read_b128 v[154:157], v244 offset:32768
	ds_read_b128 v[158:161], v244 offset:33792
	ds_read_b128 v[162:165], v244 offset:34816
	ds_read_b128 v[166:169], v244 offset:35840
	ds_read_b128 v[170:173], v244 offset:36864
	ds_read_b128 v[182:185], v244 offset:37888
	ds_read_b128 v[186:189], v244 offset:38912
	ds_read_b128 v[190:193], v244 offset:39936
	global_load_lds_dwordx4 v220, s[28:29]
	s_mov_b32 m0, s43
	s_nop 0
	global_load_lds_dwordx4 v216, s[28:29]
	s_add_i32 s28, s57, s19
	s_mov_b32 m0, s28
	s_waitcnt vmcnt(8)
	s_waitcnt lgkmcnt(0)
	s_barrier
	s_setprio 1
	v_mfma_f32_16x16x32_bf16 v[178:181], v[78:81], v[154:157], v[178:181]
	v_mfma_f32_16x16x32_bf16 v[174:177], v[94:97], v[154:157], v[174:177]
	v_mfma_f32_16x16x32_bf16 v[138:141], v[78:81], v[162:165], v[138:141]
	v_mfma_f32_16x16x32_bf16 v[130:133], v[94:97], v[162:165], v[130:133]
	v_mfma_f32_16x16x32_bf16 v[110:113], v[78:81], v[170:173], v[110:113]
	v_mfma_f32_16x16x32_bf16 v[106:109], v[94:97], v[170:173], v[106:109]
	v_mfma_f32_16x16x32_bf16 v[82:85], v[78:81], v[186:189], v[82:85]
	v_mfma_f32_16x16x32_bf16 v[74:77], v[94:97], v[186:189], v[74:77]
	v_mfma_f32_16x16x32_bf16 v[178:181], v[86:89], v[158:161], v[178:181]
	v_mfma_f32_16x16x32_bf16 v[174:177], v[102:105], v[158:161], v[174:177]
	v_mfma_f32_16x16x32_bf16 v[138:141], v[86:89], v[166:169], v[138:141]
	v_mfma_f32_16x16x32_bf16 v[130:133], v[102:105], v[166:169], v[130:133]
	v_mfma_f32_16x16x32_bf16 v[110:113], v[86:89], v[182:185], v[110:113]
	v_mfma_f32_16x16x32_bf16 v[106:109], v[102:105], v[182:185], v[106:109]
	v_mfma_f32_16x16x32_bf16 v[82:85], v[86:89], v[190:193], v[82:85]
	v_mfma_f32_16x16x32_bf16 v[74:77], v[102:105], v[190:193], v[74:77]
	s_setprio 0
	s_setprio 1
	v_mfma_f32_16x16x32_bf16 v[150:153], v[118:121], v[154:157], v[150:153]
	v_mfma_f32_16x16x32_bf16 v[146:149], v[134:137], v[154:157], v[146:149]
	v_mfma_f32_16x16x32_bf16 v[122:125], v[118:121], v[162:165], v[122:125]
	v_mfma_f32_16x16x32_bf16 v[114:117], v[134:137], v[162:165], v[114:117]
	v_mfma_f32_16x16x32_bf16 v[98:101], v[118:121], v[170:173], v[98:101]
	v_mfma_f32_16x16x32_bf16 v[90:93], v[134:137], v[170:173], v[90:93]
	v_mfma_f32_16x16x32_bf16 v[70:73], v[118:121], v[186:189], v[70:73]
	v_mfma_f32_16x16x32_bf16 v[66:69], v[134:137], v[186:189], v[66:69]
	v_mfma_f32_16x16x32_bf16 v[150:153], v[126:129], v[158:161], v[150:153]
	v_mfma_f32_16x16x32_bf16 v[146:149], v[142:145], v[158:161], v[146:149]
	v_mfma_f32_16x16x32_bf16 v[122:125], v[126:129], v[166:169], v[122:125]
	v_mfma_f32_16x16x32_bf16 v[114:117], v[142:145], v[166:169], v[114:117]
	v_mfma_f32_16x16x32_bf16 v[98:101], v[126:129], v[182:185], v[98:101]
	v_mfma_f32_16x16x32_bf16 v[90:93], v[142:145], v[182:185], v[90:93]
	v_mfma_f32_16x16x32_bf16 v[70:73], v[126:129], v[190:193], v[70:73]
	v_mfma_f32_16x16x32_bf16 v[66:69], v[142:145], v[190:193], v[66:69]
	s_setprio 0
	s_barrier
; #define PG8_STAGE(bufoff, gbase, voff) do { _Pragma("unroll") for (int _i = 0; _i < 2; ++_i) \
;         __builtin_amdgcn_global_load_lds((const unsigned*)((const char*)(gbase) + (voff)[_i]), (PG8_LAS unsigned*)(lds + (bufoff) + ldsw + _i * 8192), 16, 0, 0); } while (0)
; #define PG8_LDA(dst, b, h) do { _Pragma("unroll") for (int m = 0; m < 4; ++m) _Pragma("unroll") for (int k = 0; k < 2; ++k) dst[m][k] = *(const PG8_LAS bf16x8*)(lds + PG8_SA(b, h) + aoff + m * 2048 + k * 1024); } while (0)
; #define PG8_WAIT_V(n) asm volatile("s_waitcnt vmcnt(" #n ")" ::: "memory")
; template <class Epi, class Sched, bool ALIGN_EPI = false, bool SP2 = false>
; __device__ __forceinline__ void gemm_phase(PG8_LAS unsigned char* lds, const Gemm g, const Sched& S, const Epi& E, const int tid_in) {
;     ...
;         for (int t = 0; t < nt; t += 2) {
;             if constexpr (Epi::KSPLIT > 0) { if (t == Epi::KSPLIT / BK) E.midk(acc, cur, wr, wc, fr, fq); }
;             const bool last = (t == nt - 2);
;             const char* a1 = cA + (size_t)(t + 1) * kstep;
;             const char* a2 = last ? nA : cA + (size_t)(t + 2) * kstep; const char* b2 = last ? nB : cB + (size_t)(t + 2) * kstep;
;             const char* a3 = a2 + kstep; const char* b3 = b2 + kstep;
;             if (last && has_next) S.a_ready(nxt);
;             if constexpr (SP2) {
;             PG8_LDB(B0, 0, 0); PG8_LDB(B1, 0, 1); PG8_SCHED; PG8_LDA(At, 0, 0); PG8_STAGE(PG8_SA(1, 1), a1 + hstep, voffA);
;             PG8_WAIT_V(8); PG8_WAIT_L(0); PG8_BAR; PG8_MMA(0, 0, At, B0); PG8_MMA(0, 1, At, B1); PG8_BAR; PG8_SCHED;
;             PG8_LDA(At, 0, 1); PG8_STAGE(PG8_SB(0, 0), b2, voffB); PG8_STAGE(PG8_SB(0, 1), b2 + hstep, voffB); PG8_STAGE(PG8_SA(0, 0), a2, voffA);
;             PG8_WAIT_V(8); PG8_WAIT_L(0); PG8_BAR; PG8_MMA(1, 0, At, B0); PG8_MMA(1, 1, At, B1); PG8_BAR; PG8_SCHED;
;             PG8_LDB(B0, 1, 0); PG8_LDB(B1, 1, 1); PG8_SCHED; PG8_LDA(At, 1, 0); PG8_STAGE(PG8_SA(0, 1), a2 + hstep, voffA);
;             PG8_WAIT_V(8); PG8_WAIT_L(0); PG8_BAR; PG8_MMA(0, 0, At, B0); PG8_MMA(0, 1, At, B1); PG8_BAR; PG8_SCHED;
;             PG8_LDA(At, 1, 1); PG8_STAGE(PG8_SB(1, 0), b3, voffB); PG8_STAGE(PG8_SB(1, 1), b3 + hstep, voffB); PG8_STAGE(PG8_SA(1, 0), a3, voffA);
;             PG8_WAIT_V(8); PG8_WAIT_L(0); PG8_BAR; PG8_MMA(1, 0, At, B0); PG8_MMA(1, 1, At, B1); PG8_BAR; PG8_SCHED;
	ds_read_b128 v[154:157], v244 offset:49152
	ds_read_b128 v[158:161], v244 offset:50176
	ds_read_b128 v[162:165], v244 offset:51200
	ds_read_b128 v[166:169], v244 offset:52224
	ds_read_b128 v[170:173], v244 offset:53248
	ds_read_b128 v[182:185], v244 offset:54272
	ds_read_b128 v[186:189], v244 offset:55296
	ds_read_b128 v[190:193], v244 offset:56320
	global_load_lds_dwordx4 v218, s[98:99]
	s_add_i32 m0, s28, 0x2000
	s_add_u32 s28, s34, 0x160080
	s_addc_u32 s29, s35, 0
	s_add_i32 s34, s58, s19
	global_load_lds_dwordx4 v214, s[98:99]
	s_mov_b32 m0, s34
	s_nop 0
	global_load_lds_dwordx4 v218, s[28:29]
	s_add_i32 m0, s34, 0x2000
	s_nop 0
	global_load_lds_dwordx4 v214, s[28:29]
	s_mov_b32 m0, s46
	s_nop 0
	global_load_lds_dwordx4 v220, s[100:101]
	s_add_i32 s56, s56, 2
	s_add_u32 s54, s54, 0x100
	s_addc_u32 s55, s55, 0
	s_mov_b64 s[28:29], s[30:31]
	s_add_u32 s30, s28, 0x100
	s_addc_u32 s31, s29, 0
	s_add_i32 s57, 0, 0x10000
	s_cmpk_eq_i32 s56, 0x54
	s_cselect_b32 s39, s25, s31
	s_cselect_b32 s38, s24, s30
	s_cselect_b32 s35, s27, s55
	s_cselect_b32 s34, s26, s54
	s_add_i32 s58, 0, 0x14000
	s_cmpk_gt_u32 s56, 0x55
	s_waitcnt vmcnt(7)
	s_waitcnt lgkmcnt(0)
	s_barrier
	s_setprio 1
	v_mfma_f32_16x16x32_bf16 v[62:65], v[78:81], v[154:157], v[62:65]
	v_mfma_f32_16x16x32_bf16 v[58:61], v[94:97], v[154:157], v[58:61]
	v_mfma_f32_16x16x32_bf16 v[46:49], v[78:81], v[162:165], v[46:49]
	v_mfma_f32_16x16x32_bf16 v[42:45], v[94:97], v[162:165], v[42:45]
	v_mfma_f32_16x16x32_bf16 v[30:33], v[78:81], v[170:173], v[30:33]
	v_mfma_f32_16x16x32_bf16 v[26:29], v[94:97], v[170:173], v[26:29]
	v_mfma_f32_16x16x32_bf16 v[12:15], v[78:81], v[186:189], v[12:15]
	v_mfma_f32_16x16x32_bf16 v[8:11], v[94:97], v[186:189], v[8:11]
	v_mfma_f32_16x16x32_bf16 v[62:65], v[86:89], v[158:161], v[62:65]
	v_mfma_f32_16x16x32_bf16 v[58:61], v[102:105], v[158:161], v[58:61]
	v_mfma_f32_16x16x32_bf16 v[46:49], v[86:89], v[166:169], v[46:49]
	v_mfma_f32_16x16x32_bf16 v[42:45], v[102:105], v[166:169], v[42:45]
	v_mfma_f32_16x16x32_bf16 v[30:33], v[86:89], v[182:185], v[30:33]
	v_mfma_f32_16x16x32_bf16 v[26:29], v[102:105], v[182:185], v[26:29]
	v_mfma_f32_16x16x32_bf16 v[12:15], v[86:89], v[190:193], v[12:15]
	v_mfma_f32_16x16x32_bf16 v[8:11], v[102:105], v[190:193], v[8:11]
	s_setprio 0
	s_setprio 1
	v_mfma_f32_16x16x32_bf16 v[54:57], v[118:121], v[154:157], v[54:57]
	v_mfma_f32_16x16x32_bf16 v[50:53], v[134:137], v[154:157], v[50:53]
	v_mfma_f32_16x16x32_bf16 v[38:41], v[118:121], v[162:165], v[38:41]
	v_mfma_f32_16x16x32_bf16 v[34:37], v[134:137], v[162:165], v[34:37]
	v_mfma_f32_16x16x32_bf16 v[22:25], v[118:121], v[170:173], v[22:25]
	v_mfma_f32_16x16x32_bf16 v[16:19], v[134:137], v[170:173], v[16:19]
	v_mfma_f32_16x16x32_bf16 v[4:7], v[118:121], v[186:189], v[4:7]
	v_mfma_f32_16x16x32_bf16 v[0:3], v[134:137], v[186:189], v[0:3]
	v_mfma_f32_16x16x32_bf16 v[54:57], v[126:129], v[158:161], v[54:57]
	v_mfma_f32_16x16x32_bf16 v[50:53], v[142:145], v[158:161], v[50:53]
	v_mfma_f32_16x16x32_bf16 v[38:41], v[126:129], v[166:169], v[38:41]
	v_mfma_f32_16x16x32_bf16 v[34:37], v[142:145], v[166:169], v[34:37]
	v_mfma_f32_16x16x32_bf16 v[22:25], v[126:129], v[182:185], v[22:25]
	v_mfma_f32_16x16x32_bf16 v[16:19], v[142:145], v[182:185], v[16:19]
	v_mfma_f32_16x16x32_bf16 v[4:7], v[126:129], v[190:193], v[4:7]
	v_mfma_f32_16x16x32_bf16 v[0:3], v[142:145], v[190:193], v[0:3]
	s_setprio 0
	s_barrier
.LBB0_1305:
	s_mov_b32 m0, s47
	s_nop 0
	global_load_lds_dwordx4 v216, s[100:101]
	ds_read_b128 v[78:81], v196
	ds_read_b128 v[86:89], v196 offset:1024
	ds_read_b128 v[94:97], v196 offset:2048
	ds_read_b128 v[102:105], v196 offset:3072
	ds_read_b128 v[118:121], v197
	ds_read_b128 v[126:129], v197 offset:1024
	ds_read_b128 v[134:137], v197 offset:2048
	ds_read_b128 v[142:145], v197 offset:3072
	v_lshl_add_u64 v[194:195], s[28:29], 0, v[222:223]
	s_add_i32 m0, s40, 0xc000
	ds_read_b128 v[154:157], v244
	ds_read_b128 v[158:161], v244 offset:1024
	ds_read_b128 v[162:165], v244 offset:2048
	ds_read_b128 v[166:169], v244 offset:3072
	ds_read_b128 v[170:173], v244 offset:4096
	ds_read_b128 v[182:185], v244 offset:5120
	ds_read_b128 v[186:189], v244 offset:6144
	ds_read_b128 v[190:193], v244 offset:7168
	global_load_lds_dwordx4 v[194:195], off
	v_lshl_add_u64 v[194:195], s[28:29], 0, v[224:225]
	s_add_i32 m0, s40, 0xe000
	s_nop 0
	global_load_lds_dwordx4 v[194:195], off
	s_add_i32 s28, s57, s19
	s_add_u32 s98, s34, 0x80
	s_addc_u32 s99, s35, 0
	s_mov_b32 m0, s28
	s_waitcnt vmcnt(8)
	s_waitcnt lgkmcnt(0)
	s_barrier
; #define PG8_STAGE(bufoff, gbase, voff) do { _Pragma("unroll") for (int _i = 0; _i < 2; ++_i) \
;         __builtin_amdgcn_global_load_lds((const unsigned*)((const char*)(gbase) + (voff)[_i]), (PG8_LAS unsigned*)(lds + (bufoff) + ldsw + _i * 8192), 16, 0, 0); } while (0)
; #define PG8_LDA(dst, b, h) do { _Pragma("unroll") for (int m = 0; m < 4; ++m) _Pragma("unroll") for (int k = 0; k < 2; ++k) dst[m][k] = *(const PG8_LAS bf16x8*)(lds + PG8_SA(b, h) + aoff + m * 2048 + k * 1024); } while (0)
; #define PG8_LDB(dst, b, h) do { _Pragma("unroll") for (int n = 0; n < 2; ++n) _Pragma("unroll") for (int k = 0; k < 2; ++k) dst[n][k] = *(const PG8_LAS bf16x8*)(lds + PG8_SB(b, h) + boff + n * 2048 + k * 1024); } while (0)
; #define PG8_MMA(ai, bj, At, Bt) do { __builtin_amdgcn_s_setprio(1); _Pragma("unroll") for (int m = 0; m < 4; ++m) _Pragma("unroll") for (int n = 0; n < 2; ++n) _Pragma("unroll") for (int k = 0; k < 2; ++k) \
;         acc[ai][bj][m][n] = __builtin_amdgcn_mfma_f32_16x16x32_bf16(Bt[n][k], At[m][k], acc[ai][bj][m][n], 0, 0, 0); __builtin_amdgcn_s_setprio(0); } while (0)
; template <class Epi, class Sched, bool ALIGN_EPI = false, bool SP2 = false>
; __device__ __forceinline__ void gemm_phase(PG8_LAS unsigned char* lds, const Gemm g, const Sched& S, const Epi& E, const int tid_in) {
;     ...
;             if constexpr (SP2) {
;             PG8_LDB(B0, 0, 0); PG8_LDB(B1, 0, 1); PG8_SCHED; PG8_LDA(At, 0, 0); PG8_STAGE(PG8_SA(1, 1), a1 + hstep, voffA);
;             PG8_WAIT_V(8); PG8_WAIT_L(0); PG8_BAR; PG8_MMA(0, 0, At, B0); PG8_MMA(0, 1, At, B1); PG8_BAR; PG8_SCHED;
;             PG8_LDA(At, 0, 1); PG8_STAGE(PG8_SB(0, 0), b2, voffB); PG8_STAGE(PG8_SB(0, 1), b2 + hstep, voffB); PG8_STAGE(PG8_SA(0, 0), a2, voffA);
;             PG8_WAIT_V(8); PG8_WAIT_L(0); PG8_BAR; PG8_MMA(1, 0, At, B0); PG8_MMA(1, 1, At, B1); PG8_BAR; PG8_SCHED;
;             PG8_LDB(B0, 1, 0); PG8_LDB(B1, 1, 1); PG8_SCHED; PG8_LDA(At, 1, 0); PG8_STAGE(PG8_SA(0, 1), a2 + hstep, voffA);
;             PG8_WAIT_V(8); PG8_WAIT_L(0); PG8_BAR; PG8_MMA(0, 0, At, B0); PG8_MMA(0, 1, At, B1); PG8_BAR; PG8_SCHED;
;             PG8_LDA(At, 1, 1); PG8_STAGE(PG8_SB(1, 0), b3, voffB); PG8_STAGE(PG8_SB(1, 1), b3 + hstep, voffB); PG8_STAGE(PG8_SA(1, 0), a3, voffA);
;             PG8_WAIT_V(8); PG8_WAIT_L(0); PG8_BAR; PG8_MMA(1, 0, At, B0); PG8_MMA(1, 1, At, B1); PG8_BAR; PG8_SCHED;
	s_setprio 1
	v_mfma_f32_16x16x32_bf16 v[178:181], v[78:81], v[154:157], v[178:181]
	v_mfma_f32_16x16x32_bf16 v[174:177], v[94:97], v[154:157], v[174:177]
	v_mfma_f32_16x16x32_bf16 v[138:141], v[78:81], v[162:165], v[138:141]
	v_mfma_f32_16x16x32_bf16 v[130:133], v[94:97], v[162:165], v[130:133]
	v_mfma_f32_16x16x32_bf16 v[110:113], v[78:81], v[170:173], v[110:113]
	v_mfma_f32_16x16x32_bf16 v[106:109], v[94:97], v[170:173], v[106:109]
	v_mfma_f32_16x16x32_bf16 v[82:85], v[78:81], v[186:189], v[82:85]
	v_mfma_f32_16x16x32_bf16 v[74:77], v[94:97], v[186:189], v[74:77]
	v_mfma_f32_16x16x32_bf16 v[178:181], v[86:89], v[158:161], v[178:181]
	v_mfma_f32_16x16x32_bf16 v[174:177], v[102:105], v[158:161], v[174:177]
	v_mfma_f32_16x16x32_bf16 v[138:141], v[86:89], v[166:169], v[138:141]
	v_mfma_f32_16x16x32_bf16 v[130:133], v[102:105], v[166:169], v[130:133]
	v_mfma_f32_16x16x32_bf16 v[110:113], v[86:89], v[182:185], v[110:113]
	v_mfma_f32_16x16x32_bf16 v[106:109], v[102:105], v[182:185], v[106:109]
	v_mfma_f32_16x16x32_bf16 v[82:85], v[86:89], v[190:193], v[82:85]
	v_mfma_f32_16x16x32_bf16 v[74:77], v[102:105], v[190:193], v[74:77]
	s_setprio 0
	s_setprio 1
	v_mfma_f32_16x16x32_bf16 v[150:153], v[118:121], v[154:157], v[150:153]
	v_mfma_f32_16x16x32_bf16 v[146:149], v[134:137], v[154:157], v[146:149]
	v_mfma_f32_16x16x32_bf16 v[122:125], v[118:121], v[162:165], v[122:125]
	v_mfma_f32_16x16x32_bf16 v[114:117], v[134:137], v[162:165], v[114:117]
	v_mfma_f32_16x16x32_bf16 v[98:101], v[118:121], v[170:173], v[98:101]
	v_mfma_f32_16x16x32_bf16 v[90:93], v[134:137], v[170:173], v[90:93]
	v_mfma_f32_16x16x32_bf16 v[70:73], v[118:121], v[186:189], v[70:73]
	v_mfma_f32_16x16x32_bf16 v[66:69], v[134:137], v[186:189], v[66:69]
	v_mfma_f32_16x16x32_bf16 v[150:153], v[126:129], v[158:161], v[150:153]
	v_mfma_f32_16x16x32_bf16 v[146:149], v[142:145], v[158:161], v[146:149]
	v_mfma_f32_16x16x32_bf16 v[122:125], v[126:129], v[166:169], v[122:125]
	v_mfma_f32_16x16x32_bf16 v[114:117], v[142:145], v[166:169], v[114:117]
	v_mfma_f32_16x16x32_bf16 v[98:101], v[126:129], v[182:185], v[98:101]
	v_mfma_f32_16x16x32_bf16 v[90:93], v[142:145], v[182:185], v[90:93]
	v_mfma_f32_16x16x32_bf16 v[70:73], v[126:129], v[190:193], v[70:73]
	v_mfma_f32_16x16x32_bf16 v[66:69], v[142:145], v[190:193], v[66:69]
	s_setprio 0
	s_barrier
	ds_read_b128 v[154:157], v244 offset:16384
	ds_read_b128 v[158:161], v244 offset:17408
	ds_read_b128 v[162:165], v244 offset:18432
	ds_read_b128 v[166:169], v244 offset:19456
	ds_read_b128 v[170:173], v244 offset:20480
	ds_read_b128 v[182:185], v244 offset:21504
	ds_read_b128 v[186:189], v244 offset:22528
	ds_read_b128 v[190:193], v244 offset:23552
	global_load_lds_dwordx4 v218, s[34:35]
	s_add_i32 m0, s28, 0x2000
	s_add_u32 s28, s34, 0x160000
	s_addc_u32 s29, s35, 0
	s_add_i32 s57, s58, s19
	global_load_lds_dwordx4 v214, s[34:35]
	s_mov_b32 m0, s57
	s_add_u32 s100, s38, 0x80
	s_addc_u32 s101, s39, 0
	global_load_lds_dwordx4 v218, s[28:29]
	s_add_i32 m0, s57, 0x2000
	s_nop 0
	global_load_lds_dwordx4 v214, s[28:29]
	s_mov_b32 m0, s40
	s_nop 0
	global_load_lds_dwordx4 v220, s[38:39]
	s_add_i32 s57, 0, 0x18000
	s_add_i32 s58, 0, 0x1c000
	s_waitcnt vmcnt(7)
	s_waitcnt lgkmcnt(0)
	s_barrier
	s_setprio 1
	v_mfma_f32_16x16x32_bf16 v[62:65], v[78:81], v[154:157], v[62:65]
	v_mfma_f32_16x16x32_bf16 v[58:61], v[94:97], v[154:157], v[58:61]
	v_mfma_f32_16x16x32_bf16 v[46:49], v[78:81], v[162:165], v[46:49]
	v_mfma_f32_16x16x32_bf16 v[42:45], v[94:97], v[162:165], v[42:45]
	v_mfma_f32_16x16x32_bf16 v[30:33], v[78:81], v[170:173], v[30:33]
	v_mfma_f32_16x16x32_bf16 v[26:29], v[94:97], v[170:173], v[26:29]
	v_mfma_f32_16x16x32_bf16 v[12:15], v[78:81], v[186:189], v[12:15]
	v_mfma_f32_16x16x32_bf16 v[8:11], v[94:97], v[186:189], v[8:11]
	v_mfma_f32_16x16x32_bf16 v[62:65], v[86:89], v[158:161], v[62:65]
	v_mfma_f32_16x16x32_bf16 v[58:61], v[102:105], v[158:161], v[58:61]
	v_mfma_f32_16x16x32_bf16 v[46:49], v[86:89], v[166:169], v[46:49]
	v_mfma_f32_16x16x32_bf16 v[42:45], v[102:105], v[166:169], v[42:45]
	v_mfma_f32_16x16x32_bf16 v[30:33], v[86:89], v[182:185], v[30:33]
	v_mfma_f32_16x16x32_bf16 v[26:29], v[102:105], v[182:185], v[26:29]
	v_mfma_f32_16x16x32_bf16 v[12:15], v[86:89], v[190:193], v[12:15]
	v_mfma_f32_16x16x32_bf16 v[8:11], v[102:105], v[190:193], v[8:11]
	s_setprio 0
	s_setprio 1
	v_mfma_f32_16x16x32_bf16 v[54:57], v[118:121], v[154:157], v[54:57]
	v_mfma_f32_16x16x32_bf16 v[50:53], v[134:137], v[154:157], v[50:53]
	v_mfma_f32_16x16x32_bf16 v[38:41], v[118:121], v[162:165], v[38:41]
	v_mfma_f32_16x16x32_bf16 v[34:37], v[134:137], v[162:165], v[34:37]
	v_mfma_f32_16x16x32_bf16 v[22:25], v[118:121], v[170:173], v[22:25]
	v_mfma_f32_16x16x32_bf16 v[16:19], v[134:137], v[170:173], v[16:19]
	v_mfma_f32_16x16x32_bf16 v[4:7], v[118:121], v[186:189], v[4:7]
	v_mfma_f32_16x16x32_bf16 v[0:3], v[134:137], v[186:189], v[0:3]
	v_mfma_f32_16x16x32_bf16 v[54:57], v[126:129], v[158:161], v[54:57]
	v_mfma_f32_16x16x32_bf16 v[50:53], v[142:145], v[158:161], v[50:53]
	v_mfma_f32_16x16x32_bf16 v[38:41], v[126:129], v[166:169], v[38:41]
	v_mfma_f32_16x16x32_bf16 v[34:37], v[142:145], v[166:169], v[34:37]
	v_mfma_f32_16x16x32_bf16 v[22:25], v[126:129], v[182:185], v[22:25]
	v_mfma_f32_16x16x32_bf16 v[16:19], v[142:145], v[182:185], v[16:19]
	v_mfma_f32_16x16x32_bf16 v[4:7], v[126:129], v[190:193], v[4:7]
	v_mfma_f32_16x16x32_bf16 v[0:3], v[142:145], v[190:193], v[0:3]
	s_setprio 0
	s_barrier
; #define PG8_STAGE(bufoff, gbase, voff) do { _Pragma("unroll") for (int _i = 0; _i < 2; ++_i) \
;         __builtin_amdgcn_global_load_lds((const unsigned*)((const char*)(gbase) + (voff)[_i]), (PG8_LAS unsigned*)(lds + (bufoff) + ldsw + _i * 8192), 16, 0, 0); } while (0)
; #define PG8_LDA(dst, b, h) do { _Pragma("unroll") for (int m = 0; m < 4; ++m) _Pragma("unroll") for (int k = 0; k < 2; ++k) dst[m][k] = *(const PG8_LAS bf16x8*)(lds + PG8_SA(b, h) + aoff + m * 2048 + k * 1024); } while (0)
; #define PG8_WAIT_V(n) asm volatile("s_waitcnt vmcnt(" #n ")" ::: "memory")
; template <class Epi, class Sched, bool ALIGN_EPI = false, bool SP2 = false>
; __device__ __forceinline__ void gemm_phase(PG8_LAS unsigned char* lds, const Gemm g, const Sched& S, const Epi& E, const int tid_in) {
;     ...
;         for (int t = 0; t < nt; t += 2) {
;             if constexpr (Epi::KSPLIT > 0) { if (t == Epi::KSPLIT / BK) E.midk(acc, cur, wr, wc, fr, fq); }
;             const bool last = (t == nt - 2);
;             const char* a1 = cA + (size_t)(t + 1) * kstep;
;             const char* a2 = last ? nA : cA + (size_t)(t + 2) * kstep; const char* b2 = last ? nB : cB + (size_t)(t + 2) * kstep;
;             const char* a3 = a2 + kstep; const char* b3 = b2 + kstep;
;             if (last && has_next) S.a_ready(nxt);
;             if constexpr (SP2) {
;             PG8_LDB(B0, 0, 0); PG8_LDB(B1, 0, 1); PG8_SCHED; PG8_LDA(At, 0, 0); PG8_STAGE(PG8_SA(1, 1), a1 + hstep, voffA);
;             PG8_WAIT_V(8); PG8_WAIT_L(0); PG8_BAR; PG8_MMA(0, 0, At, B0); PG8_MMA(0, 1, At, B1); PG8_BAR; PG8_SCHED;
;             PG8_LDA(At, 0, 1); PG8_STAGE(PG8_SB(0, 0), b2, voffB); PG8_STAGE(PG8_SB(0, 1), b2 + hstep, voffB); PG8_STAGE(PG8_SA(0, 0), a2, voffA);
;             PG8_WAIT_V(8); PG8_WAIT_L(0); PG8_BAR; PG8_MMA(1, 0, At, B0); PG8_MMA(1, 1, At, B1); PG8_BAR; PG8_SCHED;
;             PG8_LDB(B0, 1, 0); PG8_LDB(B1, 1, 1); PG8_SCHED; PG8_LDA(At, 1, 0); PG8_STAGE(PG8_SA(0, 1), a2 + hstep, voffA);
;             PG8_WAIT_V(8); PG8_WAIT_L(0); PG8_BAR; PG8_MMA(0, 0, At, B0); PG8_MMA(0, 1, At, B1); PG8_BAR; PG8_SCHED;
;             PG8_LDA(At, 1, 1); PG8_STAGE(PG8_SB(1, 0), b3, voffB); PG8_STAGE(PG8_SB(1, 1), b3 + hstep, voffB); PG8_STAGE(PG8_SA(1, 0), a3, voffA);
;             PG8_WAIT_V(8); PG8_WAIT_L(0); PG8_BAR; PG8_MMA(1, 0, At, B0); PG8_MMA(1, 1, At, B1); PG8_BAR; PG8_SCHED;
	ds_read_b128 v[78:81], v198
	ds_read_b128 v[86:89], v198 offset:1024
	ds_read_b128 v[94:97], v198 offset:2048
	ds_read_b128 v[102:105], v198 offset:3072
	ds_read_b128 v[118:121], v199
	ds_read_b128 v[126:129], v199 offset:1024
	ds_read_b128 v[134:137], v199 offset:2048
	ds_read_b128 v[142:145], v199 offset:3072
	s_add_u32 s28, s38, 0x160000
	s_addc_u32 s29, s39, 0
	s_mov_b32 m0, s41
	s_nop 0
	global_load_lds_dwordx4 v216, s[38:39]
	s_mov_b32 m0, s42
	ds_read_b128 v[154:157], v244 offset:32768
	ds_read_b128 v[158:161], v244 offset:33792
	ds_read_b128 v[162:165], v244 offset:34816
	ds_read_b128 v[166:169], v244 offset:35840
	ds_read_b128 v[170:173], v244 offset:36864
	ds_read_b128 v[182:185], v244 offset:37888
	ds_read_b128 v[186:189], v244 offset:38912
	ds_read_b128 v[190:193], v244 offset:39936
	global_load_lds_dwordx4 v220, s[28:29]
	s_mov_b32 m0, s43
	s_nop 0
	global_load_lds_dwordx4 v216, s[28:29]
	s_add_i32 s28, s57, s19
	s_mov_b32 m0, s28
	s_waitcnt vmcnt(8)
	s_waitcnt lgkmcnt(0)
	s_barrier
	s_setprio 1
	v_mfma_f32_16x16x32_bf16 v[178:181], v[78:81], v[154:157], v[178:181]
	v_mfma_f32_16x16x32_bf16 v[174:177], v[94:97], v[154:157], v[174:177]
	v_mfma_f32_16x16x32_bf16 v[138:141], v[78:81], v[162:165], v[138:141]
	v_mfma_f32_16x16x32_bf16 v[130:133], v[94:97], v[162:165], v[130:133]
	v_mfma_f32_16x16x32_bf16 v[110:113], v[78:81], v[170:173], v[110:113]
	v_mfma_f32_16x16x32_bf16 v[106:109], v[94:97], v[170:173], v[106:109]
	v_mfma_f32_16x16x32_bf16 v[82:85], v[78:81], v[186:189], v[82:85]
	v_mfma_f32_16x16x32_bf16 v[74:77], v[94:97], v[186:189], v[74:77]
	v_mfma_f32_16x16x32_bf16 v[178:181], v[86:89], v[158:161], v[178:181]
	v_mfma_f32_16x16x32_bf16 v[174:177], v[102:105], v[158:161], v[174:177]
	v_mfma_f32_16x16x32_bf16 v[138:141], v[86:89], v[166:169], v[138:141]
	v_mfma_f32_16x16x32_bf16 v[130:133], v[102:105], v[166:169], v[130:133]
	v_mfma_f32_16x16x32_bf16 v[110:113], v[86:89], v[182:185], v[110:113]
	v_mfma_f32_16x16x32_bf16 v[106:109], v[102:105], v[182:185], v[106:109]
	v_mfma_f32_16x16x32_bf16 v[82:85], v[86:89], v[190:193], v[82:85]
	v_mfma_f32_16x16x32_bf16 v[74:77], v[102:105], v[190:193], v[74:77]
	s_setprio 0
	s_setprio 1
	v_mfma_f32_16x16x32_bf16 v[150:153], v[118:121], v[154:157], v[150:153]
	v_mfma_f32_16x16x32_bf16 v[146:149], v[134:137], v[154:157], v[146:149]
	v_mfma_f32_16x16x32_bf16 v[122:125], v[118:121], v[162:165], v[122:125]
	v_mfma_f32_16x16x32_bf16 v[114:117], v[134:137], v[162:165], v[114:117]
	v_mfma_f32_16x16x32_bf16 v[98:101], v[118:121], v[170:173], v[98:101]
	v_mfma_f32_16x16x32_bf16 v[90:93], v[134:137], v[170:173], v[90:93]
	v_mfma_f32_16x16x32_bf16 v[70:73], v[118:121], v[186:189], v[70:73]
	v_mfma_f32_16x16x32_bf16 v[66:69], v[134:137], v[186:189], v[66:69]
	v_mfma_f32_16x16x32_bf16 v[150:153], v[126:129], v[158:161], v[150:153]
	v_mfma_f32_16x16x32_bf16 v[146:149], v[142:145], v[158:161], v[146:149]
	v_mfma_f32_16x16x32_bf16 v[122:125], v[126:129], v[166:169], v[122:125]
	v_mfma_f32_16x16x32_bf16 v[114:117], v[142:145], v[166:169], v[114:117]
	v_mfma_f32_16x16x32_bf16 v[98:101], v[126:129], v[182:185], v[98:101]
	v_mfma_f32_16x16x32_bf16 v[90:93], v[142:145], v[182:185], v[90:93]
	v_mfma_f32_16x16x32_bf16 v[70:73], v[126:129], v[190:193], v[70:73]
	v_mfma_f32_16x16x32_bf16 v[66:69], v[142:145], v[190:193], v[66:69]
	s_setprio 0
	s_barrier
	ds_read_b128 v[154:157], v244 offset:49152
	ds_read_b128 v[158:161], v244 offset:50176
	ds_read_b128 v[162:165], v244 offset:51200
	ds_read_b128 v[166:169], v244 offset:52224
	ds_read_b128 v[170:173], v244 offset:53248
	ds_read_b128 v[182:185], v244 offset:54272
	ds_read_b128 v[186:189], v244 offset:55296
	ds_read_b128 v[190:193], v244 offset:56320
	global_load_lds_dwordx4 v218, s[98:99]
	s_add_i32 m0, s28, 0x2000
	s_add_u32 s28, s34, 0x160080
	s_addc_u32 s29, s35, 0
	s_add_i32 s34, s58, s19
	global_load_lds_dwordx4 v214, s[98:99]
	s_mov_b32 m0, s34
	s_nop 0
	global_load_lds_dwordx4 v218, s[28:29]
	s_add_i32 m0, s34, 0x2000
	s_nop 0
	global_load_lds_dwordx4 v214, s[28:29]
	s_mov_b32 m0, s46
	s_nop 0
	global_load_lds_dwordx4 v220, s[100:101]
	s_add_i32 s56, s56, 2
	s_add_u32 s54, s54, 0x100
	s_addc_u32 s55, s55, 0
	s_mov_b64 s[28:29], s[30:31]
	s_add_u32 s30, s28, 0x100
	s_addc_u32 s31, s29, 0
	s_add_i32 s57, 0, 0x10000
	s_cmpk_eq_i32 s56, 0x54
	s_cselect_b32 s39, s25, s31
	s_cselect_b32 s38, s24, s30
	s_cselect_b32 s35, s27, s55
	s_cselect_b32 s34, s26, s54
	s_add_i32 s58, 0, 0x14000
	s_cmpk_gt_u32 s56, 0x55
	s_waitcnt vmcnt(7)
	s_waitcnt lgkmcnt(0)
	s_barrier
	s_setprio 1
	v_mfma_f32_16x16x32_bf16 v[62:65], v[78:81], v[154:157], v[62:65]
	v_mfma_f32_16x16x32_bf16 v[58:61], v[94:97], v[154:157], v[58:61]
	v_mfma_f32_16x16x32_bf16 v[46:49], v[78:81], v[162:165], v[46:49]
	v_mfma_f32_16x16x32_bf16 v[42:45], v[94:97], v[162:165], v[42:45]
	v_mfma_f32_16x16x32_bf16 v[30:33], v[78:81], v[170:173], v[30:33]
	v_mfma_f32_16x16x32_bf16 v[26:29], v[94:97], v[170:173], v[26:29]
	v_mfma_f32_16x16x32_bf16 v[12:15], v[78:81], v[186:189], v[12:15]
	v_mfma_f32_16x16x32_bf16 v[8:11], v[94:97], v[186:189], v[8:11]
	v_mfma_f32_16x16x32_bf16 v[62:65], v[86:89], v[158:161], v[62:65]
	v_mfma_f32_16x16x32_bf16 v[58:61], v[102:105], v[158:161], v[58:61]
	v_mfma_f32_16x16x32_bf16 v[46:49], v[86:89], v[166:169], v[46:49]
	v_mfma_f32_16x16x32_bf16 v[42:45], v[102:105], v[166:169], v[42:45]
	v_mfma_f32_16x16x32_bf16 v[30:33], v[86:89], v[182:185], v[30:33]
	v_mfma_f32_16x16x32_bf16 v[26:29], v[102:105], v[182:185], v[26:29]
	v_mfma_f32_16x16x32_bf16 v[12:15], v[86:89], v[190:193], v[12:15]
	v_mfma_f32_16x16x32_bf16 v[8:11], v[102:105], v[190:193], v[8:11]
	s_setprio 0
	s_setprio 1
	v_mfma_f32_16x16x32_bf16 v[54:57], v[118:121], v[154:157], v[54:57]
	v_mfma_f32_16x16x32_bf16 v[50:53], v[134:137], v[154:157], v[50:53]
	v_mfma_f32_16x16x32_bf16 v[38:41], v[118:121], v[162:165], v[38:41]
	v_mfma_f32_16x16x32_bf16 v[34:37], v[134:137], v[162:165], v[34:37]
	v_mfma_f32_16x16x32_bf16 v[22:25], v[118:121], v[170:173], v[22:25]
	v_mfma_f32_16x16x32_bf16 v[16:19], v[134:137], v[170:173], v[16:19]
	v_mfma_f32_16x16x32_bf16 v[4:7], v[118:121], v[186:189], v[4:7]
	v_mfma_f32_16x16x32_bf16 v[0:3], v[134:137], v[186:189], v[0:3]
	v_mfma_f32_16x16x32_bf16 v[54:57], v[126:129], v[158:161], v[54:57]
	v_mfma_f32_16x16x32_bf16 v[50:53], v[142:145], v[158:161], v[50:53]
	v_mfma_f32_16x16x32_bf16 v[38:41], v[126:129], v[166:169], v[38:41]
	v_mfma_f32_16x16x32_bf16 v[34:37], v[142:145], v[166:169], v[34:37]
	v_mfma_f32_16x16x32_bf16 v[22:25], v[126:129], v[182:185], v[22:25]
	v_mfma_f32_16x16x32_bf16 v[16:19], v[142:145], v[182:185], v[16:19]
	v_mfma_f32_16x16x32_bf16 v[4:7], v[126:129], v[190:193], v[4:7]
	v_mfma_f32_16x16x32_bf16 v[0:3], v[142:145], v[190:193], v[0:3]
	s_setprio 0
	s_barrier
	s_cbranch_scc0 .LBB0_1305
	v_mov_b32_e32 v207, 0x7f800000
	s_and_b64 vcc, exec, s[22:23]
	s_cbranch_vccz .LBB0_1308
	s_barrier
